# loop-edge edits: loop-carried updates + exit test moved in front of the iteration's last barrier (15 sites); GU segment head leads with its LDS reads
# baseline (speedup 1.0000x reference)
; #define PG8_STAGE(bufoff, gbase, voff) do { _Pragma("unroll") for (int _i = 0; _i < 2; ++_i) \
;         __builtin_amdgcn_global_load_lds((const unsigned*)((const char*)(gbase) + (voff)[_i]), (LAS unsigned*)(lds + (bufoff) + ldsw + _i * 8192), 16, 0, 0); } while (0)
; #define PG8_LDA(dst, b, h) do { _Pragma("unroll") for (int m = 0; m < 4; ++m) _Pragma("unroll") for (int k = 0; k < 2; ++k) dst[m][k] = *(const LAS bf16x8*)(lds + PG8_SA(b, h) + aoff + m * 2048 + k * 1024); } while (0)
; #define PG8_LDB(dst, b, h) do { _Pragma("unroll") for (int n = 0; n < 2; ++n) _Pragma("unroll") for (int k = 0; k < 2; ++k) dst[n][k] = *(const LAS bf16x8*)(lds + PG8_SB(b, h) + boff + n * 2048 + k * 1024); } while (0)
; #define PG8_WAIT_V(n) asm volatile("s_waitcnt vmcnt(" #n ")" ::: "memory")
; #define PG8_BAR __builtin_amdgcn_s_barrier()
; template <class Epi, bool ALIGN_EPI>
; __device__ __forceinline__ void gemm_phase(LAS unsigned char* lds, const Gemm g, const StaticOrder& S, const Epi& E, const int tid) {
;     ...
;         for (int t = 0; t < nt; t += 2) {
;             const bool last = (t == nt - 2);
;             const char* a1 = cA + (size_t)(t + 1) * kstep;
;             const char* a2 = last ? nA : cA + (size_t)(t + 2) * kstep; const char* b2 = last ? nB : cB + (size_t)(t + 2) * kstep;
;             const char* a3 = a2 + kstep; const char* b3 = b2 + kstep;
;             PG8_LDB(B0, 0, 0); PG8_LDB(B1, 0, 1); PG8_SCHED; PG8_LDA(At, 0, 0); PG8_STAGE(PG8_SA(1, 1), a1 + hA, voffA);
;             PG8_WAIT_V(8); PG8_WAIT_L(0); PG8_BAR; PG8_MMA(0, 0, At, B0); PG8_MMA(0, 1, At, B1); PG8_BAR; PG8_SCHED;
;             PG8_LDA(At, 0, 1); PG8_STAGE(PG8_SB(0, 0), b2, voffB); PG8_STAGE(PG8_SB(0, 1), b2 + hB, voffB); PG8_STAGE(PG8_SA(0, 0), a2, voffA);
;             PG8_WAIT_V(8); PG8_WAIT_L(0); PG8_BAR; PG8_MMA(1, 0, At, B0); PG8_MMA(1, 1, At, B1); PG8_BAR; PG8_SCHED;
;             PG8_LDB(B0, 1, 0); PG8_LDB(B1, 1, 1); PG8_SCHED; PG8_LDA(At, 1, 0); PG8_STAGE(PG8_SA(0, 1), a2 + hA, voffA);
;             PG8_WAIT_V(8); PG8_WAIT_L(0); PG8_BAR; PG8_MMA(0, 0, At, B0); PG8_MMA(0, 1, At, B1); PG8_BAR; PG8_SCHED;
;             PG8_LDA(At, 1, 1); PG8_STAGE(PG8_SB(1, 0), b3, voffB); PG8_STAGE(PG8_SB(1, 1), b3 + hB, voffB); PG8_STAGE(PG8_SA(1, 0), a3, voffA);
;             PG8_WAIT_V(8); PG8_WAIT_L(0); PG8_BAR; PG8_MMA(1, 0, At, B0); PG8_MMA(1, 1, At, B1); PG8_BAR; PG8_SCHED;
.LBB0_234:
	s_andn2_b64 vcc, exec, s[36:37]
	s_waitcnt lgkmcnt(0)
	s_cbranch_vccnz .LBB0_238
	s_add_u32 s12, s46, 0x100
	v_lshl_add_u64 v[128:129], v[128:129], 0, s[92:93]
	s_addc_u32 s13, s47, 0
	s_mov_b32 s46, 0
	s_add_i32 s47, s46, 2
	s_cmp_eq_u32 s60, s46
	s_cselect_b64 vcc, -1, 0
	s_cselect_b32 s71, s15, s13
	s_cselect_b32 s70, s14, s12
	s_add_i32 s46, 0, 0x14000
	v_lshl_add_u64 v[130:131], v[128:129], 0, s[92:93]
	v_add_u32_e32 v142, s33, v218
	v_add_u32_e32 v166, s46, v218
	v_cndmask_b32_e32 v159, v131, v165, vcc
	v_cndmask_b32_e32 v158, v130, v164, vcc
	ds_read_b128 v[130:133], v142
	ds_read_b128 v[134:137], v142 offset:1024
	ds_read_b128 v[138:141], v142 offset:2048
	ds_read_b128 v[142:145], v142 offset:3072
	ds_read_b128 v[146:149], v166
	ds_read_b128 v[150:153], v166 offset:1024
	ds_read_b128 v[154:157], v166 offset:2048
	ds_read_b128 v[186:189], v166 offset:3072
	v_lshl_add_u64 v[166:167], v[128:129], 0, v[160:161]
	s_add_i32 m0, s53, 0xc000
	ds_read_b128 v[190:193], v219
	ds_read_b128 v[194:197], v219 offset:1024
	ds_read_b128 v[198:201], v219 offset:2048
	ds_read_b128 v[202:205], v219 offset:3072
	ds_read_b128 v[206:209], v219 offset:4096
	ds_read_b128 v[210:213], v219 offset:5120
	ds_read_b128 v[240:243], v219 offset:6144
	ds_read_b128 v[244:247], v219 offset:7168
	global_load_lds_dwordx4 v[166:167], off
	v_lshl_add_u64 v[166:167], v[128:129], 0, v[162:163]
	s_add_i32 m0, s53, 0xe000
	s_nop 0
	global_load_lds_dwordx4 v[166:167], off
	s_waitcnt vmcnt(8)
	s_waitcnt lgkmcnt(0)
	s_barrier
	s_setprio 1
	s_waitcnt lgkmcnt(0)
	v_mfma_f32_16x16x32_bf16 v[120:123], v[130:133], v[190:193], 0
	v_mfma_f32_16x16x32_bf16 v[124:127], v[138:141], v[190:193], 0
	v_mfma_f32_16x16x32_bf16 v[108:111], v[130:133], v[198:201], 0
	v_mfma_f32_16x16x32_bf16 v[104:107], v[138:141], v[198:201], 0
	v_mfma_f32_16x16x32_bf16 v[92:95], v[130:133], v[206:209], 0
	v_mfma_f32_16x16x32_bf16 v[88:91], v[138:141], v[206:209], 0
	v_mfma_f32_16x16x32_bf16 v[76:79], v[130:133], v[240:243], 0
	v_mfma_f32_16x16x32_bf16 v[72:75], v[138:141], v[240:243], 0
	v_mfma_f32_16x16x32_bf16 v[120:123], v[134:137], v[194:197], v[120:123]
	v_mfma_f32_16x16x32_bf16 v[124:127], v[142:145], v[194:197], v[124:127]
	v_mfma_f32_16x16x32_bf16 v[108:111], v[134:137], v[202:205], v[108:111]
	v_mfma_f32_16x16x32_bf16 v[104:107], v[142:145], v[202:205], v[104:107]
	v_mfma_f32_16x16x32_bf16 v[92:95], v[134:137], v[210:213], v[92:95]
	v_mfma_f32_16x16x32_bf16 v[88:91], v[142:145], v[210:213], v[88:91]
	v_mfma_f32_16x16x32_bf16 v[76:79], v[134:137], v[244:247], v[76:79]
	v_mfma_f32_16x16x32_bf16 v[72:75], v[142:145], v[244:247], v[72:75]
	s_setprio 0
	s_setprio 1
	v_mfma_f32_16x16x32_bf16 v[116:119], v[146:149], v[190:193], 0
	v_mfma_f32_16x16x32_bf16 v[112:115], v[154:157], v[190:193], 0
	v_mfma_f32_16x16x32_bf16 v[100:103], v[146:149], v[198:201], 0
	v_mfma_f32_16x16x32_bf16 v[96:99], v[154:157], v[198:201], 0
	v_mfma_f32_16x16x32_bf16 v[84:87], v[146:149], v[206:209], 0
	v_mfma_f32_16x16x32_bf16 v[80:83], v[154:157], v[206:209], 0
	v_mfma_f32_16x16x32_bf16 v[68:71], v[146:149], v[240:243], 0
	v_mfma_f32_16x16x32_bf16 v[64:67], v[154:157], v[240:243], 0
	v_mfma_f32_16x16x32_bf16 v[116:119], v[150:153], v[194:197], v[116:119]
	v_mfma_f32_16x16x32_bf16 v[112:115], v[186:189], v[194:197], v[112:115]
	v_mfma_f32_16x16x32_bf16 v[100:103], v[150:153], v[202:205], v[100:103]
	v_mfma_f32_16x16x32_bf16 v[96:99], v[186:189], v[202:205], v[96:99]
	v_mfma_f32_16x16x32_bf16 v[84:87], v[150:153], v[210:213], v[84:87]
	v_mfma_f32_16x16x32_bf16 v[80:83], v[186:189], v[210:213], v[80:83]
	v_mfma_f32_16x16x32_bf16 v[68:71], v[150:153], v[244:247], v[68:71]
	v_mfma_f32_16x16x32_bf16 v[64:67], v[186:189], v[244:247], v[64:67]
	s_setprio 0
	s_barrier
	s_add_i32 s72, s33, s52
	v_lshl_add_u64 v[166:167], s[70:71], 0, v[180:181]
	s_mov_b32 m0, s72
	ds_read_b128 v[190:193], v219 offset:16384
	ds_read_b128 v[194:197], v219 offset:17408
	ds_read_b128 v[198:201], v219 offset:18432
	ds_read_b128 v[202:205], v219 offset:19456
	ds_read_b128 v[206:209], v219 offset:20480
	ds_read_b128 v[210:213], v219 offset:21504
	ds_read_b128 v[240:243], v219 offset:22528
	ds_read_b128 v[244:247], v219 offset:23552
	global_load_lds_dwordx4 v[166:167], off
	s_add_i32 m0, s72, 0x2000
	v_lshl_add_u64 v[214:215], s[70:71], 0, v[184:185]
	s_add_u32 s70, s70, s49
	s_addc_u32 s71, s71, 0
	s_add_i32 s46, s46, s52
	global_load_lds_dwordx4 v[214:215], off
	v_lshl_add_u64 v[220:221], s[70:71], 0, v[180:181]
	s_mov_b32 m0, s46
	v_lshl_add_u64 v[226:227], s[70:71], 0, v[184:185]
	global_load_lds_dwordx4 v[220:221], off
	s_add_i32 m0, s46, 0x2000
	v_lshl_add_u64 v[248:249], v[158:159], 0, v[178:179]
	global_load_lds_dwordx4 v[226:227], off
	s_mov_b32 m0, s53
	v_lshl_add_u64 v[250:251], v[158:159], 0, v[182:183]
	global_load_lds_dwordx4 v[248:249], off
	s_mov_b32 m0, s54
	s_nop 0
	global_load_lds_dwordx4 v[250:251], off
	s_waitcnt vmcnt(8)
	s_waitcnt lgkmcnt(0)
	s_barrier
; #define PG8_STAGE(bufoff, gbase, voff) do { _Pragma("unroll") for (int _i = 0; _i < 2; ++_i) \
;         __builtin_amdgcn_global_load_lds((const unsigned*)((const char*)(gbase) + (voff)[_i]), (LAS unsigned*)(lds + (bufoff) + ldsw + _i * 8192), 16, 0, 0); } while (0)
; #define PG8_LDA(dst, b, h) do { _Pragma("unroll") for (int m = 0; m < 4; ++m) _Pragma("unroll") for (int k = 0; k < 2; ++k) dst[m][k] = *(const LAS bf16x8*)(lds + PG8_SA(b, h) + aoff + m * 2048 + k * 1024); } while (0)
; #define PG8_LDB(dst, b, h) do { _Pragma("unroll") for (int n = 0; n < 2; ++n) _Pragma("unroll") for (int k = 0; k < 2; ++k) dst[n][k] = *(const LAS bf16x8*)(lds + PG8_SB(b, h) + boff + n * 2048 + k * 1024); } while (0)
; #define PG8_MMA(ai, bj, At, Bt) do { __builtin_amdgcn_s_setprio(1); _Pragma("unroll") for (int k = 0; k < 2; ++k) _Pragma("unroll") for (int m = 0; m < 4; ++m) _Pragma("unroll") for (int n = 0; n < 2; ++n) \
;         acc[ai][bj][m][n] = __builtin_amdgcn_mfma_f32_16x16x32_bf16(Bt[n][k], At[m][k], acc[ai][bj][m][n], 0, 0, 0); __builtin_amdgcn_s_setprio(0); } while (0)
; #define PG8_WAIT_V(n) asm volatile("s_waitcnt vmcnt(" #n ")" ::: "memory")
; #define PG8_WAIT_L(n) asm volatile("s_waitcnt lgkmcnt(" #n ")" ::: "memory")
; #define PG8_BAR __builtin_amdgcn_s_barrier()
; #define PG8_SCHED __builtin_amdgcn_sched_barrier(0)
; template <class Epi, bool ALIGN_EPI>
; __device__ __forceinline__ void gemm_phase(LAS unsigned char* lds, const Gemm g, const StaticOrder& S, const Epi& E, const int tid) {
;     ...
;             PG8_WAIT_V(8); PG8_WAIT_L(0); PG8_BAR; PG8_MMA(1, 0, At, B0); PG8_MMA(1, 1, At, B1); PG8_BAR; PG8_SCHED;
;             PG8_LDB(B0, 1, 0); PG8_LDB(B1, 1, 1); PG8_SCHED; PG8_LDA(At, 1, 0); PG8_STAGE(PG8_SA(0, 1), a2 + hA, voffA);
;             PG8_WAIT_V(8); PG8_WAIT_L(0); PG8_BAR; PG8_MMA(0, 0, At, B0); PG8_MMA(0, 1, At, B1); PG8_BAR; PG8_SCHED;
;             PG8_LDA(At, 1, 1); PG8_STAGE(PG8_SB(1, 0), b3, voffB); PG8_STAGE(PG8_SB(1, 1), b3 + hB, voffB); PG8_STAGE(PG8_SA(1, 0), a3, voffA);
;             PG8_WAIT_V(8); PG8_WAIT_L(0); PG8_BAR; PG8_MMA(1, 0, At, B0); PG8_MMA(1, 1, At, B1); PG8_BAR; PG8_SCHED;
	s_setprio 1
	s_waitcnt lgkmcnt(0)
	v_mfma_f32_16x16x32_bf16 v[60:63], v[130:133], v[190:193], 0
	v_mfma_f32_16x16x32_bf16 v[56:59], v[138:141], v[190:193], 0
	v_mfma_f32_16x16x32_bf16 v[44:47], v[130:133], v[198:201], 0
	v_mfma_f32_16x16x32_bf16 v[40:43], v[138:141], v[198:201], 0
	v_mfma_f32_16x16x32_bf16 v[28:31], v[130:133], v[206:209], 0
	v_mfma_f32_16x16x32_bf16 v[24:27], v[138:141], v[206:209], 0
	v_mfma_f32_16x16x32_bf16 v[12:15], v[130:133], v[240:243], 0
	v_mfma_f32_16x16x32_bf16 v[8:11], v[138:141], v[240:243], 0
	v_mfma_f32_16x16x32_bf16 v[60:63], v[134:137], v[194:197], v[60:63]
	v_mfma_f32_16x16x32_bf16 v[56:59], v[142:145], v[194:197], v[56:59]
	v_mfma_f32_16x16x32_bf16 v[44:47], v[134:137], v[202:205], v[44:47]
	v_mfma_f32_16x16x32_bf16 v[40:43], v[142:145], v[202:205], v[40:43]
	v_mfma_f32_16x16x32_bf16 v[28:31], v[134:137], v[210:213], v[28:31]
	v_mfma_f32_16x16x32_bf16 v[24:27], v[142:145], v[210:213], v[24:27]
	v_mfma_f32_16x16x32_bf16 v[12:15], v[134:137], v[244:247], v[12:15]
	v_mfma_f32_16x16x32_bf16 v[8:11], v[142:145], v[244:247], v[8:11]
	s_setprio 0
	s_setprio 1
	v_mfma_f32_16x16x32_bf16 v[52:55], v[146:149], v[190:193], 0
	v_mfma_f32_16x16x32_bf16 v[48:51], v[154:157], v[190:193], 0
	v_mfma_f32_16x16x32_bf16 v[36:39], v[146:149], v[198:201], 0
	v_mfma_f32_16x16x32_bf16 v[32:35], v[154:157], v[198:201], 0
	v_mfma_f32_16x16x32_bf16 v[20:23], v[146:149], v[206:209], 0
	v_mfma_f32_16x16x32_bf16 v[16:19], v[154:157], v[206:209], 0
	v_mfma_f32_16x16x32_bf16 v[4:7], v[146:149], v[240:243], 0
	v_mfma_f32_16x16x32_bf16 v[0:3], v[154:157], v[240:243], 0
	v_mfma_f32_16x16x32_bf16 v[52:55], v[150:153], v[194:197], v[52:55]
	v_mfma_f32_16x16x32_bf16 v[48:51], v[186:189], v[194:197], v[48:51]
	v_mfma_f32_16x16x32_bf16 v[36:39], v[150:153], v[202:205], v[36:39]
	v_mfma_f32_16x16x32_bf16 v[32:35], v[186:189], v[202:205], v[32:35]
	v_mfma_f32_16x16x32_bf16 v[20:23], v[150:153], v[210:213], v[20:23]
	v_mfma_f32_16x16x32_bf16 v[16:19], v[186:189], v[210:213], v[16:19]
	v_mfma_f32_16x16x32_bf16 v[4:7], v[150:153], v[244:247], v[4:7]
	v_mfma_f32_16x16x32_bf16 v[0:3], v[186:189], v[244:247], v[0:3]
	s_setprio 0
	s_barrier
	s_add_i32 s46, 0, 0x18000
	s_add_i32 s70, 0, 0x1c000
	v_add_u32_e32 v142, s46, v218
	v_add_u32_e32 v168, s70, v218
	ds_read_b128 v[130:133], v142
	ds_read_b128 v[134:137], v142 offset:1024
	ds_read_b128 v[138:141], v142 offset:2048
	ds_read_b128 v[142:145], v142 offset:3072
	ds_read_b128 v[146:149], v168
	ds_read_b128 v[150:153], v168 offset:1024
	ds_read_b128 v[154:157], v168 offset:2048
	ds_read_b128 v[186:189], v168 offset:3072
	v_lshl_add_u64 v[158:159], v[158:159], 0, s[94:95]
	s_mov_b32 m0, s55
	v_lshl_add_u64 v[252:253], v[158:159], 0, v[178:179]
	ds_read_b128 v[190:193], v219 offset:32768
	ds_read_b128 v[194:197], v219 offset:33792
	ds_read_b128 v[198:201], v219 offset:34816
	ds_read_b128 v[202:205], v219 offset:35840
	ds_read_b128 v[206:209], v219 offset:36864
	ds_read_b128 v[210:213], v219 offset:37888
	ds_read_b128 v[240:243], v219 offset:38912
	ds_read_b128 v[244:247], v219 offset:39936
	global_load_lds_dwordx4 v[252:253], off
	v_lshl_add_u64 v[158:159], v[158:159], 0, v[182:183]
	s_mov_b32 m0, s56
	s_nop 0
	global_load_lds_dwordx4 v[158:159], off
	s_waitcnt vmcnt(8)
	s_waitcnt lgkmcnt(0)
	s_barrier
	s_setprio 1
	s_waitcnt lgkmcnt(0)
	v_mfma_f32_16x16x32_bf16 v[120:123], v[130:133], v[190:193], v[120:123]
	v_mfma_f32_16x16x32_bf16 v[124:127], v[138:141], v[190:193], v[124:127]
	v_mfma_f32_16x16x32_bf16 v[108:111], v[130:133], v[198:201], v[108:111]
	v_mfma_f32_16x16x32_bf16 v[104:107], v[138:141], v[198:201], v[104:107]
	v_mfma_f32_16x16x32_bf16 v[92:95], v[130:133], v[206:209], v[92:95]
	v_mfma_f32_16x16x32_bf16 v[88:91], v[138:141], v[206:209], v[88:91]
	v_mfma_f32_16x16x32_bf16 v[76:79], v[130:133], v[240:243], v[76:79]
	v_mfma_f32_16x16x32_bf16 v[72:75], v[138:141], v[240:243], v[72:75]
	v_mfma_f32_16x16x32_bf16 v[120:123], v[134:137], v[194:197], v[120:123]
	v_mfma_f32_16x16x32_bf16 v[124:127], v[142:145], v[194:197], v[124:127]
	v_mfma_f32_16x16x32_bf16 v[108:111], v[134:137], v[202:205], v[108:111]
	v_mfma_f32_16x16x32_bf16 v[104:107], v[142:145], v[202:205], v[104:107]
	v_mfma_f32_16x16x32_bf16 v[92:95], v[134:137], v[210:213], v[92:95]
	v_mfma_f32_16x16x32_bf16 v[88:91], v[142:145], v[210:213], v[88:91]
	v_mfma_f32_16x16x32_bf16 v[76:79], v[134:137], v[244:247], v[76:79]
	v_mfma_f32_16x16x32_bf16 v[72:75], v[142:145], v[244:247], v[72:75]
	s_setprio 0
	s_setprio 1
	v_mfma_f32_16x16x32_bf16 v[116:119], v[146:149], v[190:193], v[116:119]
	v_mfma_f32_16x16x32_bf16 v[112:115], v[154:157], v[190:193], v[112:115]
	v_mfma_f32_16x16x32_bf16 v[100:103], v[146:149], v[198:201], v[100:103]
	v_mfma_f32_16x16x32_bf16 v[96:99], v[154:157], v[198:201], v[96:99]
	v_mfma_f32_16x16x32_bf16 v[84:87], v[146:149], v[206:209], v[84:87]
	v_mfma_f32_16x16x32_bf16 v[80:83], v[154:157], v[206:209], v[80:83]
	v_mfma_f32_16x16x32_bf16 v[68:71], v[146:149], v[240:243], v[68:71]
	v_mfma_f32_16x16x32_bf16 v[64:67], v[154:157], v[240:243], v[64:67]
	v_mfma_f32_16x16x32_bf16 v[116:119], v[150:153], v[194:197], v[116:119]
	v_mfma_f32_16x16x32_bf16 v[112:115], v[186:189], v[194:197], v[112:115]
	v_mfma_f32_16x16x32_bf16 v[100:103], v[150:153], v[202:205], v[100:103]
	v_mfma_f32_16x16x32_bf16 v[96:99], v[186:189], v[202:205], v[96:99]
	v_mfma_f32_16x16x32_bf16 v[84:87], v[150:153], v[210:213], v[84:87]
	v_mfma_f32_16x16x32_bf16 v[80:83], v[186:189], v[210:213], v[80:83]
	v_mfma_f32_16x16x32_bf16 v[68:71], v[150:153], v[244:247], v[68:71]
	v_mfma_f32_16x16x32_bf16 v[64:67], v[186:189], v[244:247], v[64:67]
	s_setprio 0
	s_barrier
; #define PG8_STAGE(bufoff, gbase, voff) do { _Pragma("unroll") for (int _i = 0; _i < 2; ++_i) \
;         __builtin_amdgcn_global_load_lds((const unsigned*)((const char*)(gbase) + (voff)[_i]), (LAS unsigned*)(lds + (bufoff) + ldsw + _i * 8192), 16, 0, 0); } while (0)
; #define PG8_LDA(dst, b, h) do { _Pragma("unroll") for (int m = 0; m < 4; ++m) _Pragma("unroll") for (int k = 0; k < 2; ++k) dst[m][k] = *(const LAS bf16x8*)(lds + PG8_SA(b, h) + aoff + m * 2048 + k * 1024); } while (0)
; #define PG8_LDB(dst, b, h) do { _Pragma("unroll") for (int n = 0; n < 2; ++n) _Pragma("unroll") for (int k = 0; k < 2; ++k) dst[n][k] = *(const LAS bf16x8*)(lds + PG8_SB(b, h) + boff + n * 2048 + k * 1024); } while (0)
; #define PG8_MMA(ai, bj, At, Bt) do { __builtin_amdgcn_s_setprio(1); _Pragma("unroll") for (int k = 0; k < 2; ++k) _Pragma("unroll") for (int m = 0; m < 4; ++m) _Pragma("unroll") for (int n = 0; n < 2; ++n) \
;         acc[ai][bj][m][n] = __builtin_amdgcn_mfma_f32_16x16x32_bf16(Bt[n][k], At[m][k], acc[ai][bj][m][n], 0, 0, 0); __builtin_amdgcn_s_setprio(0); } while (0)
; template <class Epi, bool ALIGN_EPI>
; __device__ __forceinline__ void gemm_phase(LAS unsigned char* lds, const Gemm g, const StaticOrder& S, const Epi& E, const int tid) {
;     ...
;         for (int t = 0; t < nt; t += 2) {
;             const bool last = (t == nt - 2);
;             const char* a1 = cA + (size_t)(t + 1) * kstep;
;             const char* a2 = last ? nA : cA + (size_t)(t + 2) * kstep; const char* b2 = last ? nB : cB + (size_t)(t + 2) * kstep;
;             const char* a3 = a2 + kstep; const char* b3 = b2 + kstep;
;             PG8_LDB(B0, 0, 0); PG8_LDB(B1, 0, 1); PG8_SCHED; PG8_LDA(At, 0, 0); PG8_STAGE(PG8_SA(1, 1), a1 + hA, voffA);
;             PG8_WAIT_V(8); PG8_WAIT_L(0); PG8_BAR; PG8_MMA(0, 0, At, B0); PG8_MMA(0, 1, At, B1); PG8_BAR; PG8_SCHED;
;             PG8_LDA(At, 0, 1); PG8_STAGE(PG8_SB(0, 0), b2, voffB); PG8_STAGE(PG8_SB(0, 1), b2 + hB, voffB); PG8_STAGE(PG8_SA(0, 0), a2, voffA);
;     ...
;             PG8_WAIT_V(8); PG8_WAIT_L(0); PG8_BAR; PG8_MMA(0, 0, At, B0); PG8_MMA(0, 1, At, B1); PG8_BAR; PG8_SCHED;
;             PG8_LDA(At, 1, 1); PG8_STAGE(PG8_SB(1, 0), b3, voffB); PG8_STAGE(PG8_SB(1, 1), b3 + hB, voffB); PG8_STAGE(PG8_SA(1, 0), a3, voffA);
;             PG8_WAIT_V(8); PG8_WAIT_L(0); PG8_BAR; PG8_MMA(1, 0, At, B0); PG8_MMA(1, 1, At, B1); PG8_BAR; PG8_SCHED;
;         }
	s_add_i32 s46, s46, s52
	v_lshl_add_u64 v[158:159], v[166:167], 0, s[92:93]
	s_mov_b32 m0, s46
	ds_read_b128 v[190:193], v219 offset:49152
	ds_read_b128 v[194:197], v219 offset:50176
	ds_read_b128 v[198:201], v219 offset:51200
	ds_read_b128 v[202:205], v219 offset:52224
	ds_read_b128 v[206:209], v219 offset:53248
	ds_read_b128 v[210:213], v219 offset:54272
	ds_read_b128 v[240:243], v219 offset:55296
	ds_read_b128 v[244:247], v219 offset:56320
	global_load_lds_dwordx4 v[158:159], off
	v_lshl_add_u64 v[158:159], v[214:215], 0, s[92:93]
	s_add_i32 m0, s46, 0x2000
	s_add_i32 s46, s70, s52
	global_load_lds_dwordx4 v[158:159], off
	v_lshl_add_u64 v[158:159], v[220:221], 0, s[92:93]
	s_mov_b32 m0, s46
	s_nop 0
	global_load_lds_dwordx4 v[158:159], off
	v_lshl_add_u64 v[158:159], v[226:227], 0, s[92:93]
	s_add_i32 m0, s46, 0x2000
	s_nop 0
	global_load_lds_dwordx4 v[158:159], off
	v_lshl_add_u64 v[158:159], v[248:249], 0, s[92:93]
	s_mov_b32 m0, s57
	s_nop 0
	global_load_lds_dwordx4 v[158:159], off
	v_lshl_add_u64 v[158:159], v[250:251], 0, s[92:93]
	s_mov_b32 m0, s58
	s_nop 0
	global_load_lds_dwordx4 v[158:159], off
	s_waitcnt vmcnt(8)
	s_waitcnt lgkmcnt(0)
	s_barrier
	s_setprio 1
	s_waitcnt lgkmcnt(0)
	v_mfma_f32_16x16x32_bf16 v[60:63], v[130:133], v[190:193], v[60:63]
	v_mfma_f32_16x16x32_bf16 v[56:59], v[138:141], v[190:193], v[56:59]
	v_mfma_f32_16x16x32_bf16 v[44:47], v[130:133], v[198:201], v[44:47]
	v_mfma_f32_16x16x32_bf16 v[40:43], v[138:141], v[198:201], v[40:43]
	v_mfma_f32_16x16x32_bf16 v[28:31], v[130:133], v[206:209], v[28:31]
	v_mfma_f32_16x16x32_bf16 v[24:27], v[138:141], v[206:209], v[24:27]
	v_mfma_f32_16x16x32_bf16 v[12:15], v[130:133], v[240:243], v[12:15]
	v_mfma_f32_16x16x32_bf16 v[8:11], v[138:141], v[240:243], v[8:11]
	v_mfma_f32_16x16x32_bf16 v[60:63], v[134:137], v[194:197], v[60:63]
	v_mfma_f32_16x16x32_bf16 v[56:59], v[142:145], v[194:197], v[56:59]
	v_mfma_f32_16x16x32_bf16 v[44:47], v[134:137], v[202:205], v[44:47]
	v_mfma_f32_16x16x32_bf16 v[40:43], v[142:145], v[202:205], v[40:43]
	v_mfma_f32_16x16x32_bf16 v[28:31], v[134:137], v[210:213], v[28:31]
	v_mfma_f32_16x16x32_bf16 v[24:27], v[142:145], v[210:213], v[24:27]
	v_mfma_f32_16x16x32_bf16 v[12:15], v[134:137], v[244:247], v[12:15]
	v_mfma_f32_16x16x32_bf16 v[8:11], v[142:145], v[244:247], v[8:11]
	s_setprio 0
	s_setprio 1
	v_mfma_f32_16x16x32_bf16 v[52:55], v[146:149], v[190:193], v[52:55]
	v_mfma_f32_16x16x32_bf16 v[48:51], v[154:157], v[190:193], v[48:51]
	v_mfma_f32_16x16x32_bf16 v[36:39], v[146:149], v[198:201], v[36:39]
	v_mfma_f32_16x16x32_bf16 v[32:35], v[154:157], v[198:201], v[32:35]
	v_mfma_f32_16x16x32_bf16 v[20:23], v[146:149], v[206:209], v[20:23]
	v_mfma_f32_16x16x32_bf16 v[16:19], v[154:157], v[206:209], v[16:19]
	v_mfma_f32_16x16x32_bf16 v[4:7], v[146:149], v[240:243], v[4:7]
	v_mfma_f32_16x16x32_bf16 v[0:3], v[154:157], v[240:243], v[0:3]
	v_mfma_f32_16x16x32_bf16 v[52:55], v[150:153], v[194:197], v[52:55]
	v_mfma_f32_16x16x32_bf16 v[48:51], v[186:189], v[194:197], v[48:51]
	v_mfma_f32_16x16x32_bf16 v[36:39], v[150:153], v[202:205], v[36:39]
	v_mfma_f32_16x16x32_bf16 v[32:35], v[186:189], v[202:205], v[32:35]
	v_mfma_f32_16x16x32_bf16 v[20:23], v[150:153], v[210:213], v[20:23]
	v_mfma_f32_16x16x32_bf16 v[16:19], v[186:189], v[210:213], v[16:19]
	v_mfma_f32_16x16x32_bf16 v[4:7], v[150:153], v[244:247], v[4:7]
	v_mfma_f32_16x16x32_bf16 v[0:3], v[186:189], v[244:247], v[0:3]
	s_setprio 0
	s_add_u32 s12, s12, 0x100
	s_addc_u32 s13, s13, 0
	v_lshl_add_u64 v[128:129], v[128:129], 0, s[80:81]
	s_cmp_ge_u32 s47, s48
	s_mov_b32 s46, s47
	s_barrier
	s_cbranch_scc1 .Lpl1_after
.LBB0_236:
	s_add_i32 s47, s46, 2
	s_cmp_eq_u32 s60, s46
	s_cselect_b64 vcc, -1, 0
	s_cselect_b32 s71, s15, s13
	s_cselect_b32 s70, s14, s12
	s_add_i32 s46, 0, 0x14000
	v_lshl_add_u64 v[130:131], v[128:129], 0, s[92:93]
	v_add_u32_e32 v142, s33, v218
	v_add_u32_e32 v166, s46, v218
	v_cndmask_b32_e32 v159, v131, v165, vcc
	v_cndmask_b32_e32 v158, v130, v164, vcc
	ds_read_b128 v[130:133], v142
	ds_read_b128 v[134:137], v142 offset:1024
	ds_read_b128 v[138:141], v142 offset:2048
	ds_read_b128 v[142:145], v142 offset:3072
	ds_read_b128 v[146:149], v166
	ds_read_b128 v[150:153], v166 offset:1024
	ds_read_b128 v[154:157], v166 offset:2048
	ds_read_b128 v[186:189], v166 offset:3072
	v_lshl_add_u64 v[166:167], v[128:129], 0, v[160:161]
	s_add_i32 m0, s53, 0xc000
	ds_read_b128 v[190:193], v219
	ds_read_b128 v[194:197], v219 offset:1024
	ds_read_b128 v[198:201], v219 offset:2048
	ds_read_b128 v[202:205], v219 offset:3072
	ds_read_b128 v[206:209], v219 offset:4096
	ds_read_b128 v[210:213], v219 offset:5120
	ds_read_b128 v[240:243], v219 offset:6144
	ds_read_b128 v[244:247], v219 offset:7168
	global_load_lds_dwordx4 v[166:167], off
	v_lshl_add_u64 v[166:167], v[128:129], 0, v[162:163]
	s_add_i32 m0, s53, 0xe000
	s_nop 0
	global_load_lds_dwordx4 v[166:167], off
	s_waitcnt vmcnt(8)
	s_waitcnt lgkmcnt(0)
	s_barrier
; #define PG8_STAGE(bufoff, gbase, voff) do { _Pragma("unroll") for (int _i = 0; _i < 2; ++_i) \
;         __builtin_amdgcn_global_load_lds((const unsigned*)((const char*)(gbase) + (voff)[_i]), (LAS unsigned*)(lds + (bufoff) + ldsw + _i * 8192), 16, 0, 0); } while (0)
; #define PG8_LDA(dst, b, h) do { _Pragma("unroll") for (int m = 0; m < 4; ++m) _Pragma("unroll") for (int k = 0; k < 2; ++k) dst[m][k] = *(const LAS bf16x8*)(lds + PG8_SA(b, h) + aoff + m * 2048 + k * 1024); } while (0)
; #define PG8_LDB(dst, b, h) do { _Pragma("unroll") for (int n = 0; n < 2; ++n) _Pragma("unroll") for (int k = 0; k < 2; ++k) dst[n][k] = *(const LAS bf16x8*)(lds + PG8_SB(b, h) + boff + n * 2048 + k * 1024); } while (0)
; #define PG8_MMA(ai, bj, At, Bt) do { __builtin_amdgcn_s_setprio(1); _Pragma("unroll") for (int k = 0; k < 2; ++k) _Pragma("unroll") for (int m = 0; m < 4; ++m) _Pragma("unroll") for (int n = 0; n < 2; ++n) \
;         acc[ai][bj][m][n] = __builtin_amdgcn_mfma_f32_16x16x32_bf16(Bt[n][k], At[m][k], acc[ai][bj][m][n], 0, 0, 0); __builtin_amdgcn_s_setprio(0); } while (0)
; #define PG8_WAIT_V(n) asm volatile("s_waitcnt vmcnt(" #n ")" ::: "memory")
; #define PG8_WAIT_L(n) asm volatile("s_waitcnt lgkmcnt(" #n ")" ::: "memory")
; #define PG8_BAR __builtin_amdgcn_s_barrier()
; #define PG8_SCHED __builtin_amdgcn_sched_barrier(0)
; template <class Epi, bool ALIGN_EPI>
; __device__ __forceinline__ void gemm_phase(LAS unsigned char* lds, const Gemm g, const StaticOrder& S, const Epi& E, const int tid) {
;     ...
;             PG8_WAIT_V(8); PG8_WAIT_L(0); PG8_BAR; PG8_MMA(0, 0, At, B0); PG8_MMA(0, 1, At, B1); PG8_BAR; PG8_SCHED;
;             PG8_LDA(At, 0, 1); PG8_STAGE(PG8_SB(0, 0), b2, voffB); PG8_STAGE(PG8_SB(0, 1), b2 + hB, voffB); PG8_STAGE(PG8_SA(0, 0), a2, voffA);
;             PG8_WAIT_V(8); PG8_WAIT_L(0); PG8_BAR; PG8_MMA(1, 0, At, B0); PG8_MMA(1, 1, At, B1); PG8_BAR; PG8_SCHED;
;             PG8_LDB(B0, 1, 0); PG8_LDB(B1, 1, 1); PG8_SCHED; PG8_LDA(At, 1, 0); PG8_STAGE(PG8_SA(0, 1), a2 + hA, voffA);
;             PG8_WAIT_V(8); PG8_WAIT_L(0); PG8_BAR; PG8_MMA(0, 0, At, B0); PG8_MMA(0, 1, At, B1); PG8_BAR; PG8_SCHED;
	s_setprio 1
	s_waitcnt lgkmcnt(0)
	v_mfma_f32_16x16x32_bf16 v[120:123], v[130:133], v[190:193], v[120:123]
	v_mfma_f32_16x16x32_bf16 v[124:127], v[138:141], v[190:193], v[124:127]
	v_mfma_f32_16x16x32_bf16 v[108:111], v[130:133], v[198:201], v[108:111]
	v_mfma_f32_16x16x32_bf16 v[104:107], v[138:141], v[198:201], v[104:107]
	v_mfma_f32_16x16x32_bf16 v[92:95], v[130:133], v[206:209], v[92:95]
	v_mfma_f32_16x16x32_bf16 v[88:91], v[138:141], v[206:209], v[88:91]
	v_mfma_f32_16x16x32_bf16 v[76:79], v[130:133], v[240:243], v[76:79]
	v_mfma_f32_16x16x32_bf16 v[72:75], v[138:141], v[240:243], v[72:75]
	v_mfma_f32_16x16x32_bf16 v[120:123], v[134:137], v[194:197], v[120:123]
	v_mfma_f32_16x16x32_bf16 v[124:127], v[142:145], v[194:197], v[124:127]
	v_mfma_f32_16x16x32_bf16 v[108:111], v[134:137], v[202:205], v[108:111]
	v_mfma_f32_16x16x32_bf16 v[104:107], v[142:145], v[202:205], v[104:107]
	v_mfma_f32_16x16x32_bf16 v[92:95], v[134:137], v[210:213], v[92:95]
	v_mfma_f32_16x16x32_bf16 v[88:91], v[142:145], v[210:213], v[88:91]
	v_mfma_f32_16x16x32_bf16 v[76:79], v[134:137], v[244:247], v[76:79]
	v_mfma_f32_16x16x32_bf16 v[72:75], v[142:145], v[244:247], v[72:75]
	s_setprio 0
	s_setprio 1
	v_mfma_f32_16x16x32_bf16 v[116:119], v[146:149], v[190:193], v[116:119]
	v_mfma_f32_16x16x32_bf16 v[112:115], v[154:157], v[190:193], v[112:115]
	v_mfma_f32_16x16x32_bf16 v[100:103], v[146:149], v[198:201], v[100:103]
	v_mfma_f32_16x16x32_bf16 v[96:99], v[154:157], v[198:201], v[96:99]
	v_mfma_f32_16x16x32_bf16 v[84:87], v[146:149], v[206:209], v[84:87]
	v_mfma_f32_16x16x32_bf16 v[80:83], v[154:157], v[206:209], v[80:83]
	v_mfma_f32_16x16x32_bf16 v[68:71], v[146:149], v[240:243], v[68:71]
	v_mfma_f32_16x16x32_bf16 v[64:67], v[154:157], v[240:243], v[64:67]
	v_mfma_f32_16x16x32_bf16 v[116:119], v[150:153], v[194:197], v[116:119]
	v_mfma_f32_16x16x32_bf16 v[112:115], v[186:189], v[194:197], v[112:115]
	v_mfma_f32_16x16x32_bf16 v[100:103], v[150:153], v[202:205], v[100:103]
	v_mfma_f32_16x16x32_bf16 v[96:99], v[186:189], v[202:205], v[96:99]
	v_mfma_f32_16x16x32_bf16 v[84:87], v[150:153], v[210:213], v[84:87]
	v_mfma_f32_16x16x32_bf16 v[80:83], v[186:189], v[210:213], v[80:83]
	v_mfma_f32_16x16x32_bf16 v[68:71], v[150:153], v[244:247], v[68:71]
	v_mfma_f32_16x16x32_bf16 v[64:67], v[186:189], v[244:247], v[64:67]
	s_setprio 0
	s_barrier
	s_add_i32 s72, s33, s52
	v_lshl_add_u64 v[166:167], s[70:71], 0, v[180:181]
	s_mov_b32 m0, s72
	ds_read_b128 v[190:193], v219 offset:16384
	ds_read_b128 v[194:197], v219 offset:17408
	ds_read_b128 v[198:201], v219 offset:18432
	ds_read_b128 v[202:205], v219 offset:19456
	ds_read_b128 v[206:209], v219 offset:20480
	ds_read_b128 v[210:213], v219 offset:21504
	ds_read_b128 v[240:243], v219 offset:22528
	ds_read_b128 v[244:247], v219 offset:23552
	global_load_lds_dwordx4 v[166:167], off
	s_add_i32 m0, s72, 0x2000
	v_lshl_add_u64 v[214:215], s[70:71], 0, v[184:185]
	s_add_u32 s70, s70, s49
	s_addc_u32 s71, s71, 0
	s_add_i32 s46, s46, s52
	global_load_lds_dwordx4 v[214:215], off
	v_lshl_add_u64 v[220:221], s[70:71], 0, v[180:181]
	s_mov_b32 m0, s46
	v_lshl_add_u64 v[226:227], s[70:71], 0, v[184:185]
	global_load_lds_dwordx4 v[220:221], off
	s_add_i32 m0, s46, 0x2000
	v_lshl_add_u64 v[248:249], v[158:159], 0, v[178:179]
	global_load_lds_dwordx4 v[226:227], off
	s_mov_b32 m0, s53
	v_lshl_add_u64 v[250:251], v[158:159], 0, v[182:183]
	global_load_lds_dwordx4 v[248:249], off
	s_mov_b32 m0, s54
	s_nop 0
	global_load_lds_dwordx4 v[250:251], off
	s_waitcnt vmcnt(8)
	s_waitcnt lgkmcnt(0)
	s_barrier
	s_setprio 1
	s_waitcnt lgkmcnt(0)
	v_mfma_f32_16x16x32_bf16 v[60:63], v[130:133], v[190:193], v[60:63]
	v_mfma_f32_16x16x32_bf16 v[56:59], v[138:141], v[190:193], v[56:59]
	v_mfma_f32_16x16x32_bf16 v[44:47], v[130:133], v[198:201], v[44:47]
	v_mfma_f32_16x16x32_bf16 v[40:43], v[138:141], v[198:201], v[40:43]
	v_mfma_f32_16x16x32_bf16 v[28:31], v[130:133], v[206:209], v[28:31]
	v_mfma_f32_16x16x32_bf16 v[24:27], v[138:141], v[206:209], v[24:27]
	v_mfma_f32_16x16x32_bf16 v[12:15], v[130:133], v[240:243], v[12:15]
	v_mfma_f32_16x16x32_bf16 v[8:11], v[138:141], v[240:243], v[8:11]
	v_mfma_f32_16x16x32_bf16 v[60:63], v[134:137], v[194:197], v[60:63]
	v_mfma_f32_16x16x32_bf16 v[56:59], v[142:145], v[194:197], v[56:59]
	v_mfma_f32_16x16x32_bf16 v[44:47], v[134:137], v[202:205], v[44:47]
	v_mfma_f32_16x16x32_bf16 v[40:43], v[142:145], v[202:205], v[40:43]
	v_mfma_f32_16x16x32_bf16 v[28:31], v[134:137], v[210:213], v[28:31]
	v_mfma_f32_16x16x32_bf16 v[24:27], v[142:145], v[210:213], v[24:27]
	v_mfma_f32_16x16x32_bf16 v[12:15], v[134:137], v[244:247], v[12:15]
	v_mfma_f32_16x16x32_bf16 v[8:11], v[142:145], v[244:247], v[8:11]
	s_setprio 0
	s_setprio 1
	v_mfma_f32_16x16x32_bf16 v[52:55], v[146:149], v[190:193], v[52:55]
	v_mfma_f32_16x16x32_bf16 v[48:51], v[154:157], v[190:193], v[48:51]
	v_mfma_f32_16x16x32_bf16 v[36:39], v[146:149], v[198:201], v[36:39]
	v_mfma_f32_16x16x32_bf16 v[32:35], v[154:157], v[198:201], v[32:35]
	v_mfma_f32_16x16x32_bf16 v[20:23], v[146:149], v[206:209], v[20:23]
	v_mfma_f32_16x16x32_bf16 v[16:19], v[154:157], v[206:209], v[16:19]
	v_mfma_f32_16x16x32_bf16 v[4:7], v[146:149], v[240:243], v[4:7]
	v_mfma_f32_16x16x32_bf16 v[0:3], v[154:157], v[240:243], v[0:3]
	v_mfma_f32_16x16x32_bf16 v[52:55], v[150:153], v[194:197], v[52:55]
	v_mfma_f32_16x16x32_bf16 v[48:51], v[186:189], v[194:197], v[48:51]
	v_mfma_f32_16x16x32_bf16 v[36:39], v[150:153], v[202:205], v[36:39]
	v_mfma_f32_16x16x32_bf16 v[32:35], v[186:189], v[202:205], v[32:35]
	v_mfma_f32_16x16x32_bf16 v[20:23], v[150:153], v[210:213], v[20:23]
	v_mfma_f32_16x16x32_bf16 v[16:19], v[186:189], v[210:213], v[16:19]
	v_mfma_f32_16x16x32_bf16 v[4:7], v[150:153], v[244:247], v[4:7]
	v_mfma_f32_16x16x32_bf16 v[0:3], v[186:189], v[244:247], v[0:3]
	s_setprio 0
	s_barrier
; #define PG8_STAGE(bufoff, gbase, voff) do { _Pragma("unroll") for (int _i = 0; _i < 2; ++_i) \
;         __builtin_amdgcn_global_load_lds((const unsigned*)((const char*)(gbase) + (voff)[_i]), (LAS unsigned*)(lds + (bufoff) + ldsw + _i * 8192), 16, 0, 0); } while (0)
; #define PG8_LDA(dst, b, h) do { _Pragma("unroll") for (int m = 0; m < 4; ++m) _Pragma("unroll") for (int k = 0; k < 2; ++k) dst[m][k] = *(const LAS bf16x8*)(lds + PG8_SA(b, h) + aoff + m * 2048 + k * 1024); } while (0)
; #define PG8_MMA(ai, bj, At, Bt) do { __builtin_amdgcn_s_setprio(1); _Pragma("unroll") for (int k = 0; k < 2; ++k) _Pragma("unroll") for (int m = 0; m < 4; ++m) _Pragma("unroll") for (int n = 0; n < 2; ++n) \
;         acc[ai][bj][m][n] = __builtin_amdgcn_mfma_f32_16x16x32_bf16(Bt[n][k], At[m][k], acc[ai][bj][m][n], 0, 0, 0); __builtin_amdgcn_s_setprio(0); } while (0)
; #define PG8_WAIT_V(n) asm volatile("s_waitcnt vmcnt(" #n ")" ::: "memory")
; #define PG8_WAIT_L(n) asm volatile("s_waitcnt lgkmcnt(" #n ")" ::: "memory")
; #define PG8_BAR __builtin_amdgcn_s_barrier()
; #define PG8_SCHED __builtin_amdgcn_sched_barrier(0)
; template <class Epi, bool ALIGN_EPI>
; __device__ __forceinline__ void gemm_phase(LAS unsigned char* lds, const Gemm g, const StaticOrder& S, const Epi& E, const int tid) {
;     ...
;             PG8_LDA(At, 1, 1); PG8_STAGE(PG8_SB(1, 0), b3, voffB); PG8_STAGE(PG8_SB(1, 1), b3 + hB, voffB); PG8_STAGE(PG8_SA(1, 0), a3, voffA);
;             PG8_WAIT_V(8); PG8_WAIT_L(0); PG8_BAR; PG8_MMA(1, 0, At, B0); PG8_MMA(1, 1, At, B1); PG8_BAR; PG8_SCHED;
	s_add_i32 s46, 0, 0x18000
	s_add_i32 s70, 0, 0x1c000
	v_add_u32_e32 v142, s46, v218
	v_add_u32_e32 v168, s70, v218
	ds_read_b128 v[130:133], v142
	ds_read_b128 v[134:137], v142 offset:1024
	ds_read_b128 v[138:141], v142 offset:2048
	ds_read_b128 v[142:145], v142 offset:3072
	ds_read_b128 v[146:149], v168
	ds_read_b128 v[150:153], v168 offset:1024
	ds_read_b128 v[154:157], v168 offset:2048
	ds_read_b128 v[186:189], v168 offset:3072
	v_lshl_add_u64 v[158:159], v[158:159], 0, s[94:95]
	s_mov_b32 m0, s55
	v_lshl_add_u64 v[252:253], v[158:159], 0, v[178:179]
	ds_read_b128 v[190:193], v219 offset:32768
	ds_read_b128 v[194:197], v219 offset:33792
	ds_read_b128 v[198:201], v219 offset:34816
	ds_read_b128 v[202:205], v219 offset:35840
	ds_read_b128 v[206:209], v219 offset:36864
	ds_read_b128 v[210:213], v219 offset:37888
	ds_read_b128 v[240:243], v219 offset:38912
	ds_read_b128 v[244:247], v219 offset:39936
	global_load_lds_dwordx4 v[252:253], off
	v_lshl_add_u64 v[158:159], v[158:159], 0, v[182:183]
	s_mov_b32 m0, s56
	s_nop 0
	global_load_lds_dwordx4 v[158:159], off
	s_waitcnt vmcnt(8)
	s_waitcnt lgkmcnt(0)
	s_barrier
	s_setprio 1
	s_waitcnt lgkmcnt(0)
	v_mfma_f32_16x16x32_bf16 v[120:123], v[130:133], v[190:193], v[120:123]
	v_mfma_f32_16x16x32_bf16 v[124:127], v[138:141], v[190:193], v[124:127]
	v_mfma_f32_16x16x32_bf16 v[108:111], v[130:133], v[198:201], v[108:111]
	v_mfma_f32_16x16x32_bf16 v[104:107], v[138:141], v[198:201], v[104:107]
	v_mfma_f32_16x16x32_bf16 v[92:95], v[130:133], v[206:209], v[92:95]
	v_mfma_f32_16x16x32_bf16 v[88:91], v[138:141], v[206:209], v[88:91]
	v_mfma_f32_16x16x32_bf16 v[76:79], v[130:133], v[240:243], v[76:79]
	v_mfma_f32_16x16x32_bf16 v[72:75], v[138:141], v[240:243], v[72:75]
	v_mfma_f32_16x16x32_bf16 v[120:123], v[134:137], v[194:197], v[120:123]
	v_mfma_f32_16x16x32_bf16 v[124:127], v[142:145], v[194:197], v[124:127]
	v_mfma_f32_16x16x32_bf16 v[108:111], v[134:137], v[202:205], v[108:111]
	v_mfma_f32_16x16x32_bf16 v[104:107], v[142:145], v[202:205], v[104:107]
	v_mfma_f32_16x16x32_bf16 v[92:95], v[134:137], v[210:213], v[92:95]
	v_mfma_f32_16x16x32_bf16 v[88:91], v[142:145], v[210:213], v[88:91]
	v_mfma_f32_16x16x32_bf16 v[76:79], v[134:137], v[244:247], v[76:79]
	v_mfma_f32_16x16x32_bf16 v[72:75], v[142:145], v[244:247], v[72:75]
	s_setprio 0
	s_setprio 1
	v_mfma_f32_16x16x32_bf16 v[116:119], v[146:149], v[190:193], v[116:119]
	v_mfma_f32_16x16x32_bf16 v[112:115], v[154:157], v[190:193], v[112:115]
	v_mfma_f32_16x16x32_bf16 v[100:103], v[146:149], v[198:201], v[100:103]
	v_mfma_f32_16x16x32_bf16 v[96:99], v[154:157], v[198:201], v[96:99]
	v_mfma_f32_16x16x32_bf16 v[84:87], v[146:149], v[206:209], v[84:87]
	v_mfma_f32_16x16x32_bf16 v[80:83], v[154:157], v[206:209], v[80:83]
	v_mfma_f32_16x16x32_bf16 v[68:71], v[146:149], v[240:243], v[68:71]
	v_mfma_f32_16x16x32_bf16 v[64:67], v[154:157], v[240:243], v[64:67]
	v_mfma_f32_16x16x32_bf16 v[116:119], v[150:153], v[194:197], v[116:119]
	v_mfma_f32_16x16x32_bf16 v[112:115], v[186:189], v[194:197], v[112:115]
	v_mfma_f32_16x16x32_bf16 v[100:103], v[150:153], v[202:205], v[100:103]
	v_mfma_f32_16x16x32_bf16 v[96:99], v[186:189], v[202:205], v[96:99]
	v_mfma_f32_16x16x32_bf16 v[84:87], v[150:153], v[210:213], v[84:87]
	v_mfma_f32_16x16x32_bf16 v[80:83], v[186:189], v[210:213], v[80:83]
	v_mfma_f32_16x16x32_bf16 v[68:71], v[150:153], v[244:247], v[68:71]
	v_mfma_f32_16x16x32_bf16 v[64:67], v[186:189], v[244:247], v[64:67]
	s_setprio 0
	s_barrier
; #define PG8_STAGE(bufoff, gbase, voff) do { _Pragma("unroll") for (int _i = 0; _i < 2; ++_i) \
;         __builtin_amdgcn_global_load_lds((const unsigned*)((const char*)(gbase) + (voff)[_i]), (LAS unsigned*)(lds + (bufoff) + ldsw + _i * 8192), 16, 0, 0); } while (0)
; #define PG8_LDA(dst, b, h) do { _Pragma("unroll") for (int m = 0; m < 4; ++m) _Pragma("unroll") for (int k = 0; k < 2; ++k) dst[m][k] = *(const LAS bf16x8*)(lds + PG8_SA(b, h) + aoff + m * 2048 + k * 1024); } while (0)
; #define PG8_MMA(ai, bj, At, Bt) do { __builtin_amdgcn_s_setprio(1); _Pragma("unroll") for (int k = 0; k < 2; ++k) _Pragma("unroll") for (int m = 0; m < 4; ++m) _Pragma("unroll") for (int n = 0; n < 2; ++n) \
;         acc[ai][bj][m][n] = __builtin_amdgcn_mfma_f32_16x16x32_bf16(Bt[n][k], At[m][k], acc[ai][bj][m][n], 0, 0, 0); __builtin_amdgcn_s_setprio(0); } while (0)
; #define PG8_WAIT_V(n) asm volatile("s_waitcnt vmcnt(" #n ")" ::: "memory")
; #define PG8_WAIT_L(n) asm volatile("s_waitcnt lgkmcnt(" #n ")" ::: "memory")
; #define PG8_BAR __builtin_amdgcn_s_barrier()
; #define PG8_SCHED __builtin_amdgcn_sched_barrier(0)
; template <class Epi, bool ALIGN_EPI>
; __device__ __forceinline__ void gemm_phase(LAS unsigned char* lds, const Gemm g, const StaticOrder& S, const Epi& E, const int tid) {
;     ...
;             PG8_LDA(At, 1, 1); PG8_STAGE(PG8_SB(1, 0), b3, voffB); PG8_STAGE(PG8_SB(1, 1), b3 + hB, voffB); PG8_STAGE(PG8_SA(1, 0), a3, voffA);
;             PG8_WAIT_V(8); PG8_WAIT_L(0); PG8_BAR; PG8_MMA(1, 0, At, B0); PG8_MMA(1, 1, At, B1); PG8_BAR; PG8_SCHED;
;         }
	s_add_i32 s46, s46, s52
	v_lshl_add_u64 v[158:159], v[166:167], 0, s[92:93]
	s_mov_b32 m0, s46
	ds_read_b128 v[190:193], v219 offset:49152
	ds_read_b128 v[194:197], v219 offset:50176
	ds_read_b128 v[198:201], v219 offset:51200
	ds_read_b128 v[202:205], v219 offset:52224
	ds_read_b128 v[206:209], v219 offset:53248
	ds_read_b128 v[210:213], v219 offset:54272
	ds_read_b128 v[240:243], v219 offset:55296
	ds_read_b128 v[244:247], v219 offset:56320
	global_load_lds_dwordx4 v[158:159], off
	v_lshl_add_u64 v[158:159], v[214:215], 0, s[92:93]
	s_add_i32 m0, s46, 0x2000
	s_add_i32 s46, s70, s52
	global_load_lds_dwordx4 v[158:159], off
	v_lshl_add_u64 v[158:159], v[220:221], 0, s[92:93]
	s_mov_b32 m0, s46
	s_nop 0
	global_load_lds_dwordx4 v[158:159], off
	v_lshl_add_u64 v[158:159], v[226:227], 0, s[92:93]
	s_add_i32 m0, s46, 0x2000
	s_nop 0
	global_load_lds_dwordx4 v[158:159], off
	v_lshl_add_u64 v[158:159], v[248:249], 0, s[92:93]
	s_mov_b32 m0, s57
	s_nop 0
	global_load_lds_dwordx4 v[158:159], off
	v_lshl_add_u64 v[158:159], v[250:251], 0, s[92:93]
	s_mov_b32 m0, s58
	s_nop 0
	global_load_lds_dwordx4 v[158:159], off
	s_waitcnt vmcnt(8)
	s_waitcnt lgkmcnt(0)
	s_barrier
	s_setprio 1
	s_waitcnt lgkmcnt(0)
	v_mfma_f32_16x16x32_bf16 v[60:63], v[130:133], v[190:193], v[60:63]
	v_mfma_f32_16x16x32_bf16 v[56:59], v[138:141], v[190:193], v[56:59]
	v_mfma_f32_16x16x32_bf16 v[44:47], v[130:133], v[198:201], v[44:47]
	v_mfma_f32_16x16x32_bf16 v[40:43], v[138:141], v[198:201], v[40:43]
	v_mfma_f32_16x16x32_bf16 v[28:31], v[130:133], v[206:209], v[28:31]
	v_mfma_f32_16x16x32_bf16 v[24:27], v[138:141], v[206:209], v[24:27]
	v_mfma_f32_16x16x32_bf16 v[12:15], v[130:133], v[240:243], v[12:15]
	v_mfma_f32_16x16x32_bf16 v[8:11], v[138:141], v[240:243], v[8:11]
	v_mfma_f32_16x16x32_bf16 v[60:63], v[134:137], v[194:197], v[60:63]
	v_mfma_f32_16x16x32_bf16 v[56:59], v[142:145], v[194:197], v[56:59]
	v_mfma_f32_16x16x32_bf16 v[44:47], v[134:137], v[202:205], v[44:47]
	v_mfma_f32_16x16x32_bf16 v[40:43], v[142:145], v[202:205], v[40:43]
	v_mfma_f32_16x16x32_bf16 v[28:31], v[134:137], v[210:213], v[28:31]
	v_mfma_f32_16x16x32_bf16 v[24:27], v[142:145], v[210:213], v[24:27]
	v_mfma_f32_16x16x32_bf16 v[12:15], v[134:137], v[244:247], v[12:15]
	v_mfma_f32_16x16x32_bf16 v[8:11], v[142:145], v[244:247], v[8:11]
	s_setprio 0
	s_setprio 1
	v_mfma_f32_16x16x32_bf16 v[52:55], v[146:149], v[190:193], v[52:55]
	v_mfma_f32_16x16x32_bf16 v[48:51], v[154:157], v[190:193], v[48:51]
	v_mfma_f32_16x16x32_bf16 v[36:39], v[146:149], v[198:201], v[36:39]
	v_mfma_f32_16x16x32_bf16 v[32:35], v[154:157], v[198:201], v[32:35]
	v_mfma_f32_16x16x32_bf16 v[20:23], v[146:149], v[206:209], v[20:23]
	v_mfma_f32_16x16x32_bf16 v[16:19], v[154:157], v[206:209], v[16:19]
	v_mfma_f32_16x16x32_bf16 v[4:7], v[146:149], v[240:243], v[4:7]
	v_mfma_f32_16x16x32_bf16 v[0:3], v[154:157], v[240:243], v[0:3]
	v_mfma_f32_16x16x32_bf16 v[52:55], v[150:153], v[194:197], v[52:55]
	v_mfma_f32_16x16x32_bf16 v[48:51], v[186:189], v[194:197], v[48:51]
	v_mfma_f32_16x16x32_bf16 v[36:39], v[150:153], v[202:205], v[36:39]
	v_mfma_f32_16x16x32_bf16 v[32:35], v[186:189], v[202:205], v[32:35]
	v_mfma_f32_16x16x32_bf16 v[20:23], v[150:153], v[210:213], v[20:23]
	v_mfma_f32_16x16x32_bf16 v[16:19], v[186:189], v[210:213], v[16:19]
	v_mfma_f32_16x16x32_bf16 v[4:7], v[150:153], v[244:247], v[4:7]
	v_mfma_f32_16x16x32_bf16 v[0:3], v[186:189], v[244:247], v[0:3]
	s_setprio 0
	s_add_u32 s12, s12, 0x100
	s_addc_u32 s13, s13, 0
	v_lshl_add_u64 v[128:129], v[128:129], 0, s[80:81]
	s_cmp_ge_u32 s47, s48
	s_mov_b32 s46, s47
	s_barrier
	s_cbranch_scc0 .LBB0_236

; #define PG8_STAGE(bufoff, gbase, voff) do { _Pragma("unroll") for (int _i = 0; _i < 2; ++_i) \
;         __builtin_amdgcn_global_load_lds((const unsigned*)((const char*)(gbase) + (voff)[_i]), (LAS unsigned*)(lds + (bufoff) + ldsw + _i * 8192), 16, 0, 0); } while (0)
; #define PG8_LDA(dst, b, h) do { _Pragma("unroll") for (int m = 0; m < 4; ++m) _Pragma("unroll") for (int k = 0; k < 2; ++k) dst[m][k] = *(const LAS bf16x8*)(lds + PG8_SA(b, h) + aoff + m * 2048 + k * 1024); } while (0)
; #define PG8_LDB(dst, b, h) do { _Pragma("unroll") for (int n = 0; n < 2; ++n) _Pragma("unroll") for (int k = 0; k < 2; ++k) dst[n][k] = *(const LAS bf16x8*)(lds + PG8_SB(b, h) + boff + n * 2048 + k * 1024); } while (0)
; #define PG8_MMA(ai, bj, At, Bt) do { __builtin_amdgcn_s_setprio(1); _Pragma("unroll") for (int k = 0; k < 2; ++k) _Pragma("unroll") for (int m = 0; m < 4; ++m) _Pragma("unroll") for (int n = 0; n < 2; ++n) \
;         acc[ai][bj][m][n] = __builtin_amdgcn_mfma_f32_16x16x32_bf16(Bt[n][k], At[m][k], acc[ai][bj][m][n], 0, 0, 0); __builtin_amdgcn_s_setprio(0); } while (0)
; #define PG8_WAIT_V(n) asm volatile("s_waitcnt vmcnt(" #n ")" ::: "memory")
; #define PG8_WAIT_L(n) asm volatile("s_waitcnt lgkmcnt(" #n ")" ::: "memory")
; #define PG8_BAR __builtin_amdgcn_s_barrier()
; #define PG8_SCHED __builtin_amdgcn_sched_barrier(0)
; template <class Epi, bool ALIGN_EPI>
; __device__ __forceinline__ void gemm_phase(LAS unsigned char* lds, const Gemm g, const StaticOrder& S, const Epi& E, const int tid) {
;     ...
;         for (int t = 0; t < nt; t += 2) {
;             const bool last = (t == nt - 2);
;             const char* a1 = cA + (size_t)(t + 1) * kstep;
;             const char* a2 = last ? nA : cA + (size_t)(t + 2) * kstep; const char* b2 = last ? nB : cB + (size_t)(t + 2) * kstep;
;             const char* a3 = a2 + kstep; const char* b3 = b2 + kstep;
;             PG8_LDB(B0, 0, 0); PG8_LDB(B1, 0, 1); PG8_SCHED; PG8_LDA(At, 0, 0); PG8_STAGE(PG8_SA(1, 1), a1 + hA, voffA);
;             PG8_WAIT_V(8); PG8_WAIT_L(0); PG8_BAR; PG8_MMA(0, 0, At, B0); PG8_MMA(0, 1, At, B1); PG8_BAR; PG8_SCHED;
;             PG8_LDA(At, 0, 1); PG8_STAGE(PG8_SB(0, 0), b2, voffB); PG8_STAGE(PG8_SB(0, 1), b2 + hB, voffB); PG8_STAGE(PG8_SA(0, 0), a2, voffA);
.LBB0_272:
	s_andn2_b64 vcc, exec, s[36:37]
	s_cbranch_vccnz .LBB0_276
	s_add_u32 s10, s14, 0x100
	v_lshl_add_u64 v[128:129], v[128:129], 0, s[92:93]
	s_addc_u32 s11, s15, 0
	s_mov_b32 s14, 0
	s_add_i32 s15, s14, 2
	s_cmp_eq_u32 s57, s14
	s_cselect_b64 vcc, -1, 0
	s_cselect_b32 s69, s13, s11
	s_cselect_b32 s68, s12, s10
	s_add_i32 s14, 0, 0x14000
	v_lshl_add_u64 v[130:131], v[128:129], 0, s[92:93]
	v_add_u32_e32 v142, s33, v239
	v_add_u32_e32 v158, s14, v239
	v_cndmask_b32_e32 v167, v131, v191, vcc
	v_cndmask_b32_e32 v166, v130, v190, vcc
	ds_read_b128 v[130:133], v142
	ds_read_b128 v[134:137], v142 offset:1024
	ds_read_b128 v[138:141], v142 offset:2048
	ds_read_b128 v[142:145], v142 offset:3072
	ds_read_b128 v[146:149], v158
	ds_read_b128 v[150:153], v158 offset:1024
	ds_read_b128 v[154:157], v158 offset:2048
	ds_read_b128 v[158:161], v158 offset:3072
	v_lshl_add_u64 v[220:221], v[128:129], 0, v[186:187]
	s_add_i32 m0, s51, 0xc000
	ds_read_b128 v[162:165], v171
	ds_read_b128 v[192:195], v171 offset:1024
	ds_read_b128 v[196:199], v171 offset:2048
	ds_read_b128 v[200:203], v171 offset:3072
	ds_read_b128 v[204:207], v171 offset:4096
	ds_read_b128 v[208:211], v171 offset:5120
	ds_read_b128 v[212:215], v171 offset:6144
	ds_read_b128 v[216:219], v171 offset:7168
	global_load_lds_dwordx4 v[220:221], off
	v_lshl_add_u64 v[220:221], v[128:129], 0, v[188:189]
	s_add_i32 m0, s51, 0xe000
	s_nop 0
	global_load_lds_dwordx4 v[220:221], off
	s_waitcnt vmcnt(8)
	s_waitcnt lgkmcnt(0)
	s_barrier
	s_setprio 1
	s_waitcnt lgkmcnt(0)
	v_mfma_f32_16x16x32_bf16 v[124:127], v[130:133], v[162:165], 0
	v_mfma_f32_16x16x32_bf16 v[120:123], v[138:141], v[162:165], 0
	v_mfma_f32_16x16x32_bf16 v[108:111], v[130:133], v[196:199], 0
	v_mfma_f32_16x16x32_bf16 v[104:107], v[138:141], v[196:199], 0
	v_mfma_f32_16x16x32_bf16 v[92:95], v[130:133], v[204:207], 0
	v_mfma_f32_16x16x32_bf16 v[88:91], v[138:141], v[204:207], 0
	v_mfma_f32_16x16x32_bf16 v[76:79], v[130:133], v[212:215], 0
	v_mfma_f32_16x16x32_bf16 v[72:75], v[138:141], v[212:215], 0
	v_mfma_f32_16x16x32_bf16 v[124:127], v[134:137], v[192:195], v[124:127]
	v_mfma_f32_16x16x32_bf16 v[120:123], v[142:145], v[192:195], v[120:123]
	v_mfma_f32_16x16x32_bf16 v[108:111], v[134:137], v[200:203], v[108:111]
	v_mfma_f32_16x16x32_bf16 v[104:107], v[142:145], v[200:203], v[104:107]
	v_mfma_f32_16x16x32_bf16 v[92:95], v[134:137], v[208:211], v[92:95]
	v_mfma_f32_16x16x32_bf16 v[88:91], v[142:145], v[208:211], v[88:91]
	v_mfma_f32_16x16x32_bf16 v[76:79], v[134:137], v[216:219], v[76:79]
	v_mfma_f32_16x16x32_bf16 v[72:75], v[142:145], v[216:219], v[72:75]
	s_setprio 0
	s_setprio 1
	v_mfma_f32_16x16x32_bf16 v[116:119], v[146:149], v[162:165], 0
	v_mfma_f32_16x16x32_bf16 v[112:115], v[154:157], v[162:165], 0
	v_mfma_f32_16x16x32_bf16 v[100:103], v[146:149], v[196:199], 0
	v_mfma_f32_16x16x32_bf16 v[96:99], v[154:157], v[196:199], 0
	v_mfma_f32_16x16x32_bf16 v[84:87], v[146:149], v[204:207], 0
	v_mfma_f32_16x16x32_bf16 v[80:83], v[154:157], v[204:207], 0
	v_mfma_f32_16x16x32_bf16 v[68:71], v[146:149], v[212:215], 0
	v_mfma_f32_16x16x32_bf16 v[64:67], v[154:157], v[212:215], 0
	v_mfma_f32_16x16x32_bf16 v[116:119], v[150:153], v[192:195], v[116:119]
	v_mfma_f32_16x16x32_bf16 v[112:115], v[158:161], v[192:195], v[112:115]
	v_mfma_f32_16x16x32_bf16 v[100:103], v[150:153], v[200:203], v[100:103]
	v_mfma_f32_16x16x32_bf16 v[96:99], v[158:161], v[200:203], v[96:99]
	v_mfma_f32_16x16x32_bf16 v[84:87], v[150:153], v[208:211], v[84:87]
	v_mfma_f32_16x16x32_bf16 v[80:83], v[158:161], v[208:211], v[80:83]
	v_mfma_f32_16x16x32_bf16 v[68:71], v[150:153], v[216:219], v[68:71]
	v_mfma_f32_16x16x32_bf16 v[64:67], v[158:161], v[216:219], v[64:67]
	s_setprio 0
	s_barrier
	s_add_i32 s70, s33, s47
	v_lshl_add_u64 v[220:221], s[68:69], 0, v[180:181]
	s_mov_b32 m0, s70
	ds_read_b128 v[162:165], v171 offset:16384
	ds_read_b128 v[192:195], v171 offset:17408
	ds_read_b128 v[196:199], v171 offset:18432
	ds_read_b128 v[200:203], v171 offset:19456
	ds_read_b128 v[204:207], v171 offset:20480
	ds_read_b128 v[208:211], v171 offset:21504
	ds_read_b128 v[212:215], v171 offset:22528
	ds_read_b128 v[216:219], v171 offset:23552
	global_load_lds_dwordx4 v[220:221], off
	s_add_i32 m0, s70, 0x2000
	v_lshl_add_u64 v[226:227], s[68:69], 0, v[184:185]
	s_add_u32 s68, s68, s49
	s_addc_u32 s69, s69, 0
	s_add_i32 s14, s14, s47
	global_load_lds_dwordx4 v[226:227], off
	v_lshl_add_u64 v[240:241], s[68:69], 0, v[180:181]
	s_mov_b32 m0, s14
	v_lshl_add_u64 v[242:243], s[68:69], 0, v[184:185]
	global_load_lds_dwordx4 v[240:241], off
	s_add_i32 m0, s14, 0x2000
	v_lshl_add_u64 v[244:245], v[166:167], 0, v[178:179]
	global_load_lds_dwordx4 v[242:243], off
	s_mov_b32 m0, s51
	v_lshl_add_u64 v[246:247], v[166:167], 0, v[182:183]
	global_load_lds_dwordx4 v[244:245], off
	s_mov_b32 m0, s52
	s_nop 0
	global_load_lds_dwordx4 v[246:247], off
	s_waitcnt vmcnt(8)
	s_waitcnt lgkmcnt(0)
	s_barrier
; #define PG8_STAGE(bufoff, gbase, voff) do { _Pragma("unroll") for (int _i = 0; _i < 2; ++_i) \
;         __builtin_amdgcn_global_load_lds((const unsigned*)((const char*)(gbase) + (voff)[_i]), (LAS unsigned*)(lds + (bufoff) + ldsw + _i * 8192), 16, 0, 0); } while (0)
; #define PG8_LDA(dst, b, h) do { _Pragma("unroll") for (int m = 0; m < 4; ++m) _Pragma("unroll") for (int k = 0; k < 2; ++k) dst[m][k] = *(const LAS bf16x8*)(lds + PG8_SA(b, h) + aoff + m * 2048 + k * 1024); } while (0)
; #define PG8_LDB(dst, b, h) do { _Pragma("unroll") for (int n = 0; n < 2; ++n) _Pragma("unroll") for (int k = 0; k < 2; ++k) dst[n][k] = *(const LAS bf16x8*)(lds + PG8_SB(b, h) + boff + n * 2048 + k * 1024); } while (0)
; #define PG8_MMA(ai, bj, At, Bt) do { __builtin_amdgcn_s_setprio(1); _Pragma("unroll") for (int k = 0; k < 2; ++k) _Pragma("unroll") for (int m = 0; m < 4; ++m) _Pragma("unroll") for (int n = 0; n < 2; ++n) \
;         acc[ai][bj][m][n] = __builtin_amdgcn_mfma_f32_16x16x32_bf16(Bt[n][k], At[m][k], acc[ai][bj][m][n], 0, 0, 0); __builtin_amdgcn_s_setprio(0); } while (0)
; #define PG8_WAIT_V(n) asm volatile("s_waitcnt vmcnt(" #n ")" ::: "memory")
; #define PG8_WAIT_L(n) asm volatile("s_waitcnt lgkmcnt(" #n ")" ::: "memory")
; #define PG8_BAR __builtin_amdgcn_s_barrier()
; #define PG8_SCHED __builtin_amdgcn_sched_barrier(0)
; template <class Epi, bool ALIGN_EPI>
; __device__ __forceinline__ void gemm_phase(LAS unsigned char* lds, const Gemm g, const StaticOrder& S, const Epi& E, const int tid) {
;     ...
;             PG8_LDA(At, 0, 1); PG8_STAGE(PG8_SB(0, 0), b2, voffB); PG8_STAGE(PG8_SB(0, 1), b2 + hB, voffB); PG8_STAGE(PG8_SA(0, 0), a2, voffA);
;             PG8_WAIT_V(8); PG8_WAIT_L(0); PG8_BAR; PG8_MMA(1, 0, At, B0); PG8_MMA(1, 1, At, B1); PG8_BAR; PG8_SCHED;
;             PG8_LDB(B0, 1, 0); PG8_LDB(B1, 1, 1); PG8_SCHED; PG8_LDA(At, 1, 0); PG8_STAGE(PG8_SA(0, 1), a2 + hA, voffA);
;             PG8_WAIT_V(8); PG8_WAIT_L(0); PG8_BAR; PG8_MMA(0, 0, At, B0); PG8_MMA(0, 1, At, B1); PG8_BAR; PG8_SCHED;
;             PG8_LDA(At, 1, 1); PG8_STAGE(PG8_SB(1, 0), b3, voffB); PG8_STAGE(PG8_SB(1, 1), b3 + hB, voffB); PG8_STAGE(PG8_SA(1, 0), a3, voffA);
;             PG8_WAIT_V(8); PG8_WAIT_L(0); PG8_BAR; PG8_MMA(1, 0, At, B0); PG8_MMA(1, 1, At, B1); PG8_BAR; PG8_SCHED;
	s_setprio 1
	s_waitcnt lgkmcnt(0)
	v_mfma_f32_16x16x32_bf16 v[60:63], v[130:133], v[162:165], 0
	v_mfma_f32_16x16x32_bf16 v[56:59], v[138:141], v[162:165], 0
	v_mfma_f32_16x16x32_bf16 v[44:47], v[130:133], v[196:199], 0
	v_mfma_f32_16x16x32_bf16 v[40:43], v[138:141], v[196:199], 0
	v_mfma_f32_16x16x32_bf16 v[28:31], v[130:133], v[204:207], 0
	v_mfma_f32_16x16x32_bf16 v[24:27], v[138:141], v[204:207], 0
	v_mfma_f32_16x16x32_bf16 v[12:15], v[130:133], v[212:215], 0
	v_mfma_f32_16x16x32_bf16 v[8:11], v[138:141], v[212:215], 0
	v_mfma_f32_16x16x32_bf16 v[60:63], v[134:137], v[192:195], v[60:63]
	v_mfma_f32_16x16x32_bf16 v[56:59], v[142:145], v[192:195], v[56:59]
	v_mfma_f32_16x16x32_bf16 v[44:47], v[134:137], v[200:203], v[44:47]
	v_mfma_f32_16x16x32_bf16 v[40:43], v[142:145], v[200:203], v[40:43]
	v_mfma_f32_16x16x32_bf16 v[28:31], v[134:137], v[208:211], v[28:31]
	v_mfma_f32_16x16x32_bf16 v[24:27], v[142:145], v[208:211], v[24:27]
	v_mfma_f32_16x16x32_bf16 v[12:15], v[134:137], v[216:219], v[12:15]
	v_mfma_f32_16x16x32_bf16 v[8:11], v[142:145], v[216:219], v[8:11]
	s_setprio 0
	s_setprio 1
	v_mfma_f32_16x16x32_bf16 v[52:55], v[146:149], v[162:165], 0
	v_mfma_f32_16x16x32_bf16 v[48:51], v[154:157], v[162:165], 0
	v_mfma_f32_16x16x32_bf16 v[36:39], v[146:149], v[196:199], 0
	v_mfma_f32_16x16x32_bf16 v[32:35], v[154:157], v[196:199], 0
	v_mfma_f32_16x16x32_bf16 v[20:23], v[146:149], v[204:207], 0
	v_mfma_f32_16x16x32_bf16 v[16:19], v[154:157], v[204:207], 0
	v_mfma_f32_16x16x32_bf16 v[4:7], v[146:149], v[212:215], 0
	v_mfma_f32_16x16x32_bf16 v[0:3], v[154:157], v[212:215], 0
	v_mfma_f32_16x16x32_bf16 v[52:55], v[150:153], v[192:195], v[52:55]
	v_mfma_f32_16x16x32_bf16 v[48:51], v[158:161], v[192:195], v[48:51]
	v_mfma_f32_16x16x32_bf16 v[36:39], v[150:153], v[200:203], v[36:39]
	v_mfma_f32_16x16x32_bf16 v[32:35], v[158:161], v[200:203], v[32:35]
	v_mfma_f32_16x16x32_bf16 v[20:23], v[150:153], v[208:211], v[20:23]
	v_mfma_f32_16x16x32_bf16 v[16:19], v[158:161], v[208:211], v[16:19]
	v_mfma_f32_16x16x32_bf16 v[4:7], v[150:153], v[216:219], v[4:7]
	v_mfma_f32_16x16x32_bf16 v[0:3], v[158:161], v[216:219], v[0:3]
	s_setprio 0
	s_barrier
	s_add_i32 s14, 0, 0x18000
	s_add_i32 s68, 0, 0x1c000
	v_add_u32_e32 v142, s14, v239
	v_add_u32_e32 v158, s68, v239
	ds_read_b128 v[130:133], v142
	ds_read_b128 v[134:137], v142 offset:1024
	ds_read_b128 v[138:141], v142 offset:2048
	ds_read_b128 v[142:145], v142 offset:3072
	ds_read_b128 v[146:149], v158
	ds_read_b128 v[150:153], v158 offset:1024
	ds_read_b128 v[154:157], v158 offset:2048
	ds_read_b128 v[158:161], v158 offset:3072
	v_lshl_add_u64 v[166:167], v[166:167], 0, s[94:95]
	s_mov_b32 m0, s53
	v_lshl_add_u64 v[248:249], v[166:167], 0, v[178:179]
	ds_read_b128 v[162:165], v171 offset:32768
	ds_read_b128 v[192:195], v171 offset:33792
	ds_read_b128 v[196:199], v171 offset:34816
	ds_read_b128 v[200:203], v171 offset:35840
	ds_read_b128 v[204:207], v171 offset:36864
	ds_read_b128 v[208:211], v171 offset:37888
	ds_read_b128 v[212:215], v171 offset:38912
	ds_read_b128 v[216:219], v171 offset:39936
	global_load_lds_dwordx4 v[248:249], off
	v_lshl_add_u64 v[166:167], v[166:167], 0, v[182:183]
	s_mov_b32 m0, s54
	s_nop 0
	global_load_lds_dwordx4 v[166:167], off
	s_waitcnt vmcnt(8)
	s_waitcnt lgkmcnt(0)
	s_barrier
	s_setprio 1
	s_waitcnt lgkmcnt(0)
	v_mfma_f32_16x16x32_bf16 v[124:127], v[130:133], v[162:165], v[124:127]
	v_mfma_f32_16x16x32_bf16 v[120:123], v[138:141], v[162:165], v[120:123]
	v_mfma_f32_16x16x32_bf16 v[108:111], v[130:133], v[196:199], v[108:111]
	v_mfma_f32_16x16x32_bf16 v[104:107], v[138:141], v[196:199], v[104:107]
	v_mfma_f32_16x16x32_bf16 v[92:95], v[130:133], v[204:207], v[92:95]
	v_mfma_f32_16x16x32_bf16 v[88:91], v[138:141], v[204:207], v[88:91]
	v_mfma_f32_16x16x32_bf16 v[76:79], v[130:133], v[212:215], v[76:79]
	v_mfma_f32_16x16x32_bf16 v[72:75], v[138:141], v[212:215], v[72:75]
	v_mfma_f32_16x16x32_bf16 v[124:127], v[134:137], v[192:195], v[124:127]
	v_mfma_f32_16x16x32_bf16 v[120:123], v[142:145], v[192:195], v[120:123]
	v_mfma_f32_16x16x32_bf16 v[108:111], v[134:137], v[200:203], v[108:111]
	v_mfma_f32_16x16x32_bf16 v[104:107], v[142:145], v[200:203], v[104:107]
	v_mfma_f32_16x16x32_bf16 v[92:95], v[134:137], v[208:211], v[92:95]
	v_mfma_f32_16x16x32_bf16 v[88:91], v[142:145], v[208:211], v[88:91]
	v_mfma_f32_16x16x32_bf16 v[76:79], v[134:137], v[216:219], v[76:79]
	v_mfma_f32_16x16x32_bf16 v[72:75], v[142:145], v[216:219], v[72:75]
	s_setprio 0
	s_setprio 1
	v_mfma_f32_16x16x32_bf16 v[116:119], v[146:149], v[162:165], v[116:119]
	v_mfma_f32_16x16x32_bf16 v[112:115], v[154:157], v[162:165], v[112:115]
	v_mfma_f32_16x16x32_bf16 v[100:103], v[146:149], v[196:199], v[100:103]
	v_mfma_f32_16x16x32_bf16 v[96:99], v[154:157], v[196:199], v[96:99]
	v_mfma_f32_16x16x32_bf16 v[84:87], v[146:149], v[204:207], v[84:87]
	v_mfma_f32_16x16x32_bf16 v[80:83], v[154:157], v[204:207], v[80:83]
	v_mfma_f32_16x16x32_bf16 v[68:71], v[146:149], v[212:215], v[68:71]
	v_mfma_f32_16x16x32_bf16 v[64:67], v[154:157], v[212:215], v[64:67]
	v_mfma_f32_16x16x32_bf16 v[116:119], v[150:153], v[192:195], v[116:119]
	v_mfma_f32_16x16x32_bf16 v[112:115], v[158:161], v[192:195], v[112:115]
	v_mfma_f32_16x16x32_bf16 v[100:103], v[150:153], v[200:203], v[100:103]
	v_mfma_f32_16x16x32_bf16 v[96:99], v[158:161], v[200:203], v[96:99]
	v_mfma_f32_16x16x32_bf16 v[84:87], v[150:153], v[208:211], v[84:87]
	v_mfma_f32_16x16x32_bf16 v[80:83], v[158:161], v[208:211], v[80:83]
	v_mfma_f32_16x16x32_bf16 v[68:71], v[150:153], v[216:219], v[68:71]
	v_mfma_f32_16x16x32_bf16 v[64:67], v[158:161], v[216:219], v[64:67]
	s_setprio 0
	s_barrier
; #define PG8_STAGE(bufoff, gbase, voff) do { _Pragma("unroll") for (int _i = 0; _i < 2; ++_i) \
;         __builtin_amdgcn_global_load_lds((const unsigned*)((const char*)(gbase) + (voff)[_i]), (LAS unsigned*)(lds + (bufoff) + ldsw + _i * 8192), 16, 0, 0); } while (0)
; #define PG8_LDA(dst, b, h) do { _Pragma("unroll") for (int m = 0; m < 4; ++m) _Pragma("unroll") for (int k = 0; k < 2; ++k) dst[m][k] = *(const LAS bf16x8*)(lds + PG8_SA(b, h) + aoff + m * 2048 + k * 1024); } while (0)
; #define PG8_LDB(dst, b, h) do { _Pragma("unroll") for (int n = 0; n < 2; ++n) _Pragma("unroll") for (int k = 0; k < 2; ++k) dst[n][k] = *(const LAS bf16x8*)(lds + PG8_SB(b, h) + boff + n * 2048 + k * 1024); } while (0)
; #define PG8_MMA(ai, bj, At, Bt) do { __builtin_amdgcn_s_setprio(1); _Pragma("unroll") for (int k = 0; k < 2; ++k) _Pragma("unroll") for (int m = 0; m < 4; ++m) _Pragma("unroll") for (int n = 0; n < 2; ++n) \
;         acc[ai][bj][m][n] = __builtin_amdgcn_mfma_f32_16x16x32_bf16(Bt[n][k], At[m][k], acc[ai][bj][m][n], 0, 0, 0); __builtin_amdgcn_s_setprio(0); } while (0)
; #define PG8_WAIT_V(n) asm volatile("s_waitcnt vmcnt(" #n ")" ::: "memory")
; #define PG8_WAIT_L(n) asm volatile("s_waitcnt lgkmcnt(" #n ")" ::: "memory")
; #define PG8_BAR __builtin_amdgcn_s_barrier()
; #define PG8_SCHED __builtin_amdgcn_sched_barrier(0)
; template <class Epi, bool ALIGN_EPI>
; __device__ __forceinline__ void gemm_phase(LAS unsigned char* lds, const Gemm g, const StaticOrder& S, const Epi& E, const int tid) {
;     ...
;             PG8_LDB(B0, 0, 0); PG8_LDB(B1, 0, 1); PG8_SCHED; PG8_LDA(At, 0, 0); PG8_STAGE(PG8_SA(1, 1), a1 + hA, voffA);
;             PG8_WAIT_V(8); PG8_WAIT_L(0); PG8_BAR; PG8_MMA(0, 0, At, B0); PG8_MMA(0, 1, At, B1); PG8_BAR; PG8_SCHED;
;     ...
;             PG8_WAIT_V(8); PG8_WAIT_L(0); PG8_BAR; PG8_MMA(0, 0, At, B0); PG8_MMA(0, 1, At, B1); PG8_BAR; PG8_SCHED;
;             PG8_LDA(At, 1, 1); PG8_STAGE(PG8_SB(1, 0), b3, voffB); PG8_STAGE(PG8_SB(1, 1), b3 + hB, voffB); PG8_STAGE(PG8_SA(1, 0), a3, voffA);
;             PG8_WAIT_V(8); PG8_WAIT_L(0); PG8_BAR; PG8_MMA(1, 0, At, B0); PG8_MMA(1, 1, At, B1); PG8_BAR; PG8_SCHED;
;         }
	s_add_i32 s14, s14, s47
	v_lshl_add_u64 v[166:167], v[220:221], 0, s[92:93]
	s_mov_b32 m0, s14
	ds_read_b128 v[162:165], v171 offset:49152
	ds_read_b128 v[192:195], v171 offset:50176
	ds_read_b128 v[196:199], v171 offset:51200
	ds_read_b128 v[200:203], v171 offset:52224
	ds_read_b128 v[204:207], v171 offset:53248
	ds_read_b128 v[208:211], v171 offset:54272
	ds_read_b128 v[212:215], v171 offset:55296
	ds_read_b128 v[216:219], v171 offset:56320
	global_load_lds_dwordx4 v[166:167], off
	v_lshl_add_u64 v[166:167], v[226:227], 0, s[92:93]
	s_add_i32 m0, s14, 0x2000
	s_add_i32 s14, s68, s47
	global_load_lds_dwordx4 v[166:167], off
	v_lshl_add_u64 v[166:167], v[240:241], 0, s[92:93]
	s_mov_b32 m0, s14
	s_nop 0
	global_load_lds_dwordx4 v[166:167], off
	v_lshl_add_u64 v[166:167], v[242:243], 0, s[92:93]
	s_add_i32 m0, s14, 0x2000
	s_nop 0
	global_load_lds_dwordx4 v[166:167], off
	v_lshl_add_u64 v[166:167], v[244:245], 0, s[92:93]
	s_mov_b32 m0, s55
	s_nop 0
	global_load_lds_dwordx4 v[166:167], off
	v_lshl_add_u64 v[166:167], v[246:247], 0, s[92:93]
	s_mov_b32 m0, s56
	s_nop 0
	global_load_lds_dwordx4 v[166:167], off
	s_waitcnt vmcnt(8)
	s_waitcnt lgkmcnt(0)
	s_barrier
	s_setprio 1
	s_waitcnt lgkmcnt(0)
	v_mfma_f32_16x16x32_bf16 v[60:63], v[130:133], v[162:165], v[60:63]
	v_mfma_f32_16x16x32_bf16 v[56:59], v[138:141], v[162:165], v[56:59]
	v_mfma_f32_16x16x32_bf16 v[44:47], v[130:133], v[196:199], v[44:47]
	v_mfma_f32_16x16x32_bf16 v[40:43], v[138:141], v[196:199], v[40:43]
	v_mfma_f32_16x16x32_bf16 v[28:31], v[130:133], v[204:207], v[28:31]
	v_mfma_f32_16x16x32_bf16 v[24:27], v[138:141], v[204:207], v[24:27]
	v_mfma_f32_16x16x32_bf16 v[12:15], v[130:133], v[212:215], v[12:15]
	v_mfma_f32_16x16x32_bf16 v[8:11], v[138:141], v[212:215], v[8:11]
	v_mfma_f32_16x16x32_bf16 v[60:63], v[134:137], v[192:195], v[60:63]
	v_mfma_f32_16x16x32_bf16 v[56:59], v[142:145], v[192:195], v[56:59]
	v_mfma_f32_16x16x32_bf16 v[44:47], v[134:137], v[200:203], v[44:47]
	v_mfma_f32_16x16x32_bf16 v[40:43], v[142:145], v[200:203], v[40:43]
	v_mfma_f32_16x16x32_bf16 v[28:31], v[134:137], v[208:211], v[28:31]
	v_mfma_f32_16x16x32_bf16 v[24:27], v[142:145], v[208:211], v[24:27]
	v_mfma_f32_16x16x32_bf16 v[12:15], v[134:137], v[216:219], v[12:15]
	v_mfma_f32_16x16x32_bf16 v[8:11], v[142:145], v[216:219], v[8:11]
	s_setprio 0
	s_setprio 1
	v_mfma_f32_16x16x32_bf16 v[52:55], v[146:149], v[162:165], v[52:55]
	v_mfma_f32_16x16x32_bf16 v[48:51], v[154:157], v[162:165], v[48:51]
	v_mfma_f32_16x16x32_bf16 v[36:39], v[146:149], v[196:199], v[36:39]
	v_mfma_f32_16x16x32_bf16 v[32:35], v[154:157], v[196:199], v[32:35]
	v_mfma_f32_16x16x32_bf16 v[20:23], v[146:149], v[204:207], v[20:23]
	v_mfma_f32_16x16x32_bf16 v[16:19], v[154:157], v[204:207], v[16:19]
	v_mfma_f32_16x16x32_bf16 v[4:7], v[146:149], v[212:215], v[4:7]
	v_mfma_f32_16x16x32_bf16 v[0:3], v[154:157], v[212:215], v[0:3]
	v_mfma_f32_16x16x32_bf16 v[52:55], v[150:153], v[192:195], v[52:55]
	v_mfma_f32_16x16x32_bf16 v[48:51], v[158:161], v[192:195], v[48:51]
	v_mfma_f32_16x16x32_bf16 v[36:39], v[150:153], v[200:203], v[36:39]
	v_mfma_f32_16x16x32_bf16 v[32:35], v[158:161], v[200:203], v[32:35]
	v_mfma_f32_16x16x32_bf16 v[20:23], v[150:153], v[208:211], v[20:23]
	v_mfma_f32_16x16x32_bf16 v[16:19], v[158:161], v[208:211], v[16:19]
	v_mfma_f32_16x16x32_bf16 v[4:7], v[150:153], v[216:219], v[4:7]
	v_mfma_f32_16x16x32_bf16 v[0:3], v[158:161], v[216:219], v[0:3]
	s_setprio 0
	s_add_u32 s10, s10, 0x100
	s_addc_u32 s11, s11, 0
	v_lshl_add_u64 v[128:129], v[128:129], 0, s[80:81]
	s_cmp_ge_u32 s15, s48
	s_mov_b32 s14, s15
	s_barrier
	s_cbranch_scc1 .Lpl2_after
.LBB0_274:
	s_add_i32 s15, s14, 2
	s_cmp_eq_u32 s57, s14
	s_cselect_b64 vcc, -1, 0
	s_cselect_b32 s69, s13, s11
	s_cselect_b32 s68, s12, s10
	s_add_i32 s14, 0, 0x14000
	v_lshl_add_u64 v[130:131], v[128:129], 0, s[92:93]
	v_add_u32_e32 v142, s33, v239
	v_add_u32_e32 v158, s14, v239
	v_cndmask_b32_e32 v167, v131, v191, vcc
	v_cndmask_b32_e32 v166, v130, v190, vcc
	ds_read_b128 v[130:133], v142
	ds_read_b128 v[134:137], v142 offset:1024
	ds_read_b128 v[138:141], v142 offset:2048
	ds_read_b128 v[142:145], v142 offset:3072
	ds_read_b128 v[146:149], v158
	ds_read_b128 v[150:153], v158 offset:1024
	ds_read_b128 v[154:157], v158 offset:2048
	ds_read_b128 v[158:161], v158 offset:3072
	v_lshl_add_u64 v[220:221], v[128:129], 0, v[186:187]
	s_add_i32 m0, s51, 0xc000
	ds_read_b128 v[162:165], v171
	ds_read_b128 v[192:195], v171 offset:1024
	ds_read_b128 v[196:199], v171 offset:2048
	ds_read_b128 v[200:203], v171 offset:3072
	ds_read_b128 v[204:207], v171 offset:4096
	ds_read_b128 v[208:211], v171 offset:5120
	ds_read_b128 v[212:215], v171 offset:6144
	ds_read_b128 v[216:219], v171 offset:7168
	global_load_lds_dwordx4 v[220:221], off
	v_lshl_add_u64 v[220:221], v[128:129], 0, v[188:189]
	s_add_i32 m0, s51, 0xe000
	s_nop 0
	global_load_lds_dwordx4 v[220:221], off
	s_waitcnt vmcnt(8)
	s_waitcnt lgkmcnt(0)
	s_barrier
; #define PG8_STAGE(bufoff, gbase, voff) do { _Pragma("unroll") for (int _i = 0; _i < 2; ++_i) \
;         __builtin_amdgcn_global_load_lds((const unsigned*)((const char*)(gbase) + (voff)[_i]), (LAS unsigned*)(lds + (bufoff) + ldsw + _i * 8192), 16, 0, 0); } while (0)
; #define PG8_LDA(dst, b, h) do { _Pragma("unroll") for (int m = 0; m < 4; ++m) _Pragma("unroll") for (int k = 0; k < 2; ++k) dst[m][k] = *(const LAS bf16x8*)(lds + PG8_SA(b, h) + aoff + m * 2048 + k * 1024); } while (0)
; #define PG8_LDB(dst, b, h) do { _Pragma("unroll") for (int n = 0; n < 2; ++n) _Pragma("unroll") for (int k = 0; k < 2; ++k) dst[n][k] = *(const LAS bf16x8*)(lds + PG8_SB(b, h) + boff + n * 2048 + k * 1024); } while (0)
; #define PG8_MMA(ai, bj, At, Bt) do { __builtin_amdgcn_s_setprio(1); _Pragma("unroll") for (int k = 0; k < 2; ++k) _Pragma("unroll") for (int m = 0; m < 4; ++m) _Pragma("unroll") for (int n = 0; n < 2; ++n) \
;         acc[ai][bj][m][n] = __builtin_amdgcn_mfma_f32_16x16x32_bf16(Bt[n][k], At[m][k], acc[ai][bj][m][n], 0, 0, 0); __builtin_amdgcn_s_setprio(0); } while (0)
; #define PG8_WAIT_V(n) asm volatile("s_waitcnt vmcnt(" #n ")" ::: "memory")
; #define PG8_WAIT_L(n) asm volatile("s_waitcnt lgkmcnt(" #n ")" ::: "memory")
; #define PG8_BAR __builtin_amdgcn_s_barrier()
; #define PG8_SCHED __builtin_amdgcn_sched_barrier(0)
; template <class Epi, bool ALIGN_EPI>
; __device__ __forceinline__ void gemm_phase(LAS unsigned char* lds, const Gemm g, const StaticOrder& S, const Epi& E, const int tid) {
;     ...
;             PG8_WAIT_V(8); PG8_WAIT_L(0); PG8_BAR; PG8_MMA(0, 0, At, B0); PG8_MMA(0, 1, At, B1); PG8_BAR; PG8_SCHED;
;             PG8_LDA(At, 0, 1); PG8_STAGE(PG8_SB(0, 0), b2, voffB); PG8_STAGE(PG8_SB(0, 1), b2 + hB, voffB); PG8_STAGE(PG8_SA(0, 0), a2, voffA);
;             PG8_WAIT_V(8); PG8_WAIT_L(0); PG8_BAR; PG8_MMA(1, 0, At, B0); PG8_MMA(1, 1, At, B1); PG8_BAR; PG8_SCHED;
;             PG8_LDB(B0, 1, 0); PG8_LDB(B1, 1, 1); PG8_SCHED; PG8_LDA(At, 1, 0); PG8_STAGE(PG8_SA(0, 1), a2 + hA, voffA);
;             PG8_WAIT_V(8); PG8_WAIT_L(0); PG8_BAR; PG8_MMA(0, 0, At, B0); PG8_MMA(0, 1, At, B1); PG8_BAR; PG8_SCHED;
	s_setprio 1
	s_waitcnt lgkmcnt(0)
	v_mfma_f32_16x16x32_bf16 v[124:127], v[130:133], v[162:165], v[124:127]
	v_mfma_f32_16x16x32_bf16 v[120:123], v[138:141], v[162:165], v[120:123]
	v_mfma_f32_16x16x32_bf16 v[108:111], v[130:133], v[196:199], v[108:111]
	v_mfma_f32_16x16x32_bf16 v[104:107], v[138:141], v[196:199], v[104:107]
	v_mfma_f32_16x16x32_bf16 v[92:95], v[130:133], v[204:207], v[92:95]
	v_mfma_f32_16x16x32_bf16 v[88:91], v[138:141], v[204:207], v[88:91]
	v_mfma_f32_16x16x32_bf16 v[76:79], v[130:133], v[212:215], v[76:79]
	v_mfma_f32_16x16x32_bf16 v[72:75], v[138:141], v[212:215], v[72:75]
	v_mfma_f32_16x16x32_bf16 v[124:127], v[134:137], v[192:195], v[124:127]
	v_mfma_f32_16x16x32_bf16 v[120:123], v[142:145], v[192:195], v[120:123]
	v_mfma_f32_16x16x32_bf16 v[108:111], v[134:137], v[200:203], v[108:111]
	v_mfma_f32_16x16x32_bf16 v[104:107], v[142:145], v[200:203], v[104:107]
	v_mfma_f32_16x16x32_bf16 v[92:95], v[134:137], v[208:211], v[92:95]
	v_mfma_f32_16x16x32_bf16 v[88:91], v[142:145], v[208:211], v[88:91]
	v_mfma_f32_16x16x32_bf16 v[76:79], v[134:137], v[216:219], v[76:79]
	v_mfma_f32_16x16x32_bf16 v[72:75], v[142:145], v[216:219], v[72:75]
	s_setprio 0
	s_setprio 1
	v_mfma_f32_16x16x32_bf16 v[116:119], v[146:149], v[162:165], v[116:119]
	v_mfma_f32_16x16x32_bf16 v[112:115], v[154:157], v[162:165], v[112:115]
	v_mfma_f32_16x16x32_bf16 v[100:103], v[146:149], v[196:199], v[100:103]
	v_mfma_f32_16x16x32_bf16 v[96:99], v[154:157], v[196:199], v[96:99]
	v_mfma_f32_16x16x32_bf16 v[84:87], v[146:149], v[204:207], v[84:87]
	v_mfma_f32_16x16x32_bf16 v[80:83], v[154:157], v[204:207], v[80:83]
	v_mfma_f32_16x16x32_bf16 v[68:71], v[146:149], v[212:215], v[68:71]
	v_mfma_f32_16x16x32_bf16 v[64:67], v[154:157], v[212:215], v[64:67]
	v_mfma_f32_16x16x32_bf16 v[116:119], v[150:153], v[192:195], v[116:119]
	v_mfma_f32_16x16x32_bf16 v[112:115], v[158:161], v[192:195], v[112:115]
	v_mfma_f32_16x16x32_bf16 v[100:103], v[150:153], v[200:203], v[100:103]
	v_mfma_f32_16x16x32_bf16 v[96:99], v[158:161], v[200:203], v[96:99]
	v_mfma_f32_16x16x32_bf16 v[84:87], v[150:153], v[208:211], v[84:87]
	v_mfma_f32_16x16x32_bf16 v[80:83], v[158:161], v[208:211], v[80:83]
	v_mfma_f32_16x16x32_bf16 v[68:71], v[150:153], v[216:219], v[68:71]
	v_mfma_f32_16x16x32_bf16 v[64:67], v[158:161], v[216:219], v[64:67]
	s_setprio 0
	s_barrier
	s_add_i32 s70, s33, s47
	v_lshl_add_u64 v[220:221], s[68:69], 0, v[180:181]
	s_mov_b32 m0, s70
	ds_read_b128 v[162:165], v171 offset:16384
	ds_read_b128 v[192:195], v171 offset:17408
	ds_read_b128 v[196:199], v171 offset:18432
	ds_read_b128 v[200:203], v171 offset:19456
	ds_read_b128 v[204:207], v171 offset:20480
	ds_read_b128 v[208:211], v171 offset:21504
	ds_read_b128 v[212:215], v171 offset:22528
	ds_read_b128 v[216:219], v171 offset:23552
	global_load_lds_dwordx4 v[220:221], off
	s_add_i32 m0, s70, 0x2000
	v_lshl_add_u64 v[226:227], s[68:69], 0, v[184:185]
	s_add_u32 s68, s68, s49
	s_addc_u32 s69, s69, 0
	s_add_i32 s14, s14, s47
	global_load_lds_dwordx4 v[226:227], off
	v_lshl_add_u64 v[240:241], s[68:69], 0, v[180:181]
	s_mov_b32 m0, s14
	v_lshl_add_u64 v[242:243], s[68:69], 0, v[184:185]
	global_load_lds_dwordx4 v[240:241], off
	s_add_i32 m0, s14, 0x2000
	v_lshl_add_u64 v[244:245], v[166:167], 0, v[178:179]
	global_load_lds_dwordx4 v[242:243], off
	s_mov_b32 m0, s51
	v_lshl_add_u64 v[246:247], v[166:167], 0, v[182:183]
	global_load_lds_dwordx4 v[244:245], off
	s_mov_b32 m0, s52
	s_nop 0
	global_load_lds_dwordx4 v[246:247], off
	s_waitcnt vmcnt(8)
	s_waitcnt lgkmcnt(0)
	s_barrier
	s_setprio 1
	s_waitcnt lgkmcnt(0)
	v_mfma_f32_16x16x32_bf16 v[60:63], v[130:133], v[162:165], v[60:63]
	v_mfma_f32_16x16x32_bf16 v[56:59], v[138:141], v[162:165], v[56:59]
	v_mfma_f32_16x16x32_bf16 v[44:47], v[130:133], v[196:199], v[44:47]
	v_mfma_f32_16x16x32_bf16 v[40:43], v[138:141], v[196:199], v[40:43]
	v_mfma_f32_16x16x32_bf16 v[28:31], v[130:133], v[204:207], v[28:31]
	v_mfma_f32_16x16x32_bf16 v[24:27], v[138:141], v[204:207], v[24:27]
	v_mfma_f32_16x16x32_bf16 v[12:15], v[130:133], v[212:215], v[12:15]
	v_mfma_f32_16x16x32_bf16 v[8:11], v[138:141], v[212:215], v[8:11]
	v_mfma_f32_16x16x32_bf16 v[60:63], v[134:137], v[192:195], v[60:63]
	v_mfma_f32_16x16x32_bf16 v[56:59], v[142:145], v[192:195], v[56:59]
	v_mfma_f32_16x16x32_bf16 v[44:47], v[134:137], v[200:203], v[44:47]
	v_mfma_f32_16x16x32_bf16 v[40:43], v[142:145], v[200:203], v[40:43]
	v_mfma_f32_16x16x32_bf16 v[28:31], v[134:137], v[208:211], v[28:31]
	v_mfma_f32_16x16x32_bf16 v[24:27], v[142:145], v[208:211], v[24:27]
	v_mfma_f32_16x16x32_bf16 v[12:15], v[134:137], v[216:219], v[12:15]
	v_mfma_f32_16x16x32_bf16 v[8:11], v[142:145], v[216:219], v[8:11]
	s_setprio 0
	s_setprio 1
	v_mfma_f32_16x16x32_bf16 v[52:55], v[146:149], v[162:165], v[52:55]
	v_mfma_f32_16x16x32_bf16 v[48:51], v[154:157], v[162:165], v[48:51]
	v_mfma_f32_16x16x32_bf16 v[36:39], v[146:149], v[196:199], v[36:39]
	v_mfma_f32_16x16x32_bf16 v[32:35], v[154:157], v[196:199], v[32:35]
	v_mfma_f32_16x16x32_bf16 v[20:23], v[146:149], v[204:207], v[20:23]
	v_mfma_f32_16x16x32_bf16 v[16:19], v[154:157], v[204:207], v[16:19]
	v_mfma_f32_16x16x32_bf16 v[4:7], v[146:149], v[212:215], v[4:7]
	v_mfma_f32_16x16x32_bf16 v[0:3], v[154:157], v[212:215], v[0:3]
	v_mfma_f32_16x16x32_bf16 v[52:55], v[150:153], v[192:195], v[52:55]
	v_mfma_f32_16x16x32_bf16 v[48:51], v[158:161], v[192:195], v[48:51]
	v_mfma_f32_16x16x32_bf16 v[36:39], v[150:153], v[200:203], v[36:39]
	v_mfma_f32_16x16x32_bf16 v[32:35], v[158:161], v[200:203], v[32:35]
	v_mfma_f32_16x16x32_bf16 v[20:23], v[150:153], v[208:211], v[20:23]
	v_mfma_f32_16x16x32_bf16 v[16:19], v[158:161], v[208:211], v[16:19]
	v_mfma_f32_16x16x32_bf16 v[4:7], v[150:153], v[216:219], v[4:7]
	v_mfma_f32_16x16x32_bf16 v[0:3], v[158:161], v[216:219], v[0:3]
	s_setprio 0
	s_barrier
; #define PG8_STAGE(bufoff, gbase, voff) do { _Pragma("unroll") for (int _i = 0; _i < 2; ++_i) \
;         __builtin_amdgcn_global_load_lds((const unsigned*)((const char*)(gbase) + (voff)[_i]), (LAS unsigned*)(lds + (bufoff) + ldsw + _i * 8192), 16, 0, 0); } while (0)
; #define PG8_LDA(dst, b, h) do { _Pragma("unroll") for (int m = 0; m < 4; ++m) _Pragma("unroll") for (int k = 0; k < 2; ++k) dst[m][k] = *(const LAS bf16x8*)(lds + PG8_SA(b, h) + aoff + m * 2048 + k * 1024); } while (0)
; #define PG8_MMA(ai, bj, At, Bt) do { __builtin_amdgcn_s_setprio(1); _Pragma("unroll") for (int k = 0; k < 2; ++k) _Pragma("unroll") for (int m = 0; m < 4; ++m) _Pragma("unroll") for (int n = 0; n < 2; ++n) \
;         acc[ai][bj][m][n] = __builtin_amdgcn_mfma_f32_16x16x32_bf16(Bt[n][k], At[m][k], acc[ai][bj][m][n], 0, 0, 0); __builtin_amdgcn_s_setprio(0); } while (0)
; #define PG8_WAIT_V(n) asm volatile("s_waitcnt vmcnt(" #n ")" ::: "memory")
; #define PG8_WAIT_L(n) asm volatile("s_waitcnt lgkmcnt(" #n ")" ::: "memory")
; #define PG8_BAR __builtin_amdgcn_s_barrier()
; #define PG8_SCHED __builtin_amdgcn_sched_barrier(0)
; template <class Epi, bool ALIGN_EPI>
; __device__ __forceinline__ void gemm_phase(LAS unsigned char* lds, const Gemm g, const StaticOrder& S, const Epi& E, const int tid) {
;     ...
;             PG8_LDA(At, 1, 1); PG8_STAGE(PG8_SB(1, 0), b3, voffB); PG8_STAGE(PG8_SB(1, 1), b3 + hB, voffB); PG8_STAGE(PG8_SA(1, 0), a3, voffA);
;             PG8_WAIT_V(8); PG8_WAIT_L(0); PG8_BAR; PG8_MMA(1, 0, At, B0); PG8_MMA(1, 1, At, B1); PG8_BAR; PG8_SCHED;
	s_add_i32 s14, 0, 0x18000
	s_add_i32 s68, 0, 0x1c000
	v_add_u32_e32 v142, s14, v239
	v_add_u32_e32 v158, s68, v239
	ds_read_b128 v[130:133], v142
	ds_read_b128 v[134:137], v142 offset:1024
	ds_read_b128 v[138:141], v142 offset:2048
	ds_read_b128 v[142:145], v142 offset:3072
	ds_read_b128 v[146:149], v158
	ds_read_b128 v[150:153], v158 offset:1024
	ds_read_b128 v[154:157], v158 offset:2048
	ds_read_b128 v[158:161], v158 offset:3072
	v_lshl_add_u64 v[166:167], v[166:167], 0, s[94:95]
	s_mov_b32 m0, s53
	v_lshl_add_u64 v[248:249], v[166:167], 0, v[178:179]
	ds_read_b128 v[162:165], v171 offset:32768
	ds_read_b128 v[192:195], v171 offset:33792
	ds_read_b128 v[196:199], v171 offset:34816
	ds_read_b128 v[200:203], v171 offset:35840
	ds_read_b128 v[204:207], v171 offset:36864
	ds_read_b128 v[208:211], v171 offset:37888
	ds_read_b128 v[212:215], v171 offset:38912
	ds_read_b128 v[216:219], v171 offset:39936
	global_load_lds_dwordx4 v[248:249], off
	v_lshl_add_u64 v[166:167], v[166:167], 0, v[182:183]
	s_mov_b32 m0, s54
	s_nop 0
	global_load_lds_dwordx4 v[166:167], off
	s_waitcnt vmcnt(8)
	s_waitcnt lgkmcnt(0)
	s_barrier
	s_setprio 1
	s_waitcnt lgkmcnt(0)
	v_mfma_f32_16x16x32_bf16 v[124:127], v[130:133], v[162:165], v[124:127]
	v_mfma_f32_16x16x32_bf16 v[120:123], v[138:141], v[162:165], v[120:123]
	v_mfma_f32_16x16x32_bf16 v[108:111], v[130:133], v[196:199], v[108:111]
	v_mfma_f32_16x16x32_bf16 v[104:107], v[138:141], v[196:199], v[104:107]
	v_mfma_f32_16x16x32_bf16 v[92:95], v[130:133], v[204:207], v[92:95]
	v_mfma_f32_16x16x32_bf16 v[88:91], v[138:141], v[204:207], v[88:91]
	v_mfma_f32_16x16x32_bf16 v[76:79], v[130:133], v[212:215], v[76:79]
	v_mfma_f32_16x16x32_bf16 v[72:75], v[138:141], v[212:215], v[72:75]
	v_mfma_f32_16x16x32_bf16 v[124:127], v[134:137], v[192:195], v[124:127]
	v_mfma_f32_16x16x32_bf16 v[120:123], v[142:145], v[192:195], v[120:123]
	v_mfma_f32_16x16x32_bf16 v[108:111], v[134:137], v[200:203], v[108:111]
	v_mfma_f32_16x16x32_bf16 v[104:107], v[142:145], v[200:203], v[104:107]
	v_mfma_f32_16x16x32_bf16 v[92:95], v[134:137], v[208:211], v[92:95]
	v_mfma_f32_16x16x32_bf16 v[88:91], v[142:145], v[208:211], v[88:91]
	v_mfma_f32_16x16x32_bf16 v[76:79], v[134:137], v[216:219], v[76:79]
	v_mfma_f32_16x16x32_bf16 v[72:75], v[142:145], v[216:219], v[72:75]
	s_setprio 0
	s_setprio 1
	v_mfma_f32_16x16x32_bf16 v[116:119], v[146:149], v[162:165], v[116:119]
	v_mfma_f32_16x16x32_bf16 v[112:115], v[154:157], v[162:165], v[112:115]
	v_mfma_f32_16x16x32_bf16 v[100:103], v[146:149], v[196:199], v[100:103]
	v_mfma_f32_16x16x32_bf16 v[96:99], v[154:157], v[196:199], v[96:99]
	v_mfma_f32_16x16x32_bf16 v[84:87], v[146:149], v[204:207], v[84:87]
	v_mfma_f32_16x16x32_bf16 v[80:83], v[154:157], v[204:207], v[80:83]
	v_mfma_f32_16x16x32_bf16 v[68:71], v[146:149], v[212:215], v[68:71]
	v_mfma_f32_16x16x32_bf16 v[64:67], v[154:157], v[212:215], v[64:67]
	v_mfma_f32_16x16x32_bf16 v[116:119], v[150:153], v[192:195], v[116:119]
	v_mfma_f32_16x16x32_bf16 v[112:115], v[158:161], v[192:195], v[112:115]
	v_mfma_f32_16x16x32_bf16 v[100:103], v[150:153], v[200:203], v[100:103]
	v_mfma_f32_16x16x32_bf16 v[96:99], v[158:161], v[200:203], v[96:99]
	v_mfma_f32_16x16x32_bf16 v[84:87], v[150:153], v[208:211], v[84:87]
	v_mfma_f32_16x16x32_bf16 v[80:83], v[158:161], v[208:211], v[80:83]
	v_mfma_f32_16x16x32_bf16 v[68:71], v[150:153], v[216:219], v[68:71]
	v_mfma_f32_16x16x32_bf16 v[64:67], v[158:161], v[216:219], v[64:67]
	s_setprio 0
	s_barrier
; #define PG8_STAGE(bufoff, gbase, voff) do { _Pragma("unroll") for (int _i = 0; _i < 2; ++_i) \
;         __builtin_amdgcn_global_load_lds((const unsigned*)((const char*)(gbase) + (voff)[_i]), (LAS unsigned*)(lds + (bufoff) + ldsw + _i * 8192), 16, 0, 0); } while (0)
; #define PG8_LDA(dst, b, h) do { _Pragma("unroll") for (int m = 0; m < 4; ++m) _Pragma("unroll") for (int k = 0; k < 2; ++k) dst[m][k] = *(const LAS bf16x8*)(lds + PG8_SA(b, h) + aoff + m * 2048 + k * 1024); } while (0)
; #define PG8_MMA(ai, bj, At, Bt) do { __builtin_amdgcn_s_setprio(1); _Pragma("unroll") for (int k = 0; k < 2; ++k) _Pragma("unroll") for (int m = 0; m < 4; ++m) _Pragma("unroll") for (int n = 0; n < 2; ++n) \
;         acc[ai][bj][m][n] = __builtin_amdgcn_mfma_f32_16x16x32_bf16(Bt[n][k], At[m][k], acc[ai][bj][m][n], 0, 0, 0); __builtin_amdgcn_s_setprio(0); } while (0)
; #define PG8_WAIT_V(n) asm volatile("s_waitcnt vmcnt(" #n ")" ::: "memory")
; #define PG8_WAIT_L(n) asm volatile("s_waitcnt lgkmcnt(" #n ")" ::: "memory")
; #define PG8_BAR __builtin_amdgcn_s_barrier()
; #define PG8_SCHED __builtin_amdgcn_sched_barrier(0)
; template <class Epi, bool ALIGN_EPI>
; __device__ __forceinline__ void gemm_phase(LAS unsigned char* lds, const Gemm g, const StaticOrder& S, const Epi& E, const int tid) {
;     ...
;             PG8_LDA(At, 1, 1); PG8_STAGE(PG8_SB(1, 0), b3, voffB); PG8_STAGE(PG8_SB(1, 1), b3 + hB, voffB); PG8_STAGE(PG8_SA(1, 0), a3, voffA);
;             PG8_WAIT_V(8); PG8_WAIT_L(0); PG8_BAR; PG8_MMA(1, 0, At, B0); PG8_MMA(1, 1, At, B1); PG8_BAR; PG8_SCHED;
;         }
	s_add_i32 s14, s14, s47
	v_lshl_add_u64 v[166:167], v[220:221], 0, s[92:93]
	s_mov_b32 m0, s14
	ds_read_b128 v[162:165], v171 offset:49152
	ds_read_b128 v[192:195], v171 offset:50176
	ds_read_b128 v[196:199], v171 offset:51200
	ds_read_b128 v[200:203], v171 offset:52224
	ds_read_b128 v[204:207], v171 offset:53248
	ds_read_b128 v[208:211], v171 offset:54272
	ds_read_b128 v[212:215], v171 offset:55296
	ds_read_b128 v[216:219], v171 offset:56320
	global_load_lds_dwordx4 v[166:167], off
	v_lshl_add_u64 v[166:167], v[226:227], 0, s[92:93]
	s_add_i32 m0, s14, 0x2000
	s_add_i32 s14, s68, s47
	global_load_lds_dwordx4 v[166:167], off
	v_lshl_add_u64 v[166:167], v[240:241], 0, s[92:93]
	s_mov_b32 m0, s14
	s_nop 0
	global_load_lds_dwordx4 v[166:167], off
	v_lshl_add_u64 v[166:167], v[242:243], 0, s[92:93]
	s_add_i32 m0, s14, 0x2000
	s_nop 0
	global_load_lds_dwordx4 v[166:167], off
	v_lshl_add_u64 v[166:167], v[244:245], 0, s[92:93]
	s_mov_b32 m0, s55
	s_nop 0
	global_load_lds_dwordx4 v[166:167], off
	v_lshl_add_u64 v[166:167], v[246:247], 0, s[92:93]
	s_mov_b32 m0, s56
	s_nop 0
	global_load_lds_dwordx4 v[166:167], off
	s_waitcnt vmcnt(8)
	s_waitcnt lgkmcnt(0)
	s_barrier
	s_setprio 1
	s_waitcnt lgkmcnt(0)
	v_mfma_f32_16x16x32_bf16 v[60:63], v[130:133], v[162:165], v[60:63]
	v_mfma_f32_16x16x32_bf16 v[56:59], v[138:141], v[162:165], v[56:59]
	v_mfma_f32_16x16x32_bf16 v[44:47], v[130:133], v[196:199], v[44:47]
	v_mfma_f32_16x16x32_bf16 v[40:43], v[138:141], v[196:199], v[40:43]
	v_mfma_f32_16x16x32_bf16 v[28:31], v[130:133], v[204:207], v[28:31]
	v_mfma_f32_16x16x32_bf16 v[24:27], v[138:141], v[204:207], v[24:27]
	v_mfma_f32_16x16x32_bf16 v[12:15], v[130:133], v[212:215], v[12:15]
	v_mfma_f32_16x16x32_bf16 v[8:11], v[138:141], v[212:215], v[8:11]
	v_mfma_f32_16x16x32_bf16 v[60:63], v[134:137], v[192:195], v[60:63]
	v_mfma_f32_16x16x32_bf16 v[56:59], v[142:145], v[192:195], v[56:59]
	v_mfma_f32_16x16x32_bf16 v[44:47], v[134:137], v[200:203], v[44:47]
	v_mfma_f32_16x16x32_bf16 v[40:43], v[142:145], v[200:203], v[40:43]
	v_mfma_f32_16x16x32_bf16 v[28:31], v[134:137], v[208:211], v[28:31]
	v_mfma_f32_16x16x32_bf16 v[24:27], v[142:145], v[208:211], v[24:27]
	v_mfma_f32_16x16x32_bf16 v[12:15], v[134:137], v[216:219], v[12:15]
	v_mfma_f32_16x16x32_bf16 v[8:11], v[142:145], v[216:219], v[8:11]
	s_setprio 0
	s_setprio 1
	v_mfma_f32_16x16x32_bf16 v[52:55], v[146:149], v[162:165], v[52:55]
	v_mfma_f32_16x16x32_bf16 v[48:51], v[154:157], v[162:165], v[48:51]
	v_mfma_f32_16x16x32_bf16 v[36:39], v[146:149], v[196:199], v[36:39]
	v_mfma_f32_16x16x32_bf16 v[32:35], v[154:157], v[196:199], v[32:35]
	v_mfma_f32_16x16x32_bf16 v[20:23], v[146:149], v[204:207], v[20:23]
	v_mfma_f32_16x16x32_bf16 v[16:19], v[154:157], v[204:207], v[16:19]
	v_mfma_f32_16x16x32_bf16 v[4:7], v[146:149], v[212:215], v[4:7]
	v_mfma_f32_16x16x32_bf16 v[0:3], v[154:157], v[212:215], v[0:3]
	v_mfma_f32_16x16x32_bf16 v[52:55], v[150:153], v[192:195], v[52:55]
	v_mfma_f32_16x16x32_bf16 v[48:51], v[158:161], v[192:195], v[48:51]
	v_mfma_f32_16x16x32_bf16 v[36:39], v[150:153], v[200:203], v[36:39]
	v_mfma_f32_16x16x32_bf16 v[32:35], v[158:161], v[200:203], v[32:35]
	v_mfma_f32_16x16x32_bf16 v[20:23], v[150:153], v[208:211], v[20:23]
	v_mfma_f32_16x16x32_bf16 v[16:19], v[158:161], v[208:211], v[16:19]
	v_mfma_f32_16x16x32_bf16 v[4:7], v[150:153], v[216:219], v[4:7]
	v_mfma_f32_16x16x32_bf16 v[0:3], v[158:161], v[216:219], v[0:3]
	s_setprio 0
	s_add_u32 s10, s10, 0x100
	s_addc_u32 s11, s11, 0
	v_lshl_add_u64 v[128:129], v[128:129], 0, s[80:81]
	s_cmp_ge_u32 s15, s48
	s_mov_b32 s14, s15
	s_barrier
	s_cbranch_scc0 .LBB0_274

; __device__ __forceinline__ unsigned cvt_pk_bf16(float lo, float hi) { unsigned r; asm volatile("v_cvt_pk_bf16_f32 %0, %1, %2" : "=v"(r) : "v"(lo), "v"(hi)); return r; }
; __device__ __forceinline__ float siluf_(float x) { return x * sigmoidf_(x); }
; #define PG8_STAGE(bufoff, gbase, voff) do { _Pragma("unroll") for (int _i = 0; _i < 2; ++_i) \
;         __builtin_amdgcn_global_load_lds((const unsigned*)((const char*)(gbase) + (voff)[_i]), (LAS unsigned*)(lds + (bufoff) + ldsw + _i * 8192), 16, 0, 0); } while (0)
; #define PG8_LDA(dst, b, h) do { _Pragma("unroll") for (int m = 0; m < 4; ++m) _Pragma("unroll") for (int k = 0; k < 2; ++k) dst[m][k] = *(const LAS bf16x8*)(lds + PG8_SA(b, h) + aoff + m * 2048 + k * 1024); } while (0)
; #define PG8_LDB(dst, b, h) do { _Pragma("unroll") for (int n = 0; n < 2; ++n) _Pragma("unroll") for (int k = 0; k < 2; ++k) dst[n][k] = *(const LAS bf16x8*)(lds + PG8_SB(b, h) + boff + n * 2048 + k * 1024); } while (0)
; #define PG8_WAIT_V(n) asm volatile("s_waitcnt vmcnt(" #n ")" ::: "memory")
; #define PG8_WAIT_L(n) asm volatile("s_waitcnt lgkmcnt(" #n ")" ::: "memory")
; #define PG8_BAR __builtin_amdgcn_s_barrier()
; #define PG8_SCHED __builtin_amdgcn_sched_barrier(0)
;     __device__ __forceinline__ void operator()(const f32x4 (&acc)[2][2][4][2], const Unit& u, int wr, int wc, int fr, int fq) const {
;     ...
;             for (int m = 0; m < 4; ++m) { const int row = row0 + ai * HALF + m * 16; bf16_t* rowp = O + (size_t)row * ldc + col0; const float rs = rsv[ai][m];
;                 f32x4 v0, v1;
; #pragma unroll
;                 for (int j = 0; j < 4; ++j) { v0[j] = siluf_(acc[ai][0][m][0][j] * rs) * (acc[ai][1][m][0][j] * rs); v1[j] = siluf_(acc[ai][0][m][1][j] * rs) * (acc[ai][1][m][1][j] * rs); }
;                 u32x4 w; w.x = cvt_pk_bf16(v0[0], v0[1]); w.y = cvt_pk_bf16(v0[2], v0[3]); w.z = cvt_pk_bf16(v1[0], v1[1]); w.w = cvt_pk_bf16(v1[2], v1[3]);
;                 *(u32x4*)rowp = w; }
; template <class Epi, bool ALIGN_EPI>
; __device__ __forceinline__ void gemm_phase(LAS unsigned char* lds, const Gemm g, const StaticOrder& S, const Epi& E, const int tid) {
;     ...
;             PG8_LDB(B0, 0, 0); PG8_LDB(B1, 0, 1); PG8_SCHED; PG8_LDA(At, 0, 0); PG8_STAGE(PG8_SA(1, 1), a1 + hA, voffA);
;             PG8_WAIT_V(8); PG8_WAIT_L(0); PG8_BAR; PG8_MMA(0, 0, At, B0); PG8_MMA(0, 1, At, B1); PG8_BAR; PG8_SCHED;
.Lgu_first_epi:
	v_add_u32_e32 v150, s33, v151
	ds_read_b128 v[146:149], v150
	ds_read_b128 v[154:157], v150 offset:1024
	ds_read_b128 v[158:161], v150 offset:2048
	ds_read_b128 v[162:165], v150 offset:3072
	s_add_i32 s11, s10, 2
	s_cmp_eq_u32 s58, s10
	s_cselect_b64 vcc, -1, 0
	s_add_i32 s10, 0, 0x14000
	v_add_u32_e32 v150, s10, v151
	ds_read_b128 v[176:179], v150
	ds_read_b128 v[180:183], v150 offset:1024
	ds_read_b128 v[184:187], v150 offset:2048
	ds_read_b128 v[188:191], v150 offset:3072
	v_lshl_add_u64 v[226:227], v[142:143], 0, s[92:93]
	v_cndmask_b32_e32 v167, v227, v139, vcc
	v_cndmask_b32_e32 v166, v226, v138, vcc
	v_cndmask_b32_e32 v221, v145, v141, vcc
	v_cndmask_b32_e32 v220, v144, v140, vcc
	v_lshl_add_u64 v[226:227], v[142:143], 0, v[134:135]
	s_add_i32 m0, s51, 0xc000
	ds_read_b128 v[192:195], v153
	ds_read_b128 v[196:199], v153 offset:1024
	ds_read_b128 v[200:203], v153 offset:2048
	ds_read_b128 v[204:207], v153 offset:3072
	ds_read_b128 v[208:211], v153 offset:4096
	ds_read_b128 v[212:215], v153 offset:5120
	ds_read_b128 v[216:219], v153 offset:6144
	ds_read_b128 v[240:243], v153 offset:7168
	global_load_lds_dwordx4 v[226:227], off
	v_lshl_add_u64 v[226:227], v[142:143], 0, v[136:137]
	s_add_i32 m0, s51, 0xe000
	s_nop 0
	global_load_lds_dwordx4 v[226:227], off
	s_waitcnt vmcnt(12)
	s_waitcnt lgkmcnt(0)
	s_barrier
	s_setprio 1
	s_waitcnt lgkmcnt(0)
	v_mfma_f32_16x16x32_bf16 v[120:123], v[146:149], v[192:195], 0
	s_lshl_b32 s98, s28, 5
	s_mov_b32 s99, 0
	s_mov_b32 s100, 0xbfb8aa3b
	s_mov_b32 s101, 0xbfb8aa3b
	v_mul_f32_e32 v56, v238, v56
	v_mul_f32_e32 v57, v238, v57
	v_mul_f32_e32 v58, v238, v58
	v_mul_f32_e32 v59, v238, v59
	v_mul_f32_e32 v60, v238, v60
	v_mul_f32_e32 v61, v238, v61
	v_mfma_f32_16x16x32_bf16 v[112:115], v[158:161], v[192:195], 0
	v_mul_f32_e32 v62, v238, v62
	v_mul_f32_e32 v63, v238, v63
	v_mul_f32_e32 v224, s100, v56
	v_mul_f32_e32 v225, s101, v57
	v_mul_f32_e32 v228, s100, v58
	v_mul_f32_e32 v229, s101, v59
	v_exp_f32_e32 v224, v224
	v_exp_f32_e32 v225, v225
	v_exp_f32_e32 v228, v228
	v_exp_f32_e32 v229, v229
	v_mfma_f32_16x16x32_bf16 v[104:107], v[146:149], v[200:203], 0
	v_add_f32_e32 v224, 1.0, v224
	v_add_f32_e32 v225, 1.0, v225
	v_add_f32_e32 v228, 1.0, v228
	v_add_f32_e32 v229, 1.0, v229
	v_rcp_f32_e32 v224, v224
	v_rcp_f32_e32 v225, v225
	v_rcp_f32_e32 v228, v228
	v_rcp_f32_e32 v229, v229
	v_nop
	v_mul_f32_e32 v56, v224, v56
	v_mfma_f32_16x16x32_bf16 v[96:99], v[158:161], v[200:203], 0
	v_mul_f32_e32 v57, v225, v57
	v_mul_f32_e32 v58, v228, v58
	v_mul_f32_e32 v59, v229, v59
	v_mul_f32_e32 v56, v60, v56
	v_mul_f32_e32 v57, v61, v57
	v_mul_f32_e32 v58, v62, v58
	v_mul_f32_e32 v59, v63, v59
	v_mul_f32_e32 v48, v238, v48
	v_mul_f32_e32 v49, v238, v49
	v_mul_f32_e32 v50, v238, v50
	v_mfma_f32_16x16x32_bf16 v[88:91], v[146:149], v[208:211], 0
	v_mul_f32_e32 v51, v238, v51
	v_mul_f32_e32 v52, v238, v52
	v_mul_f32_e32 v53, v238, v53
	v_mul_f32_e32 v54, v238, v54
	v_mul_f32_e32 v55, v238, v55
	v_mul_f32_e32 v224, s100, v48
	v_mul_f32_e32 v225, s101, v49
	v_mul_f32_e32 v228, s100, v50
	v_mul_f32_e32 v229, s101, v51
	v_exp_f32_e32 v224, v224
	v_mfma_f32_16x16x32_bf16 v[80:83], v[158:161], v[208:211], 0
	v_exp_f32_e32 v225, v225
	v_exp_f32_e32 v228, v228
	v_exp_f32_e32 v229, v229
	v_add_f32_e32 v224, 1.0, v224
	v_add_f32_e32 v225, 1.0, v225
	v_add_f32_e32 v228, 1.0, v228
	v_add_f32_e32 v229, 1.0, v229
	v_rcp_f32_e32 v224, v224
	v_rcp_f32_e32 v225, v225
	v_rcp_f32_e32 v228, v228
	v_mfma_f32_16x16x32_bf16 v[72:75], v[146:149], v[216:219], 0
	v_rcp_f32_e32 v229, v229
	v_nop
	v_mul_f32_e32 v48, v224, v48
	v_mul_f32_e32 v49, v225, v49
	v_mul_f32_e32 v50, v228, v50
	v_mul_f32_e32 v51, v229, v51
	v_mul_f32_e32 v48, v52, v48
	v_mul_f32_e32 v49, v53, v49
	v_mul_f32_e32 v50, v54, v50
	v_mul_f32_e32 v51, v55, v51
	v_mfma_f32_16x16x32_bf16 v[64:67], v[158:161], v[216:219], 0
	v_cvt_pk_bf16_f32 v56, v56, v57
	v_cvt_pk_bf16_f32 v57, v58, v59
	v_cvt_pk_bf16_f32 v58, v48, v49
	v_cvt_pk_bf16_f32 v59, v50, v51
	global_store_dwordx4 v[232:233], v[56:59], off
	v_lshl_add_u64 v[232:233], v[232:233], 0, s[98:99]
	v_mul_f32_e32 v40, v239, v40
	v_mul_f32_e32 v41, v239, v41
	v_mul_f32_e32 v42, v239, v42
	v_mul_f32_e32 v43, v239, v43
	v_mfma_f32_16x16x32_bf16 v[120:123], v[154:157], v[196:199], v[120:123]
	v_mul_f32_e32 v44, v239, v44
	v_mul_f32_e32 v45, v239, v45
	v_mul_f32_e32 v46, v239, v46
	v_mul_f32_e32 v47, v239, v47
	v_mul_f32_e32 v224, s100, v40
	v_mul_f32_e32 v225, s101, v41
	v_mul_f32_e32 v228, s100, v42
	v_mul_f32_e32 v229, s101, v43
	v_exp_f32_e32 v224, v224
	v_exp_f32_e32 v225, v225
	v_mfma_f32_16x16x32_bf16 v[112:115], v[162:165], v[196:199], v[112:115]
	v_exp_f32_e32 v228, v228
	v_exp_f32_e32 v229, v229
	v_add_f32_e32 v224, 1.0, v224
	v_add_f32_e32 v225, 1.0, v225
	v_add_f32_e32 v228, 1.0, v228
	v_add_f32_e32 v229, 1.0, v229
	v_rcp_f32_e32 v224, v224
	v_rcp_f32_e32 v225, v225
	v_rcp_f32_e32 v228, v228
	v_rcp_f32_e32 v229, v229
	v_mfma_f32_16x16x32_bf16 v[104:107], v[154:157], v[204:207], v[104:107]
	v_nop
	v_mul_f32_e32 v40, v224, v40
	v_mul_f32_e32 v41, v225, v41
	v_mul_f32_e32 v42, v228, v42
	v_mul_f32_e32 v43, v229, v43
	v_mul_f32_e32 v40, v44, v40
	v_mul_f32_e32 v41, v45, v41
	v_mul_f32_e32 v42, v46, v42
	v_mul_f32_e32 v43, v47, v43
	v_mul_f32_e32 v32, v239, v32
	v_mfma_f32_16x16x32_bf16 v[96:99], v[162:165], v[204:207], v[96:99]
	v_mul_f32_e32 v33, v239, v33
	v_mul_f32_e32 v34, v239, v34
	v_mul_f32_e32 v35, v239, v35
	v_mul_f32_e32 v36, v239, v36
	v_mul_f32_e32 v37, v239, v37
	v_mul_f32_e32 v38, v239, v38
	v_mul_f32_e32 v39, v239, v39
	v_mul_f32_e32 v224, s100, v32
	v_mul_f32_e32 v225, s101, v33
; __device__ __forceinline__ unsigned cvt_pk_bf16(float lo, float hi) { unsigned r; asm volatile("v_cvt_pk_bf16_f32 %0, %1, %2" : "=v"(r) : "v"(lo), "v"(hi)); return r; }
; __device__ __forceinline__ float siluf_(float x) { return x * sigmoidf_(x); }
; #define PG8_MMA(ai, bj, At, Bt) do { __builtin_amdgcn_s_setprio(1); _Pragma("unroll") for (int k = 0; k < 2; ++k) _Pragma("unroll") for (int m = 0; m < 4; ++m) _Pragma("unroll") for (int n = 0; n < 2; ++n) \
;         acc[ai][bj][m][n] = __builtin_amdgcn_mfma_f32_16x16x32_bf16(Bt[n][k], At[m][k], acc[ai][bj][m][n], 0, 0, 0); __builtin_amdgcn_s_setprio(0); } while (0)
; #define PG8_WAIT_V(n) asm volatile("s_waitcnt vmcnt(" #n ")" ::: "memory")
; #define PG8_WAIT_L(n) asm volatile("s_waitcnt lgkmcnt(" #n ")" ::: "memory")
; #define PG8_BAR __builtin_amdgcn_s_barrier()
; #define PG8_SCHED __builtin_amdgcn_sched_barrier(0)
;     __device__ __forceinline__ void operator()(const f32x4 (&acc)[2][2][4][2], const Unit& u, int wr, int wc, int fr, int fq) const {
;     ...
;             for (int m = 0; m < 4; ++m) { const int row = row0 + ai * HALF + m * 16; bf16_t* rowp = O + (size_t)row * ldc + col0; const float rs = rsv[ai][m];
;                 f32x4 v0, v1;
; #pragma unroll
;                 for (int j = 0; j < 4; ++j) { v0[j] = siluf_(acc[ai][0][m][0][j] * rs) * (acc[ai][1][m][0][j] * rs); v1[j] = siluf_(acc[ai][0][m][1][j] * rs) * (acc[ai][1][m][1][j] * rs); }
;                 u32x4 w; w.x = cvt_pk_bf16(v0[0], v0[1]); w.y = cvt_pk_bf16(v0[2], v0[3]); w.z = cvt_pk_bf16(v1[0], v1[1]); w.w = cvt_pk_bf16(v1[2], v1[3]);
;                 *(u32x4*)rowp = w; }
; template <class Epi, bool ALIGN_EPI>
; __device__ __forceinline__ void gemm_phase(LAS unsigned char* lds, const Gemm g, const StaticOrder& S, const Epi& E, const int tid) {
;     ...
;             PG8_WAIT_V(8); PG8_WAIT_L(0); PG8_BAR; PG8_MMA(0, 0, At, B0); PG8_MMA(0, 1, At, B1); PG8_BAR; PG8_SCHED;
	v_mul_f32_e32 v228, s100, v34
	v_mfma_f32_16x16x32_bf16 v[88:91], v[154:157], v[212:215], v[88:91]
	v_mul_f32_e32 v229, s101, v35
	v_exp_f32_e32 v224, v224
	v_exp_f32_e32 v225, v225
	v_exp_f32_e32 v228, v228
	v_exp_f32_e32 v229, v229
	v_add_f32_e32 v224, 1.0, v224
	v_add_f32_e32 v225, 1.0, v225
	v_add_f32_e32 v228, 1.0, v228
	v_add_f32_e32 v229, 1.0, v229
	v_rcp_f32_e32 v224, v224
	v_mfma_f32_16x16x32_bf16 v[80:83], v[162:165], v[212:215], v[80:83]
	v_rcp_f32_e32 v225, v225
	v_rcp_f32_e32 v228, v228
	v_rcp_f32_e32 v229, v229
	v_nop
	v_mul_f32_e32 v32, v224, v32
	v_mul_f32_e32 v33, v225, v33
	v_mul_f32_e32 v34, v228, v34
	v_mul_f32_e32 v35, v229, v35
	v_mul_f32_e32 v32, v36, v32
	v_mul_f32_e32 v33, v37, v33
	v_mfma_f32_16x16x32_bf16 v[72:75], v[154:157], v[240:243], v[72:75]
	v_mul_f32_e32 v34, v38, v34
	v_mul_f32_e32 v35, v39, v35
	v_cvt_pk_bf16_f32 v40, v40, v41
	v_cvt_pk_bf16_f32 v41, v42, v43
	v_cvt_pk_bf16_f32 v42, v32, v33
	v_cvt_pk_bf16_f32 v43, v34, v35
	global_store_dwordx4 v[232:233], v[40:43], off
	v_lshl_add_u64 v[232:233], v[232:233], 0, s[98:99]
	v_mul_f32_e32 v24, v230, v24
	v_mul_f32_e32 v25, v230, v25
	v_mfma_f32_16x16x32_bf16 v[64:67], v[162:165], v[240:243], v[64:67]
	v_mul_f32_e32 v26, v230, v26
	v_mul_f32_e32 v27, v230, v27
	v_mul_f32_e32 v28, v230, v28
	v_mul_f32_e32 v29, v230, v29
	v_mul_f32_e32 v30, v230, v30
	v_mul_f32_e32 v31, v230, v31
	v_mul_f32_e32 v224, s100, v24
	v_mul_f32_e32 v225, s101, v25
	v_mul_f32_e32 v228, s100, v26
	v_mul_f32_e32 v229, s101, v27
	s_setprio 0
	s_setprio 1
	v_mfma_f32_16x16x32_bf16 v[124:127], v[176:179], v[192:195], 0
	v_exp_f32_e32 v224, v224
	v_exp_f32_e32 v225, v225
	v_exp_f32_e32 v228, v228
	v_exp_f32_e32 v229, v229
	v_add_f32_e32 v224, 1.0, v224
	v_add_f32_e32 v225, 1.0, v225
	v_add_f32_e32 v228, 1.0, v228
	v_add_f32_e32 v229, 1.0, v229
	v_rcp_f32_e32 v224, v224
	v_rcp_f32_e32 v225, v225
	v_mfma_f32_16x16x32_bf16 v[116:119], v[184:187], v[192:195], 0
	v_rcp_f32_e32 v228, v228
	v_rcp_f32_e32 v229, v229
	v_nop
	v_mul_f32_e32 v24, v224, v24
	v_mul_f32_e32 v25, v225, v25
	v_mul_f32_e32 v26, v228, v26
	v_mul_f32_e32 v27, v229, v27
	v_mul_f32_e32 v24, v28, v24
	v_mul_f32_e32 v25, v29, v25
	v_mul_f32_e32 v26, v30, v26
	v_mfma_f32_16x16x32_bf16 v[108:111], v[176:179], v[200:203], 0
	v_mul_f32_e32 v27, v31, v27
	v_mul_f32_e32 v16, v230, v16
	v_mul_f32_e32 v17, v230, v17
	v_mul_f32_e32 v18, v230, v18
	v_mul_f32_e32 v19, v230, v19
	v_mul_f32_e32 v20, v230, v20
	v_mul_f32_e32 v21, v230, v21
	v_mul_f32_e32 v22, v230, v22
	v_mul_f32_e32 v23, v230, v23
	v_mul_f32_e32 v224, s100, v16
	v_mfma_f32_16x16x32_bf16 v[100:103], v[184:187], v[200:203], 0
	v_mul_f32_e32 v225, s101, v17
	v_mul_f32_e32 v228, s100, v18
	v_mul_f32_e32 v229, s101, v19
	v_exp_f32_e32 v224, v224
	v_exp_f32_e32 v225, v225
	v_exp_f32_e32 v228, v228
	v_exp_f32_e32 v229, v229
	v_add_f32_e32 v224, 1.0, v224
	v_add_f32_e32 v225, 1.0, v225
	v_add_f32_e32 v228, 1.0, v228
	v_mfma_f32_16x16x32_bf16 v[92:95], v[176:179], v[208:211], 0
	v_add_f32_e32 v229, 1.0, v229
	v_rcp_f32_e32 v224, v224
	v_rcp_f32_e32 v225, v225
	v_rcp_f32_e32 v228, v228
	v_rcp_f32_e32 v229, v229
	v_nop
	v_mul_f32_e32 v16, v224, v16
	v_mul_f32_e32 v17, v225, v17
	v_mul_f32_e32 v18, v228, v18
	v_mul_f32_e32 v19, v229, v19
	v_mfma_f32_16x16x32_bf16 v[84:87], v[184:187], v[208:211], 0
	v_mul_f32_e32 v16, v20, v16
	v_mul_f32_e32 v17, v21, v17
	v_mul_f32_e32 v18, v22, v18
	v_mul_f32_e32 v19, v23, v19
	v_cvt_pk_bf16_f32 v24, v24, v25
	v_cvt_pk_bf16_f32 v25, v26, v27
	v_cvt_pk_bf16_f32 v26, v16, v17
	v_cvt_pk_bf16_f32 v27, v18, v19
	global_store_dwordx4 v[232:233], v[24:27], off
	v_lshl_add_u64 v[232:233], v[232:233], 0, s[98:99]
	v_mfma_f32_16x16x32_bf16 v[76:79], v[176:179], v[216:219], 0
	v_mul_f32_e32 v8, v231, v8
	v_mul_f32_e32 v9, v231, v9
	v_mul_f32_e32 v10, v231, v10
	v_mul_f32_e32 v11, v231, v11
	v_mul_f32_e32 v12, v231, v12
	v_mul_f32_e32 v13, v231, v13
	v_mul_f32_e32 v14, v231, v14
	v_mul_f32_e32 v15, v231, v15
	v_mul_f32_e32 v224, s100, v8
	v_mul_f32_e32 v225, s101, v9
	v_mfma_f32_16x16x32_bf16 v[68:71], v[184:187], v[216:219], 0
	v_mul_f32_e32 v228, s100, v10
	v_mul_f32_e32 v229, s101, v11
	v_exp_f32_e32 v224, v224
	v_exp_f32_e32 v225, v225
	v_exp_f32_e32 v228, v228
	v_exp_f32_e32 v229, v229
	v_add_f32_e32 v224, 1.0, v224
	v_add_f32_e32 v225, 1.0, v225
	v_add_f32_e32 v228, 1.0, v228
	v_add_f32_e32 v229, 1.0, v229
	v_mfma_f32_16x16x32_bf16 v[124:127], v[180:183], v[196:199], v[124:127]
	v_rcp_f32_e32 v224, v224
	v_rcp_f32_e32 v225, v225
	v_rcp_f32_e32 v228, v228
	v_rcp_f32_e32 v229, v229
	v_nop
	v_mul_f32_e32 v8, v224, v8
	v_mul_f32_e32 v9, v225, v9
	v_mul_f32_e32 v10, v228, v10
	v_mul_f32_e32 v11, v229, v11
	v_mul_f32_e32 v8, v12, v8
	v_mfma_f32_16x16x32_bf16 v[116:119], v[188:191], v[196:199], v[116:119]
	v_mul_f32_e32 v9, v13, v9
	v_mul_f32_e32 v10, v14, v10
	v_mul_f32_e32 v11, v15, v11
	v_mul_f32_e32 v4, v231, v4
	v_mul_f32_e32 v5, v231, v5
	v_mul_f32_e32 v6, v231, v6
	v_mul_f32_e32 v7, v231, v7
	v_mul_f32_e32 v0, v231, v0
	v_mul_f32_e32 v1, v231, v1
	v_mul_f32_e32 v2, v231, v2
	v_mfma_f32_16x16x32_bf16 v[108:111], v[180:183], v[204:207], v[108:111]
	v_mul_f32_e32 v3, v231, v3
	v_mul_f32_e32 v224, s100, v4
	v_mul_f32_e32 v225, s101, v5
	v_mul_f32_e32 v228, s100, v6
	v_mul_f32_e32 v229, s101, v7
	v_exp_f32_e32 v224, v224
	v_exp_f32_e32 v225, v225
	v_exp_f32_e32 v228, v228
	v_exp_f32_e32 v229, v229
	v_add_f32_e32 v224, 1.0, v224
	v_mfma_f32_16x16x32_bf16 v[100:103], v[188:191], v[204:207], v[100:103]
	v_add_f32_e32 v225, 1.0, v225
	v_add_f32_e32 v228, 1.0, v228
	v_add_f32_e32 v229, 1.0, v229
	v_rcp_f32_e32 v224, v224
	v_rcp_f32_e32 v225, v225
	v_rcp_f32_e32 v228, v228
	v_rcp_f32_e32 v229, v229
	v_nop
	v_mul_f32_e32 v4, v224, v4
	v_mul_f32_e32 v5, v225, v5
	v_mfma_f32_16x16x32_bf16 v[92:95], v[180:183], v[212:215], v[92:95]
	v_mul_f32_e32 v6, v228, v6
	v_mul_f32_e32 v7, v229, v7
	v_mul_f32_e32 v4, v0, v4
	v_mul_f32_e32 v5, v1, v5
	v_mul_f32_e32 v6, v2, v6
	v_mul_f32_e32 v7, v3, v7
	v_cvt_pk_bf16_f32 v8, v8, v9
	v_cvt_pk_bf16_f32 v9, v10, v11
	v_cvt_pk_bf16_f32 v10, v4, v5
	v_cvt_pk_bf16_f32 v11, v6, v7
	v_mfma_f32_16x16x32_bf16 v[84:87], v[188:191], v[212:215], v[84:87]
	global_store_dwordx4 v[232:233], v[8:11], off
	v_mfma_f32_16x16x32_bf16 v[76:79], v[180:183], v[240:243], v[76:79]
	v_mfma_f32_16x16x32_bf16 v[68:71], v[188:191], v[240:243], v[68:71]
	s_setprio 0
	s_barrier
; #define PG8_STAGE(bufoff, gbase, voff) do { _Pragma("unroll") for (int _i = 0; _i < 2; ++_i) \
;         __builtin_amdgcn_global_load_lds((const unsigned*)((const char*)(gbase) + (voff)[_i]), (LAS unsigned*)(lds + (bufoff) + ldsw + _i * 8192), 16, 0, 0); } while (0)
; #define PG8_LDA(dst, b, h) do { _Pragma("unroll") for (int m = 0; m < 4; ++m) _Pragma("unroll") for (int k = 0; k < 2; ++k) dst[m][k] = *(const LAS bf16x8*)(lds + PG8_SA(b, h) + aoff + m * 2048 + k * 1024); } while (0)
; #define PG8_LDB(dst, b, h) do { _Pragma("unroll") for (int n = 0; n < 2; ++n) _Pragma("unroll") for (int k = 0; k < 2; ++k) dst[n][k] = *(const LAS bf16x8*)(lds + PG8_SB(b, h) + boff + n * 2048 + k * 1024); } while (0)
; #define PG8_MMA(ai, bj, At, Bt) do { __builtin_amdgcn_s_setprio(1); _Pragma("unroll") for (int k = 0; k < 2; ++k) _Pragma("unroll") for (int m = 0; m < 4; ++m) _Pragma("unroll") for (int n = 0; n < 2; ++n) \
;         acc[ai][bj][m][n] = __builtin_amdgcn_mfma_f32_16x16x32_bf16(Bt[n][k], At[m][k], acc[ai][bj][m][n], 0, 0, 0); __builtin_amdgcn_s_setprio(0); } while (0)
; #define PG8_WAIT_V(n) asm volatile("s_waitcnt vmcnt(" #n ")" ::: "memory")
; #define PG8_WAIT_L(n) asm volatile("s_waitcnt lgkmcnt(" #n ")" ::: "memory")
; #define PG8_BAR __builtin_amdgcn_s_barrier()
; #define PG8_SCHED __builtin_amdgcn_sched_barrier(0)
; template <class Epi, bool ALIGN_EPI>
; __device__ __forceinline__ void gemm_phase(LAS unsigned char* lds, const Gemm g, const StaticOrder& S, const Epi& E, const int tid) {
;     ...
;             PG8_LDA(At, 0, 1); PG8_STAGE(PG8_SB(0, 0), b2, voffB); PG8_STAGE(PG8_SB(0, 1), b2 + hB, voffB); PG8_STAGE(PG8_SA(0, 0), a2, voffA);
;             PG8_WAIT_V(8); PG8_WAIT_L(0); PG8_BAR; PG8_MMA(1, 0, At, B0); PG8_MMA(1, 1, At, B1); PG8_BAR; PG8_SCHED;
;             PG8_LDB(B0, 1, 0); PG8_LDB(B1, 1, 1); PG8_SCHED; PG8_LDA(At, 1, 0); PG8_STAGE(PG8_SA(0, 1), a2 + hA, voffA);
;             PG8_WAIT_V(8); PG8_WAIT_L(0); PG8_BAR; PG8_MMA(0, 0, At, B0); PG8_MMA(0, 1, At, B1); PG8_BAR; PG8_SCHED;
	s_add_i32 s65, s33, s45
	v_lshl_add_u64 v[226:227], v[220:221], 0, v[168:169]
	s_mov_b32 m0, s65
	ds_read_b128 v[192:195], v153 offset:16384
	ds_read_b128 v[196:199], v153 offset:17408
	ds_read_b128 v[200:203], v153 offset:18432
	ds_read_b128 v[204:207], v153 offset:19456
	ds_read_b128 v[208:211], v153 offset:20480
	ds_read_b128 v[212:215], v153 offset:21504
	ds_read_b128 v[216:219], v153 offset:22528
	ds_read_b128 v[240:243], v153 offset:23552
	global_load_lds_dwordx4 v[226:227], off
	v_lshl_add_u64 v[244:245], v[220:221], 0, v[128:129]
	s_add_i32 m0, s65, 0x2000
	v_lshl_add_u64 v[220:221], v[220:221], 0, s[12:13]
	s_add_i32 s10, s10, s45
	global_load_lds_dwordx4 v[244:245], off
	v_lshl_add_u64 v[246:247], v[220:221], 0, v[168:169]
	s_mov_b32 m0, s10
	v_lshl_add_u64 v[220:221], v[220:221], 0, v[128:129]
	global_load_lds_dwordx4 v[246:247], off
	s_add_i32 m0, s10, 0x2000
	v_lshl_add_u64 v[248:249], v[166:167], 0, v[132:133]
	global_load_lds_dwordx4 v[220:221], off
	s_mov_b32 m0, s51
	v_lshl_add_u64 v[250:251], v[166:167], 0, v[130:131]
	global_load_lds_dwordx4 v[248:249], off
	s_mov_b32 m0, s52
	s_nop 0
	global_load_lds_dwordx4 v[250:251], off
	s_waitcnt vmcnt(16)
	s_waitcnt lgkmcnt(0)
	s_barrier
	s_setprio 1
	s_waitcnt lgkmcnt(0)
	v_mfma_f32_16x16x32_bf16 v[56:59], v[146:149], v[192:195], 0
	v_mfma_f32_16x16x32_bf16 v[48:51], v[158:161], v[192:195], 0
	v_mfma_f32_16x16x32_bf16 v[40:43], v[146:149], v[200:203], 0
	v_mfma_f32_16x16x32_bf16 v[32:35], v[158:161], v[200:203], 0
	v_mfma_f32_16x16x32_bf16 v[24:27], v[146:149], v[208:211], 0
	v_mfma_f32_16x16x32_bf16 v[16:19], v[158:161], v[208:211], 0
	v_mfma_f32_16x16x32_bf16 v[8:11], v[146:149], v[216:219], 0
	v_mfma_f32_16x16x32_bf16 v[4:7], v[158:161], v[216:219], 0
	v_mfma_f32_16x16x32_bf16 v[56:59], v[154:157], v[196:199], v[56:59]
	v_mfma_f32_16x16x32_bf16 v[48:51], v[162:165], v[196:199], v[48:51]
	v_mfma_f32_16x16x32_bf16 v[40:43], v[154:157], v[204:207], v[40:43]
	v_mfma_f32_16x16x32_bf16 v[32:35], v[162:165], v[204:207], v[32:35]
	v_mfma_f32_16x16x32_bf16 v[24:27], v[154:157], v[212:215], v[24:27]
	v_mfma_f32_16x16x32_bf16 v[16:19], v[162:165], v[212:215], v[16:19]
	v_mfma_f32_16x16x32_bf16 v[8:11], v[154:157], v[240:243], v[8:11]
	v_mfma_f32_16x16x32_bf16 v[4:7], v[162:165], v[240:243], v[4:7]
	s_setprio 0
	s_setprio 1
	v_mfma_f32_16x16x32_bf16 v[60:63], v[176:179], v[192:195], 0
	v_mfma_f32_16x16x32_bf16 v[52:55], v[184:187], v[192:195], 0
	v_mfma_f32_16x16x32_bf16 v[44:47], v[176:179], v[200:203], 0
	v_mfma_f32_16x16x32_bf16 v[36:39], v[184:187], v[200:203], 0
	v_mfma_f32_16x16x32_bf16 v[28:31], v[176:179], v[208:211], 0
	v_mfma_f32_16x16x32_bf16 v[20:23], v[184:187], v[208:211], 0
	v_mfma_f32_16x16x32_bf16 v[12:15], v[176:179], v[216:219], 0
	v_mfma_f32_16x16x32_bf16 v[0:3], v[184:187], v[216:219], 0
	v_mfma_f32_16x16x32_bf16 v[60:63], v[180:183], v[196:199], v[60:63]
	v_mfma_f32_16x16x32_bf16 v[52:55], v[188:191], v[196:199], v[52:55]
	v_mfma_f32_16x16x32_bf16 v[44:47], v[180:183], v[204:207], v[44:47]
	v_mfma_f32_16x16x32_bf16 v[36:39], v[188:191], v[204:207], v[36:39]
	v_mfma_f32_16x16x32_bf16 v[28:31], v[180:183], v[212:215], v[28:31]
	v_mfma_f32_16x16x32_bf16 v[20:23], v[188:191], v[212:215], v[20:23]
	v_mfma_f32_16x16x32_bf16 v[12:15], v[180:183], v[240:243], v[12:15]
	v_mfma_f32_16x16x32_bf16 v[0:3], v[188:191], v[240:243], v[0:3]
	s_setprio 0
	s_barrier
	s_add_i32 s10, 0, 0x18000
	v_add_u32_e32 v150, s10, v151
	s_add_i32 s65, 0, 0x1c000
	ds_read_b128 v[146:149], v150
	ds_read_b128 v[154:157], v150 offset:1024
	ds_read_b128 v[158:161], v150 offset:2048
	ds_read_b128 v[162:165], v150 offset:3072
	v_add_u32_e32 v150, s65, v151
	ds_read_b128 v[176:179], v150
	ds_read_b128 v[180:183], v150 offset:1024
	ds_read_b128 v[184:187], v150 offset:2048
	ds_read_b128 v[188:191], v150 offset:3072
	v_lshl_add_u64 v[166:167], v[166:167], 0, s[94:95]
	s_mov_b32 m0, s53
	v_lshl_add_u64 v[252:253], v[166:167], 0, v[132:133]
	ds_read_b128 v[192:195], v153 offset:32768
	ds_read_b128 v[196:199], v153 offset:33792
	ds_read_b128 v[200:203], v153 offset:34816
	ds_read_b128 v[204:207], v153 offset:35840
	ds_read_b128 v[208:211], v153 offset:36864
	ds_read_b128 v[212:215], v153 offset:37888
	ds_read_b128 v[216:219], v153 offset:38912
	ds_read_b128 v[240:243], v153 offset:39936
	global_load_lds_dwordx4 v[252:253], off
	v_lshl_add_u64 v[166:167], v[166:167], 0, v[130:131]
	s_mov_b32 m0, s54
	s_nop 0
	global_load_lds_dwordx4 v[166:167], off
	s_waitcnt vmcnt(12)
	s_waitcnt lgkmcnt(0)
	s_barrier
; #define PG8_STAGE(bufoff, gbase, voff) do { _Pragma("unroll") for (int _i = 0; _i < 2; ++_i) \
;         __builtin_amdgcn_global_load_lds((const unsigned*)((const char*)(gbase) + (voff)[_i]), (LAS unsigned*)(lds + (bufoff) + ldsw + _i * 8192), 16, 0, 0); } while (0)
; #define PG8_LDA(dst, b, h) do { _Pragma("unroll") for (int m = 0; m < 4; ++m) _Pragma("unroll") for (int k = 0; k < 2; ++k) dst[m][k] = *(const LAS bf16x8*)(lds + PG8_SA(b, h) + aoff + m * 2048 + k * 1024); } while (0)
; #define PG8_MMA(ai, bj, At, Bt) do { __builtin_amdgcn_s_setprio(1); _Pragma("unroll") for (int k = 0; k < 2; ++k) _Pragma("unroll") for (int m = 0; m < 4; ++m) _Pragma("unroll") for (int n = 0; n < 2; ++n) \
;         acc[ai][bj][m][n] = __builtin_amdgcn_mfma_f32_16x16x32_bf16(Bt[n][k], At[m][k], acc[ai][bj][m][n], 0, 0, 0); __builtin_amdgcn_s_setprio(0); } while (0)
; #define PG8_WAIT_V(n) asm volatile("s_waitcnt vmcnt(" #n ")" ::: "memory")
; #define PG8_WAIT_L(n) asm volatile("s_waitcnt lgkmcnt(" #n ")" ::: "memory")
; #define PG8_BAR __builtin_amdgcn_s_barrier()
; #define PG8_SCHED __builtin_amdgcn_sched_barrier(0)
; template <class Epi, bool ALIGN_EPI>
; __device__ __forceinline__ void gemm_phase(LAS unsigned char* lds, const Gemm g, const StaticOrder& S, const Epi& E, const int tid) {
;     ...
;             PG8_WAIT_V(8); PG8_WAIT_L(0); PG8_BAR; PG8_MMA(0, 0, At, B0); PG8_MMA(0, 1, At, B1); PG8_BAR; PG8_SCHED;
;             PG8_LDA(At, 1, 1); PG8_STAGE(PG8_SB(1, 0), b3, voffB); PG8_STAGE(PG8_SB(1, 1), b3 + hB, voffB); PG8_STAGE(PG8_SA(1, 0), a3, voffA);
;             PG8_WAIT_V(8); PG8_WAIT_L(0); PG8_BAR; PG8_MMA(1, 0, At, B0); PG8_MMA(1, 1, At, B1); PG8_BAR; PG8_SCHED;
;         }
	s_setprio 1
	s_waitcnt lgkmcnt(0)
	v_mfma_f32_16x16x32_bf16 v[120:123], v[146:149], v[192:195], v[120:123]
	v_mfma_f32_16x16x32_bf16 v[112:115], v[158:161], v[192:195], v[112:115]
	v_mfma_f32_16x16x32_bf16 v[104:107], v[146:149], v[200:203], v[104:107]
	v_mfma_f32_16x16x32_bf16 v[96:99], v[158:161], v[200:203], v[96:99]
	v_mfma_f32_16x16x32_bf16 v[88:91], v[146:149], v[208:211], v[88:91]
	v_mfma_f32_16x16x32_bf16 v[80:83], v[158:161], v[208:211], v[80:83]
	v_mfma_f32_16x16x32_bf16 v[72:75], v[146:149], v[216:219], v[72:75]
	v_mfma_f32_16x16x32_bf16 v[64:67], v[158:161], v[216:219], v[64:67]
	v_mfma_f32_16x16x32_bf16 v[120:123], v[154:157], v[196:199], v[120:123]
	v_mfma_f32_16x16x32_bf16 v[112:115], v[162:165], v[196:199], v[112:115]
	v_mfma_f32_16x16x32_bf16 v[104:107], v[154:157], v[204:207], v[104:107]
	v_mfma_f32_16x16x32_bf16 v[96:99], v[162:165], v[204:207], v[96:99]
	v_mfma_f32_16x16x32_bf16 v[88:91], v[154:157], v[212:215], v[88:91]
	v_mfma_f32_16x16x32_bf16 v[80:83], v[162:165], v[212:215], v[80:83]
	v_mfma_f32_16x16x32_bf16 v[72:75], v[154:157], v[240:243], v[72:75]
	v_mfma_f32_16x16x32_bf16 v[64:67], v[162:165], v[240:243], v[64:67]
	s_setprio 0
	s_setprio 1
	v_mfma_f32_16x16x32_bf16 v[124:127], v[176:179], v[192:195], v[124:127]
	v_mfma_f32_16x16x32_bf16 v[116:119], v[184:187], v[192:195], v[116:119]
	v_mfma_f32_16x16x32_bf16 v[108:111], v[176:179], v[200:203], v[108:111]
	v_mfma_f32_16x16x32_bf16 v[100:103], v[184:187], v[200:203], v[100:103]
	v_mfma_f32_16x16x32_bf16 v[92:95], v[176:179], v[208:211], v[92:95]
	v_mfma_f32_16x16x32_bf16 v[84:87], v[184:187], v[208:211], v[84:87]
	v_mfma_f32_16x16x32_bf16 v[76:79], v[176:179], v[216:219], v[76:79]
	v_mfma_f32_16x16x32_bf16 v[68:71], v[184:187], v[216:219], v[68:71]
	v_mfma_f32_16x16x32_bf16 v[124:127], v[180:183], v[196:199], v[124:127]
	v_mfma_f32_16x16x32_bf16 v[116:119], v[188:191], v[196:199], v[116:119]
	v_mfma_f32_16x16x32_bf16 v[108:111], v[180:183], v[204:207], v[108:111]
	v_mfma_f32_16x16x32_bf16 v[100:103], v[188:191], v[204:207], v[100:103]
	v_mfma_f32_16x16x32_bf16 v[92:95], v[180:183], v[212:215], v[92:95]
	v_mfma_f32_16x16x32_bf16 v[84:87], v[188:191], v[212:215], v[84:87]
	v_mfma_f32_16x16x32_bf16 v[76:79], v[180:183], v[240:243], v[76:79]
	v_mfma_f32_16x16x32_bf16 v[68:71], v[188:191], v[240:243], v[68:71]
	s_setprio 0
	s_barrier
	s_add_i32 s10, s10, s45
	v_lshl_add_u64 v[166:167], v[226:227], 0, s[92:93]
	s_mov_b32 m0, s10
	ds_read_b128 v[192:195], v153 offset:49152
	ds_read_b128 v[196:199], v153 offset:50176
	ds_read_b128 v[200:203], v153 offset:51200
	ds_read_b128 v[204:207], v153 offset:52224
	ds_read_b128 v[208:211], v153 offset:53248
	ds_read_b128 v[212:215], v153 offset:54272
	ds_read_b128 v[216:219], v153 offset:55296
	ds_read_b128 v[240:243], v153 offset:56320
	global_load_lds_dwordx4 v[166:167], off
	v_lshl_add_u64 v[166:167], v[244:245], 0, s[92:93]
	s_add_i32 m0, s10, 0x2000
	s_add_i32 s10, s65, s45
	global_load_lds_dwordx4 v[166:167], off
	v_lshl_add_u64 v[166:167], v[246:247], 0, s[92:93]
	s_mov_b32 m0, s10
	s_nop 0
	global_load_lds_dwordx4 v[166:167], off
	v_lshl_add_u64 v[166:167], v[220:221], 0, s[92:93]
	s_add_i32 m0, s10, 0x2000
	s_nop 0
	global_load_lds_dwordx4 v[166:167], off
	v_lshl_add_u64 v[166:167], v[248:249], 0, s[92:93]
	s_mov_b32 m0, s56
	s_nop 0
	global_load_lds_dwordx4 v[166:167], off
	v_lshl_add_u64 v[166:167], v[250:251], 0, s[92:93]
	s_mov_b32 m0, s57
	s_nop 0
	global_load_lds_dwordx4 v[166:167], off
	s_waitcnt vmcnt(8)
	s_waitcnt lgkmcnt(0)
	s_barrier
	s_setprio 1
	s_waitcnt lgkmcnt(0)
	v_mfma_f32_16x16x32_bf16 v[56:59], v[146:149], v[192:195], v[56:59]
	v_mfma_f32_16x16x32_bf16 v[48:51], v[158:161], v[192:195], v[48:51]
	v_mfma_f32_16x16x32_bf16 v[40:43], v[146:149], v[200:203], v[40:43]
	v_mfma_f32_16x16x32_bf16 v[32:35], v[158:161], v[200:203], v[32:35]
	v_mfma_f32_16x16x32_bf16 v[24:27], v[146:149], v[208:211], v[24:27]
	v_mfma_f32_16x16x32_bf16 v[16:19], v[158:161], v[208:211], v[16:19]
	v_mfma_f32_16x16x32_bf16 v[8:11], v[146:149], v[216:219], v[8:11]
	v_mfma_f32_16x16x32_bf16 v[4:7], v[158:161], v[216:219], v[4:7]
	v_mfma_f32_16x16x32_bf16 v[56:59], v[154:157], v[196:199], v[56:59]
	v_mfma_f32_16x16x32_bf16 v[48:51], v[162:165], v[196:199], v[48:51]
	v_mfma_f32_16x16x32_bf16 v[40:43], v[154:157], v[204:207], v[40:43]
	v_mfma_f32_16x16x32_bf16 v[32:35], v[162:165], v[204:207], v[32:35]
	v_mfma_f32_16x16x32_bf16 v[24:27], v[154:157], v[212:215], v[24:27]
	v_mfma_f32_16x16x32_bf16 v[16:19], v[162:165], v[212:215], v[16:19]
	v_mfma_f32_16x16x32_bf16 v[8:11], v[154:157], v[240:243], v[8:11]
	v_mfma_f32_16x16x32_bf16 v[4:7], v[162:165], v[240:243], v[4:7]
	s_setprio 0
	s_setprio 1
	v_mfma_f32_16x16x32_bf16 v[60:63], v[176:179], v[192:195], v[60:63]
	v_mfma_f32_16x16x32_bf16 v[52:55], v[184:187], v[192:195], v[52:55]
	v_mfma_f32_16x16x32_bf16 v[44:47], v[176:179], v[200:203], v[44:47]
	v_mfma_f32_16x16x32_bf16 v[36:39], v[184:187], v[200:203], v[36:39]
	v_mfma_f32_16x16x32_bf16 v[28:31], v[176:179], v[208:211], v[28:31]
	v_mfma_f32_16x16x32_bf16 v[20:23], v[184:187], v[208:211], v[20:23]
	v_mfma_f32_16x16x32_bf16 v[12:15], v[176:179], v[216:219], v[12:15]
	v_mfma_f32_16x16x32_bf16 v[0:3], v[184:187], v[216:219], v[0:3]
	v_mfma_f32_16x16x32_bf16 v[60:63], v[180:183], v[196:199], v[60:63]
	v_mfma_f32_16x16x32_bf16 v[52:55], v[188:191], v[196:199], v[52:55]
	v_mfma_f32_16x16x32_bf16 v[44:47], v[180:183], v[204:207], v[44:47]
	v_mfma_f32_16x16x32_bf16 v[36:39], v[188:191], v[204:207], v[36:39]
	v_mfma_f32_16x16x32_bf16 v[28:31], v[180:183], v[212:215], v[28:31]
	v_mfma_f32_16x16x32_bf16 v[20:23], v[188:191], v[212:215], v[20:23]
	v_mfma_f32_16x16x32_bf16 v[12:15], v[180:183], v[240:243], v[12:15]
	v_mfma_f32_16x16x32_bf16 v[0:3], v[188:191], v[240:243], v[0:3]
	s_setprio 0
	v_lshl_add_u64 v[142:143], v[142:143], 0, s[80:81]
	v_lshl_add_u64 v[144:145], v[144:145], 0, s[80:81]
	s_mov_b32 s10, s11
	s_cmp_eq_u32 s10, s58
	s_barrier
	s_cbranch_scc1 .Lgu_last
	s_branch .LBB0_308
; #define PG8_STAGE(bufoff, gbase, voff) do { _Pragma("unroll") for (int _i = 0; _i < 2; ++_i) \
;         __builtin_amdgcn_global_load_lds((const unsigned*)((const char*)(gbase) + (voff)[_i]), (LAS unsigned*)(lds + (bufoff) + ldsw + _i * 8192), 16, 0, 0); } while (0)
; #define PG8_LDA(dst, b, h) do { _Pragma("unroll") for (int m = 0; m < 4; ++m) _Pragma("unroll") for (int k = 0; k < 2; ++k) dst[m][k] = *(const LAS bf16x8*)(lds + PG8_SA(b, h) + aoff + m * 2048 + k * 1024); } while (0)
; #define PG8_LDB(dst, b, h) do { _Pragma("unroll") for (int n = 0; n < 2; ++n) _Pragma("unroll") for (int k = 0; k < 2; ++k) dst[n][k] = *(const LAS bf16x8*)(lds + PG8_SB(b, h) + boff + n * 2048 + k * 1024); } while (0)
; #define PG8_MMA(ai, bj, At, Bt) do { __builtin_amdgcn_s_setprio(1); _Pragma("unroll") for (int k = 0; k < 2; ++k) _Pragma("unroll") for (int m = 0; m < 4; ++m) _Pragma("unroll") for (int n = 0; n < 2; ++n) \
;         acc[ai][bj][m][n] = __builtin_amdgcn_mfma_f32_16x16x32_bf16(Bt[n][k], At[m][k], acc[ai][bj][m][n], 0, 0, 0); __builtin_amdgcn_s_setprio(0); } while (0)
; #define PG8_WAIT_V(n) asm volatile("s_waitcnt vmcnt(" #n ")" ::: "memory")
; #define PG8_WAIT_L(n) asm volatile("s_waitcnt lgkmcnt(" #n ")" ::: "memory")
; #define PG8_BAR __builtin_amdgcn_s_barrier()
; #define PG8_SCHED __builtin_amdgcn_sched_barrier(0)
; template <class Epi, bool ALIGN_EPI>
; __device__ __forceinline__ void gemm_phase(LAS unsigned char* lds, const Gemm g, const StaticOrder& S, const Epi& E, const int tid) {
;     ...
;             const bool last = (t == nt - 2);
;             const char* a1 = cA + (size_t)(t + 1) * kstep;
;             const char* a2 = last ? nA : cA + (size_t)(t + 2) * kstep; const char* b2 = last ? nB : cB + (size_t)(t + 2) * kstep;
;             const char* a3 = a2 + kstep; const char* b3 = b2 + kstep;
;             PG8_LDB(B0, 0, 0); PG8_LDB(B1, 0, 1); PG8_SCHED; PG8_LDA(At, 0, 0); PG8_STAGE(PG8_SA(1, 1), a1 + hA, voffA);
;             PG8_WAIT_V(8); PG8_WAIT_L(0); PG8_BAR; PG8_MMA(0, 0, At, B0); PG8_MMA(0, 1, At, B1); PG8_BAR; PG8_SCHED;
;             PG8_LDA(At, 0, 1); PG8_STAGE(PG8_SB(0, 0), b2, voffB); PG8_STAGE(PG8_SB(0, 1), b2 + hB, voffB); PG8_STAGE(PG8_SA(0, 0), a2, voffA);
;             PG8_WAIT_V(8); PG8_WAIT_L(0); PG8_BAR; PG8_MMA(1, 0, At, B0); PG8_MMA(1, 1, At, B1); PG8_BAR; PG8_SCHED;
.Lgu_first:
	v_add_u32_e32 v150, s33, v151
	ds_read_b128 v[146:149], v150
	ds_read_b128 v[154:157], v150 offset:1024
	ds_read_b128 v[158:161], v150 offset:2048
	ds_read_b128 v[162:165], v150 offset:3072
	s_add_i32 s11, s10, 2
	s_cmp_eq_u32 s58, s10
	s_cselect_b64 vcc, -1, 0
	s_add_i32 s10, 0, 0x14000
	v_add_u32_e32 v150, s10, v151
	ds_read_b128 v[176:179], v150
	ds_read_b128 v[180:183], v150 offset:1024
	ds_read_b128 v[184:187], v150 offset:2048
	ds_read_b128 v[188:191], v150 offset:3072
	v_lshl_add_u64 v[226:227], v[142:143], 0, s[92:93]
	v_cndmask_b32_e32 v167, v227, v139, vcc
	v_cndmask_b32_e32 v166, v226, v138, vcc
	v_cndmask_b32_e32 v221, v145, v141, vcc
	v_cndmask_b32_e32 v220, v144, v140, vcc
	v_lshl_add_u64 v[226:227], v[142:143], 0, v[134:135]
	s_add_i32 m0, s51, 0xc000
	ds_read_b128 v[192:195], v153
	ds_read_b128 v[196:199], v153 offset:1024
	ds_read_b128 v[200:203], v153 offset:2048
	ds_read_b128 v[204:207], v153 offset:3072
	ds_read_b128 v[208:211], v153 offset:4096
	ds_read_b128 v[212:215], v153 offset:5120
	ds_read_b128 v[216:219], v153 offset:6144
	ds_read_b128 v[240:243], v153 offset:7168
	global_load_lds_dwordx4 v[226:227], off
	v_lshl_add_u64 v[226:227], v[142:143], 0, v[136:137]
	s_add_i32 m0, s51, 0xe000
	s_nop 0
	global_load_lds_dwordx4 v[226:227], off
	s_waitcnt vmcnt(8)
	s_waitcnt lgkmcnt(0)
	s_barrier
	s_setprio 1
	s_waitcnt lgkmcnt(0)
	v_mfma_f32_16x16x32_bf16 v[120:123], v[146:149], v[192:195], 0
	v_mfma_f32_16x16x32_bf16 v[112:115], v[158:161], v[192:195], 0
	v_mfma_f32_16x16x32_bf16 v[104:107], v[146:149], v[200:203], 0
	v_mfma_f32_16x16x32_bf16 v[96:99], v[158:161], v[200:203], 0
	v_mfma_f32_16x16x32_bf16 v[88:91], v[146:149], v[208:211], 0
	v_mfma_f32_16x16x32_bf16 v[80:83], v[158:161], v[208:211], 0
	v_mfma_f32_16x16x32_bf16 v[72:75], v[146:149], v[216:219], 0
	v_mfma_f32_16x16x32_bf16 v[64:67], v[158:161], v[216:219], 0
	v_mfma_f32_16x16x32_bf16 v[120:123], v[154:157], v[196:199], v[120:123]
	v_mfma_f32_16x16x32_bf16 v[112:115], v[162:165], v[196:199], v[112:115]
	v_mfma_f32_16x16x32_bf16 v[104:107], v[154:157], v[204:207], v[104:107]
	v_mfma_f32_16x16x32_bf16 v[96:99], v[162:165], v[204:207], v[96:99]
	v_mfma_f32_16x16x32_bf16 v[88:91], v[154:157], v[212:215], v[88:91]
	v_mfma_f32_16x16x32_bf16 v[80:83], v[162:165], v[212:215], v[80:83]
	v_mfma_f32_16x16x32_bf16 v[72:75], v[154:157], v[240:243], v[72:75]
	v_mfma_f32_16x16x32_bf16 v[64:67], v[162:165], v[240:243], v[64:67]
	s_setprio 0
	s_setprio 1
	v_mfma_f32_16x16x32_bf16 v[124:127], v[176:179], v[192:195], 0
	v_mfma_f32_16x16x32_bf16 v[116:119], v[184:187], v[192:195], 0
	v_mfma_f32_16x16x32_bf16 v[108:111], v[176:179], v[200:203], 0
	v_mfma_f32_16x16x32_bf16 v[100:103], v[184:187], v[200:203], 0
	v_mfma_f32_16x16x32_bf16 v[92:95], v[176:179], v[208:211], 0
	v_mfma_f32_16x16x32_bf16 v[84:87], v[184:187], v[208:211], 0
	v_mfma_f32_16x16x32_bf16 v[76:79], v[176:179], v[216:219], 0
	v_mfma_f32_16x16x32_bf16 v[68:71], v[184:187], v[216:219], 0
	v_mfma_f32_16x16x32_bf16 v[124:127], v[180:183], v[196:199], v[124:127]
	v_mfma_f32_16x16x32_bf16 v[116:119], v[188:191], v[196:199], v[116:119]
	v_mfma_f32_16x16x32_bf16 v[108:111], v[180:183], v[204:207], v[108:111]
	v_mfma_f32_16x16x32_bf16 v[100:103], v[188:191], v[204:207], v[100:103]
	v_mfma_f32_16x16x32_bf16 v[92:95], v[180:183], v[212:215], v[92:95]
	v_mfma_f32_16x16x32_bf16 v[84:87], v[188:191], v[212:215], v[84:87]
	v_mfma_f32_16x16x32_bf16 v[76:79], v[180:183], v[240:243], v[76:79]
	v_mfma_f32_16x16x32_bf16 v[68:71], v[188:191], v[240:243], v[68:71]
	s_setprio 0
	s_barrier
	s_add_i32 s65, s33, s45
	v_lshl_add_u64 v[226:227], v[220:221], 0, v[168:169]
	s_mov_b32 m0, s65
	ds_read_b128 v[192:195], v153 offset:16384
	ds_read_b128 v[196:199], v153 offset:17408
	ds_read_b128 v[200:203], v153 offset:18432
	ds_read_b128 v[204:207], v153 offset:19456
	ds_read_b128 v[208:211], v153 offset:20480
	ds_read_b128 v[212:215], v153 offset:21504
	ds_read_b128 v[216:219], v153 offset:22528
	ds_read_b128 v[240:243], v153 offset:23552
	global_load_lds_dwordx4 v[226:227], off
	v_lshl_add_u64 v[244:245], v[220:221], 0, v[128:129]
	s_add_i32 m0, s65, 0x2000
	v_lshl_add_u64 v[220:221], v[220:221], 0, s[12:13]
	s_add_i32 s10, s10, s45
	global_load_lds_dwordx4 v[244:245], off
	v_lshl_add_u64 v[246:247], v[220:221], 0, v[168:169]
	s_mov_b32 m0, s10
	v_lshl_add_u64 v[220:221], v[220:221], 0, v[128:129]
	global_load_lds_dwordx4 v[246:247], off
	s_add_i32 m0, s10, 0x2000
	v_lshl_add_u64 v[248:249], v[166:167], 0, v[132:133]
	global_load_lds_dwordx4 v[220:221], off
	s_mov_b32 m0, s51
	v_lshl_add_u64 v[250:251], v[166:167], 0, v[130:131]
	global_load_lds_dwordx4 v[248:249], off
	s_mov_b32 m0, s52
	s_nop 0
	global_load_lds_dwordx4 v[250:251], off
	s_waitcnt vmcnt(8)
	s_waitcnt lgkmcnt(0)
	s_barrier
; #define PG8_STAGE(bufoff, gbase, voff) do { _Pragma("unroll") for (int _i = 0; _i < 2; ++_i) \
;         __builtin_amdgcn_global_load_lds((const unsigned*)((const char*)(gbase) + (voff)[_i]), (LAS unsigned*)(lds + (bufoff) + ldsw + _i * 8192), 16, 0, 0); } while (0)
; #define PG8_LDA(dst, b, h) do { _Pragma("unroll") for (int m = 0; m < 4; ++m) _Pragma("unroll") for (int k = 0; k < 2; ++k) dst[m][k] = *(const LAS bf16x8*)(lds + PG8_SA(b, h) + aoff + m * 2048 + k * 1024); } while (0)
; #define PG8_LDB(dst, b, h) do { _Pragma("unroll") for (int n = 0; n < 2; ++n) _Pragma("unroll") for (int k = 0; k < 2; ++k) dst[n][k] = *(const LAS bf16x8*)(lds + PG8_SB(b, h) + boff + n * 2048 + k * 1024); } while (0)
; #define PG8_MMA(ai, bj, At, Bt) do { __builtin_amdgcn_s_setprio(1); _Pragma("unroll") for (int k = 0; k < 2; ++k) _Pragma("unroll") for (int m = 0; m < 4; ++m) _Pragma("unroll") for (int n = 0; n < 2; ++n) \
;         acc[ai][bj][m][n] = __builtin_amdgcn_mfma_f32_16x16x32_bf16(Bt[n][k], At[m][k], acc[ai][bj][m][n], 0, 0, 0); __builtin_amdgcn_s_setprio(0); } while (0)
; #define PG8_WAIT_V(n) asm volatile("s_waitcnt vmcnt(" #n ")" ::: "memory")
; #define PG8_WAIT_L(n) asm volatile("s_waitcnt lgkmcnt(" #n ")" ::: "memory")
; #define PG8_BAR __builtin_amdgcn_s_barrier()
; #define PG8_SCHED __builtin_amdgcn_sched_barrier(0)
; template <class Epi, bool ALIGN_EPI>
; __device__ __forceinline__ void gemm_phase(LAS unsigned char* lds, const Gemm g, const StaticOrder& S, const Epi& E, const int tid) {
;     ...
;             PG8_WAIT_V(8); PG8_WAIT_L(0); PG8_BAR; PG8_MMA(1, 0, At, B0); PG8_MMA(1, 1, At, B1); PG8_BAR; PG8_SCHED;
;             PG8_LDB(B0, 1, 0); PG8_LDB(B1, 1, 1); PG8_SCHED; PG8_LDA(At, 1, 0); PG8_STAGE(PG8_SA(0, 1), a2 + hA, voffA);
;             PG8_WAIT_V(8); PG8_WAIT_L(0); PG8_BAR; PG8_MMA(0, 0, At, B0); PG8_MMA(0, 1, At, B1); PG8_BAR; PG8_SCHED;
	s_setprio 1
	s_waitcnt lgkmcnt(0)
	v_mfma_f32_16x16x32_bf16 v[56:59], v[146:149], v[192:195], 0
	v_mfma_f32_16x16x32_bf16 v[48:51], v[158:161], v[192:195], 0
	v_mfma_f32_16x16x32_bf16 v[40:43], v[146:149], v[200:203], 0
	v_mfma_f32_16x16x32_bf16 v[32:35], v[158:161], v[200:203], 0
	v_mfma_f32_16x16x32_bf16 v[24:27], v[146:149], v[208:211], 0
	v_mfma_f32_16x16x32_bf16 v[16:19], v[158:161], v[208:211], 0
	v_mfma_f32_16x16x32_bf16 v[8:11], v[146:149], v[216:219], 0
	v_mfma_f32_16x16x32_bf16 v[4:7], v[158:161], v[216:219], 0
	v_mfma_f32_16x16x32_bf16 v[56:59], v[154:157], v[196:199], v[56:59]
	v_mfma_f32_16x16x32_bf16 v[48:51], v[162:165], v[196:199], v[48:51]
	v_mfma_f32_16x16x32_bf16 v[40:43], v[154:157], v[204:207], v[40:43]
	v_mfma_f32_16x16x32_bf16 v[32:35], v[162:165], v[204:207], v[32:35]
	v_mfma_f32_16x16x32_bf16 v[24:27], v[154:157], v[212:215], v[24:27]
	v_mfma_f32_16x16x32_bf16 v[16:19], v[162:165], v[212:215], v[16:19]
	v_mfma_f32_16x16x32_bf16 v[8:11], v[154:157], v[240:243], v[8:11]
	v_mfma_f32_16x16x32_bf16 v[4:7], v[162:165], v[240:243], v[4:7]
	s_setprio 0
	s_setprio 1
	v_mfma_f32_16x16x32_bf16 v[60:63], v[176:179], v[192:195], 0
	v_mfma_f32_16x16x32_bf16 v[52:55], v[184:187], v[192:195], 0
	v_mfma_f32_16x16x32_bf16 v[44:47], v[176:179], v[200:203], 0
	v_mfma_f32_16x16x32_bf16 v[36:39], v[184:187], v[200:203], 0
	v_mfma_f32_16x16x32_bf16 v[28:31], v[176:179], v[208:211], 0
	v_mfma_f32_16x16x32_bf16 v[20:23], v[184:187], v[208:211], 0
	v_mfma_f32_16x16x32_bf16 v[12:15], v[176:179], v[216:219], 0
	v_mfma_f32_16x16x32_bf16 v[0:3], v[184:187], v[216:219], 0
	v_mfma_f32_16x16x32_bf16 v[60:63], v[180:183], v[196:199], v[60:63]
	v_mfma_f32_16x16x32_bf16 v[52:55], v[188:191], v[196:199], v[52:55]
	v_mfma_f32_16x16x32_bf16 v[44:47], v[180:183], v[204:207], v[44:47]
	v_mfma_f32_16x16x32_bf16 v[36:39], v[188:191], v[204:207], v[36:39]
	v_mfma_f32_16x16x32_bf16 v[28:31], v[180:183], v[212:215], v[28:31]
	v_mfma_f32_16x16x32_bf16 v[20:23], v[188:191], v[212:215], v[20:23]
	v_mfma_f32_16x16x32_bf16 v[12:15], v[180:183], v[240:243], v[12:15]
	v_mfma_f32_16x16x32_bf16 v[0:3], v[188:191], v[240:243], v[0:3]
	s_setprio 0
	s_barrier
	s_add_i32 s10, 0, 0x18000
	v_add_u32_e32 v150, s10, v151
	s_add_i32 s65, 0, 0x1c000
	ds_read_b128 v[146:149], v150
	ds_read_b128 v[154:157], v150 offset:1024
	ds_read_b128 v[158:161], v150 offset:2048
	ds_read_b128 v[162:165], v150 offset:3072
	v_add_u32_e32 v150, s65, v151
	ds_read_b128 v[176:179], v150
	ds_read_b128 v[180:183], v150 offset:1024
	ds_read_b128 v[184:187], v150 offset:2048
	ds_read_b128 v[188:191], v150 offset:3072
	v_lshl_add_u64 v[166:167], v[166:167], 0, s[94:95]
	s_mov_b32 m0, s53
	v_lshl_add_u64 v[252:253], v[166:167], 0, v[132:133]
	ds_read_b128 v[192:195], v153 offset:32768
	ds_read_b128 v[196:199], v153 offset:33792
	ds_read_b128 v[200:203], v153 offset:34816
	ds_read_b128 v[204:207], v153 offset:35840
	ds_read_b128 v[208:211], v153 offset:36864
	ds_read_b128 v[212:215], v153 offset:37888
	ds_read_b128 v[216:219], v153 offset:38912
	ds_read_b128 v[240:243], v153 offset:39936
	global_load_lds_dwordx4 v[252:253], off
	v_lshl_add_u64 v[166:167], v[166:167], 0, v[130:131]
	s_mov_b32 m0, s54
	s_nop 0
	global_load_lds_dwordx4 v[166:167], off
	s_waitcnt vmcnt(8)
	s_waitcnt lgkmcnt(0)
	s_barrier
	s_setprio 1
	s_waitcnt lgkmcnt(0)
	v_mfma_f32_16x16x32_bf16 v[120:123], v[146:149], v[192:195], v[120:123]
	v_mfma_f32_16x16x32_bf16 v[112:115], v[158:161], v[192:195], v[112:115]
	v_mfma_f32_16x16x32_bf16 v[104:107], v[146:149], v[200:203], v[104:107]
	v_mfma_f32_16x16x32_bf16 v[96:99], v[158:161], v[200:203], v[96:99]
	v_mfma_f32_16x16x32_bf16 v[88:91], v[146:149], v[208:211], v[88:91]
	v_mfma_f32_16x16x32_bf16 v[80:83], v[158:161], v[208:211], v[80:83]
	v_mfma_f32_16x16x32_bf16 v[72:75], v[146:149], v[216:219], v[72:75]
	v_mfma_f32_16x16x32_bf16 v[64:67], v[158:161], v[216:219], v[64:67]
	v_mfma_f32_16x16x32_bf16 v[120:123], v[154:157], v[196:199], v[120:123]
	v_mfma_f32_16x16x32_bf16 v[112:115], v[162:165], v[196:199], v[112:115]
	v_mfma_f32_16x16x32_bf16 v[104:107], v[154:157], v[204:207], v[104:107]
	v_mfma_f32_16x16x32_bf16 v[96:99], v[162:165], v[204:207], v[96:99]
	v_mfma_f32_16x16x32_bf16 v[88:91], v[154:157], v[212:215], v[88:91]
	v_mfma_f32_16x16x32_bf16 v[80:83], v[162:165], v[212:215], v[80:83]
	v_mfma_f32_16x16x32_bf16 v[72:75], v[154:157], v[240:243], v[72:75]
	v_mfma_f32_16x16x32_bf16 v[64:67], v[162:165], v[240:243], v[64:67]
	s_setprio 0
	s_setprio 1
	v_mfma_f32_16x16x32_bf16 v[124:127], v[176:179], v[192:195], v[124:127]
	v_mfma_f32_16x16x32_bf16 v[116:119], v[184:187], v[192:195], v[116:119]
	v_mfma_f32_16x16x32_bf16 v[108:111], v[176:179], v[200:203], v[108:111]
	v_mfma_f32_16x16x32_bf16 v[100:103], v[184:187], v[200:203], v[100:103]
	v_mfma_f32_16x16x32_bf16 v[92:95], v[176:179], v[208:211], v[92:95]
	v_mfma_f32_16x16x32_bf16 v[84:87], v[184:187], v[208:211], v[84:87]
	v_mfma_f32_16x16x32_bf16 v[76:79], v[176:179], v[216:219], v[76:79]
	v_mfma_f32_16x16x32_bf16 v[68:71], v[184:187], v[216:219], v[68:71]
	v_mfma_f32_16x16x32_bf16 v[124:127], v[180:183], v[196:199], v[124:127]
	v_mfma_f32_16x16x32_bf16 v[116:119], v[188:191], v[196:199], v[116:119]
	v_mfma_f32_16x16x32_bf16 v[108:111], v[180:183], v[204:207], v[108:111]
	v_mfma_f32_16x16x32_bf16 v[100:103], v[188:191], v[204:207], v[100:103]
	v_mfma_f32_16x16x32_bf16 v[92:95], v[180:183], v[212:215], v[92:95]
	v_mfma_f32_16x16x32_bf16 v[84:87], v[188:191], v[212:215], v[84:87]
	v_mfma_f32_16x16x32_bf16 v[76:79], v[180:183], v[240:243], v[76:79]
	v_mfma_f32_16x16x32_bf16 v[68:71], v[188:191], v[240:243], v[68:71]
	s_setprio 0
	s_barrier
; #define PG8_STAGE(bufoff, gbase, voff) do { _Pragma("unroll") for (int _i = 0; _i < 2; ++_i) \
;         __builtin_amdgcn_global_load_lds((const unsigned*)((const char*)(gbase) + (voff)[_i]), (LAS unsigned*)(lds + (bufoff) + ldsw + _i * 8192), 16, 0, 0); } while (0)
; #define PG8_LDA(dst, b, h) do { _Pragma("unroll") for (int m = 0; m < 4; ++m) _Pragma("unroll") for (int k = 0; k < 2; ++k) dst[m][k] = *(const LAS bf16x8*)(lds + PG8_SA(b, h) + aoff + m * 2048 + k * 1024); } while (0)
; #define PG8_LDB(dst, b, h) do { _Pragma("unroll") for (int n = 0; n < 2; ++n) _Pragma("unroll") for (int k = 0; k < 2; ++k) dst[n][k] = *(const LAS bf16x8*)(lds + PG8_SB(b, h) + boff + n * 2048 + k * 1024); } while (0)
; #define PG8_MMA(ai, bj, At, Bt) do { __builtin_amdgcn_s_setprio(1); _Pragma("unroll") for (int k = 0; k < 2; ++k) _Pragma("unroll") for (int m = 0; m < 4; ++m) _Pragma("unroll") for (int n = 0; n < 2; ++n) \
;         acc[ai][bj][m][n] = __builtin_amdgcn_mfma_f32_16x16x32_bf16(Bt[n][k], At[m][k], acc[ai][bj][m][n], 0, 0, 0); __builtin_amdgcn_s_setprio(0); } while (0)
; #define PG8_WAIT_V(n) asm volatile("s_waitcnt vmcnt(" #n ")" ::: "memory")
; template <class Epi, bool ALIGN_EPI>
; __device__ __forceinline__ void gemm_phase(LAS unsigned char* lds, const Gemm g, const StaticOrder& S, const Epi& E, const int tid) {
;     ...
;             PG8_LDB(B0, 0, 0); PG8_LDB(B1, 0, 1); PG8_SCHED; PG8_LDA(At, 0, 0); PG8_STAGE(PG8_SA(1, 1), a1 + hA, voffA);
;             PG8_WAIT_V(8); PG8_WAIT_L(0); PG8_BAR; PG8_MMA(0, 0, At, B0); PG8_MMA(0, 1, At, B1); PG8_BAR; PG8_SCHED;
;             PG8_LDA(At, 0, 1); PG8_STAGE(PG8_SB(0, 0), b2, voffB); PG8_STAGE(PG8_SB(0, 1), b2 + hB, voffB); PG8_STAGE(PG8_SA(0, 0), a2, voffA);
;             PG8_WAIT_V(8); PG8_WAIT_L(0); PG8_BAR; PG8_MMA(1, 0, At, B0); PG8_MMA(1, 1, At, B1); PG8_BAR; PG8_SCHED;
;             PG8_LDB(B0, 1, 0); PG8_LDB(B1, 1, 1); PG8_SCHED; PG8_LDA(At, 1, 0); PG8_STAGE(PG8_SA(0, 1), a2 + hA, voffA);
;             PG8_WAIT_V(8); PG8_WAIT_L(0); PG8_BAR; PG8_MMA(0, 0, At, B0); PG8_MMA(0, 1, At, B1); PG8_BAR; PG8_SCHED;
;             PG8_LDA(At, 1, 1); PG8_STAGE(PG8_SB(1, 0), b3, voffB); PG8_STAGE(PG8_SB(1, 1), b3 + hB, voffB); PG8_STAGE(PG8_SA(1, 0), a3, voffA);
;             PG8_WAIT_V(8); PG8_WAIT_L(0); PG8_BAR; PG8_MMA(1, 0, At, B0); PG8_MMA(1, 1, At, B1); PG8_BAR; PG8_SCHED;
;         }
	s_add_i32 s10, s10, s45
	v_lshl_add_u64 v[166:167], v[226:227], 0, s[92:93]
	s_mov_b32 m0, s10
	ds_read_b128 v[192:195], v153 offset:49152
	ds_read_b128 v[196:199], v153 offset:50176
	ds_read_b128 v[200:203], v153 offset:51200
	ds_read_b128 v[204:207], v153 offset:52224
	ds_read_b128 v[208:211], v153 offset:53248
	ds_read_b128 v[212:215], v153 offset:54272
	ds_read_b128 v[216:219], v153 offset:55296
	ds_read_b128 v[240:243], v153 offset:56320
	global_load_lds_dwordx4 v[166:167], off
	v_lshl_add_u64 v[166:167], v[244:245], 0, s[92:93]
	s_add_i32 m0, s10, 0x2000
	s_add_i32 s10, s65, s45
	global_load_lds_dwordx4 v[166:167], off
	v_lshl_add_u64 v[166:167], v[246:247], 0, s[92:93]
	s_mov_b32 m0, s10
	s_nop 0
	global_load_lds_dwordx4 v[166:167], off
	v_lshl_add_u64 v[166:167], v[220:221], 0, s[92:93]
	s_add_i32 m0, s10, 0x2000
	s_nop 0
	global_load_lds_dwordx4 v[166:167], off
	v_lshl_add_u64 v[166:167], v[248:249], 0, s[92:93]
	s_mov_b32 m0, s56
	s_nop 0
	global_load_lds_dwordx4 v[166:167], off
	v_lshl_add_u64 v[166:167], v[250:251], 0, s[92:93]
	s_mov_b32 m0, s57
	s_nop 0
	global_load_lds_dwordx4 v[166:167], off
	s_waitcnt vmcnt(8)
	s_waitcnt lgkmcnt(0)
	s_barrier
	s_setprio 1
	s_waitcnt lgkmcnt(0)
	v_mfma_f32_16x16x32_bf16 v[56:59], v[146:149], v[192:195], v[56:59]
	v_mfma_f32_16x16x32_bf16 v[48:51], v[158:161], v[192:195], v[48:51]
	v_mfma_f32_16x16x32_bf16 v[40:43], v[146:149], v[200:203], v[40:43]
	v_mfma_f32_16x16x32_bf16 v[32:35], v[158:161], v[200:203], v[32:35]
	v_mfma_f32_16x16x32_bf16 v[24:27], v[146:149], v[208:211], v[24:27]
	v_mfma_f32_16x16x32_bf16 v[16:19], v[158:161], v[208:211], v[16:19]
	v_mfma_f32_16x16x32_bf16 v[8:11], v[146:149], v[216:219], v[8:11]
	v_mfma_f32_16x16x32_bf16 v[4:7], v[158:161], v[216:219], v[4:7]
	v_mfma_f32_16x16x32_bf16 v[56:59], v[154:157], v[196:199], v[56:59]
	v_mfma_f32_16x16x32_bf16 v[48:51], v[162:165], v[196:199], v[48:51]
	v_mfma_f32_16x16x32_bf16 v[40:43], v[154:157], v[204:207], v[40:43]
	v_mfma_f32_16x16x32_bf16 v[32:35], v[162:165], v[204:207], v[32:35]
	v_mfma_f32_16x16x32_bf16 v[24:27], v[154:157], v[212:215], v[24:27]
	v_mfma_f32_16x16x32_bf16 v[16:19], v[162:165], v[212:215], v[16:19]
	v_mfma_f32_16x16x32_bf16 v[8:11], v[154:157], v[240:243], v[8:11]
	v_mfma_f32_16x16x32_bf16 v[4:7], v[162:165], v[240:243], v[4:7]
	s_setprio 0
	s_setprio 1
	v_mfma_f32_16x16x32_bf16 v[60:63], v[176:179], v[192:195], v[60:63]
	v_mfma_f32_16x16x32_bf16 v[52:55], v[184:187], v[192:195], v[52:55]
	v_mfma_f32_16x16x32_bf16 v[44:47], v[176:179], v[200:203], v[44:47]
	v_mfma_f32_16x16x32_bf16 v[36:39], v[184:187], v[200:203], v[36:39]
	v_mfma_f32_16x16x32_bf16 v[28:31], v[176:179], v[208:211], v[28:31]
	v_mfma_f32_16x16x32_bf16 v[20:23], v[184:187], v[208:211], v[20:23]
	v_mfma_f32_16x16x32_bf16 v[12:15], v[176:179], v[216:219], v[12:15]
	v_mfma_f32_16x16x32_bf16 v[0:3], v[184:187], v[216:219], v[0:3]
	v_mfma_f32_16x16x32_bf16 v[60:63], v[180:183], v[196:199], v[60:63]
	v_mfma_f32_16x16x32_bf16 v[52:55], v[188:191], v[196:199], v[52:55]
	v_mfma_f32_16x16x32_bf16 v[44:47], v[180:183], v[204:207], v[44:47]
	v_mfma_f32_16x16x32_bf16 v[36:39], v[188:191], v[204:207], v[36:39]
	v_mfma_f32_16x16x32_bf16 v[28:31], v[180:183], v[212:215], v[28:31]
	v_mfma_f32_16x16x32_bf16 v[20:23], v[188:191], v[212:215], v[20:23]
	v_mfma_f32_16x16x32_bf16 v[12:15], v[180:183], v[240:243], v[12:15]
	v_mfma_f32_16x16x32_bf16 v[0:3], v[188:191], v[240:243], v[0:3]
	s_setprio 0
	v_lshl_add_u64 v[142:143], v[142:143], 0, s[80:81]
	v_lshl_add_u64 v[144:145], v[144:145], 0, s[80:81]
	s_mov_b32 s10, s11
	s_cmp_eq_u32 s10, s58
	s_barrier
	s_cbranch_scc1 .Lgu_last
.LBB0_308:
	v_add_u32_e32 v150, s33, v151
	ds_read_b128 v[146:149], v150
	ds_read_b128 v[154:157], v150 offset:1024
	ds_read_b128 v[158:161], v150 offset:2048
	ds_read_b128 v[162:165], v150 offset:3072
	s_add_i32 s11, s10, 2
	s_cmp_eq_u32 s58, s10
	s_cselect_b64 vcc, -1, 0
	s_add_i32 s10, 0, 0x14000
	v_add_u32_e32 v150, s10, v151
	ds_read_b128 v[176:179], v150
	ds_read_b128 v[180:183], v150 offset:1024
	ds_read_b128 v[184:187], v150 offset:2048
	ds_read_b128 v[188:191], v150 offset:3072
	v_lshl_add_u64 v[226:227], v[142:143], 0, s[92:93]
	v_cndmask_b32_e32 v167, v227, v139, vcc
	v_cndmask_b32_e32 v166, v226, v138, vcc
	v_cndmask_b32_e32 v221, v145, v141, vcc
	v_cndmask_b32_e32 v220, v144, v140, vcc
	v_lshl_add_u64 v[226:227], v[142:143], 0, v[134:135]
	s_add_i32 m0, s51, 0xc000
	ds_read_b128 v[192:195], v153
	ds_read_b128 v[196:199], v153 offset:1024
	ds_read_b128 v[200:203], v153 offset:2048
	ds_read_b128 v[204:207], v153 offset:3072
	ds_read_b128 v[208:211], v153 offset:4096
	ds_read_b128 v[212:215], v153 offset:5120
	ds_read_b128 v[216:219], v153 offset:6144
	ds_read_b128 v[240:243], v153 offset:7168
	global_load_lds_dwordx4 v[226:227], off
	v_lshl_add_u64 v[226:227], v[142:143], 0, v[136:137]
	s_add_i32 m0, s51, 0xe000
	s_nop 0
	global_load_lds_dwordx4 v[226:227], off
	s_waitcnt vmcnt(8)
	s_waitcnt lgkmcnt(0)
	s_barrier
; #define PG8_STAGE(bufoff, gbase, voff) do { _Pragma("unroll") for (int _i = 0; _i < 2; ++_i) \
;         __builtin_amdgcn_global_load_lds((const unsigned*)((const char*)(gbase) + (voff)[_i]), (LAS unsigned*)(lds + (bufoff) + ldsw + _i * 8192), 16, 0, 0); } while (0)
; #define PG8_LDA(dst, b, h) do { _Pragma("unroll") for (int m = 0; m < 4; ++m) _Pragma("unroll") for (int k = 0; k < 2; ++k) dst[m][k] = *(const LAS bf16x8*)(lds + PG8_SA(b, h) + aoff + m * 2048 + k * 1024); } while (0)
; #define PG8_LDB(dst, b, h) do { _Pragma("unroll") for (int n = 0; n < 2; ++n) _Pragma("unroll") for (int k = 0; k < 2; ++k) dst[n][k] = *(const LAS bf16x8*)(lds + PG8_SB(b, h) + boff + n * 2048 + k * 1024); } while (0)
; #define PG8_MMA(ai, bj, At, Bt) do { __builtin_amdgcn_s_setprio(1); _Pragma("unroll") for (int k = 0; k < 2; ++k) _Pragma("unroll") for (int m = 0; m < 4; ++m) _Pragma("unroll") for (int n = 0; n < 2; ++n) \
;         acc[ai][bj][m][n] = __builtin_amdgcn_mfma_f32_16x16x32_bf16(Bt[n][k], At[m][k], acc[ai][bj][m][n], 0, 0, 0); __builtin_amdgcn_s_setprio(0); } while (0)
; #define PG8_WAIT_V(n) asm volatile("s_waitcnt vmcnt(" #n ")" ::: "memory")
; #define PG8_WAIT_L(n) asm volatile("s_waitcnt lgkmcnt(" #n ")" ::: "memory")
; #define PG8_BAR __builtin_amdgcn_s_barrier()
; #define PG8_SCHED __builtin_amdgcn_sched_barrier(0)
; template <class Epi, bool ALIGN_EPI>
; __device__ __forceinline__ void gemm_phase(LAS unsigned char* lds, const Gemm g, const StaticOrder& S, const Epi& E, const int tid) {
;     ...
;             PG8_WAIT_V(8); PG8_WAIT_L(0); PG8_BAR; PG8_MMA(0, 0, At, B0); PG8_MMA(0, 1, At, B1); PG8_BAR; PG8_SCHED;
;             PG8_LDA(At, 0, 1); PG8_STAGE(PG8_SB(0, 0), b2, voffB); PG8_STAGE(PG8_SB(0, 1), b2 + hB, voffB); PG8_STAGE(PG8_SA(0, 0), a2, voffA);
;             PG8_WAIT_V(8); PG8_WAIT_L(0); PG8_BAR; PG8_MMA(1, 0, At, B0); PG8_MMA(1, 1, At, B1); PG8_BAR; PG8_SCHED;
;             PG8_LDB(B0, 1, 0); PG8_LDB(B1, 1, 1); PG8_SCHED; PG8_LDA(At, 1, 0); PG8_STAGE(PG8_SA(0, 1), a2 + hA, voffA);
;             PG8_WAIT_V(8); PG8_WAIT_L(0); PG8_BAR; PG8_MMA(0, 0, At, B0); PG8_MMA(0, 1, At, B1); PG8_BAR; PG8_SCHED;
	s_setprio 1
	s_waitcnt lgkmcnt(0)
	v_mfma_f32_16x16x32_bf16 v[120:123], v[146:149], v[192:195], v[120:123]
	v_mfma_f32_16x16x32_bf16 v[112:115], v[158:161], v[192:195], v[112:115]
	v_mfma_f32_16x16x32_bf16 v[104:107], v[146:149], v[200:203], v[104:107]
	v_mfma_f32_16x16x32_bf16 v[96:99], v[158:161], v[200:203], v[96:99]
	v_mfma_f32_16x16x32_bf16 v[88:91], v[146:149], v[208:211], v[88:91]
	v_mfma_f32_16x16x32_bf16 v[80:83], v[158:161], v[208:211], v[80:83]
	v_mfma_f32_16x16x32_bf16 v[72:75], v[146:149], v[216:219], v[72:75]
	v_mfma_f32_16x16x32_bf16 v[64:67], v[158:161], v[216:219], v[64:67]
	v_mfma_f32_16x16x32_bf16 v[120:123], v[154:157], v[196:199], v[120:123]
	v_mfma_f32_16x16x32_bf16 v[112:115], v[162:165], v[196:199], v[112:115]
	v_mfma_f32_16x16x32_bf16 v[104:107], v[154:157], v[204:207], v[104:107]
	v_mfma_f32_16x16x32_bf16 v[96:99], v[162:165], v[204:207], v[96:99]
	v_mfma_f32_16x16x32_bf16 v[88:91], v[154:157], v[212:215], v[88:91]
	v_mfma_f32_16x16x32_bf16 v[80:83], v[162:165], v[212:215], v[80:83]
	v_mfma_f32_16x16x32_bf16 v[72:75], v[154:157], v[240:243], v[72:75]
	v_mfma_f32_16x16x32_bf16 v[64:67], v[162:165], v[240:243], v[64:67]
	s_setprio 0
	s_setprio 1
	v_mfma_f32_16x16x32_bf16 v[124:127], v[176:179], v[192:195], v[124:127]
	v_mfma_f32_16x16x32_bf16 v[116:119], v[184:187], v[192:195], v[116:119]
	v_mfma_f32_16x16x32_bf16 v[108:111], v[176:179], v[200:203], v[108:111]
	v_mfma_f32_16x16x32_bf16 v[100:103], v[184:187], v[200:203], v[100:103]
	v_mfma_f32_16x16x32_bf16 v[92:95], v[176:179], v[208:211], v[92:95]
	v_mfma_f32_16x16x32_bf16 v[84:87], v[184:187], v[208:211], v[84:87]
	v_mfma_f32_16x16x32_bf16 v[76:79], v[176:179], v[216:219], v[76:79]
	v_mfma_f32_16x16x32_bf16 v[68:71], v[184:187], v[216:219], v[68:71]
	v_mfma_f32_16x16x32_bf16 v[124:127], v[180:183], v[196:199], v[124:127]
	v_mfma_f32_16x16x32_bf16 v[116:119], v[188:191], v[196:199], v[116:119]
	v_mfma_f32_16x16x32_bf16 v[108:111], v[180:183], v[204:207], v[108:111]
	v_mfma_f32_16x16x32_bf16 v[100:103], v[188:191], v[204:207], v[100:103]
	v_mfma_f32_16x16x32_bf16 v[92:95], v[180:183], v[212:215], v[92:95]
	v_mfma_f32_16x16x32_bf16 v[84:87], v[188:191], v[212:215], v[84:87]
	v_mfma_f32_16x16x32_bf16 v[76:79], v[180:183], v[240:243], v[76:79]
	v_mfma_f32_16x16x32_bf16 v[68:71], v[188:191], v[240:243], v[68:71]
	s_setprio 0
	s_barrier
	s_add_i32 s65, s33, s45
	v_lshl_add_u64 v[226:227], v[220:221], 0, v[168:169]
	s_mov_b32 m0, s65
	ds_read_b128 v[192:195], v153 offset:16384
	ds_read_b128 v[196:199], v153 offset:17408
	ds_read_b128 v[200:203], v153 offset:18432
	ds_read_b128 v[204:207], v153 offset:19456
	ds_read_b128 v[208:211], v153 offset:20480
	ds_read_b128 v[212:215], v153 offset:21504
	ds_read_b128 v[216:219], v153 offset:22528
	ds_read_b128 v[240:243], v153 offset:23552
	global_load_lds_dwordx4 v[226:227], off
	v_lshl_add_u64 v[244:245], v[220:221], 0, v[128:129]
	s_add_i32 m0, s65, 0x2000
	v_lshl_add_u64 v[220:221], v[220:221], 0, s[12:13]
	s_add_i32 s10, s10, s45
	global_load_lds_dwordx4 v[244:245], off
	v_lshl_add_u64 v[246:247], v[220:221], 0, v[168:169]
	s_mov_b32 m0, s10
	v_lshl_add_u64 v[220:221], v[220:221], 0, v[128:129]
	global_load_lds_dwordx4 v[246:247], off
	s_add_i32 m0, s10, 0x2000
	v_lshl_add_u64 v[248:249], v[166:167], 0, v[132:133]
	global_load_lds_dwordx4 v[220:221], off
	s_mov_b32 m0, s51
	v_lshl_add_u64 v[250:251], v[166:167], 0, v[130:131]
	global_load_lds_dwordx4 v[248:249], off
	s_mov_b32 m0, s52
	s_nop 0
	global_load_lds_dwordx4 v[250:251], off
	s_waitcnt vmcnt(8)
	s_waitcnt lgkmcnt(0)
	s_barrier
	s_setprio 1
	s_waitcnt lgkmcnt(0)
	v_mfma_f32_16x16x32_bf16 v[56:59], v[146:149], v[192:195], v[56:59]
	v_mfma_f32_16x16x32_bf16 v[48:51], v[158:161], v[192:195], v[48:51]
	v_mfma_f32_16x16x32_bf16 v[40:43], v[146:149], v[200:203], v[40:43]
	v_mfma_f32_16x16x32_bf16 v[32:35], v[158:161], v[200:203], v[32:35]
	v_mfma_f32_16x16x32_bf16 v[24:27], v[146:149], v[208:211], v[24:27]
	v_mfma_f32_16x16x32_bf16 v[16:19], v[158:161], v[208:211], v[16:19]
	v_mfma_f32_16x16x32_bf16 v[8:11], v[146:149], v[216:219], v[8:11]
	v_mfma_f32_16x16x32_bf16 v[4:7], v[158:161], v[216:219], v[4:7]
	v_mfma_f32_16x16x32_bf16 v[56:59], v[154:157], v[196:199], v[56:59]
	v_mfma_f32_16x16x32_bf16 v[48:51], v[162:165], v[196:199], v[48:51]
	v_mfma_f32_16x16x32_bf16 v[40:43], v[154:157], v[204:207], v[40:43]
	v_mfma_f32_16x16x32_bf16 v[32:35], v[162:165], v[204:207], v[32:35]
	v_mfma_f32_16x16x32_bf16 v[24:27], v[154:157], v[212:215], v[24:27]
	v_mfma_f32_16x16x32_bf16 v[16:19], v[162:165], v[212:215], v[16:19]
	v_mfma_f32_16x16x32_bf16 v[8:11], v[154:157], v[240:243], v[8:11]
	v_mfma_f32_16x16x32_bf16 v[4:7], v[162:165], v[240:243], v[4:7]
	s_setprio 0
	s_setprio 1
	v_mfma_f32_16x16x32_bf16 v[60:63], v[176:179], v[192:195], v[60:63]
	v_mfma_f32_16x16x32_bf16 v[52:55], v[184:187], v[192:195], v[52:55]
	v_mfma_f32_16x16x32_bf16 v[44:47], v[176:179], v[200:203], v[44:47]
	v_mfma_f32_16x16x32_bf16 v[36:39], v[184:187], v[200:203], v[36:39]
	v_mfma_f32_16x16x32_bf16 v[28:31], v[176:179], v[208:211], v[28:31]
	v_mfma_f32_16x16x32_bf16 v[20:23], v[184:187], v[208:211], v[20:23]
	v_mfma_f32_16x16x32_bf16 v[12:15], v[176:179], v[216:219], v[12:15]
	v_mfma_f32_16x16x32_bf16 v[0:3], v[184:187], v[216:219], v[0:3]
	v_mfma_f32_16x16x32_bf16 v[60:63], v[180:183], v[196:199], v[60:63]
	v_mfma_f32_16x16x32_bf16 v[52:55], v[188:191], v[196:199], v[52:55]
	v_mfma_f32_16x16x32_bf16 v[44:47], v[180:183], v[204:207], v[44:47]
	v_mfma_f32_16x16x32_bf16 v[36:39], v[188:191], v[204:207], v[36:39]
	v_mfma_f32_16x16x32_bf16 v[28:31], v[180:183], v[212:215], v[28:31]
	v_mfma_f32_16x16x32_bf16 v[20:23], v[188:191], v[212:215], v[20:23]
	v_mfma_f32_16x16x32_bf16 v[12:15], v[180:183], v[240:243], v[12:15]
	v_mfma_f32_16x16x32_bf16 v[0:3], v[188:191], v[240:243], v[0:3]
	s_setprio 0
	s_barrier
; #define PG8_STAGE(bufoff, gbase, voff) do { _Pragma("unroll") for (int _i = 0; _i < 2; ++_i) \
;         __builtin_amdgcn_global_load_lds((const unsigned*)((const char*)(gbase) + (voff)[_i]), (LAS unsigned*)(lds + (bufoff) + ldsw + _i * 8192), 16, 0, 0); } while (0)
; #define PG8_LDA(dst, b, h) do { _Pragma("unroll") for (int m = 0; m < 4; ++m) _Pragma("unroll") for (int k = 0; k < 2; ++k) dst[m][k] = *(const LAS bf16x8*)(lds + PG8_SA(b, h) + aoff + m * 2048 + k * 1024); } while (0)
; #define PG8_LDB(dst, b, h) do { _Pragma("unroll") for (int n = 0; n < 2; ++n) _Pragma("unroll") for (int k = 0; k < 2; ++k) dst[n][k] = *(const LAS bf16x8*)(lds + PG8_SB(b, h) + boff + n * 2048 + k * 1024); } while (0)
; #define PG8_MMA(ai, bj, At, Bt) do { __builtin_amdgcn_s_setprio(1); _Pragma("unroll") for (int k = 0; k < 2; ++k) _Pragma("unroll") for (int m = 0; m < 4; ++m) _Pragma("unroll") for (int n = 0; n < 2; ++n) \
;         acc[ai][bj][m][n] = __builtin_amdgcn_mfma_f32_16x16x32_bf16(Bt[n][k], At[m][k], acc[ai][bj][m][n], 0, 0, 0); __builtin_amdgcn_s_setprio(0); } while (0)
; #define PG8_WAIT_V(n) asm volatile("s_waitcnt vmcnt(" #n ")" ::: "memory")
; #define PG8_WAIT_L(n) asm volatile("s_waitcnt lgkmcnt(" #n ")" ::: "memory")
; #define PG8_BAR __builtin_amdgcn_s_barrier()
; #define PG8_SCHED __builtin_amdgcn_sched_barrier(0)
; template <class Epi, bool ALIGN_EPI>
; __device__ __forceinline__ void gemm_phase(LAS unsigned char* lds, const Gemm g, const StaticOrder& S, const Epi& E, const int tid) {
;     ...
;             PG8_LDB(B0, 1, 0); PG8_LDB(B1, 1, 1); PG8_SCHED; PG8_LDA(At, 1, 0); PG8_STAGE(PG8_SA(0, 1), a2 + hA, voffA);
;             PG8_WAIT_V(8); PG8_WAIT_L(0); PG8_BAR; PG8_MMA(0, 0, At, B0); PG8_MMA(0, 1, At, B1); PG8_BAR; PG8_SCHED;
;             PG8_LDA(At, 1, 1); PG8_STAGE(PG8_SB(1, 0), b3, voffB); PG8_STAGE(PG8_SB(1, 1), b3 + hB, voffB); PG8_STAGE(PG8_SA(1, 0), a3, voffA);
;             PG8_WAIT_V(8); PG8_WAIT_L(0); PG8_BAR; PG8_MMA(1, 0, At, B0); PG8_MMA(1, 1, At, B1); PG8_BAR; PG8_SCHED;
	s_add_i32 s10, 0, 0x18000
	v_add_u32_e32 v150, s10, v151
	s_add_i32 s65, 0, 0x1c000
	ds_read_b128 v[146:149], v150
	ds_read_b128 v[154:157], v150 offset:1024
	ds_read_b128 v[158:161], v150 offset:2048
	ds_read_b128 v[162:165], v150 offset:3072
	v_add_u32_e32 v150, s65, v151
	ds_read_b128 v[176:179], v150
	ds_read_b128 v[180:183], v150 offset:1024
	ds_read_b128 v[184:187], v150 offset:2048
	ds_read_b128 v[188:191], v150 offset:3072
	v_lshl_add_u64 v[166:167], v[166:167], 0, s[94:95]
	s_mov_b32 m0, s53
	v_lshl_add_u64 v[252:253], v[166:167], 0, v[132:133]
	ds_read_b128 v[192:195], v153 offset:32768
	ds_read_b128 v[196:199], v153 offset:33792
	ds_read_b128 v[200:203], v153 offset:34816
	ds_read_b128 v[204:207], v153 offset:35840
	ds_read_b128 v[208:211], v153 offset:36864
	ds_read_b128 v[212:215], v153 offset:37888
	ds_read_b128 v[216:219], v153 offset:38912
	ds_read_b128 v[240:243], v153 offset:39936
	global_load_lds_dwordx4 v[252:253], off
	v_lshl_add_u64 v[166:167], v[166:167], 0, v[130:131]
	s_mov_b32 m0, s54
	s_nop 0
	global_load_lds_dwordx4 v[166:167], off
	s_waitcnt vmcnt(8)
	s_waitcnt lgkmcnt(0)
	s_barrier
	s_setprio 1
	s_waitcnt lgkmcnt(0)
	v_mfma_f32_16x16x32_bf16 v[120:123], v[146:149], v[192:195], v[120:123]
	v_mfma_f32_16x16x32_bf16 v[112:115], v[158:161], v[192:195], v[112:115]
	v_mfma_f32_16x16x32_bf16 v[104:107], v[146:149], v[200:203], v[104:107]
	v_mfma_f32_16x16x32_bf16 v[96:99], v[158:161], v[200:203], v[96:99]
	v_mfma_f32_16x16x32_bf16 v[88:91], v[146:149], v[208:211], v[88:91]
	v_mfma_f32_16x16x32_bf16 v[80:83], v[158:161], v[208:211], v[80:83]
	v_mfma_f32_16x16x32_bf16 v[72:75], v[146:149], v[216:219], v[72:75]
	v_mfma_f32_16x16x32_bf16 v[64:67], v[158:161], v[216:219], v[64:67]
	v_mfma_f32_16x16x32_bf16 v[120:123], v[154:157], v[196:199], v[120:123]
	v_mfma_f32_16x16x32_bf16 v[112:115], v[162:165], v[196:199], v[112:115]
	v_mfma_f32_16x16x32_bf16 v[104:107], v[154:157], v[204:207], v[104:107]
	v_mfma_f32_16x16x32_bf16 v[96:99], v[162:165], v[204:207], v[96:99]
	v_mfma_f32_16x16x32_bf16 v[88:91], v[154:157], v[212:215], v[88:91]
	v_mfma_f32_16x16x32_bf16 v[80:83], v[162:165], v[212:215], v[80:83]
	v_mfma_f32_16x16x32_bf16 v[72:75], v[154:157], v[240:243], v[72:75]
	v_mfma_f32_16x16x32_bf16 v[64:67], v[162:165], v[240:243], v[64:67]
	s_setprio 0
	s_setprio 1
	v_mfma_f32_16x16x32_bf16 v[124:127], v[176:179], v[192:195], v[124:127]
	v_mfma_f32_16x16x32_bf16 v[116:119], v[184:187], v[192:195], v[116:119]
	v_mfma_f32_16x16x32_bf16 v[108:111], v[176:179], v[200:203], v[108:111]
	v_mfma_f32_16x16x32_bf16 v[100:103], v[184:187], v[200:203], v[100:103]
	v_mfma_f32_16x16x32_bf16 v[92:95], v[176:179], v[208:211], v[92:95]
	v_mfma_f32_16x16x32_bf16 v[84:87], v[184:187], v[208:211], v[84:87]
	v_mfma_f32_16x16x32_bf16 v[76:79], v[176:179], v[216:219], v[76:79]
	v_mfma_f32_16x16x32_bf16 v[68:71], v[184:187], v[216:219], v[68:71]
	v_mfma_f32_16x16x32_bf16 v[124:127], v[180:183], v[196:199], v[124:127]
	v_mfma_f32_16x16x32_bf16 v[116:119], v[188:191], v[196:199], v[116:119]
	v_mfma_f32_16x16x32_bf16 v[108:111], v[180:183], v[204:207], v[108:111]
	v_mfma_f32_16x16x32_bf16 v[100:103], v[188:191], v[204:207], v[100:103]
	v_mfma_f32_16x16x32_bf16 v[92:95], v[180:183], v[212:215], v[92:95]
	v_mfma_f32_16x16x32_bf16 v[84:87], v[188:191], v[212:215], v[84:87]
	v_mfma_f32_16x16x32_bf16 v[76:79], v[180:183], v[240:243], v[76:79]
	v_mfma_f32_16x16x32_bf16 v[68:71], v[188:191], v[240:243], v[68:71]
	s_setprio 0
	s_barrier
	s_add_i32 s10, s10, s45
	v_lshl_add_u64 v[166:167], v[226:227], 0, s[92:93]
	s_mov_b32 m0, s10
	ds_read_b128 v[192:195], v153 offset:49152
	ds_read_b128 v[196:199], v153 offset:50176
	ds_read_b128 v[200:203], v153 offset:51200
	ds_read_b128 v[204:207], v153 offset:52224
	ds_read_b128 v[208:211], v153 offset:53248
	ds_read_b128 v[212:215], v153 offset:54272
	ds_read_b128 v[216:219], v153 offset:55296
	ds_read_b128 v[240:243], v153 offset:56320
	global_load_lds_dwordx4 v[166:167], off
	v_lshl_add_u64 v[166:167], v[244:245], 0, s[92:93]
	s_add_i32 m0, s10, 0x2000
	s_add_i32 s10, s65, s45
	global_load_lds_dwordx4 v[166:167], off
	v_lshl_add_u64 v[166:167], v[246:247], 0, s[92:93]
	s_mov_b32 m0, s10
	s_nop 0
	global_load_lds_dwordx4 v[166:167], off
	v_lshl_add_u64 v[166:167], v[220:221], 0, s[92:93]
	s_add_i32 m0, s10, 0x2000
	s_nop 0
	global_load_lds_dwordx4 v[166:167], off
	v_lshl_add_u64 v[166:167], v[248:249], 0, s[92:93]
	s_mov_b32 m0, s56
	s_nop 0
	global_load_lds_dwordx4 v[166:167], off
	v_lshl_add_u64 v[166:167], v[250:251], 0, s[92:93]
	s_mov_b32 m0, s57
	s_nop 0
	global_load_lds_dwordx4 v[166:167], off
	s_waitcnt vmcnt(8)
	s_waitcnt lgkmcnt(0)
	s_barrier
; #define PG8_STAGE(bufoff, gbase, voff) do { _Pragma("unroll") for (int _i = 0; _i < 2; ++_i) \
;         __builtin_amdgcn_global_load_lds((const unsigned*)((const char*)(gbase) + (voff)[_i]), (LAS unsigned*)(lds + (bufoff) + ldsw + _i * 8192), 16, 0, 0); } while (0)
; #define PG8_LDA(dst, b, h) do { _Pragma("unroll") for (int m = 0; m < 4; ++m) _Pragma("unroll") for (int k = 0; k < 2; ++k) dst[m][k] = *(const LAS bf16x8*)(lds + PG8_SA(b, h) + aoff + m * 2048 + k * 1024); } while (0)
; #define PG8_LDB(dst, b, h) do { _Pragma("unroll") for (int n = 0; n < 2; ++n) _Pragma("unroll") for (int k = 0; k < 2; ++k) dst[n][k] = *(const LAS bf16x8*)(lds + PG8_SB(b, h) + boff + n * 2048 + k * 1024); } while (0)
; #define PG8_MMA(ai, bj, At, Bt) do { __builtin_amdgcn_s_setprio(1); _Pragma("unroll") for (int k = 0; k < 2; ++k) _Pragma("unroll") for (int m = 0; m < 4; ++m) _Pragma("unroll") for (int n = 0; n < 2; ++n) \
;         acc[ai][bj][m][n] = __builtin_amdgcn_mfma_f32_16x16x32_bf16(Bt[n][k], At[m][k], acc[ai][bj][m][n], 0, 0, 0); __builtin_amdgcn_s_setprio(0); } while (0)
; #define PG8_WAIT_V(n) asm volatile("s_waitcnt vmcnt(" #n ")" ::: "memory")
; template <class Epi, bool ALIGN_EPI>
; __device__ __forceinline__ void gemm_phase(LAS unsigned char* lds, const Gemm g, const StaticOrder& S, const Epi& E, const int tid) {
;     ...
;             PG8_LDB(B0, 0, 0); PG8_LDB(B1, 0, 1); PG8_SCHED; PG8_LDA(At, 0, 0); PG8_STAGE(PG8_SA(1, 1), a1 + hA, voffA);
;             PG8_WAIT_V(8); PG8_WAIT_L(0); PG8_BAR; PG8_MMA(0, 0, At, B0); PG8_MMA(0, 1, At, B1); PG8_BAR; PG8_SCHED;
;             PG8_LDA(At, 0, 1); PG8_STAGE(PG8_SB(0, 0), b2, voffB); PG8_STAGE(PG8_SB(0, 1), b2 + hB, voffB); PG8_STAGE(PG8_SA(0, 0), a2, voffA);
;             PG8_WAIT_V(8); PG8_WAIT_L(0); PG8_BAR; PG8_MMA(1, 0, At, B0); PG8_MMA(1, 1, At, B1); PG8_BAR; PG8_SCHED;
;             PG8_LDB(B0, 1, 0); PG8_LDB(B1, 1, 1); PG8_SCHED; PG8_LDA(At, 1, 0); PG8_STAGE(PG8_SA(0, 1), a2 + hA, voffA);
;             PG8_WAIT_V(8); PG8_WAIT_L(0); PG8_BAR; PG8_MMA(0, 0, At, B0); PG8_MMA(0, 1, At, B1); PG8_BAR; PG8_SCHED;
;             PG8_LDA(At, 1, 1); PG8_STAGE(PG8_SB(1, 0), b3, voffB); PG8_STAGE(PG8_SB(1, 1), b3 + hB, voffB); PG8_STAGE(PG8_SA(1, 0), a3, voffA);
;             PG8_WAIT_V(8); PG8_WAIT_L(0); PG8_BAR; PG8_MMA(1, 0, At, B0); PG8_MMA(1, 1, At, B1); PG8_BAR; PG8_SCHED;
;         }
	s_setprio 1
	s_waitcnt lgkmcnt(0)
	v_mfma_f32_16x16x32_bf16 v[56:59], v[146:149], v[192:195], v[56:59]
	v_mfma_f32_16x16x32_bf16 v[48:51], v[158:161], v[192:195], v[48:51]
	v_mfma_f32_16x16x32_bf16 v[40:43], v[146:149], v[200:203], v[40:43]
	v_mfma_f32_16x16x32_bf16 v[32:35], v[158:161], v[200:203], v[32:35]
	v_mfma_f32_16x16x32_bf16 v[24:27], v[146:149], v[208:211], v[24:27]
	v_mfma_f32_16x16x32_bf16 v[16:19], v[158:161], v[208:211], v[16:19]
	v_mfma_f32_16x16x32_bf16 v[8:11], v[146:149], v[216:219], v[8:11]
	v_mfma_f32_16x16x32_bf16 v[4:7], v[158:161], v[216:219], v[4:7]
	v_mfma_f32_16x16x32_bf16 v[56:59], v[154:157], v[196:199], v[56:59]
	v_mfma_f32_16x16x32_bf16 v[48:51], v[162:165], v[196:199], v[48:51]
	v_mfma_f32_16x16x32_bf16 v[40:43], v[154:157], v[204:207], v[40:43]
	v_mfma_f32_16x16x32_bf16 v[32:35], v[162:165], v[204:207], v[32:35]
	v_mfma_f32_16x16x32_bf16 v[24:27], v[154:157], v[212:215], v[24:27]
	v_mfma_f32_16x16x32_bf16 v[16:19], v[162:165], v[212:215], v[16:19]
	v_mfma_f32_16x16x32_bf16 v[8:11], v[154:157], v[240:243], v[8:11]
	v_mfma_f32_16x16x32_bf16 v[4:7], v[162:165], v[240:243], v[4:7]
	s_setprio 0
	s_setprio 1
	v_mfma_f32_16x16x32_bf16 v[60:63], v[176:179], v[192:195], v[60:63]
	v_mfma_f32_16x16x32_bf16 v[52:55], v[184:187], v[192:195], v[52:55]
	v_mfma_f32_16x16x32_bf16 v[44:47], v[176:179], v[200:203], v[44:47]
	v_mfma_f32_16x16x32_bf16 v[36:39], v[184:187], v[200:203], v[36:39]
	v_mfma_f32_16x16x32_bf16 v[28:31], v[176:179], v[208:211], v[28:31]
	v_mfma_f32_16x16x32_bf16 v[20:23], v[184:187], v[208:211], v[20:23]
	v_mfma_f32_16x16x32_bf16 v[12:15], v[176:179], v[216:219], v[12:15]
	v_mfma_f32_16x16x32_bf16 v[0:3], v[184:187], v[216:219], v[0:3]
	v_mfma_f32_16x16x32_bf16 v[60:63], v[180:183], v[196:199], v[60:63]
	v_mfma_f32_16x16x32_bf16 v[52:55], v[188:191], v[196:199], v[52:55]
	v_mfma_f32_16x16x32_bf16 v[44:47], v[180:183], v[204:207], v[44:47]
	v_mfma_f32_16x16x32_bf16 v[36:39], v[188:191], v[204:207], v[36:39]
	v_mfma_f32_16x16x32_bf16 v[28:31], v[180:183], v[212:215], v[28:31]
	v_mfma_f32_16x16x32_bf16 v[20:23], v[188:191], v[212:215], v[20:23]
	v_mfma_f32_16x16x32_bf16 v[12:15], v[180:183], v[240:243], v[12:15]
	v_mfma_f32_16x16x32_bf16 v[0:3], v[188:191], v[240:243], v[0:3]
	s_setprio 0
	v_lshl_add_u64 v[142:143], v[142:143], 0, s[80:81]
	v_lshl_add_u64 v[144:145], v[144:145], 0, s[80:81]
	s_mov_b32 s10, s11
	s_cmp_lg_u32 s10, s58
	s_barrier
	s_cbranch_scc1 .LBB0_308
.Lgu_last:
	v_add_u32_e32 v150, s33, v151
	ds_read_b128 v[146:149], v150
	ds_read_b128 v[154:157], v150 offset:1024
	ds_read_b128 v[158:161], v150 offset:2048
	ds_read_b128 v[162:165], v150 offset:3072
	s_add_i32 s11, s10, 2
	s_cmp_eq_u32 s58, s10
	s_cselect_b64 vcc, -1, 0
	s_add_i32 s10, 0, 0x14000
	v_add_u32_e32 v150, s10, v151
	ds_read_b128 v[176:179], v150
	ds_read_b128 v[180:183], v150 offset:1024
	ds_read_b128 v[184:187], v150 offset:2048
	ds_read_b128 v[188:191], v150 offset:3072
	v_lshl_add_u64 v[226:227], v[142:143], 0, s[92:93]
	v_cndmask_b32_e32 v167, v227, v139, vcc
	v_cndmask_b32_e32 v166, v226, v138, vcc
	v_cndmask_b32_e32 v221, v145, v141, vcc
	v_cndmask_b32_e32 v220, v144, v140, vcc
	v_lshl_add_u64 v[226:227], v[142:143], 0, v[134:135]
	s_add_i32 m0, s51, 0xc000
	ds_read_b128 v[192:195], v153
	ds_read_b128 v[196:199], v153 offset:1024
	ds_read_b128 v[200:203], v153 offset:2048
	ds_read_b128 v[204:207], v153 offset:3072
	ds_read_b128 v[208:211], v153 offset:4096
	ds_read_b128 v[212:215], v153 offset:5120
	ds_read_b128 v[216:219], v153 offset:6144
	ds_read_b128 v[240:243], v153 offset:7168
	global_load_lds_dwordx4 v[226:227], off
	v_lshl_add_u64 v[226:227], v[142:143], 0, v[136:137]
	s_add_i32 m0, s51, 0xe000
	s_nop 0
	global_load_lds_dwordx4 v[226:227], off
	s_waitcnt vmcnt(8)
	s_waitcnt lgkmcnt(0)
	s_barrier
	s_setprio 1
	s_waitcnt lgkmcnt(0)
	v_mfma_f32_16x16x32_bf16 v[120:123], v[146:149], v[192:195], v[120:123]
	v_mfma_f32_16x16x32_bf16 v[112:115], v[158:161], v[192:195], v[112:115]
	v_mfma_f32_16x16x32_bf16 v[104:107], v[146:149], v[200:203], v[104:107]
	v_mfma_f32_16x16x32_bf16 v[96:99], v[158:161], v[200:203], v[96:99]
	v_mfma_f32_16x16x32_bf16 v[88:91], v[146:149], v[208:211], v[88:91]
	v_mfma_f32_16x16x32_bf16 v[80:83], v[158:161], v[208:211], v[80:83]
	v_mfma_f32_16x16x32_bf16 v[72:75], v[146:149], v[216:219], v[72:75]
	v_mfma_f32_16x16x32_bf16 v[64:67], v[158:161], v[216:219], v[64:67]
	v_mfma_f32_16x16x32_bf16 v[120:123], v[154:157], v[196:199], v[120:123]
	v_mfma_f32_16x16x32_bf16 v[112:115], v[162:165], v[196:199], v[112:115]
	v_mfma_f32_16x16x32_bf16 v[104:107], v[154:157], v[204:207], v[104:107]
	v_mfma_f32_16x16x32_bf16 v[96:99], v[162:165], v[204:207], v[96:99]
	v_mfma_f32_16x16x32_bf16 v[88:91], v[154:157], v[212:215], v[88:91]
	v_mfma_f32_16x16x32_bf16 v[80:83], v[162:165], v[212:215], v[80:83]
	v_mfma_f32_16x16x32_bf16 v[72:75], v[154:157], v[240:243], v[72:75]
	v_mfma_f32_16x16x32_bf16 v[64:67], v[162:165], v[240:243], v[64:67]
	s_setprio 0
	s_setprio 1
	v_mfma_f32_16x16x32_bf16 v[124:127], v[176:179], v[192:195], v[124:127]
	v_mfma_f32_16x16x32_bf16 v[116:119], v[184:187], v[192:195], v[116:119]
	v_mfma_f32_16x16x32_bf16 v[108:111], v[176:179], v[200:203], v[108:111]
	v_mfma_f32_16x16x32_bf16 v[100:103], v[184:187], v[200:203], v[100:103]
	v_mfma_f32_16x16x32_bf16 v[92:95], v[176:179], v[208:211], v[92:95]
	v_mfma_f32_16x16x32_bf16 v[84:87], v[184:187], v[208:211], v[84:87]
	v_mfma_f32_16x16x32_bf16 v[76:79], v[176:179], v[216:219], v[76:79]
	v_mfma_f32_16x16x32_bf16 v[68:71], v[184:187], v[216:219], v[68:71]
	v_mfma_f32_16x16x32_bf16 v[124:127], v[180:183], v[196:199], v[124:127]
	v_mfma_f32_16x16x32_bf16 v[116:119], v[188:191], v[196:199], v[116:119]
	v_mfma_f32_16x16x32_bf16 v[108:111], v[180:183], v[204:207], v[108:111]
	v_mfma_f32_16x16x32_bf16 v[100:103], v[188:191], v[204:207], v[100:103]
	v_mfma_f32_16x16x32_bf16 v[92:95], v[180:183], v[212:215], v[92:95]
	v_mfma_f32_16x16x32_bf16 v[84:87], v[188:191], v[212:215], v[84:87]
	v_mfma_f32_16x16x32_bf16 v[76:79], v[180:183], v[240:243], v[76:79]
	v_mfma_f32_16x16x32_bf16 v[68:71], v[188:191], v[240:243], v[68:71]
	s_setprio 0
	s_barrier
; #define PG8_STAGE(bufoff, gbase, voff) do { _Pragma("unroll") for (int _i = 0; _i < 2; ++_i) \
;         __builtin_amdgcn_global_load_lds((const unsigned*)((const char*)(gbase) + (voff)[_i]), (LAS unsigned*)(lds + (bufoff) + ldsw + _i * 8192), 16, 0, 0); } while (0)
; #define PG8_LDA(dst, b, h) do { _Pragma("unroll") for (int m = 0; m < 4; ++m) _Pragma("unroll") for (int k = 0; k < 2; ++k) dst[m][k] = *(const LAS bf16x8*)(lds + PG8_SA(b, h) + aoff + m * 2048 + k * 1024); } while (0)
; #define PG8_LDB(dst, b, h) do { _Pragma("unroll") for (int n = 0; n < 2; ++n) _Pragma("unroll") for (int k = 0; k < 2; ++k) dst[n][k] = *(const LAS bf16x8*)(lds + PG8_SB(b, h) + boff + n * 2048 + k * 1024); } while (0)
; #define PG8_MMA(ai, bj, At, Bt) do { __builtin_amdgcn_s_setprio(1); _Pragma("unroll") for (int k = 0; k < 2; ++k) _Pragma("unroll") for (int m = 0; m < 4; ++m) _Pragma("unroll") for (int n = 0; n < 2; ++n) \
;         acc[ai][bj][m][n] = __builtin_amdgcn_mfma_f32_16x16x32_bf16(Bt[n][k], At[m][k], acc[ai][bj][m][n], 0, 0, 0); __builtin_amdgcn_s_setprio(0); } while (0)
; #define PG8_WAIT_V(n) asm volatile("s_waitcnt vmcnt(" #n ")" ::: "memory")
; #define PG8_WAIT_L(n) asm volatile("s_waitcnt lgkmcnt(" #n ")" ::: "memory")
; #define PG8_BAR __builtin_amdgcn_s_barrier()
; #define PG8_SCHED __builtin_amdgcn_sched_barrier(0)
; template <class Epi, bool ALIGN_EPI>
; __device__ __forceinline__ void gemm_phase(LAS unsigned char* lds, const Gemm g, const StaticOrder& S, const Epi& E, const int tid) {
;     ...
;             PG8_LDA(At, 0, 1); PG8_STAGE(PG8_SB(0, 0), b2, voffB); PG8_STAGE(PG8_SB(0, 1), b2 + hB, voffB); PG8_STAGE(PG8_SA(0, 0), a2, voffA);
;             PG8_WAIT_V(8); PG8_WAIT_L(0); PG8_BAR; PG8_MMA(1, 0, At, B0); PG8_MMA(1, 1, At, B1); PG8_BAR; PG8_SCHED;
;             PG8_LDB(B0, 1, 0); PG8_LDB(B1, 1, 1); PG8_SCHED; PG8_LDA(At, 1, 0); PG8_STAGE(PG8_SA(0, 1), a2 + hA, voffA);
;             PG8_WAIT_V(8); PG8_WAIT_L(0); PG8_BAR; PG8_MMA(0, 0, At, B0); PG8_MMA(0, 1, At, B1); PG8_BAR; PG8_SCHED;
	s_add_i32 s65, s33, s45
	v_lshl_add_u64 v[226:227], v[220:221], 0, v[168:169]
	s_mov_b32 m0, s65
	ds_read_b128 v[192:195], v153 offset:16384
	ds_read_b128 v[196:199], v153 offset:17408
	ds_read_b128 v[200:203], v153 offset:18432
	ds_read_b128 v[204:207], v153 offset:19456
	ds_read_b128 v[208:211], v153 offset:20480
	ds_read_b128 v[212:215], v153 offset:21504
	ds_read_b128 v[216:219], v153 offset:22528
	ds_read_b128 v[240:243], v153 offset:23552
	global_load_lds_dwordx4 v[226:227], off
	v_lshl_add_u64 v[244:245], v[220:221], 0, v[128:129]
	s_add_i32 m0, s65, 0x2000
	v_lshl_add_u64 v[220:221], v[220:221], 0, s[12:13]
	s_add_i32 s10, s10, s45
	global_load_lds_dwordx4 v[244:245], off
	v_lshl_add_u64 v[246:247], v[220:221], 0, v[168:169]
	s_mov_b32 m0, s10
	v_lshl_add_u64 v[220:221], v[220:221], 0, v[128:129]
	global_load_lds_dwordx4 v[246:247], off
	s_add_i32 m0, s10, 0x2000
	v_lshl_add_u64 v[248:249], v[166:167], 0, v[132:133]
	global_load_lds_dwordx4 v[220:221], off
	s_mov_b32 m0, s51
	v_lshl_add_u64 v[250:251], v[166:167], 0, v[130:131]
	global_load_lds_dwordx4 v[248:249], off
	s_mov_b32 m0, s52
	s_nop 0
	global_load_lds_dwordx4 v[250:251], off
	s_waitcnt vmcnt(8)
	s_waitcnt lgkmcnt(0)
	s_barrier
	s_setprio 1
	s_waitcnt lgkmcnt(0)
	v_mfma_f32_16x16x32_bf16 v[56:59], v[146:149], v[192:195], v[56:59]
	v_mfma_f32_16x16x32_bf16 v[48:51], v[158:161], v[192:195], v[48:51]
	v_mfma_f32_16x16x32_bf16 v[40:43], v[146:149], v[200:203], v[40:43]
	v_mfma_f32_16x16x32_bf16 v[32:35], v[158:161], v[200:203], v[32:35]
	v_mfma_f32_16x16x32_bf16 v[24:27], v[146:149], v[208:211], v[24:27]
	v_mfma_f32_16x16x32_bf16 v[16:19], v[158:161], v[208:211], v[16:19]
	v_mfma_f32_16x16x32_bf16 v[8:11], v[146:149], v[216:219], v[8:11]
	v_mfma_f32_16x16x32_bf16 v[4:7], v[158:161], v[216:219], v[4:7]
	v_mfma_f32_16x16x32_bf16 v[56:59], v[154:157], v[196:199], v[56:59]
	v_mfma_f32_16x16x32_bf16 v[48:51], v[162:165], v[196:199], v[48:51]
	v_mfma_f32_16x16x32_bf16 v[40:43], v[154:157], v[204:207], v[40:43]
	v_mfma_f32_16x16x32_bf16 v[32:35], v[162:165], v[204:207], v[32:35]
	v_mfma_f32_16x16x32_bf16 v[24:27], v[154:157], v[212:215], v[24:27]
	v_mfma_f32_16x16x32_bf16 v[16:19], v[162:165], v[212:215], v[16:19]
	v_mfma_f32_16x16x32_bf16 v[8:11], v[154:157], v[240:243], v[8:11]
	v_mfma_f32_16x16x32_bf16 v[4:7], v[162:165], v[240:243], v[4:7]
	s_setprio 0
	s_setprio 1
	v_mfma_f32_16x16x32_bf16 v[60:63], v[176:179], v[192:195], v[60:63]
	v_mfma_f32_16x16x32_bf16 v[52:55], v[184:187], v[192:195], v[52:55]
	v_mfma_f32_16x16x32_bf16 v[44:47], v[176:179], v[200:203], v[44:47]
	v_mfma_f32_16x16x32_bf16 v[36:39], v[184:187], v[200:203], v[36:39]
	v_mfma_f32_16x16x32_bf16 v[28:31], v[176:179], v[208:211], v[28:31]
	v_mfma_f32_16x16x32_bf16 v[20:23], v[184:187], v[208:211], v[20:23]
	v_mfma_f32_16x16x32_bf16 v[12:15], v[176:179], v[216:219], v[12:15]
	v_mfma_f32_16x16x32_bf16 v[0:3], v[184:187], v[216:219], v[0:3]
	v_mfma_f32_16x16x32_bf16 v[60:63], v[180:183], v[196:199], v[60:63]
	v_mfma_f32_16x16x32_bf16 v[52:55], v[188:191], v[196:199], v[52:55]
	v_mfma_f32_16x16x32_bf16 v[44:47], v[180:183], v[204:207], v[44:47]
	v_mfma_f32_16x16x32_bf16 v[36:39], v[188:191], v[204:207], v[36:39]
	v_mfma_f32_16x16x32_bf16 v[28:31], v[180:183], v[212:215], v[28:31]
	v_mfma_f32_16x16x32_bf16 v[20:23], v[188:191], v[212:215], v[20:23]
	v_mfma_f32_16x16x32_bf16 v[12:15], v[180:183], v[240:243], v[12:15]
	v_mfma_f32_16x16x32_bf16 v[0:3], v[188:191], v[240:243], v[0:3]
	s_setprio 0
	s_barrier
	s_add_i32 s10, 0, 0x18000
	v_add_u32_e32 v150, s10, v151
	s_add_i32 s65, 0, 0x1c000
	ds_read_b128 v[146:149], v150
	ds_read_b128 v[154:157], v150 offset:1024
	ds_read_b128 v[158:161], v150 offset:2048
	ds_read_b128 v[162:165], v150 offset:3072
	v_add_u32_e32 v150, s65, v151
	ds_read_b128 v[176:179], v150
	ds_read_b128 v[180:183], v150 offset:1024
	ds_read_b128 v[184:187], v150 offset:2048
	ds_read_b128 v[188:191], v150 offset:3072
	v_lshl_add_u64 v[166:167], v[166:167], 0, s[94:95]
	s_mov_b32 m0, s53
	v_lshl_add_u64 v[252:253], v[166:167], 0, v[132:133]
	ds_read_b128 v[192:195], v153 offset:32768
	ds_read_b128 v[196:199], v153 offset:33792
	ds_read_b128 v[200:203], v153 offset:34816
	ds_read_b128 v[204:207], v153 offset:35840
	ds_read_b128 v[208:211], v153 offset:36864
	ds_read_b128 v[212:215], v153 offset:37888
	ds_read_b128 v[216:219], v153 offset:38912
	ds_read_b128 v[240:243], v153 offset:39936
	global_load_lds_dwordx4 v[252:253], off
	v_lshl_add_u64 v[166:167], v[166:167], 0, v[130:131]
	s_mov_b32 m0, s54
	s_nop 0
	global_load_lds_dwordx4 v[166:167], off
	s_waitcnt vmcnt(8)
	s_waitcnt lgkmcnt(0)
	s_barrier
; __device__ __forceinline__ unsigned cvt_pk_bf16(float lo, float hi) { unsigned r; asm volatile("v_cvt_pk_bf16_f32 %0, %1, %2" : "=v"(r) : "v"(lo), "v"(hi)); return r; }
; __device__ __forceinline__ float siluf_(float x) { return x * sigmoidf_(x); }
; #define PG8_STAGE(bufoff, gbase, voff) do { _Pragma("unroll") for (int _i = 0; _i < 2; ++_i) \
;         __builtin_amdgcn_global_load_lds((const unsigned*)((const char*)(gbase) + (voff)[_i]), (LAS unsigned*)(lds + (bufoff) + ldsw + _i * 8192), 16, 0, 0); } while (0)
; #define PG8_LDA(dst, b, h) do { _Pragma("unroll") for (int m = 0; m < 4; ++m) _Pragma("unroll") for (int k = 0; k < 2; ++k) dst[m][k] = *(const LAS bf16x8*)(lds + PG8_SA(b, h) + aoff + m * 2048 + k * 1024); } while (0)
;     __device__ __forceinline__ void operator()(const f32x4 (&acc)[2][2][4][2], const Unit& u, int wr, int wc, int fr, int fq) const {
;         const int row0 = u.pm * BM + wr * 64 + fr, col0 = u.pn * HALF + wc * 32 + 8 * fq;
;         float rsv[2][4]; load_rstd(rsv, ssq, row0);
; #pragma unroll
;         for (int ai = 0; ai < 2; ++ai)
; #pragma unroll
;             for (int m = 0; m < 4; ++m) { const int row = row0 + ai * HALF + m * 16; bf16_t* rowp = O + (size_t)row * ldc + col0; const float rs = rsv[ai][m];
;                 f32x4 v0, v1;
; #pragma unroll
;                 for (int j = 0; j < 4; ++j) { v0[j] = siluf_(acc[ai][0][m][0][j] * rs) * (acc[ai][1][m][0][j] * rs); v1[j] = siluf_(acc[ai][0][m][1][j] * rs) * (acc[ai][1][m][1][j] * rs); }
;                 u32x4 w; w.x = cvt_pk_bf16(v0[0], v0[1]); w.y = cvt_pk_bf16(v0[2], v0[3]); w.z = cvt_pk_bf16(v1[0], v1[1]); w.w = cvt_pk_bf16(v1[2], v1[3]);
;                 *(u32x4*)rowp = w; }
; template <class Epi, bool ALIGN_EPI>
; __device__ __forceinline__ void gemm_phase(LAS unsigned char* lds, const Gemm g, const StaticOrder& S, const Epi& E, const int tid) {
;     ...
;             PG8_LDB(B0, 1, 0); PG8_LDB(B1, 1, 1); PG8_SCHED; PG8_LDA(At, 1, 0); PG8_STAGE(PG8_SA(0, 1), a2 + hA, voffA);
;             PG8_WAIT_V(8); PG8_WAIT_L(0); PG8_BAR; PG8_MMA(0, 0, At, B0); PG8_MMA(0, 1, At, B1); PG8_BAR; PG8_SCHED;
;             PG8_LDA(At, 1, 1); PG8_STAGE(PG8_SB(1, 0), b3, voffB); PG8_STAGE(PG8_SB(1, 1), b3 + hB, voffB); PG8_STAGE(PG8_SA(1, 0), a3, voffA);
;             PG8_WAIT_V(8); PG8_WAIT_L(0); PG8_BAR; PG8_MMA(1, 0, At, B0); PG8_MMA(1, 1, At, B1); PG8_BAR; PG8_SCHED;
	s_setprio 1
	s_waitcnt lgkmcnt(0)
	v_mfma_f32_16x16x32_bf16 v[120:123], v[146:149], v[192:195], v[120:123]
	v_mfma_f32_16x16x32_bf16 v[112:115], v[158:161], v[192:195], v[112:115]
	v_mfma_f32_16x16x32_bf16 v[104:107], v[146:149], v[200:203], v[104:107]
	v_mfma_f32_16x16x32_bf16 v[96:99], v[158:161], v[200:203], v[96:99]
	v_mfma_f32_16x16x32_bf16 v[88:91], v[146:149], v[208:211], v[88:91]
	v_mfma_f32_16x16x32_bf16 v[80:83], v[158:161], v[208:211], v[80:83]
	v_mfma_f32_16x16x32_bf16 v[72:75], v[146:149], v[216:219], v[72:75]
	v_mfma_f32_16x16x32_bf16 v[64:67], v[158:161], v[216:219], v[64:67]
	v_mfma_f32_16x16x32_bf16 v[120:123], v[154:157], v[196:199], v[120:123]
	v_mfma_f32_16x16x32_bf16 v[112:115], v[162:165], v[196:199], v[112:115]
	v_mfma_f32_16x16x32_bf16 v[104:107], v[154:157], v[204:207], v[104:107]
	v_mfma_f32_16x16x32_bf16 v[96:99], v[162:165], v[204:207], v[96:99]
	v_mfma_f32_16x16x32_bf16 v[88:91], v[154:157], v[212:215], v[88:91]
	v_mfma_f32_16x16x32_bf16 v[80:83], v[162:165], v[212:215], v[80:83]
	v_mfma_f32_16x16x32_bf16 v[72:75], v[154:157], v[240:243], v[72:75]
	v_mfma_f32_16x16x32_bf16 v[64:67], v[162:165], v[240:243], v[64:67]
	s_setprio 0
	s_setprio 1
	v_mfma_f32_16x16x32_bf16 v[124:127], v[176:179], v[192:195], v[124:127]
	v_mfma_f32_16x16x32_bf16 v[116:119], v[184:187], v[192:195], v[116:119]
	v_mfma_f32_16x16x32_bf16 v[108:111], v[176:179], v[200:203], v[108:111]
	v_mfma_f32_16x16x32_bf16 v[100:103], v[184:187], v[200:203], v[100:103]
	v_mfma_f32_16x16x32_bf16 v[92:95], v[176:179], v[208:211], v[92:95]
	v_mfma_f32_16x16x32_bf16 v[84:87], v[184:187], v[208:211], v[84:87]
	v_mfma_f32_16x16x32_bf16 v[76:79], v[176:179], v[216:219], v[76:79]
	v_mfma_f32_16x16x32_bf16 v[68:71], v[184:187], v[216:219], v[68:71]
	v_mfma_f32_16x16x32_bf16 v[124:127], v[180:183], v[196:199], v[124:127]
	v_mfma_f32_16x16x32_bf16 v[116:119], v[188:191], v[196:199], v[116:119]
	v_mfma_f32_16x16x32_bf16 v[108:111], v[180:183], v[204:207], v[108:111]
	v_mfma_f32_16x16x32_bf16 v[100:103], v[188:191], v[204:207], v[100:103]
	v_mfma_f32_16x16x32_bf16 v[92:95], v[180:183], v[212:215], v[92:95]
	v_mfma_f32_16x16x32_bf16 v[84:87], v[188:191], v[212:215], v[84:87]
	v_mfma_f32_16x16x32_bf16 v[76:79], v[180:183], v[240:243], v[76:79]
	v_mfma_f32_16x16x32_bf16 v[68:71], v[188:191], v[240:243], v[68:71]
	s_setprio 0
	s_barrier
	s_add_i32 s10, s10, s45
	v_lshl_add_u64 v[166:167], v[226:227], 0, s[92:93]
	s_mov_b32 m0, s10
	ds_read_b128 v[192:195], v153 offset:49152
	ds_read_b128 v[196:199], v153 offset:50176
	ds_read_b128 v[200:203], v153 offset:51200
	ds_read_b128 v[204:207], v153 offset:52224
	ds_read_b128 v[208:211], v153 offset:53248
	ds_read_b128 v[212:215], v153 offset:54272
	ds_read_b128 v[216:219], v153 offset:55296
	ds_read_b128 v[240:243], v153 offset:56320
	global_load_lds_dwordx4 v[166:167], off
	v_lshl_add_u64 v[166:167], v[244:245], 0, s[92:93]
	s_add_i32 m0, s10, 0x2000
	s_add_i32 s10, s65, s45
	global_load_lds_dwordx4 v[166:167], off
	v_lshl_add_u64 v[166:167], v[246:247], 0, s[92:93]
	s_mov_b32 m0, s10
	s_nop 0
	global_load_lds_dwordx4 v[166:167], off
	v_lshl_add_u64 v[166:167], v[220:221], 0, s[92:93]
	s_add_i32 m0, s10, 0x2000
	s_nop 0
	global_load_lds_dwordx4 v[166:167], off
	v_lshl_add_u64 v[166:167], v[248:249], 0, s[92:93]
	s_mov_b32 m0, s56
	s_nop 0
	global_load_lds_dwordx4 v[166:167], off
	v_lshl_add_u64 v[166:167], v[250:251], 0, s[92:93]
	s_mov_b32 m0, s57
	s_nop 0
	global_load_lds_dwordx4 v[166:167], off
	s_waitcnt vmcnt(8)
	s_waitcnt lgkmcnt(0)
	s_barrier
	s_setprio 1
	s_waitcnt lgkmcnt(0)
	v_mfma_f32_16x16x32_bf16 v[56:59], v[146:149], v[192:195], v[56:59]
	v_lshrrev_b32_e32 v171, 8, v170
	v_and_b32_e32 v234, 15, v170
	v_lshl_add_u32 v171, v171, 6, v234
	s_lshl_b32 s98, s64, 8
	v_add_u32_e32 v171, s98, v171
	v_mul_lo_u32 v171, v171, s28
	v_bfe_u32 v234, v170, 6, 2
	v_bfe_u32 v224, v170, 4, 2
	v_lshlrev_b32_e32 v234, 5, v234
	v_lshl_or_b32 v234, v224, 3, v234
	v_mfma_f32_16x16x32_bf16 v[48:51], v[158:161], v[192:195], v[48:51]
	s_lshl_b32 s98, s63, 7
	v_add_u32_e32 v234, s98, v234
	v_add_lshl_u32 v232, v171, v234, 1
	v_mov_b32_e32 v233, 0
	v_lshl_add_u64 v[232:233], v[232:233], 0, s[30:31]
	s_lshl_b32 s98, s28, 5
	s_mov_b32 s99, 0
	s_mov_b32 s100, 0xbfb8aa3b
	s_mov_b32 s101, 0xbfb8aa3b
	v_mul_f32_e32 v120, v172, v120
	v_mfma_f32_16x16x32_bf16 v[40:43], v[146:149], v[200:203], v[40:43]
	v_mul_f32_e32 v121, v172, v121
	v_mul_f32_e32 v122, v172, v122
	v_mul_f32_e32 v123, v172, v123
	v_mul_f32_e32 v124, v172, v124
	v_mul_f32_e32 v125, v172, v125
	v_mul_f32_e32 v126, v172, v126
	v_mul_f32_e32 v127, v172, v127
	v_mul_f32_e32 v224, s100, v120
	v_mul_f32_e32 v225, s101, v121
	v_mul_f32_e32 v228, s100, v122
	v_mfma_f32_16x16x32_bf16 v[32:35], v[158:161], v[200:203], v[32:35]
	v_mul_f32_e32 v229, s101, v123
	v_exp_f32_e32 v224, v224
	v_exp_f32_e32 v225, v225
	v_exp_f32_e32 v228, v228
	v_exp_f32_e32 v229, v229
	v_add_f32_e32 v224, 1.0, v224
	v_add_f32_e32 v225, 1.0, v225
	v_add_f32_e32 v228, 1.0, v228
	v_add_f32_e32 v229, 1.0, v229
	v_rcp_f32_e32 v224, v224
	v_mfma_f32_16x16x32_bf16 v[24:27], v[146:149], v[208:211], v[24:27]
	v_rcp_f32_e32 v225, v225
	v_rcp_f32_e32 v228, v228
	v_rcp_f32_e32 v229, v229
	v_nop
	v_mul_f32_e32 v120, v224, v120
	v_mul_f32_e32 v121, v225, v121
	v_mul_f32_e32 v122, v228, v122
	v_mul_f32_e32 v123, v229, v123
	v_mul_f32_e32 v120, v124, v120
	v_mul_f32_e32 v121, v125, v121
	v_mfma_f32_16x16x32_bf16 v[16:19], v[158:161], v[208:211], v[16:19]
	v_mul_f32_e32 v122, v126, v122
	v_mul_f32_e32 v123, v127, v123
	v_mul_f32_e32 v112, v172, v112
	v_mul_f32_e32 v113, v172, v113
	v_mul_f32_e32 v114, v172, v114
; __device__ __forceinline__ unsigned cvt_pk_bf16(float lo, float hi) { unsigned r; asm volatile("v_cvt_pk_bf16_f32 %0, %1, %2" : "=v"(r) : "v"(lo), "v"(hi)); return r; }
; __device__ __forceinline__ float siluf_(float x) { return x * sigmoidf_(x); }
; #define PG8_MMA(ai, bj, At, Bt) do { __builtin_amdgcn_s_setprio(1); _Pragma("unroll") for (int k = 0; k < 2; ++k) _Pragma("unroll") for (int m = 0; m < 4; ++m) _Pragma("unroll") for (int n = 0; n < 2; ++n) \
;         acc[ai][bj][m][n] = __builtin_amdgcn_mfma_f32_16x16x32_bf16(Bt[n][k], At[m][k], acc[ai][bj][m][n], 0, 0, 0); __builtin_amdgcn_s_setprio(0); } while (0)
; #define PG8_WAIT_V(n) asm volatile("s_waitcnt vmcnt(" #n ")" ::: "memory")
; #define PG8_WAIT_L(n) asm volatile("s_waitcnt lgkmcnt(" #n ")" ::: "memory")
; #define PG8_BAR __builtin_amdgcn_s_barrier()
; #define PG8_SCHED __builtin_amdgcn_sched_barrier(0)
;     __device__ __forceinline__ void operator()(const f32x4 (&acc)[2][2][4][2], const Unit& u, int wr, int wc, int fr, int fq) const {
;     ...
;             for (int m = 0; m < 4; ++m) { const int row = row0 + ai * HALF + m * 16; bf16_t* rowp = O + (size_t)row * ldc + col0; const float rs = rsv[ai][m];
;                 f32x4 v0, v1;
; #pragma unroll
;                 for (int j = 0; j < 4; ++j) { v0[j] = siluf_(acc[ai][0][m][0][j] * rs) * (acc[ai][1][m][0][j] * rs); v1[j] = siluf_(acc[ai][0][m][1][j] * rs) * (acc[ai][1][m][1][j] * rs); }
;                 u32x4 w; w.x = cvt_pk_bf16(v0[0], v0[1]); w.y = cvt_pk_bf16(v0[2], v0[3]); w.z = cvt_pk_bf16(v1[0], v1[1]); w.w = cvt_pk_bf16(v1[2], v1[3]);
;                 *(u32x4*)rowp = w; }
; template <class Epi, bool ALIGN_EPI>
; __device__ __forceinline__ void gemm_phase(LAS unsigned char* lds, const Gemm g, const StaticOrder& S, const Epi& E, const int tid) {
;     ...
;             PG8_WAIT_V(8); PG8_WAIT_L(0); PG8_BAR; PG8_MMA(1, 0, At, B0); PG8_MMA(1, 1, At, B1); PG8_BAR; PG8_SCHED;
	v_mul_f32_e32 v115, v172, v115
	v_mul_f32_e32 v116, v172, v116
	v_mul_f32_e32 v117, v172, v117
	v_mul_f32_e32 v118, v172, v118
	v_mul_f32_e32 v119, v172, v119
	v_mfma_f32_16x16x32_bf16 v[8:11], v[146:149], v[216:219], v[8:11]
	v_mul_f32_e32 v224, s100, v112
	v_mul_f32_e32 v225, s101, v113
	v_mul_f32_e32 v228, s100, v114
	v_mul_f32_e32 v229, s101, v115
	v_exp_f32_e32 v224, v224
	v_exp_f32_e32 v225, v225
	v_exp_f32_e32 v228, v228
	v_exp_f32_e32 v229, v229
	v_add_f32_e32 v224, 1.0, v224
	v_add_f32_e32 v225, 1.0, v225
	v_mfma_f32_16x16x32_bf16 v[4:7], v[158:161], v[216:219], v[4:7]
	v_add_f32_e32 v228, 1.0, v228
	v_add_f32_e32 v229, 1.0, v229
	v_rcp_f32_e32 v224, v224
	v_rcp_f32_e32 v225, v225
	v_rcp_f32_e32 v228, v228
	v_rcp_f32_e32 v229, v229
	v_nop
	v_mul_f32_e32 v112, v224, v112
	v_mul_f32_e32 v113, v225, v113
	v_mul_f32_e32 v114, v228, v114
	v_mfma_f32_16x16x32_bf16 v[56:59], v[154:157], v[196:199], v[56:59]
	v_mul_f32_e32 v115, v229, v115
	v_mul_f32_e32 v112, v116, v112
	v_mul_f32_e32 v113, v117, v113
	v_mul_f32_e32 v114, v118, v114
	v_mul_f32_e32 v115, v119, v115
	v_cvt_pk_bf16_f32 v120, v120, v121
	v_cvt_pk_bf16_f32 v121, v122, v123
	v_cvt_pk_bf16_f32 v122, v112, v113
	v_cvt_pk_bf16_f32 v123, v114, v115
	global_store_dwordx4 v[232:233], v[120:123], off
	v_mfma_f32_16x16x32_bf16 v[48:51], v[162:165], v[196:199], v[48:51]
	v_lshl_add_u64 v[232:233], v[232:233], 0, s[98:99]
	v_mul_f32_e32 v104, v173, v104
	v_mul_f32_e32 v105, v173, v105
	v_mul_f32_e32 v106, v173, v106
	v_mul_f32_e32 v107, v173, v107
	v_mul_f32_e32 v108, v173, v108
	v_mul_f32_e32 v109, v173, v109
	v_mul_f32_e32 v110, v173, v110
	v_mul_f32_e32 v111, v173, v111
	v_mul_f32_e32 v224, s100, v104
	v_mfma_f32_16x16x32_bf16 v[40:43], v[154:157], v[204:207], v[40:43]
	v_mul_f32_e32 v225, s101, v105
	v_mul_f32_e32 v228, s100, v106
	v_mul_f32_e32 v229, s101, v107
	v_exp_f32_e32 v224, v224
	v_exp_f32_e32 v225, v225
	v_exp_f32_e32 v228, v228
	v_exp_f32_e32 v229, v229
	v_add_f32_e32 v224, 1.0, v224
	v_add_f32_e32 v225, 1.0, v225
	v_add_f32_e32 v228, 1.0, v228
	v_mfma_f32_16x16x32_bf16 v[32:35], v[162:165], v[204:207], v[32:35]
	v_add_f32_e32 v229, 1.0, v229
	v_rcp_f32_e32 v224, v224
	v_rcp_f32_e32 v225, v225
	v_rcp_f32_e32 v228, v228
	v_rcp_f32_e32 v229, v229
	v_nop
	v_mul_f32_e32 v104, v224, v104
	v_mul_f32_e32 v105, v225, v105
	v_mul_f32_e32 v106, v228, v106
	v_mul_f32_e32 v107, v229, v107
	v_mfma_f32_16x16x32_bf16 v[24:27], v[154:157], v[212:215], v[24:27]
	v_mul_f32_e32 v104, v108, v104
	v_mul_f32_e32 v105, v109, v105
	v_mul_f32_e32 v106, v110, v106
	v_mul_f32_e32 v107, v111, v107
	v_mul_f32_e32 v96, v173, v96
	v_mul_f32_e32 v97, v173, v97
	v_mul_f32_e32 v98, v173, v98
	v_mul_f32_e32 v99, v173, v99
	v_mul_f32_e32 v100, v173, v100
	v_mul_f32_e32 v101, v173, v101
	v_mfma_f32_16x16x32_bf16 v[16:19], v[162:165], v[212:215], v[16:19]
	v_mul_f32_e32 v102, v173, v102
	v_mul_f32_e32 v103, v173, v103
	v_mul_f32_e32 v224, s100, v96
	v_mul_f32_e32 v225, s101, v97
	v_mul_f32_e32 v228, s100, v98
	v_mul_f32_e32 v229, s101, v99
	v_exp_f32_e32 v224, v224
	v_exp_f32_e32 v225, v225
	v_exp_f32_e32 v228, v228
	v_exp_f32_e32 v229, v229
	v_mfma_f32_16x16x32_bf16 v[8:11], v[154:157], v[240:243], v[8:11]
	v_add_f32_e32 v224, 1.0, v224
	v_add_f32_e32 v225, 1.0, v225
	v_add_f32_e32 v228, 1.0, v228
	v_add_f32_e32 v229, 1.0, v229
	v_rcp_f32_e32 v224, v224
	v_rcp_f32_e32 v225, v225
	v_rcp_f32_e32 v228, v228
	v_rcp_f32_e32 v229, v229
	v_nop
	v_mul_f32_e32 v96, v224, v96
	v_mfma_f32_16x16x32_bf16 v[4:7], v[162:165], v[240:243], v[4:7]
	v_mul_f32_e32 v97, v225, v97
	v_mul_f32_e32 v98, v228, v98
	v_mul_f32_e32 v99, v229, v99
	v_mul_f32_e32 v96, v100, v96
	v_mul_f32_e32 v97, v101, v97
	v_mul_f32_e32 v98, v102, v98
	v_mul_f32_e32 v99, v103, v99
	v_cvt_pk_bf16_f32 v104, v104, v105
	v_cvt_pk_bf16_f32 v105, v106, v107
	v_cvt_pk_bf16_f32 v106, v96, v97
	s_setprio 0
	s_setprio 1
	v_mfma_f32_16x16x32_bf16 v[60:63], v[176:179], v[192:195], v[60:63]
	v_cvt_pk_bf16_f32 v107, v98, v99
	global_store_dwordx4 v[232:233], v[104:107], off
	v_lshl_add_u64 v[232:233], v[232:233], 0, s[98:99]
	v_mul_f32_e32 v88, v236, v88
	v_mul_f32_e32 v89, v236, v89
	v_mul_f32_e32 v90, v236, v90
	v_mul_f32_e32 v91, v236, v91
	v_mul_f32_e32 v92, v236, v92
	v_mul_f32_e32 v93, v236, v93
	v_mul_f32_e32 v94, v236, v94
	v_mfma_f32_16x16x32_bf16 v[52:55], v[184:187], v[192:195], v[52:55]
	v_mul_f32_e32 v95, v236, v95
	v_mul_f32_e32 v224, s100, v88
	v_mul_f32_e32 v225, s101, v89
	v_mul_f32_e32 v228, s100, v90
	v_mul_f32_e32 v229, s101, v91
	v_exp_f32_e32 v224, v224
	v_exp_f32_e32 v225, v225
	v_exp_f32_e32 v228, v228
	v_exp_f32_e32 v229, v229
	v_add_f32_e32 v224, 1.0, v224
	v_mfma_f32_16x16x32_bf16 v[44:47], v[176:179], v[200:203], v[44:47]
	v_add_f32_e32 v225, 1.0, v225
	v_add_f32_e32 v228, 1.0, v228
	v_add_f32_e32 v229, 1.0, v229
	v_rcp_f32_e32 v224, v224
	v_rcp_f32_e32 v225, v225
	v_rcp_f32_e32 v228, v228
	v_rcp_f32_e32 v229, v229
	v_nop
	v_mul_f32_e32 v88, v224, v88
	v_mul_f32_e32 v89, v225, v89
; __device__ __forceinline__ unsigned cvt_pk_bf16(float lo, float hi) { unsigned r; asm volatile("v_cvt_pk_bf16_f32 %0, %1, %2" : "=v"(r) : "v"(lo), "v"(hi)); return r; }
; __device__ __forceinline__ float siluf_(float x) { return x * sigmoidf_(x); }
; #define PG8_MMA(ai, bj, At, Bt) do { __builtin_amdgcn_s_setprio(1); _Pragma("unroll") for (int k = 0; k < 2; ++k) _Pragma("unroll") for (int m = 0; m < 4; ++m) _Pragma("unroll") for (int n = 0; n < 2; ++n) \
;         acc[ai][bj][m][n] = __builtin_amdgcn_mfma_f32_16x16x32_bf16(Bt[n][k], At[m][k], acc[ai][bj][m][n], 0, 0, 0); __builtin_amdgcn_s_setprio(0); } while (0)
; #define PG8_BAR __builtin_amdgcn_s_barrier()
;     __device__ __forceinline__ void operator()(const f32x4 (&acc)[2][2][4][2], const Unit& u, int wr, int wc, int fr, int fq) const {
;     ...
;             for (int m = 0; m < 4; ++m) { const int row = row0 + ai * HALF + m * 16; bf16_t* rowp = O + (size_t)row * ldc + col0; const float rs = rsv[ai][m];
;                 f32x4 v0, v1;
; #pragma unroll
;                 for (int j = 0; j < 4; ++j) { v0[j] = siluf_(acc[ai][0][m][0][j] * rs) * (acc[ai][1][m][0][j] * rs); v1[j] = siluf_(acc[ai][0][m][1][j] * rs) * (acc[ai][1][m][1][j] * rs); }
;                 u32x4 w; w.x = cvt_pk_bf16(v0[0], v0[1]); w.y = cvt_pk_bf16(v0[2], v0[3]); w.z = cvt_pk_bf16(v1[0], v1[1]); w.w = cvt_pk_bf16(v1[2], v1[3]);
;                 *(u32x4*)rowp = w; }
; template <class Epi, bool ALIGN_EPI>
; __device__ __forceinline__ void gemm_phase(LAS unsigned char* lds, const Gemm g, const StaticOrder& S, const Epi& E, const int tid) {
;     ...
;             PG8_WAIT_V(8); PG8_WAIT_L(0); PG8_BAR; PG8_MMA(1, 0, At, B0); PG8_MMA(1, 1, At, B1); PG8_BAR; PG8_SCHED;
;         }
;         if constexpr (ALIGN_EPI) { if (wr == 0) PG8_BAR; }
;         { int t2 = tid; asm volatile("" : "+v"(t2)); const int l2 = t2 & 63, w2 = __builtin_amdgcn_readfirstlane(t2 >> 6); E(acc, cur, w2 >> 2, w2 & 3, l2 & 15, l2 >> 4); }
;         if (!has_next) break;
; #pragma unroll
;         for (int a = 0; a < 2; ++a)
; #pragma unroll
;             for (int b = 0; b < 2; ++b)
; #pragma unroll
;                 for (int m = 0; m < 4; ++m)
; #pragma unroll
;                     for (int n = 0; n < 2; ++n) acc[a][b][m][n] = (f32x4){0.f, 0.f, 0.f, 0.f};
;         cur = nxt; cA = nA; cB = nB; ++ui;
;         if constexpr (ALIGN_EPI) { if (wr == 1) PG8_BAR; }
	v_mfma_f32_16x16x32_bf16 v[36:39], v[184:187], v[200:203], v[36:39]
	v_mul_f32_e32 v90, v228, v90
	v_mul_f32_e32 v91, v229, v91
	v_mul_f32_e32 v88, v92, v88
	v_mul_f32_e32 v89, v93, v89
	v_mul_f32_e32 v90, v94, v90
	v_mul_f32_e32 v91, v95, v91
	v_mul_f32_e32 v80, v236, v80
	v_mul_f32_e32 v81, v236, v81
	v_mul_f32_e32 v82, v236, v82
	v_mul_f32_e32 v83, v236, v83
	v_mfma_f32_16x16x32_bf16 v[28:31], v[176:179], v[208:211], v[28:31]
	v_mul_f32_e32 v84, v236, v84
	v_mul_f32_e32 v85, v236, v85
	v_mul_f32_e32 v86, v236, v86
	v_mul_f32_e32 v87, v236, v87
	v_mul_f32_e32 v224, s100, v80
	v_mul_f32_e32 v225, s101, v81
	v_mul_f32_e32 v228, s100, v82
	v_mul_f32_e32 v229, s101, v83
	v_exp_f32_e32 v224, v224
	v_exp_f32_e32 v225, v225
	v_mfma_f32_16x16x32_bf16 v[20:23], v[184:187], v[208:211], v[20:23]
	v_exp_f32_e32 v228, v228
	v_exp_f32_e32 v229, v229
	v_add_f32_e32 v224, 1.0, v224
	v_add_f32_e32 v225, 1.0, v225
	v_add_f32_e32 v228, 1.0, v228
	v_add_f32_e32 v229, 1.0, v229
	v_rcp_f32_e32 v224, v224
	v_rcp_f32_e32 v225, v225
	v_rcp_f32_e32 v228, v228
	v_rcp_f32_e32 v229, v229
	v_mfma_f32_16x16x32_bf16 v[12:15], v[176:179], v[216:219], v[12:15]
	v_nop
	v_mul_f32_e32 v80, v224, v80
	v_mul_f32_e32 v81, v225, v81
	v_mul_f32_e32 v82, v228, v82
	v_mul_f32_e32 v83, v229, v83
	v_mul_f32_e32 v80, v84, v80
	v_mul_f32_e32 v81, v85, v81
	v_mul_f32_e32 v82, v86, v82
	v_mul_f32_e32 v83, v87, v83
	v_cvt_pk_bf16_f32 v88, v88, v89
	v_mfma_f32_16x16x32_bf16 v[0:3], v[184:187], v[216:219], v[0:3]
	v_cvt_pk_bf16_f32 v89, v90, v91
	v_cvt_pk_bf16_f32 v90, v80, v81
	v_cvt_pk_bf16_f32 v91, v82, v83
	global_store_dwordx4 v[232:233], v[88:91], off
	v_lshl_add_u64 v[232:233], v[232:233], 0, s[98:99]
	v_mul_f32_e32 v72, v237, v72
	v_mul_f32_e32 v73, v237, v73
	v_mul_f32_e32 v74, v237, v74
	v_mul_f32_e32 v75, v237, v75
	v_mul_f32_e32 v76, v237, v76
	v_mfma_f32_16x16x32_bf16 v[60:63], v[180:183], v[196:199], v[60:63]
	v_mul_f32_e32 v77, v237, v77
	v_mul_f32_e32 v78, v237, v78
	v_mul_f32_e32 v79, v237, v79
	v_mul_f32_e32 v224, s100, v72
	v_mul_f32_e32 v225, s101, v73
	v_mul_f32_e32 v228, s100, v74
	v_mul_f32_e32 v229, s101, v75
	v_exp_f32_e32 v224, v224
	v_exp_f32_e32 v225, v225
	v_exp_f32_e32 v228, v228
	v_mfma_f32_16x16x32_bf16 v[52:55], v[188:191], v[196:199], v[52:55]
	v_exp_f32_e32 v229, v229
	v_add_f32_e32 v224, 1.0, v224
	v_add_f32_e32 v225, 1.0, v225
	v_add_f32_e32 v228, 1.0, v228
	v_add_f32_e32 v229, 1.0, v229
	v_rcp_f32_e32 v224, v224
	v_rcp_f32_e32 v225, v225
	v_rcp_f32_e32 v228, v228
	v_rcp_f32_e32 v229, v229
	v_nop
	v_mfma_f32_16x16x32_bf16 v[44:47], v[180:183], v[204:207], v[44:47]
	v_mul_f32_e32 v72, v224, v72
	v_mul_f32_e32 v73, v225, v73
	v_mul_f32_e32 v74, v228, v74
	v_mul_f32_e32 v75, v229, v75
	v_mul_f32_e32 v72, v76, v72
	v_mul_f32_e32 v73, v77, v73
	v_mul_f32_e32 v74, v78, v74
	v_mul_f32_e32 v75, v79, v75
	v_mul_f32_e32 v64, v237, v64
	v_mul_f32_e32 v65, v237, v65
	v_mfma_f32_16x16x32_bf16 v[36:39], v[188:191], v[204:207], v[36:39]
	v_mul_f32_e32 v66, v237, v66
	v_mul_f32_e32 v67, v237, v67
	v_mul_f32_e32 v68, v237, v68
	v_mul_f32_e32 v69, v237, v69
	v_mul_f32_e32 v70, v237, v70
	v_mul_f32_e32 v71, v237, v71
	v_mul_f32_e32 v224, s100, v64
	v_mul_f32_e32 v225, s101, v65
	v_mul_f32_e32 v228, s100, v66
	v_mul_f32_e32 v229, s101, v67
	v_mfma_f32_16x16x32_bf16 v[28:31], v[180:183], v[212:215], v[28:31]
	v_exp_f32_e32 v224, v224
	v_exp_f32_e32 v225, v225
	v_exp_f32_e32 v228, v228
	v_exp_f32_e32 v229, v229
	v_add_f32_e32 v224, 1.0, v224
	v_add_f32_e32 v225, 1.0, v225
	v_add_f32_e32 v228, 1.0, v228
	v_add_f32_e32 v229, 1.0, v229
	v_rcp_f32_e32 v224, v224
	v_rcp_f32_e32 v225, v225
	v_mfma_f32_16x16x32_bf16 v[20:23], v[188:191], v[212:215], v[20:23]
	v_rcp_f32_e32 v228, v228
	v_rcp_f32_e32 v229, v229
	v_nop
	v_mul_f32_e32 v64, v224, v64
	v_mul_f32_e32 v65, v225, v65
	v_mul_f32_e32 v66, v228, v66
	v_mul_f32_e32 v67, v229, v67
	v_mul_f32_e32 v64, v68, v64
	v_mul_f32_e32 v65, v69, v65
	v_mul_f32_e32 v66, v70, v66
	v_mfma_f32_16x16x32_bf16 v[12:15], v[180:183], v[240:243], v[12:15]
	v_mul_f32_e32 v67, v71, v67
	v_cvt_pk_bf16_f32 v72, v72, v73
	v_cvt_pk_bf16_f32 v73, v74, v75
	v_cvt_pk_bf16_f32 v74, v64, v65
	v_cvt_pk_bf16_f32 v75, v66, v67
	global_store_dwordx4 v[232:233], v[72:75], off
	v_lshl_add_u64 v[232:233], v[232:233], 0, s[98:99]
	v_lshl_add_u64 v[232:233], v[232:233], 0, s[98:99]
	v_lshl_add_u64 v[232:233], v[232:233], 0, s[98:99]
	v_lshl_add_u64 v[232:233], v[232:233], 0, s[98:99]
	v_mfma_f32_16x16x32_bf16 v[0:3], v[188:191], v[240:243], v[0:3]
	v_lshl_add_u64 v[232:233], v[232:233], 0, s[98:99]
	s_setprio 0
	v_lshl_add_u64 v[142:143], v[142:143], 0, s[80:81]
	v_lshl_add_u64 v[144:145], v[144:145], 0, s[80:81]
	s_and_b64 vcc, exec, s[8:9]
	s_barrier
	s_cbranch_vccnz .Lgu_notdefer
	s_cmp_lg_u32 s62, s64
	s_cbranch_scc1 .Lgu_notdefer
	s_mov_b32 s101, 1
	s_mov_b32 s63, s61
	s_mov_b32 s64, s62
	v_mov_b64_e32 v[144:145], v[140:141]
	v_mov_b64_e32 v[142:143], v[138:139]
	s_branch .LBB0_300

; #define PG8_STAGE(bufoff, gbase, voff) do { _Pragma("unroll") for (int _i = 0; _i < 2; ++_i) \
;         __builtin_amdgcn_global_load_lds((const unsigned*)((const char*)(gbase) + (voff)[_i]), (LAS unsigned*)(lds + (bufoff) + ldsw + _i * 8192), 16, 0, 0); } while (0)
; #define PG8_LDA(dst, b, h) do { _Pragma("unroll") for (int m = 0; m < 4; ++m) _Pragma("unroll") for (int k = 0; k < 2; ++k) dst[m][k] = *(const LAS bf16x8*)(lds + PG8_SA(b, h) + aoff + m * 2048 + k * 1024); } while (0)
; #define PG8_LDB(dst, b, h) do { _Pragma("unroll") for (int n = 0; n < 2; ++n) _Pragma("unroll") for (int k = 0; k < 2; ++k) dst[n][k] = *(const LAS bf16x8*)(lds + PG8_SB(b, h) + boff + n * 2048 + k * 1024); } while (0)
; #define PG8_MMA(ai, bj, At, Bt) do { __builtin_amdgcn_s_setprio(1); _Pragma("unroll") for (int k = 0; k < 2; ++k) _Pragma("unroll") for (int m = 0; m < 4; ++m) _Pragma("unroll") for (int n = 0; n < 2; ++n) \
;         acc[ai][bj][m][n] = __builtin_amdgcn_mfma_f32_16x16x32_bf16(Bt[n][k], At[m][k], acc[ai][bj][m][n], 0, 0, 0); __builtin_amdgcn_s_setprio(0); } while (0)
; #define PG8_WAIT_V(n) asm volatile("s_waitcnt vmcnt(" #n ")" ::: "memory")
; #define PG8_WAIT_L(n) asm volatile("s_waitcnt lgkmcnt(" #n ")" ::: "memory")
; #define PG8_BAR __builtin_amdgcn_s_barrier()
; #define PG8_SCHED __builtin_amdgcn_sched_barrier(0)
; template <class Epi, bool ALIGN_EPI>
; __device__ __forceinline__ void gemm_phase(LAS unsigned char* lds, const Gemm g, const StaticOrder& S, const Epi& E, const int tid) {
;     ...
;         for (int t = 0; t < nt; t += 2) {
;             const bool last = (t == nt - 2);
;             const char* a1 = cA + (size_t)(t + 1) * kstep;
;             const char* a2 = last ? nA : cA + (size_t)(t + 2) * kstep; const char* b2 = last ? nB : cB + (size_t)(t + 2) * kstep;
;             const char* a3 = a2 + kstep; const char* b3 = b2 + kstep;
;             PG8_LDB(B0, 0, 0); PG8_LDB(B1, 0, 1); PG8_SCHED; PG8_LDA(At, 0, 0); PG8_STAGE(PG8_SA(1, 1), a1 + hA, voffA);
;             PG8_WAIT_V(8); PG8_WAIT_L(0); PG8_BAR; PG8_MMA(0, 0, At, B0); PG8_MMA(0, 1, At, B1); PG8_BAR; PG8_SCHED;
;             PG8_LDA(At, 0, 1); PG8_STAGE(PG8_SB(0, 0), b2, voffB); PG8_STAGE(PG8_SB(0, 1), b2 + hB, voffB); PG8_STAGE(PG8_SA(0, 0), a2, voffA);
;             PG8_WAIT_V(8); PG8_WAIT_L(0); PG8_BAR; PG8_MMA(1, 0, At, B0); PG8_MMA(1, 1, At, B1); PG8_BAR; PG8_SCHED;
.LBB0_329:
	s_andn2_b64 vcc, exec, s[36:37]
	s_cbranch_vccnz .LBB0_332
	v_lshl_add_u64 v[142:143], v[142:143], 0, s[92:93]
	v_lshl_add_u64 v[144:145], v[144:145], 0, s[80:81]
	s_mov_b32 s10, 0
	s_add_i32 s11, s10, 2
	s_cmp_eq_u32 s58, s10
	v_lshl_add_u64 v[146:147], v[142:143], 0, s[92:93]
	s_cselect_b64 vcc, -1, 0
	v_add_u32_e32 v152, s33, v153
	s_add_i32 s10, 0, 0x14000
	v_cndmask_b32_e32 v151, v147, v139, vcc
	v_cndmask_b32_e32 v150, v146, v138, vcc
	ds_read_b128 v[146:149], v152
	ds_read_b128 v[156:159], v152 offset:1024
	ds_read_b128 v[160:163], v152 offset:2048
	ds_read_b128 v[164:167], v152 offset:3072
	v_add_u32_e32 v152, s10, v153
	ds_read_b128 v[176:179], v152
	ds_read_b128 v[180:183], v152 offset:1024
	ds_read_b128 v[184:187], v152 offset:2048
	ds_read_b128 v[188:191], v152 offset:3072
	v_cndmask_b32_e32 v221, v145, v141, vcc
	v_cndmask_b32_e32 v220, v144, v140, vcc
	v_lshl_add_u64 v[226:227], v[142:143], 0, v[134:135]
	s_add_i32 m0, s51, 0xc000
	ds_read_b128 v[192:195], v155
	ds_read_b128 v[196:199], v155 offset:1024
	ds_read_b128 v[200:203], v155 offset:2048
	ds_read_b128 v[204:207], v155 offset:3072
	ds_read_b128 v[208:211], v155 offset:4096
	ds_read_b128 v[212:215], v155 offset:5120
	ds_read_b128 v[216:219], v155 offset:6144
	ds_read_b128 v[240:243], v155 offset:7168
	global_load_lds_dwordx4 v[226:227], off
	v_lshl_add_u64 v[226:227], v[142:143], 0, v[136:137]
	s_add_i32 m0, s51, 0xe000
	s_nop 0
	global_load_lds_dwordx4 v[226:227], off
	s_waitcnt vmcnt(8)
	s_waitcnt lgkmcnt(0)
	s_barrier
	s_setprio 1
	s_waitcnt lgkmcnt(0)
	v_mfma_f32_16x16x32_bf16 v[120:123], v[146:149], v[192:195], 0
	v_mfma_f32_16x16x32_bf16 v[124:127], v[160:163], v[192:195], 0
	v_mfma_f32_16x16x32_bf16 v[108:111], v[146:149], v[200:203], 0
	v_mfma_f32_16x16x32_bf16 v[104:107], v[160:163], v[200:203], 0
	v_mfma_f32_16x16x32_bf16 v[92:95], v[146:149], v[208:211], 0
	v_mfma_f32_16x16x32_bf16 v[88:91], v[160:163], v[208:211], 0
	v_mfma_f32_16x16x32_bf16 v[76:79], v[146:149], v[216:219], 0
	v_mfma_f32_16x16x32_bf16 v[72:75], v[160:163], v[216:219], 0
	v_mfma_f32_16x16x32_bf16 v[120:123], v[156:159], v[196:199], v[120:123]
	v_mfma_f32_16x16x32_bf16 v[124:127], v[164:167], v[196:199], v[124:127]
	v_mfma_f32_16x16x32_bf16 v[108:111], v[156:159], v[204:207], v[108:111]
	v_mfma_f32_16x16x32_bf16 v[104:107], v[164:167], v[204:207], v[104:107]
	v_mfma_f32_16x16x32_bf16 v[92:95], v[156:159], v[212:215], v[92:95]
	v_mfma_f32_16x16x32_bf16 v[88:91], v[164:167], v[212:215], v[88:91]
	v_mfma_f32_16x16x32_bf16 v[76:79], v[156:159], v[240:243], v[76:79]
	v_mfma_f32_16x16x32_bf16 v[72:75], v[164:167], v[240:243], v[72:75]
	s_setprio 0
	s_setprio 1
	v_mfma_f32_16x16x32_bf16 v[116:119], v[176:179], v[192:195], 0
	v_mfma_f32_16x16x32_bf16 v[112:115], v[184:187], v[192:195], 0
	v_mfma_f32_16x16x32_bf16 v[100:103], v[176:179], v[200:203], 0
	v_mfma_f32_16x16x32_bf16 v[96:99], v[184:187], v[200:203], 0
	v_mfma_f32_16x16x32_bf16 v[84:87], v[176:179], v[208:211], 0
	v_mfma_f32_16x16x32_bf16 v[80:83], v[184:187], v[208:211], 0
	v_mfma_f32_16x16x32_bf16 v[68:71], v[176:179], v[216:219], 0
	v_mfma_f32_16x16x32_bf16 v[64:67], v[184:187], v[216:219], 0
	v_mfma_f32_16x16x32_bf16 v[116:119], v[180:183], v[196:199], v[116:119]
	v_mfma_f32_16x16x32_bf16 v[112:115], v[188:191], v[196:199], v[112:115]
	v_mfma_f32_16x16x32_bf16 v[100:103], v[180:183], v[204:207], v[100:103]
	v_mfma_f32_16x16x32_bf16 v[96:99], v[188:191], v[204:207], v[96:99]
	v_mfma_f32_16x16x32_bf16 v[84:87], v[180:183], v[212:215], v[84:87]
	v_mfma_f32_16x16x32_bf16 v[80:83], v[188:191], v[212:215], v[80:83]
	v_mfma_f32_16x16x32_bf16 v[68:71], v[180:183], v[240:243], v[68:71]
	v_mfma_f32_16x16x32_bf16 v[64:67], v[188:191], v[240:243], v[64:67]
	s_setprio 0
	s_barrier
	s_add_i32 s65, s33, s45
	v_lshl_add_u64 v[226:227], v[220:221], 0, v[168:169]
	s_mov_b32 m0, s65
	ds_read_b128 v[192:195], v155 offset:16384
	ds_read_b128 v[196:199], v155 offset:17408
	ds_read_b128 v[200:203], v155 offset:18432
	ds_read_b128 v[204:207], v155 offset:19456
	ds_read_b128 v[208:211], v155 offset:20480
	ds_read_b128 v[212:215], v155 offset:21504
	ds_read_b128 v[216:219], v155 offset:22528
	ds_read_b128 v[240:243], v155 offset:23552
	global_load_lds_dwordx4 v[226:227], off
	v_lshl_add_u64 v[244:245], v[220:221], 0, v[128:129]
	s_add_i32 m0, s65, 0x2000
	v_lshl_add_u64 v[220:221], v[220:221], 0, s[12:13]
	s_add_i32 s10, s10, s45
	global_load_lds_dwordx4 v[244:245], off
	v_lshl_add_u64 v[246:247], v[220:221], 0, v[168:169]
	s_mov_b32 m0, s10
	v_lshl_add_u64 v[220:221], v[220:221], 0, v[128:129]
	global_load_lds_dwordx4 v[246:247], off
	s_add_i32 m0, s10, 0x2000
	v_lshl_add_u64 v[248:249], v[150:151], 0, v[132:133]
	global_load_lds_dwordx4 v[220:221], off
	s_mov_b32 m0, s51
	v_lshl_add_u64 v[250:251], v[150:151], 0, v[130:131]
	global_load_lds_dwordx4 v[248:249], off
	s_mov_b32 m0, s52
	s_nop 0
	global_load_lds_dwordx4 v[250:251], off
	s_waitcnt vmcnt(8)
	s_waitcnt lgkmcnt(0)
	s_barrier
; #define PG8_STAGE(bufoff, gbase, voff) do { _Pragma("unroll") for (int _i = 0; _i < 2; ++_i) \
;         __builtin_amdgcn_global_load_lds((const unsigned*)((const char*)(gbase) + (voff)[_i]), (LAS unsigned*)(lds + (bufoff) + ldsw + _i * 8192), 16, 0, 0); } while (0)
; #define PG8_LDA(dst, b, h) do { _Pragma("unroll") for (int m = 0; m < 4; ++m) _Pragma("unroll") for (int k = 0; k < 2; ++k) dst[m][k] = *(const LAS bf16x8*)(lds + PG8_SA(b, h) + aoff + m * 2048 + k * 1024); } while (0)
; #define PG8_LDB(dst, b, h) do { _Pragma("unroll") for (int n = 0; n < 2; ++n) _Pragma("unroll") for (int k = 0; k < 2; ++k) dst[n][k] = *(const LAS bf16x8*)(lds + PG8_SB(b, h) + boff + n * 2048 + k * 1024); } while (0)
; #define PG8_MMA(ai, bj, At, Bt) do { __builtin_amdgcn_s_setprio(1); _Pragma("unroll") for (int k = 0; k < 2; ++k) _Pragma("unroll") for (int m = 0; m < 4; ++m) _Pragma("unroll") for (int n = 0; n < 2; ++n) \
;         acc[ai][bj][m][n] = __builtin_amdgcn_mfma_f32_16x16x32_bf16(Bt[n][k], At[m][k], acc[ai][bj][m][n], 0, 0, 0); __builtin_amdgcn_s_setprio(0); } while (0)
; #define PG8_WAIT_V(n) asm volatile("s_waitcnt vmcnt(" #n ")" ::: "memory")
; #define PG8_WAIT_L(n) asm volatile("s_waitcnt lgkmcnt(" #n ")" ::: "memory")
; #define PG8_BAR __builtin_amdgcn_s_barrier()
; #define PG8_SCHED __builtin_amdgcn_sched_barrier(0)
; template <class Epi, bool ALIGN_EPI>
; __device__ __forceinline__ void gemm_phase(LAS unsigned char* lds, const Gemm g, const StaticOrder& S, const Epi& E, const int tid) {
;     ...
;             PG8_WAIT_V(8); PG8_WAIT_L(0); PG8_BAR; PG8_MMA(1, 0, At, B0); PG8_MMA(1, 1, At, B1); PG8_BAR; PG8_SCHED;
;             PG8_LDB(B0, 1, 0); PG8_LDB(B1, 1, 1); PG8_SCHED; PG8_LDA(At, 1, 0); PG8_STAGE(PG8_SA(0, 1), a2 + hA, voffA);
;             PG8_WAIT_V(8); PG8_WAIT_L(0); PG8_BAR; PG8_MMA(0, 0, At, B0); PG8_MMA(0, 1, At, B1); PG8_BAR; PG8_SCHED;
	s_setprio 1
	s_waitcnt lgkmcnt(0)
	v_mfma_f32_16x16x32_bf16 v[60:63], v[146:149], v[192:195], 0
	v_mfma_f32_16x16x32_bf16 v[56:59], v[160:163], v[192:195], 0
	v_mfma_f32_16x16x32_bf16 v[44:47], v[146:149], v[200:203], 0
	v_mfma_f32_16x16x32_bf16 v[40:43], v[160:163], v[200:203], 0
	v_mfma_f32_16x16x32_bf16 v[28:31], v[146:149], v[208:211], 0
	v_mfma_f32_16x16x32_bf16 v[24:27], v[160:163], v[208:211], 0
	v_mfma_f32_16x16x32_bf16 v[12:15], v[146:149], v[216:219], 0
	v_mfma_f32_16x16x32_bf16 v[8:11], v[160:163], v[216:219], 0
	v_mfma_f32_16x16x32_bf16 v[60:63], v[156:159], v[196:199], v[60:63]
	v_mfma_f32_16x16x32_bf16 v[56:59], v[164:167], v[196:199], v[56:59]
	v_mfma_f32_16x16x32_bf16 v[44:47], v[156:159], v[204:207], v[44:47]
	v_mfma_f32_16x16x32_bf16 v[40:43], v[164:167], v[204:207], v[40:43]
	v_mfma_f32_16x16x32_bf16 v[28:31], v[156:159], v[212:215], v[28:31]
	v_mfma_f32_16x16x32_bf16 v[24:27], v[164:167], v[212:215], v[24:27]
	v_mfma_f32_16x16x32_bf16 v[12:15], v[156:159], v[240:243], v[12:15]
	v_mfma_f32_16x16x32_bf16 v[8:11], v[164:167], v[240:243], v[8:11]
	s_setprio 0
	s_setprio 1
	v_mfma_f32_16x16x32_bf16 v[52:55], v[176:179], v[192:195], 0
	v_mfma_f32_16x16x32_bf16 v[48:51], v[184:187], v[192:195], 0
	v_mfma_f32_16x16x32_bf16 v[36:39], v[176:179], v[200:203], 0
	v_mfma_f32_16x16x32_bf16 v[32:35], v[184:187], v[200:203], 0
	v_mfma_f32_16x16x32_bf16 v[20:23], v[176:179], v[208:211], 0
	v_mfma_f32_16x16x32_bf16 v[16:19], v[184:187], v[208:211], 0
	v_mfma_f32_16x16x32_bf16 v[4:7], v[176:179], v[216:219], 0
	v_mfma_f32_16x16x32_bf16 v[0:3], v[184:187], v[216:219], 0
	v_mfma_f32_16x16x32_bf16 v[52:55], v[180:183], v[196:199], v[52:55]
	v_mfma_f32_16x16x32_bf16 v[48:51], v[188:191], v[196:199], v[48:51]
	v_mfma_f32_16x16x32_bf16 v[36:39], v[180:183], v[204:207], v[36:39]
	v_mfma_f32_16x16x32_bf16 v[32:35], v[188:191], v[204:207], v[32:35]
	v_mfma_f32_16x16x32_bf16 v[20:23], v[180:183], v[212:215], v[20:23]
	v_mfma_f32_16x16x32_bf16 v[16:19], v[188:191], v[212:215], v[16:19]
	v_mfma_f32_16x16x32_bf16 v[4:7], v[180:183], v[240:243], v[4:7]
	v_mfma_f32_16x16x32_bf16 v[0:3], v[188:191], v[240:243], v[0:3]
	s_setprio 0
	s_barrier
	s_add_i32 s10, 0, 0x18000
	v_add_u32_e32 v152, s10, v153
	s_add_i32 s65, 0, 0x1c000
	ds_read_b128 v[146:149], v152
	ds_read_b128 v[156:159], v152 offset:1024
	ds_read_b128 v[160:163], v152 offset:2048
	ds_read_b128 v[164:167], v152 offset:3072
	v_add_u32_e32 v152, s65, v153
	ds_read_b128 v[176:179], v152
	ds_read_b128 v[180:183], v152 offset:1024
	ds_read_b128 v[184:187], v152 offset:2048
	ds_read_b128 v[188:191], v152 offset:3072
	v_lshl_add_u64 v[150:151], v[150:151], 0, s[94:95]
	s_mov_b32 m0, s53
	v_lshl_add_u64 v[252:253], v[150:151], 0, v[132:133]
	ds_read_b128 v[192:195], v155 offset:32768
	ds_read_b128 v[196:199], v155 offset:33792
	ds_read_b128 v[200:203], v155 offset:34816
	ds_read_b128 v[204:207], v155 offset:35840
	ds_read_b128 v[208:211], v155 offset:36864
	ds_read_b128 v[212:215], v155 offset:37888
	ds_read_b128 v[216:219], v155 offset:38912
	ds_read_b128 v[240:243], v155 offset:39936
	global_load_lds_dwordx4 v[252:253], off
	v_lshl_add_u64 v[150:151], v[150:151], 0, v[130:131]
	s_mov_b32 m0, s54
	s_nop 0
	global_load_lds_dwordx4 v[150:151], off
	s_waitcnt vmcnt(8)
	s_waitcnt lgkmcnt(0)
	s_barrier
	s_setprio 1
	s_waitcnt lgkmcnt(0)
	v_mfma_f32_16x16x32_bf16 v[120:123], v[146:149], v[192:195], v[120:123]
	v_mfma_f32_16x16x32_bf16 v[124:127], v[160:163], v[192:195], v[124:127]
	v_mfma_f32_16x16x32_bf16 v[108:111], v[146:149], v[200:203], v[108:111]
	v_mfma_f32_16x16x32_bf16 v[104:107], v[160:163], v[200:203], v[104:107]
	v_mfma_f32_16x16x32_bf16 v[92:95], v[146:149], v[208:211], v[92:95]
	v_mfma_f32_16x16x32_bf16 v[88:91], v[160:163], v[208:211], v[88:91]
	v_mfma_f32_16x16x32_bf16 v[76:79], v[146:149], v[216:219], v[76:79]
	v_mfma_f32_16x16x32_bf16 v[72:75], v[160:163], v[216:219], v[72:75]
	v_mfma_f32_16x16x32_bf16 v[120:123], v[156:159], v[196:199], v[120:123]
	v_mfma_f32_16x16x32_bf16 v[124:127], v[164:167], v[196:199], v[124:127]
	v_mfma_f32_16x16x32_bf16 v[108:111], v[156:159], v[204:207], v[108:111]
	v_mfma_f32_16x16x32_bf16 v[104:107], v[164:167], v[204:207], v[104:107]
	v_mfma_f32_16x16x32_bf16 v[92:95], v[156:159], v[212:215], v[92:95]
	v_mfma_f32_16x16x32_bf16 v[88:91], v[164:167], v[212:215], v[88:91]
	v_mfma_f32_16x16x32_bf16 v[76:79], v[156:159], v[240:243], v[76:79]
	v_mfma_f32_16x16x32_bf16 v[72:75], v[164:167], v[240:243], v[72:75]
	s_setprio 0
	s_setprio 1
	v_mfma_f32_16x16x32_bf16 v[116:119], v[176:179], v[192:195], v[116:119]
	v_mfma_f32_16x16x32_bf16 v[112:115], v[184:187], v[192:195], v[112:115]
	v_mfma_f32_16x16x32_bf16 v[100:103], v[176:179], v[200:203], v[100:103]
	v_mfma_f32_16x16x32_bf16 v[96:99], v[184:187], v[200:203], v[96:99]
	v_mfma_f32_16x16x32_bf16 v[84:87], v[176:179], v[208:211], v[84:87]
	v_mfma_f32_16x16x32_bf16 v[80:83], v[184:187], v[208:211], v[80:83]
	v_mfma_f32_16x16x32_bf16 v[68:71], v[176:179], v[216:219], v[68:71]
	v_mfma_f32_16x16x32_bf16 v[64:67], v[184:187], v[216:219], v[64:67]
	v_mfma_f32_16x16x32_bf16 v[116:119], v[180:183], v[196:199], v[116:119]
	v_mfma_f32_16x16x32_bf16 v[112:115], v[188:191], v[196:199], v[112:115]
	v_mfma_f32_16x16x32_bf16 v[100:103], v[180:183], v[204:207], v[100:103]
	v_mfma_f32_16x16x32_bf16 v[96:99], v[188:191], v[204:207], v[96:99]
	v_mfma_f32_16x16x32_bf16 v[84:87], v[180:183], v[212:215], v[84:87]
	v_mfma_f32_16x16x32_bf16 v[80:83], v[188:191], v[212:215], v[80:83]
	v_mfma_f32_16x16x32_bf16 v[68:71], v[180:183], v[240:243], v[68:71]
	v_mfma_f32_16x16x32_bf16 v[64:67], v[188:191], v[240:243], v[64:67]
	s_setprio 0
	s_barrier
; #define PG8_STAGE(bufoff, gbase, voff) do { _Pragma("unroll") for (int _i = 0; _i < 2; ++_i) \
;         __builtin_amdgcn_global_load_lds((const unsigned*)((const char*)(gbase) + (voff)[_i]), (LAS unsigned*)(lds + (bufoff) + ldsw + _i * 8192), 16, 0, 0); } while (0)
; #define PG8_LDA(dst, b, h) do { _Pragma("unroll") for (int m = 0; m < 4; ++m) _Pragma("unroll") for (int k = 0; k < 2; ++k) dst[m][k] = *(const LAS bf16x8*)(lds + PG8_SA(b, h) + aoff + m * 2048 + k * 1024); } while (0)
; #define PG8_LDB(dst, b, h) do { _Pragma("unroll") for (int n = 0; n < 2; ++n) _Pragma("unroll") for (int k = 0; k < 2; ++k) dst[n][k] = *(const LAS bf16x8*)(lds + PG8_SB(b, h) + boff + n * 2048 + k * 1024); } while (0)
; #define PG8_MMA(ai, bj, At, Bt) do { __builtin_amdgcn_s_setprio(1); _Pragma("unroll") for (int k = 0; k < 2; ++k) _Pragma("unroll") for (int m = 0; m < 4; ++m) _Pragma("unroll") for (int n = 0; n < 2; ++n) \
;         acc[ai][bj][m][n] = __builtin_amdgcn_mfma_f32_16x16x32_bf16(Bt[n][k], At[m][k], acc[ai][bj][m][n], 0, 0, 0); __builtin_amdgcn_s_setprio(0); } while (0)
; #define PG8_WAIT_V(n) asm volatile("s_waitcnt vmcnt(" #n ")" ::: "memory")
; template <class Epi, bool ALIGN_EPI>
; __device__ __forceinline__ void gemm_phase(LAS unsigned char* lds, const Gemm g, const StaticOrder& S, const Epi& E, const int tid) {
;     ...
;             PG8_LDB(B0, 0, 0); PG8_LDB(B1, 0, 1); PG8_SCHED; PG8_LDA(At, 0, 0); PG8_STAGE(PG8_SA(1, 1), a1 + hA, voffA);
;             PG8_WAIT_V(8); PG8_WAIT_L(0); PG8_BAR; PG8_MMA(0, 0, At, B0); PG8_MMA(0, 1, At, B1); PG8_BAR; PG8_SCHED;
;             PG8_LDA(At, 0, 1); PG8_STAGE(PG8_SB(0, 0), b2, voffB); PG8_STAGE(PG8_SB(0, 1), b2 + hB, voffB); PG8_STAGE(PG8_SA(0, 0), a2, voffA);
;             PG8_WAIT_V(8); PG8_WAIT_L(0); PG8_BAR; PG8_MMA(1, 0, At, B0); PG8_MMA(1, 1, At, B1); PG8_BAR; PG8_SCHED;
;             PG8_LDB(B0, 1, 0); PG8_LDB(B1, 1, 1); PG8_SCHED; PG8_LDA(At, 1, 0); PG8_STAGE(PG8_SA(0, 1), a2 + hA, voffA);
;             PG8_WAIT_V(8); PG8_WAIT_L(0); PG8_BAR; PG8_MMA(0, 0, At, B0); PG8_MMA(0, 1, At, B1); PG8_BAR; PG8_SCHED;
;             PG8_LDA(At, 1, 1); PG8_STAGE(PG8_SB(1, 0), b3, voffB); PG8_STAGE(PG8_SB(1, 1), b3 + hB, voffB); PG8_STAGE(PG8_SA(1, 0), a3, voffA);
;             PG8_WAIT_V(8); PG8_WAIT_L(0); PG8_BAR; PG8_MMA(1, 0, At, B0); PG8_MMA(1, 1, At, B1); PG8_BAR; PG8_SCHED;
;         }
	s_add_i32 s10, s10, s45
	v_lshl_add_u64 v[150:151], v[226:227], 0, s[92:93]
	s_mov_b32 m0, s10
	ds_read_b128 v[192:195], v155 offset:49152
	ds_read_b128 v[196:199], v155 offset:50176
	ds_read_b128 v[200:203], v155 offset:51200
	ds_read_b128 v[204:207], v155 offset:52224
	ds_read_b128 v[208:211], v155 offset:53248
	ds_read_b128 v[212:215], v155 offset:54272
	ds_read_b128 v[216:219], v155 offset:55296
	ds_read_b128 v[240:243], v155 offset:56320
	global_load_lds_dwordx4 v[150:151], off
	v_lshl_add_u64 v[150:151], v[244:245], 0, s[92:93]
	s_add_i32 m0, s10, 0x2000
	s_add_i32 s10, s65, s45
	global_load_lds_dwordx4 v[150:151], off
	v_lshl_add_u64 v[150:151], v[246:247], 0, s[92:93]
	s_mov_b32 m0, s10
	s_nop 0
	global_load_lds_dwordx4 v[150:151], off
	v_lshl_add_u64 v[150:151], v[220:221], 0, s[92:93]
	s_add_i32 m0, s10, 0x2000
	s_nop 0
	global_load_lds_dwordx4 v[150:151], off
	v_lshl_add_u64 v[150:151], v[248:249], 0, s[92:93]
	s_mov_b32 m0, s56
	s_nop 0
	global_load_lds_dwordx4 v[150:151], off
	v_lshl_add_u64 v[150:151], v[250:251], 0, s[92:93]
	s_mov_b32 m0, s57
	s_nop 0
	global_load_lds_dwordx4 v[150:151], off
	s_waitcnt vmcnt(8)
	s_waitcnt lgkmcnt(0)
	s_barrier
	s_setprio 1
	s_waitcnt lgkmcnt(0)
	v_mfma_f32_16x16x32_bf16 v[60:63], v[146:149], v[192:195], v[60:63]
	v_mfma_f32_16x16x32_bf16 v[56:59], v[160:163], v[192:195], v[56:59]
	v_mfma_f32_16x16x32_bf16 v[44:47], v[146:149], v[200:203], v[44:47]
	v_mfma_f32_16x16x32_bf16 v[40:43], v[160:163], v[200:203], v[40:43]
	v_mfma_f32_16x16x32_bf16 v[28:31], v[146:149], v[208:211], v[28:31]
	v_mfma_f32_16x16x32_bf16 v[24:27], v[160:163], v[208:211], v[24:27]
	v_mfma_f32_16x16x32_bf16 v[12:15], v[146:149], v[216:219], v[12:15]
	v_mfma_f32_16x16x32_bf16 v[8:11], v[160:163], v[216:219], v[8:11]
	v_mfma_f32_16x16x32_bf16 v[60:63], v[156:159], v[196:199], v[60:63]
	v_mfma_f32_16x16x32_bf16 v[56:59], v[164:167], v[196:199], v[56:59]
	v_mfma_f32_16x16x32_bf16 v[44:47], v[156:159], v[204:207], v[44:47]
	v_mfma_f32_16x16x32_bf16 v[40:43], v[164:167], v[204:207], v[40:43]
	v_mfma_f32_16x16x32_bf16 v[28:31], v[156:159], v[212:215], v[28:31]
	v_mfma_f32_16x16x32_bf16 v[24:27], v[164:167], v[212:215], v[24:27]
	v_mfma_f32_16x16x32_bf16 v[12:15], v[156:159], v[240:243], v[12:15]
	v_mfma_f32_16x16x32_bf16 v[8:11], v[164:167], v[240:243], v[8:11]
	s_setprio 0
	s_setprio 1
	v_mfma_f32_16x16x32_bf16 v[52:55], v[176:179], v[192:195], v[52:55]
	v_mfma_f32_16x16x32_bf16 v[48:51], v[184:187], v[192:195], v[48:51]
	v_mfma_f32_16x16x32_bf16 v[36:39], v[176:179], v[200:203], v[36:39]
	v_mfma_f32_16x16x32_bf16 v[32:35], v[184:187], v[200:203], v[32:35]
	v_mfma_f32_16x16x32_bf16 v[20:23], v[176:179], v[208:211], v[20:23]
	v_mfma_f32_16x16x32_bf16 v[16:19], v[184:187], v[208:211], v[16:19]
	v_mfma_f32_16x16x32_bf16 v[4:7], v[176:179], v[216:219], v[4:7]
	v_mfma_f32_16x16x32_bf16 v[0:3], v[184:187], v[216:219], v[0:3]
	v_mfma_f32_16x16x32_bf16 v[52:55], v[180:183], v[196:199], v[52:55]
	v_mfma_f32_16x16x32_bf16 v[48:51], v[188:191], v[196:199], v[48:51]
	v_mfma_f32_16x16x32_bf16 v[36:39], v[180:183], v[204:207], v[36:39]
	v_mfma_f32_16x16x32_bf16 v[32:35], v[188:191], v[204:207], v[32:35]
	v_mfma_f32_16x16x32_bf16 v[20:23], v[180:183], v[212:215], v[20:23]
	v_mfma_f32_16x16x32_bf16 v[16:19], v[188:191], v[212:215], v[16:19]
	v_mfma_f32_16x16x32_bf16 v[4:7], v[180:183], v[240:243], v[4:7]
	v_mfma_f32_16x16x32_bf16 v[0:3], v[188:191], v[240:243], v[0:3]
	s_setprio 0
	v_lshl_add_u64 v[142:143], v[142:143], 0, s[80:81]
	v_lshl_add_u64 v[144:145], v[144:145], 0, s[80:81]
	s_cmp_ge_u32 s11, s55
	s_mov_b32 s10, s11
	s_barrier
	s_cbranch_scc1 .Lpl4_after
.LBB0_331:
	s_add_i32 s11, s10, 2
	s_cmp_eq_u32 s58, s10
	v_lshl_add_u64 v[146:147], v[142:143], 0, s[92:93]
	s_cselect_b64 vcc, -1, 0
	v_add_u32_e32 v152, s33, v153
	s_add_i32 s10, 0, 0x14000
	v_cndmask_b32_e32 v151, v147, v139, vcc
	v_cndmask_b32_e32 v150, v146, v138, vcc
	ds_read_b128 v[146:149], v152
	ds_read_b128 v[156:159], v152 offset:1024
	ds_read_b128 v[160:163], v152 offset:2048
	ds_read_b128 v[164:167], v152 offset:3072
	v_add_u32_e32 v152, s10, v153
	ds_read_b128 v[176:179], v152
	ds_read_b128 v[180:183], v152 offset:1024
	ds_read_b128 v[184:187], v152 offset:2048
	ds_read_b128 v[188:191], v152 offset:3072
	v_cndmask_b32_e32 v221, v145, v141, vcc
	v_cndmask_b32_e32 v220, v144, v140, vcc
	v_lshl_add_u64 v[226:227], v[142:143], 0, v[134:135]
	s_add_i32 m0, s51, 0xc000
	ds_read_b128 v[192:195], v155
	ds_read_b128 v[196:199], v155 offset:1024
	ds_read_b128 v[200:203], v155 offset:2048
	ds_read_b128 v[204:207], v155 offset:3072
	ds_read_b128 v[208:211], v155 offset:4096
	ds_read_b128 v[212:215], v155 offset:5120
	ds_read_b128 v[216:219], v155 offset:6144
	ds_read_b128 v[240:243], v155 offset:7168
	global_load_lds_dwordx4 v[226:227], off
	v_lshl_add_u64 v[226:227], v[142:143], 0, v[136:137]
	s_add_i32 m0, s51, 0xe000
	s_nop 0
	global_load_lds_dwordx4 v[226:227], off
	s_waitcnt vmcnt(8)
	s_waitcnt lgkmcnt(0)
	s_barrier
; #define PG8_STAGE(bufoff, gbase, voff) do { _Pragma("unroll") for (int _i = 0; _i < 2; ++_i) \
;         __builtin_amdgcn_global_load_lds((const unsigned*)((const char*)(gbase) + (voff)[_i]), (LAS unsigned*)(lds + (bufoff) + ldsw + _i * 8192), 16, 0, 0); } while (0)
; #define PG8_LDA(dst, b, h) do { _Pragma("unroll") for (int m = 0; m < 4; ++m) _Pragma("unroll") for (int k = 0; k < 2; ++k) dst[m][k] = *(const LAS bf16x8*)(lds + PG8_SA(b, h) + aoff + m * 2048 + k * 1024); } while (0)
; #define PG8_LDB(dst, b, h) do { _Pragma("unroll") for (int n = 0; n < 2; ++n) _Pragma("unroll") for (int k = 0; k < 2; ++k) dst[n][k] = *(const LAS bf16x8*)(lds + PG8_SB(b, h) + boff + n * 2048 + k * 1024); } while (0)
; #define PG8_MMA(ai, bj, At, Bt) do { __builtin_amdgcn_s_setprio(1); _Pragma("unroll") for (int k = 0; k < 2; ++k) _Pragma("unroll") for (int m = 0; m < 4; ++m) _Pragma("unroll") for (int n = 0; n < 2; ++n) \
;         acc[ai][bj][m][n] = __builtin_amdgcn_mfma_f32_16x16x32_bf16(Bt[n][k], At[m][k], acc[ai][bj][m][n], 0, 0, 0); __builtin_amdgcn_s_setprio(0); } while (0)
; #define PG8_WAIT_V(n) asm volatile("s_waitcnt vmcnt(" #n ")" ::: "memory")
; #define PG8_WAIT_L(n) asm volatile("s_waitcnt lgkmcnt(" #n ")" ::: "memory")
; #define PG8_BAR __builtin_amdgcn_s_barrier()
; #define PG8_SCHED __builtin_amdgcn_sched_barrier(0)
; template <class Epi, bool ALIGN_EPI>
; __device__ __forceinline__ void gemm_phase(LAS unsigned char* lds, const Gemm g, const StaticOrder& S, const Epi& E, const int tid) {
;     ...
;             PG8_WAIT_V(8); PG8_WAIT_L(0); PG8_BAR; PG8_MMA(0, 0, At, B0); PG8_MMA(0, 1, At, B1); PG8_BAR; PG8_SCHED;
;             PG8_LDA(At, 0, 1); PG8_STAGE(PG8_SB(0, 0), b2, voffB); PG8_STAGE(PG8_SB(0, 1), b2 + hB, voffB); PG8_STAGE(PG8_SA(0, 0), a2, voffA);
;             PG8_WAIT_V(8); PG8_WAIT_L(0); PG8_BAR; PG8_MMA(1, 0, At, B0); PG8_MMA(1, 1, At, B1); PG8_BAR; PG8_SCHED;
;             PG8_LDB(B0, 1, 0); PG8_LDB(B1, 1, 1); PG8_SCHED; PG8_LDA(At, 1, 0); PG8_STAGE(PG8_SA(0, 1), a2 + hA, voffA);
;             PG8_WAIT_V(8); PG8_WAIT_L(0); PG8_BAR; PG8_MMA(0, 0, At, B0); PG8_MMA(0, 1, At, B1); PG8_BAR; PG8_SCHED;
	s_setprio 1
	s_waitcnt lgkmcnt(0)
	v_mfma_f32_16x16x32_bf16 v[120:123], v[146:149], v[192:195], v[120:123]
	v_mfma_f32_16x16x32_bf16 v[124:127], v[160:163], v[192:195], v[124:127]
	v_mfma_f32_16x16x32_bf16 v[108:111], v[146:149], v[200:203], v[108:111]
	v_mfma_f32_16x16x32_bf16 v[104:107], v[160:163], v[200:203], v[104:107]
	v_mfma_f32_16x16x32_bf16 v[92:95], v[146:149], v[208:211], v[92:95]
	v_mfma_f32_16x16x32_bf16 v[88:91], v[160:163], v[208:211], v[88:91]
	v_mfma_f32_16x16x32_bf16 v[76:79], v[146:149], v[216:219], v[76:79]
	v_mfma_f32_16x16x32_bf16 v[72:75], v[160:163], v[216:219], v[72:75]
	v_mfma_f32_16x16x32_bf16 v[120:123], v[156:159], v[196:199], v[120:123]
	v_mfma_f32_16x16x32_bf16 v[124:127], v[164:167], v[196:199], v[124:127]
	v_mfma_f32_16x16x32_bf16 v[108:111], v[156:159], v[204:207], v[108:111]
	v_mfma_f32_16x16x32_bf16 v[104:107], v[164:167], v[204:207], v[104:107]
	v_mfma_f32_16x16x32_bf16 v[92:95], v[156:159], v[212:215], v[92:95]
	v_mfma_f32_16x16x32_bf16 v[88:91], v[164:167], v[212:215], v[88:91]
	v_mfma_f32_16x16x32_bf16 v[76:79], v[156:159], v[240:243], v[76:79]
	v_mfma_f32_16x16x32_bf16 v[72:75], v[164:167], v[240:243], v[72:75]
	s_setprio 0
	s_setprio 1
	v_mfma_f32_16x16x32_bf16 v[116:119], v[176:179], v[192:195], v[116:119]
	v_mfma_f32_16x16x32_bf16 v[112:115], v[184:187], v[192:195], v[112:115]
	v_mfma_f32_16x16x32_bf16 v[100:103], v[176:179], v[200:203], v[100:103]
	v_mfma_f32_16x16x32_bf16 v[96:99], v[184:187], v[200:203], v[96:99]
	v_mfma_f32_16x16x32_bf16 v[84:87], v[176:179], v[208:211], v[84:87]
	v_mfma_f32_16x16x32_bf16 v[80:83], v[184:187], v[208:211], v[80:83]
	v_mfma_f32_16x16x32_bf16 v[68:71], v[176:179], v[216:219], v[68:71]
	v_mfma_f32_16x16x32_bf16 v[64:67], v[184:187], v[216:219], v[64:67]
	v_mfma_f32_16x16x32_bf16 v[116:119], v[180:183], v[196:199], v[116:119]
	v_mfma_f32_16x16x32_bf16 v[112:115], v[188:191], v[196:199], v[112:115]
	v_mfma_f32_16x16x32_bf16 v[100:103], v[180:183], v[204:207], v[100:103]
	v_mfma_f32_16x16x32_bf16 v[96:99], v[188:191], v[204:207], v[96:99]
	v_mfma_f32_16x16x32_bf16 v[84:87], v[180:183], v[212:215], v[84:87]
	v_mfma_f32_16x16x32_bf16 v[80:83], v[188:191], v[212:215], v[80:83]
	v_mfma_f32_16x16x32_bf16 v[68:71], v[180:183], v[240:243], v[68:71]
	v_mfma_f32_16x16x32_bf16 v[64:67], v[188:191], v[240:243], v[64:67]
	s_setprio 0
	s_barrier
	s_add_i32 s65, s33, s45
	v_lshl_add_u64 v[226:227], v[220:221], 0, v[168:169]
	s_mov_b32 m0, s65
	ds_read_b128 v[192:195], v155 offset:16384
	ds_read_b128 v[196:199], v155 offset:17408
	ds_read_b128 v[200:203], v155 offset:18432
	ds_read_b128 v[204:207], v155 offset:19456
	ds_read_b128 v[208:211], v155 offset:20480
	ds_read_b128 v[212:215], v155 offset:21504
	ds_read_b128 v[216:219], v155 offset:22528
	ds_read_b128 v[240:243], v155 offset:23552
	global_load_lds_dwordx4 v[226:227], off
	v_lshl_add_u64 v[244:245], v[220:221], 0, v[128:129]
	s_add_i32 m0, s65, 0x2000
	v_lshl_add_u64 v[220:221], v[220:221], 0, s[12:13]
	s_add_i32 s10, s10, s45
	global_load_lds_dwordx4 v[244:245], off
	v_lshl_add_u64 v[246:247], v[220:221], 0, v[168:169]
	s_mov_b32 m0, s10
	v_lshl_add_u64 v[220:221], v[220:221], 0, v[128:129]
	global_load_lds_dwordx4 v[246:247], off
	s_add_i32 m0, s10, 0x2000
	v_lshl_add_u64 v[248:249], v[150:151], 0, v[132:133]
	global_load_lds_dwordx4 v[220:221], off
	s_mov_b32 m0, s51
	v_lshl_add_u64 v[250:251], v[150:151], 0, v[130:131]
	global_load_lds_dwordx4 v[248:249], off
	s_mov_b32 m0, s52
	s_nop 0
	global_load_lds_dwordx4 v[250:251], off
	s_waitcnt vmcnt(8)
	s_waitcnt lgkmcnt(0)
	s_barrier
	s_setprio 1
	s_waitcnt lgkmcnt(0)
	v_mfma_f32_16x16x32_bf16 v[60:63], v[146:149], v[192:195], v[60:63]
	v_mfma_f32_16x16x32_bf16 v[56:59], v[160:163], v[192:195], v[56:59]
	v_mfma_f32_16x16x32_bf16 v[44:47], v[146:149], v[200:203], v[44:47]
	v_mfma_f32_16x16x32_bf16 v[40:43], v[160:163], v[200:203], v[40:43]
	v_mfma_f32_16x16x32_bf16 v[28:31], v[146:149], v[208:211], v[28:31]
	v_mfma_f32_16x16x32_bf16 v[24:27], v[160:163], v[208:211], v[24:27]
	v_mfma_f32_16x16x32_bf16 v[12:15], v[146:149], v[216:219], v[12:15]
	v_mfma_f32_16x16x32_bf16 v[8:11], v[160:163], v[216:219], v[8:11]
	v_mfma_f32_16x16x32_bf16 v[60:63], v[156:159], v[196:199], v[60:63]
	v_mfma_f32_16x16x32_bf16 v[56:59], v[164:167], v[196:199], v[56:59]
	v_mfma_f32_16x16x32_bf16 v[44:47], v[156:159], v[204:207], v[44:47]
	v_mfma_f32_16x16x32_bf16 v[40:43], v[164:167], v[204:207], v[40:43]
	v_mfma_f32_16x16x32_bf16 v[28:31], v[156:159], v[212:215], v[28:31]
	v_mfma_f32_16x16x32_bf16 v[24:27], v[164:167], v[212:215], v[24:27]
	v_mfma_f32_16x16x32_bf16 v[12:15], v[156:159], v[240:243], v[12:15]
	v_mfma_f32_16x16x32_bf16 v[8:11], v[164:167], v[240:243], v[8:11]
	s_setprio 0
	s_setprio 1
	v_mfma_f32_16x16x32_bf16 v[52:55], v[176:179], v[192:195], v[52:55]
	v_mfma_f32_16x16x32_bf16 v[48:51], v[184:187], v[192:195], v[48:51]
	v_mfma_f32_16x16x32_bf16 v[36:39], v[176:179], v[200:203], v[36:39]
	v_mfma_f32_16x16x32_bf16 v[32:35], v[184:187], v[200:203], v[32:35]
	v_mfma_f32_16x16x32_bf16 v[20:23], v[176:179], v[208:211], v[20:23]
	v_mfma_f32_16x16x32_bf16 v[16:19], v[184:187], v[208:211], v[16:19]
	v_mfma_f32_16x16x32_bf16 v[4:7], v[176:179], v[216:219], v[4:7]
	v_mfma_f32_16x16x32_bf16 v[0:3], v[184:187], v[216:219], v[0:3]
	v_mfma_f32_16x16x32_bf16 v[52:55], v[180:183], v[196:199], v[52:55]
	v_mfma_f32_16x16x32_bf16 v[48:51], v[188:191], v[196:199], v[48:51]
	v_mfma_f32_16x16x32_bf16 v[36:39], v[180:183], v[204:207], v[36:39]
	v_mfma_f32_16x16x32_bf16 v[32:35], v[188:191], v[204:207], v[32:35]
	v_mfma_f32_16x16x32_bf16 v[20:23], v[180:183], v[212:215], v[20:23]
	v_mfma_f32_16x16x32_bf16 v[16:19], v[188:191], v[212:215], v[16:19]
	v_mfma_f32_16x16x32_bf16 v[4:7], v[180:183], v[240:243], v[4:7]
	v_mfma_f32_16x16x32_bf16 v[0:3], v[188:191], v[240:243], v[0:3]
	s_setprio 0
	s_barrier
; #define PG8_STAGE(bufoff, gbase, voff) do { _Pragma("unroll") for (int _i = 0; _i < 2; ++_i) \
;         __builtin_amdgcn_global_load_lds((const unsigned*)((const char*)(gbase) + (voff)[_i]), (LAS unsigned*)(lds + (bufoff) + ldsw + _i * 8192), 16, 0, 0); } while (0)
; #define PG8_LDA(dst, b, h) do { _Pragma("unroll") for (int m = 0; m < 4; ++m) _Pragma("unroll") for (int k = 0; k < 2; ++k) dst[m][k] = *(const LAS bf16x8*)(lds + PG8_SA(b, h) + aoff + m * 2048 + k * 1024); } while (0)
; #define PG8_LDB(dst, b, h) do { _Pragma("unroll") for (int n = 0; n < 2; ++n) _Pragma("unroll") for (int k = 0; k < 2; ++k) dst[n][k] = *(const LAS bf16x8*)(lds + PG8_SB(b, h) + boff + n * 2048 + k * 1024); } while (0)
; #define PG8_MMA(ai, bj, At, Bt) do { __builtin_amdgcn_s_setprio(1); _Pragma("unroll") for (int k = 0; k < 2; ++k) _Pragma("unroll") for (int m = 0; m < 4; ++m) _Pragma("unroll") for (int n = 0; n < 2; ++n) \
;         acc[ai][bj][m][n] = __builtin_amdgcn_mfma_f32_16x16x32_bf16(Bt[n][k], At[m][k], acc[ai][bj][m][n], 0, 0, 0); __builtin_amdgcn_s_setprio(0); } while (0)
; #define PG8_WAIT_V(n) asm volatile("s_waitcnt vmcnt(" #n ")" ::: "memory")
; #define PG8_WAIT_L(n) asm volatile("s_waitcnt lgkmcnt(" #n ")" ::: "memory")
; #define PG8_BAR __builtin_amdgcn_s_barrier()
; #define PG8_SCHED __builtin_amdgcn_sched_barrier(0)
; template <class Epi, bool ALIGN_EPI>
; __device__ __forceinline__ void gemm_phase(LAS unsigned char* lds, const Gemm g, const StaticOrder& S, const Epi& E, const int tid) {
;     ...
;             PG8_LDB(B0, 1, 0); PG8_LDB(B1, 1, 1); PG8_SCHED; PG8_LDA(At, 1, 0); PG8_STAGE(PG8_SA(0, 1), a2 + hA, voffA);
;             PG8_WAIT_V(8); PG8_WAIT_L(0); PG8_BAR; PG8_MMA(0, 0, At, B0); PG8_MMA(0, 1, At, B1); PG8_BAR; PG8_SCHED;
;             PG8_LDA(At, 1, 1); PG8_STAGE(PG8_SB(1, 0), b3, voffB); PG8_STAGE(PG8_SB(1, 1), b3 + hB, voffB); PG8_STAGE(PG8_SA(1, 0), a3, voffA);
;             PG8_WAIT_V(8); PG8_WAIT_L(0); PG8_BAR; PG8_MMA(1, 0, At, B0); PG8_MMA(1, 1, At, B1); PG8_BAR; PG8_SCHED;
	s_add_i32 s10, 0, 0x18000
	v_add_u32_e32 v152, s10, v153
	s_add_i32 s65, 0, 0x1c000
	ds_read_b128 v[146:149], v152
	ds_read_b128 v[156:159], v152 offset:1024
	ds_read_b128 v[160:163], v152 offset:2048
	ds_read_b128 v[164:167], v152 offset:3072
	v_add_u32_e32 v152, s65, v153
	ds_read_b128 v[176:179], v152
	ds_read_b128 v[180:183], v152 offset:1024
	ds_read_b128 v[184:187], v152 offset:2048
	ds_read_b128 v[188:191], v152 offset:3072
	v_lshl_add_u64 v[150:151], v[150:151], 0, s[94:95]
	s_mov_b32 m0, s53
	v_lshl_add_u64 v[252:253], v[150:151], 0, v[132:133]
	ds_read_b128 v[192:195], v155 offset:32768
	ds_read_b128 v[196:199], v155 offset:33792
	ds_read_b128 v[200:203], v155 offset:34816
	ds_read_b128 v[204:207], v155 offset:35840
	ds_read_b128 v[208:211], v155 offset:36864
	ds_read_b128 v[212:215], v155 offset:37888
	ds_read_b128 v[216:219], v155 offset:38912
	ds_read_b128 v[240:243], v155 offset:39936
	global_load_lds_dwordx4 v[252:253], off
	v_lshl_add_u64 v[150:151], v[150:151], 0, v[130:131]
	s_mov_b32 m0, s54
	s_nop 0
	global_load_lds_dwordx4 v[150:151], off
	s_waitcnt vmcnt(8)
	s_waitcnt lgkmcnt(0)
	s_barrier
	s_setprio 1
	s_waitcnt lgkmcnt(0)
	v_mfma_f32_16x16x32_bf16 v[120:123], v[146:149], v[192:195], v[120:123]
	v_mfma_f32_16x16x32_bf16 v[124:127], v[160:163], v[192:195], v[124:127]
	v_mfma_f32_16x16x32_bf16 v[108:111], v[146:149], v[200:203], v[108:111]
	v_mfma_f32_16x16x32_bf16 v[104:107], v[160:163], v[200:203], v[104:107]
	v_mfma_f32_16x16x32_bf16 v[92:95], v[146:149], v[208:211], v[92:95]
	v_mfma_f32_16x16x32_bf16 v[88:91], v[160:163], v[208:211], v[88:91]
	v_mfma_f32_16x16x32_bf16 v[76:79], v[146:149], v[216:219], v[76:79]
	v_mfma_f32_16x16x32_bf16 v[72:75], v[160:163], v[216:219], v[72:75]
	v_mfma_f32_16x16x32_bf16 v[120:123], v[156:159], v[196:199], v[120:123]
	v_mfma_f32_16x16x32_bf16 v[124:127], v[164:167], v[196:199], v[124:127]
	v_mfma_f32_16x16x32_bf16 v[108:111], v[156:159], v[204:207], v[108:111]
	v_mfma_f32_16x16x32_bf16 v[104:107], v[164:167], v[204:207], v[104:107]
	v_mfma_f32_16x16x32_bf16 v[92:95], v[156:159], v[212:215], v[92:95]
	v_mfma_f32_16x16x32_bf16 v[88:91], v[164:167], v[212:215], v[88:91]
	v_mfma_f32_16x16x32_bf16 v[76:79], v[156:159], v[240:243], v[76:79]
	v_mfma_f32_16x16x32_bf16 v[72:75], v[164:167], v[240:243], v[72:75]
	s_setprio 0
	s_setprio 1
	v_mfma_f32_16x16x32_bf16 v[116:119], v[176:179], v[192:195], v[116:119]
	v_mfma_f32_16x16x32_bf16 v[112:115], v[184:187], v[192:195], v[112:115]
	v_mfma_f32_16x16x32_bf16 v[100:103], v[176:179], v[200:203], v[100:103]
	v_mfma_f32_16x16x32_bf16 v[96:99], v[184:187], v[200:203], v[96:99]
	v_mfma_f32_16x16x32_bf16 v[84:87], v[176:179], v[208:211], v[84:87]
	v_mfma_f32_16x16x32_bf16 v[80:83], v[184:187], v[208:211], v[80:83]
	v_mfma_f32_16x16x32_bf16 v[68:71], v[176:179], v[216:219], v[68:71]
	v_mfma_f32_16x16x32_bf16 v[64:67], v[184:187], v[216:219], v[64:67]
	v_mfma_f32_16x16x32_bf16 v[116:119], v[180:183], v[196:199], v[116:119]
	v_mfma_f32_16x16x32_bf16 v[112:115], v[188:191], v[196:199], v[112:115]
	v_mfma_f32_16x16x32_bf16 v[100:103], v[180:183], v[204:207], v[100:103]
	v_mfma_f32_16x16x32_bf16 v[96:99], v[188:191], v[204:207], v[96:99]
	v_mfma_f32_16x16x32_bf16 v[84:87], v[180:183], v[212:215], v[84:87]
	v_mfma_f32_16x16x32_bf16 v[80:83], v[188:191], v[212:215], v[80:83]
	v_mfma_f32_16x16x32_bf16 v[68:71], v[180:183], v[240:243], v[68:71]
	v_mfma_f32_16x16x32_bf16 v[64:67], v[188:191], v[240:243], v[64:67]
	s_setprio 0
	s_barrier
; #define PG8_STAGE(bufoff, gbase, voff) do { _Pragma("unroll") for (int _i = 0; _i < 2; ++_i) \
;         __builtin_amdgcn_global_load_lds((const unsigned*)((const char*)(gbase) + (voff)[_i]), (LAS unsigned*)(lds + (bufoff) + ldsw + _i * 8192), 16, 0, 0); } while (0)
; #define PG8_LDA(dst, b, h) do { _Pragma("unroll") for (int m = 0; m < 4; ++m) _Pragma("unroll") for (int k = 0; k < 2; ++k) dst[m][k] = *(const LAS bf16x8*)(lds + PG8_SA(b, h) + aoff + m * 2048 + k * 1024); } while (0)
; #define PG8_MMA(ai, bj, At, Bt) do { __builtin_amdgcn_s_setprio(1); _Pragma("unroll") for (int k = 0; k < 2; ++k) _Pragma("unroll") for (int m = 0; m < 4; ++m) _Pragma("unroll") for (int n = 0; n < 2; ++n) \
;         acc[ai][bj][m][n] = __builtin_amdgcn_mfma_f32_16x16x32_bf16(Bt[n][k], At[m][k], acc[ai][bj][m][n], 0, 0, 0); __builtin_amdgcn_s_setprio(0); } while (0)
; #define PG8_WAIT_V(n) asm volatile("s_waitcnt vmcnt(" #n ")" ::: "memory")
; #define PG8_WAIT_L(n) asm volatile("s_waitcnt lgkmcnt(" #n ")" ::: "memory")
; #define PG8_BAR __builtin_amdgcn_s_barrier()
; #define PG8_SCHED __builtin_amdgcn_sched_barrier(0)
; template <class Epi, bool ALIGN_EPI>
; __device__ __forceinline__ void gemm_phase(LAS unsigned char* lds, const Gemm g, const StaticOrder& S, const Epi& E, const int tid) {
;     ...
;             PG8_LDA(At, 1, 1); PG8_STAGE(PG8_SB(1, 0), b3, voffB); PG8_STAGE(PG8_SB(1, 1), b3 + hB, voffB); PG8_STAGE(PG8_SA(1, 0), a3, voffA);
;             PG8_WAIT_V(8); PG8_WAIT_L(0); PG8_BAR; PG8_MMA(1, 0, At, B0); PG8_MMA(1, 1, At, B1); PG8_BAR; PG8_SCHED;
;         }
	s_add_i32 s10, s10, s45
	v_lshl_add_u64 v[150:151], v[226:227], 0, s[92:93]
	s_mov_b32 m0, s10
	ds_read_b128 v[192:195], v155 offset:49152
	ds_read_b128 v[196:199], v155 offset:50176
	ds_read_b128 v[200:203], v155 offset:51200
	ds_read_b128 v[204:207], v155 offset:52224
	ds_read_b128 v[208:211], v155 offset:53248
	ds_read_b128 v[212:215], v155 offset:54272
	ds_read_b128 v[216:219], v155 offset:55296
	ds_read_b128 v[240:243], v155 offset:56320
	global_load_lds_dwordx4 v[150:151], off
	v_lshl_add_u64 v[150:151], v[244:245], 0, s[92:93]
	s_add_i32 m0, s10, 0x2000
	s_add_i32 s10, s65, s45
	global_load_lds_dwordx4 v[150:151], off
	v_lshl_add_u64 v[150:151], v[246:247], 0, s[92:93]
	s_mov_b32 m0, s10
	s_nop 0
	global_load_lds_dwordx4 v[150:151], off
	v_lshl_add_u64 v[150:151], v[220:221], 0, s[92:93]
	s_add_i32 m0, s10, 0x2000
	s_nop 0
	global_load_lds_dwordx4 v[150:151], off
	v_lshl_add_u64 v[150:151], v[248:249], 0, s[92:93]
	s_mov_b32 m0, s56
	s_nop 0
	global_load_lds_dwordx4 v[150:151], off
	v_lshl_add_u64 v[150:151], v[250:251], 0, s[92:93]
	s_mov_b32 m0, s57
	s_nop 0
	global_load_lds_dwordx4 v[150:151], off
	s_waitcnt vmcnt(8)
	s_waitcnt lgkmcnt(0)
	s_barrier
	s_setprio 1
	s_waitcnt lgkmcnt(0)
	v_mfma_f32_16x16x32_bf16 v[60:63], v[146:149], v[192:195], v[60:63]
	v_mfma_f32_16x16x32_bf16 v[56:59], v[160:163], v[192:195], v[56:59]
	v_mfma_f32_16x16x32_bf16 v[44:47], v[146:149], v[200:203], v[44:47]
	v_mfma_f32_16x16x32_bf16 v[40:43], v[160:163], v[200:203], v[40:43]
	v_mfma_f32_16x16x32_bf16 v[28:31], v[146:149], v[208:211], v[28:31]
	v_mfma_f32_16x16x32_bf16 v[24:27], v[160:163], v[208:211], v[24:27]
	v_mfma_f32_16x16x32_bf16 v[12:15], v[146:149], v[216:219], v[12:15]
	v_mfma_f32_16x16x32_bf16 v[8:11], v[160:163], v[216:219], v[8:11]
	v_mfma_f32_16x16x32_bf16 v[60:63], v[156:159], v[196:199], v[60:63]
	v_mfma_f32_16x16x32_bf16 v[56:59], v[164:167], v[196:199], v[56:59]
	v_mfma_f32_16x16x32_bf16 v[44:47], v[156:159], v[204:207], v[44:47]
	v_mfma_f32_16x16x32_bf16 v[40:43], v[164:167], v[204:207], v[40:43]
	v_mfma_f32_16x16x32_bf16 v[28:31], v[156:159], v[212:215], v[28:31]
	v_mfma_f32_16x16x32_bf16 v[24:27], v[164:167], v[212:215], v[24:27]
	v_mfma_f32_16x16x32_bf16 v[12:15], v[156:159], v[240:243], v[12:15]
	v_mfma_f32_16x16x32_bf16 v[8:11], v[164:167], v[240:243], v[8:11]
	s_setprio 0
	s_setprio 1
	v_mfma_f32_16x16x32_bf16 v[52:55], v[176:179], v[192:195], v[52:55]
	v_mfma_f32_16x16x32_bf16 v[48:51], v[184:187], v[192:195], v[48:51]
	v_mfma_f32_16x16x32_bf16 v[36:39], v[176:179], v[200:203], v[36:39]
	v_mfma_f32_16x16x32_bf16 v[32:35], v[184:187], v[200:203], v[32:35]
	v_mfma_f32_16x16x32_bf16 v[20:23], v[176:179], v[208:211], v[20:23]
	v_mfma_f32_16x16x32_bf16 v[16:19], v[184:187], v[208:211], v[16:19]
	v_mfma_f32_16x16x32_bf16 v[4:7], v[176:179], v[216:219], v[4:7]
	v_mfma_f32_16x16x32_bf16 v[0:3], v[184:187], v[216:219], v[0:3]
	v_mfma_f32_16x16x32_bf16 v[52:55], v[180:183], v[196:199], v[52:55]
	v_mfma_f32_16x16x32_bf16 v[48:51], v[188:191], v[196:199], v[48:51]
	v_mfma_f32_16x16x32_bf16 v[36:39], v[180:183], v[204:207], v[36:39]
	v_mfma_f32_16x16x32_bf16 v[32:35], v[188:191], v[204:207], v[32:35]
	v_mfma_f32_16x16x32_bf16 v[20:23], v[180:183], v[212:215], v[20:23]
	v_mfma_f32_16x16x32_bf16 v[16:19], v[188:191], v[212:215], v[16:19]
	v_mfma_f32_16x16x32_bf16 v[4:7], v[180:183], v[240:243], v[4:7]
	v_mfma_f32_16x16x32_bf16 v[0:3], v[188:191], v[240:243], v[0:3]
	s_setprio 0
	v_lshl_add_u64 v[142:143], v[142:143], 0, s[80:81]
	v_lshl_add_u64 v[144:145], v[144:145], 0, s[80:81]
	s_cmp_ge_u32 s11, s55
	s_mov_b32 s10, s11
	s_barrier
	s_cbranch_scc0 .LBB0_331

; __device__ __forceinline__ unsigned cvt_pk_bf16(float lo, float hi) { unsigned r; asm volatile("v_cvt_pk_bf16_f32 %0, %1, %2" : "=v"(r) : "v"(lo), "v"(hi)); return r; }
; __device__ __forceinline__ float gelu_tanh(float x) { const float u = 0.7978845608028654f * (x + 0.044715f * x * x * x); return x * fast_rcp(1.0f + fast_exp2(-2.0f * LOG2E * u)); }
; #define PG8_STAGE(bufoff, gbase, voff) do { _Pragma("unroll") for (int _i = 0; _i < 2; ++_i) \
;         __builtin_amdgcn_global_load_lds((const unsigned*)((const char*)(gbase) + (voff)[_i]), (LAS unsigned*)(lds + (bufoff) + ldsw + _i * 8192), 16, 0, 0); } while (0)
; #define PG8_LDA(dst, b, h) do { _Pragma("unroll") for (int m = 0; m < 4; ++m) _Pragma("unroll") for (int k = 0; k < 2; ++k) dst[m][k] = *(const LAS bf16x8*)(lds + PG8_SA(b, h) + aoff + m * 2048 + k * 1024); } while (0)
; #define PG8_LDB(dst, b, h) do { _Pragma("unroll") for (int n = 0; n < 2; ++n) _Pragma("unroll") for (int k = 0; k < 2; ++k) dst[n][k] = *(const LAS bf16x8*)(lds + PG8_SB(b, h) + boff + n * 2048 + k * 1024); } while (0)
; #define PG8_WAIT_V(n) asm volatile("s_waitcnt vmcnt(" #n ")" ::: "memory")
;     __device__ __forceinline__ void operator()(const f32x4 (&acc)[2][2][4][2], const Unit& u, int wr, int wc, int fr, int fq) const {
;     ...
;             for (int m = 0; m < 4; ++m) { const int row = row0 + ai * HALF + m * 16; bf16_t* rowp = O + (size_t)row * ldc + col0; const float rs = rsv[ai][m];
; #pragma unroll
;                 for (int bj = 0; bj < 2; ++bj) { f32x4 v0 = acc[ai][bj][m][0] * rs, v1 = acc[ai][bj][m][1] * rs;
;                     if (ACT == 1) {
; #pragma unroll
;                         for (int j = 0; j < 4; ++j) { v0[j] = gelu_tanh(v0[j]); v1[j] = gelu_tanh(v1[j]); } }
;                     u32x4 w; w.x = cvt_pk_bf16(v0[0], v0[1]); w.y = cvt_pk_bf16(v0[2], v0[3]); w.z = cvt_pk_bf16(v1[0], v1[1]); w.w = cvt_pk_bf16(v1[2], v1[3]);
;                     *(u32x4*)(rowp + bj * HALF) = w; } }
; template <class Epi, bool ALIGN_EPI>
; __device__ __forceinline__ void gemm_phase(LAS unsigned char* lds, const Gemm g, const StaticOrder& S, const Epi& E, const int tid) {
;     ...
;             PG8_LDB(B0, 0, 0); PG8_LDB(B1, 0, 1); PG8_SCHED; PG8_LDA(At, 0, 0); PG8_STAGE(PG8_SA(1, 1), a1 + hA, voffA);
;             PG8_WAIT_V(8); PG8_WAIT_L(0); PG8_BAR; PG8_MMA(0, 0, At, B0); PG8_MMA(0, 1, At, B1); PG8_BAR; PG8_SCHED;
.Lq5_first_epi:
	s_add_i32 s11, s10, 2
	s_cmp_eq_u32 s55, s10
	s_cselect_b64 vcc, -1, 0
	v_add_u32_e32 v148, s33, v149
	s_add_i32 s10, 0, 0x14000
	ds_read_b128 v[152:155], v148
	ds_read_b128 v[156:159], v148 offset:1024
	ds_read_b128 v[160:163], v148 offset:2048
	ds_read_b128 v[164:167], v148 offset:3072
	v_add_u32_e32 v148, s10, v149
	ds_read_b128 v[176:179], v148
	ds_read_b128 v[180:183], v148 offset:1024
	ds_read_b128 v[184:187], v148 offset:2048
	ds_read_b128 v[188:191], v148 offset:3072
	v_lshl_add_u64 v[146:147], v[142:143], 0, s[92:93]
	v_cndmask_b32_e32 v147, v147, v139, vcc
	v_cndmask_b32_e32 v146, v146, v138, vcc
	v_cndmask_b32_e32 v221, v145, v141, vcc
	v_cndmask_b32_e32 v220, v144, v140, vcc
	v_lshl_add_u64 v[244:245], v[142:143], 0, v[134:135]
	s_add_i32 m0, s25, 0xc000
	ds_read_b128 v[192:195], v151
	ds_read_b128 v[196:199], v151 offset:1024
	ds_read_b128 v[200:203], v151 offset:2048
	ds_read_b128 v[204:207], v151 offset:3072
	ds_read_b128 v[208:211], v151 offset:4096
	ds_read_b128 v[212:215], v151 offset:5120
	ds_read_b128 v[216:219], v151 offset:6144
	ds_read_b128 v[240:243], v151 offset:7168
	global_load_lds_dwordx4 v[244:245], off
	v_lshl_add_u64 v[244:245], v[142:143], 0, v[136:137]
	s_add_i32 m0, s25, 0xe000
	s_nop 0
	global_load_lds_dwordx4 v[244:245], off
	s_waitcnt vmcnt(16)
	s_waitcnt lgkmcnt(0)
	s_barrier
	s_setprio 1
	s_waitcnt lgkmcnt(0)
	v_mfma_f32_16x16x32_bf16 v[124:127], v[152:155], v[192:195], 0
	s_lshl_b32 s98, s28, 5
	s_mov_b32 s99, 0
	v_mul_f32_e32 v60, v238, v60
	v_mul_f32_e32 v61, v238, v61
	v_mfma_f32_16x16x32_bf16 v[120:123], v[160:163], v[192:195], 0
	v_mul_f32_e32 v62, v238, v62
	v_mul_f32_e32 v63, v238, v63
	v_mul_f32_e32 v56, v238, v56
	v_mul_f32_e32 v57, v238, v57
	v_mfma_f32_16x16x32_bf16 v[108:111], v[152:155], v[200:203], 0
	v_mul_f32_e32 v58, v238, v58
	v_mul_f32_e32 v59, v238, v59
	v_cvt_pk_bf16_f32 v60, v60, v61
	v_cvt_pk_bf16_f32 v61, v62, v63
	v_mfma_f32_16x16x32_bf16 v[104:107], v[160:163], v[200:203], 0
	v_cvt_pk_bf16_f32 v62, v56, v57
	v_cvt_pk_bf16_f32 v63, v58, v59
	global_store_dwordx4 v[232:233], v[60:63], off
	v_mul_f32_e32 v52, v238, v52
	v_mfma_f32_16x16x32_bf16 v[92:95], v[152:155], v[208:211], 0
	v_mul_f32_e32 v53, v238, v53
	v_mul_f32_e32 v54, v238, v54
	v_mul_f32_e32 v55, v238, v55
	v_mul_f32_e32 v48, v238, v48
	v_mfma_f32_16x16x32_bf16 v[88:91], v[160:163], v[208:211], 0
	v_mul_f32_e32 v49, v238, v49
	v_mul_f32_e32 v50, v238, v50
	v_mul_f32_e32 v51, v238, v51
	v_cvt_pk_bf16_f32 v52, v52, v53
	v_mfma_f32_16x16x32_bf16 v[76:79], v[152:155], v[216:219], 0
	v_cvt_pk_bf16_f32 v53, v54, v55
	v_cvt_pk_bf16_f32 v54, v48, v49
	v_cvt_pk_bf16_f32 v55, v50, v51
	global_store_dwordx4 v[232:233], v[52:55], off offset:256
	v_mfma_f32_16x16x32_bf16 v[72:75], v[160:163], v[216:219], 0
	v_lshl_add_u64 v[232:233], v[232:233], 0, s[98:99]
	v_mul_f32_e32 v44, v239, v44
	v_mul_f32_e32 v45, v239, v45
	v_mul_f32_e32 v46, v239, v46
	v_mfma_f32_16x16x32_bf16 v[124:127], v[156:159], v[196:199], v[124:127]
	v_mul_f32_e32 v47, v239, v47
	v_mul_f32_e32 v40, v239, v40
	v_mul_f32_e32 v41, v239, v41
	v_mul_f32_e32 v42, v239, v42
	v_mfma_f32_16x16x32_bf16 v[120:123], v[164:167], v[196:199], v[120:123]
	v_mul_f32_e32 v43, v239, v43
	v_cvt_pk_bf16_f32 v44, v44, v45
	v_cvt_pk_bf16_f32 v45, v46, v47
	v_cvt_pk_bf16_f32 v46, v40, v41
	v_mfma_f32_16x16x32_bf16 v[108:111], v[156:159], v[204:207], v[108:111]
	v_cvt_pk_bf16_f32 v47, v42, v43
	global_store_dwordx4 v[232:233], v[44:47], off
	v_mul_f32_e32 v36, v239, v36
	v_mul_f32_e32 v37, v239, v37
	v_mfma_f32_16x16x32_bf16 v[104:107], v[164:167], v[204:207], v[104:107]
	v_mul_f32_e32 v38, v239, v38
	v_mul_f32_e32 v39, v239, v39
	v_mul_f32_e32 v32, v239, v32
	v_mul_f32_e32 v33, v239, v33
	v_mfma_f32_16x16x32_bf16 v[92:95], v[156:159], v[212:215], v[92:95]
	v_mul_f32_e32 v34, v239, v34
	v_mul_f32_e32 v35, v239, v35
	v_cvt_pk_bf16_f32 v36, v36, v37
	v_cvt_pk_bf16_f32 v37, v38, v39
	v_mfma_f32_16x16x32_bf16 v[88:91], v[164:167], v[212:215], v[88:91]
	v_cvt_pk_bf16_f32 v38, v32, v33
	v_cvt_pk_bf16_f32 v39, v34, v35
	global_store_dwordx4 v[232:233], v[36:39], off offset:256
	v_lshl_add_u64 v[232:233], v[232:233], 0, s[98:99]
	v_mfma_f32_16x16x32_bf16 v[76:79], v[156:159], v[240:243], v[76:79]
	v_mul_f32_e32 v28, v230, v28
	v_mul_f32_e32 v29, v230, v29
	v_mul_f32_e32 v30, v230, v30
	v_mul_f32_e32 v31, v230, v31
	v_mfma_f32_16x16x32_bf16 v[72:75], v[164:167], v[240:243], v[72:75]
	v_mul_f32_e32 v24, v230, v24
	v_mul_f32_e32 v25, v230, v25
	v_mul_f32_e32 v26, v230, v26
	v_mul_f32_e32 v27, v230, v27
	s_setprio 0
	s_setprio 1
	v_mfma_f32_16x16x32_bf16 v[116:119], v[176:179], v[192:195], 0
	v_cvt_pk_bf16_f32 v28, v28, v29
	v_cvt_pk_bf16_f32 v29, v30, v31
	v_cvt_pk_bf16_f32 v30, v24, v25
	v_cvt_pk_bf16_f32 v31, v26, v27
	v_mfma_f32_16x16x32_bf16 v[112:115], v[184:187], v[192:195], 0
	global_store_dwordx4 v[232:233], v[28:31], off
	v_mul_f32_e32 v20, v230, v20
	v_mul_f32_e32 v21, v230, v21
	v_mul_f32_e32 v22, v230, v22
	v_mfma_f32_16x16x32_bf16 v[100:103], v[176:179], v[200:203], 0
	v_mul_f32_e32 v23, v230, v23
	v_mul_f32_e32 v16, v230, v16
	v_mul_f32_e32 v17, v230, v17
	v_mul_f32_e32 v18, v230, v18
	v_mfma_f32_16x16x32_bf16 v[96:99], v[184:187], v[200:203], 0
	v_mul_f32_e32 v19, v230, v19
	v_cvt_pk_bf16_f32 v20, v20, v21
	v_cvt_pk_bf16_f32 v21, v22, v23
	v_cvt_pk_bf16_f32 v22, v16, v17
	v_mfma_f32_16x16x32_bf16 v[84:87], v[176:179], v[208:211], 0
	v_cvt_pk_bf16_f32 v23, v18, v19
	global_store_dwordx4 v[232:233], v[20:23], off offset:256
	v_lshl_add_u64 v[232:233], v[232:233], 0, s[98:99]
	v_mul_f32_e32 v12, v231, v12
	v_mfma_f32_16x16x32_bf16 v[80:83], v[184:187], v[208:211], 0
; __device__ __forceinline__ unsigned cvt_pk_bf16(float lo, float hi) { unsigned r; asm volatile("v_cvt_pk_bf16_f32 %0, %1, %2" : "=v"(r) : "v"(lo), "v"(hi)); return r; }
; __device__ __forceinline__ float gelu_tanh(float x) { const float u = 0.7978845608028654f * (x + 0.044715f * x * x * x); return x * fast_rcp(1.0f + fast_exp2(-2.0f * LOG2E * u)); }
; #define PG8_STAGE(bufoff, gbase, voff) do { _Pragma("unroll") for (int _i = 0; _i < 2; ++_i) \
;         __builtin_amdgcn_global_load_lds((const unsigned*)((const char*)(gbase) + (voff)[_i]), (LAS unsigned*)(lds + (bufoff) + ldsw + _i * 8192), 16, 0, 0); } while (0)
; #define PG8_LDA(dst, b, h) do { _Pragma("unroll") for (int m = 0; m < 4; ++m) _Pragma("unroll") for (int k = 0; k < 2; ++k) dst[m][k] = *(const LAS bf16x8*)(lds + PG8_SA(b, h) + aoff + m * 2048 + k * 1024); } while (0)
; #define PG8_BAR __builtin_amdgcn_s_barrier()
;     __device__ __forceinline__ void operator()(const f32x4 (&acc)[2][2][4][2], const Unit& u, int wr, int wc, int fr, int fq) const {
;     ...
;             for (int m = 0; m < 4; ++m) { const int row = row0 + ai * HALF + m * 16; bf16_t* rowp = O + (size_t)row * ldc + col0; const float rs = rsv[ai][m];
; #pragma unroll
;                 for (int bj = 0; bj < 2; ++bj) { f32x4 v0 = acc[ai][bj][m][0] * rs, v1 = acc[ai][bj][m][1] * rs;
;                     if (ACT == 1) {
; #pragma unroll
;                         for (int j = 0; j < 4; ++j) { v0[j] = gelu_tanh(v0[j]); v1[j] = gelu_tanh(v1[j]); } }
;                     u32x4 w; w.x = cvt_pk_bf16(v0[0], v0[1]); w.y = cvt_pk_bf16(v0[2], v0[3]); w.z = cvt_pk_bf16(v1[0], v1[1]); w.w = cvt_pk_bf16(v1[2], v1[3]);
;                     *(u32x4*)(rowp + bj * HALF) = w; } }
; template <class Epi, bool ALIGN_EPI>
; __device__ __forceinline__ void gemm_phase(LAS unsigned char* lds, const Gemm g, const StaticOrder& S, const Epi& E, const int tid) {
;     ...
;             PG8_WAIT_V(8); PG8_WAIT_L(0); PG8_BAR; PG8_MMA(0, 0, At, B0); PG8_MMA(0, 1, At, B1); PG8_BAR; PG8_SCHED;
;             PG8_LDA(At, 0, 1); PG8_STAGE(PG8_SB(0, 0), b2, voffB); PG8_STAGE(PG8_SB(0, 1), b2 + hB, voffB); PG8_STAGE(PG8_SA(0, 0), a2, voffA);
;             PG8_WAIT_V(8); PG8_WAIT_L(0); PG8_BAR; PG8_MMA(1, 0, At, B0); PG8_MMA(1, 1, At, B1); PG8_BAR; PG8_SCHED;
;             PG8_LDB(B0, 1, 0); PG8_LDB(B1, 1, 1); PG8_SCHED; PG8_LDA(At, 1, 0); PG8_STAGE(PG8_SA(0, 1), a2 + hA, voffA);
	v_mul_f32_e32 v13, v231, v13
	v_mul_f32_e32 v14, v231, v14
	v_mul_f32_e32 v15, v231, v15
	v_mul_f32_e32 v8, v231, v8
	v_mfma_f32_16x16x32_bf16 v[68:71], v[176:179], v[216:219], 0
	v_mul_f32_e32 v9, v231, v9
	v_mul_f32_e32 v10, v231, v10
	v_mul_f32_e32 v11, v231, v11
	v_cvt_pk_bf16_f32 v12, v12, v13
	v_mfma_f32_16x16x32_bf16 v[64:67], v[184:187], v[216:219], 0
	v_cvt_pk_bf16_f32 v13, v14, v15
	v_cvt_pk_bf16_f32 v14, v8, v9
	v_cvt_pk_bf16_f32 v15, v10, v11
	global_store_dwordx4 v[232:233], v[12:15], off
	v_mfma_f32_16x16x32_bf16 v[116:119], v[180:183], v[196:199], v[116:119]
	v_mul_f32_e32 v4, v231, v4
	v_mul_f32_e32 v5, v231, v5
	v_mul_f32_e32 v6, v231, v6
	v_mul_f32_e32 v7, v231, v7
	v_mfma_f32_16x16x32_bf16 v[112:115], v[188:191], v[196:199], v[112:115]
	v_mul_f32_e32 v0, v231, v0
	v_mul_f32_e32 v1, v231, v1
	v_mul_f32_e32 v2, v231, v2
	v_mul_f32_e32 v3, v231, v3
	v_mfma_f32_16x16x32_bf16 v[100:103], v[180:183], v[204:207], v[100:103]
	v_cvt_pk_bf16_f32 v4, v4, v5
	v_cvt_pk_bf16_f32 v5, v6, v7
	v_cvt_pk_bf16_f32 v6, v0, v1
	v_cvt_pk_bf16_f32 v7, v2, v3
	v_mfma_f32_16x16x32_bf16 v[96:99], v[188:191], v[204:207], v[96:99]
	global_store_dwordx4 v[232:233], v[4:7], off offset:256
	v_mfma_f32_16x16x32_bf16 v[84:87], v[180:183], v[212:215], v[84:87]
	v_mfma_f32_16x16x32_bf16 v[80:83], v[188:191], v[212:215], v[80:83]
	v_mfma_f32_16x16x32_bf16 v[68:71], v[180:183], v[240:243], v[68:71]
	v_mfma_f32_16x16x32_bf16 v[64:67], v[188:191], v[240:243], v[64:67]
	s_setprio 0
	s_barrier
	s_add_i32 s62, s33, s45
	v_lshl_add_u64 v[244:245], v[220:221], 0, v[168:169]
	s_mov_b32 m0, s62
	ds_read_b128 v[192:195], v151 offset:16384
	ds_read_b128 v[196:199], v151 offset:17408
	ds_read_b128 v[200:203], v151 offset:18432
	ds_read_b128 v[204:207], v151 offset:19456
	ds_read_b128 v[208:211], v151 offset:20480
	ds_read_b128 v[212:215], v151 offset:21504
	ds_read_b128 v[216:219], v151 offset:22528
	ds_read_b128 v[240:243], v151 offset:23552
	global_load_lds_dwordx4 v[244:245], off
	v_lshl_add_u64 v[246:247], v[220:221], 0, v[128:129]
	s_add_i32 m0, s62, 0x2000
	v_lshl_add_u64 v[220:221], v[220:221], 0, s[12:13]
	s_add_i32 s10, s10, s45
	global_load_lds_dwordx4 v[246:247], off
	v_lshl_add_u64 v[248:249], v[220:221], 0, v[168:169]
	s_mov_b32 m0, s10
	v_lshl_add_u64 v[220:221], v[220:221], 0, v[128:129]
	global_load_lds_dwordx4 v[248:249], off
	s_add_i32 m0, s10, 0x2000
	v_lshl_add_u64 v[250:251], v[146:147], 0, v[132:133]
	global_load_lds_dwordx4 v[220:221], off
	s_mov_b32 m0, s25
	v_lshl_add_u64 v[252:253], v[146:147], 0, v[130:131]
	global_load_lds_dwordx4 v[250:251], off
	s_mov_b32 m0, s50
	s_nop 0
	global_load_lds_dwordx4 v[252:253], off
	s_waitcnt vmcnt(24)
	s_waitcnt lgkmcnt(0)
	s_barrier
	s_setprio 1
	s_waitcnt lgkmcnt(0)
	v_mfma_f32_16x16x32_bf16 v[60:63], v[152:155], v[192:195], 0
	v_mfma_f32_16x16x32_bf16 v[56:59], v[160:163], v[192:195], 0
	v_mfma_f32_16x16x32_bf16 v[44:47], v[152:155], v[200:203], 0
	v_mfma_f32_16x16x32_bf16 v[40:43], v[160:163], v[200:203], 0
	v_mfma_f32_16x16x32_bf16 v[28:31], v[152:155], v[208:211], 0
	v_mfma_f32_16x16x32_bf16 v[24:27], v[160:163], v[208:211], 0
	v_mfma_f32_16x16x32_bf16 v[12:15], v[152:155], v[216:219], 0
	v_mfma_f32_16x16x32_bf16 v[8:11], v[160:163], v[216:219], 0
	v_mfma_f32_16x16x32_bf16 v[60:63], v[156:159], v[196:199], v[60:63]
	v_mfma_f32_16x16x32_bf16 v[56:59], v[164:167], v[196:199], v[56:59]
	v_mfma_f32_16x16x32_bf16 v[44:47], v[156:159], v[204:207], v[44:47]
	v_mfma_f32_16x16x32_bf16 v[40:43], v[164:167], v[204:207], v[40:43]
	v_mfma_f32_16x16x32_bf16 v[28:31], v[156:159], v[212:215], v[28:31]
	v_mfma_f32_16x16x32_bf16 v[24:27], v[164:167], v[212:215], v[24:27]
	v_mfma_f32_16x16x32_bf16 v[12:15], v[156:159], v[240:243], v[12:15]
	v_mfma_f32_16x16x32_bf16 v[8:11], v[164:167], v[240:243], v[8:11]
	s_setprio 0
	s_setprio 1
	v_mfma_f32_16x16x32_bf16 v[52:55], v[176:179], v[192:195], 0
	v_mfma_f32_16x16x32_bf16 v[48:51], v[184:187], v[192:195], 0
	v_mfma_f32_16x16x32_bf16 v[36:39], v[176:179], v[200:203], 0
	v_mfma_f32_16x16x32_bf16 v[32:35], v[184:187], v[200:203], 0
	v_mfma_f32_16x16x32_bf16 v[20:23], v[176:179], v[208:211], 0
	v_mfma_f32_16x16x32_bf16 v[16:19], v[184:187], v[208:211], 0
	v_mfma_f32_16x16x32_bf16 v[4:7], v[176:179], v[216:219], 0
	v_mfma_f32_16x16x32_bf16 v[0:3], v[184:187], v[216:219], 0
	v_mfma_f32_16x16x32_bf16 v[52:55], v[180:183], v[196:199], v[52:55]
	v_mfma_f32_16x16x32_bf16 v[48:51], v[188:191], v[196:199], v[48:51]
	v_mfma_f32_16x16x32_bf16 v[36:39], v[180:183], v[204:207], v[36:39]
	v_mfma_f32_16x16x32_bf16 v[32:35], v[188:191], v[204:207], v[32:35]
	v_mfma_f32_16x16x32_bf16 v[20:23], v[180:183], v[212:215], v[20:23]
	v_mfma_f32_16x16x32_bf16 v[16:19], v[188:191], v[212:215], v[16:19]
	v_mfma_f32_16x16x32_bf16 v[4:7], v[180:183], v[240:243], v[4:7]
	v_mfma_f32_16x16x32_bf16 v[0:3], v[188:191], v[240:243], v[0:3]
	s_setprio 0
	s_barrier
	s_add_i32 s10, 0, 0x18000
	v_add_u32_e32 v148, s10, v149
	s_add_i32 s62, 0, 0x1c000
	ds_read_b128 v[152:155], v148
	ds_read_b128 v[156:159], v148 offset:1024
	ds_read_b128 v[160:163], v148 offset:2048
	ds_read_b128 v[164:167], v148 offset:3072
	v_add_u32_e32 v148, s62, v149
	ds_read_b128 v[176:179], v148
	ds_read_b128 v[180:183], v148 offset:1024
	ds_read_b128 v[184:187], v148 offset:2048
	ds_read_b128 v[188:191], v148 offset:3072
	v_lshl_add_u64 v[146:147], v[146:147], 0, s[94:95]
	s_mov_b32 m0, s51
	v_lshl_add_u64 v[226:227], v[146:147], 0, v[132:133]
	ds_read_b128 v[192:195], v151 offset:32768
	ds_read_b128 v[196:199], v151 offset:33792
	ds_read_b128 v[200:203], v151 offset:34816
	ds_read_b128 v[204:207], v151 offset:35840
	ds_read_b128 v[208:211], v151 offset:36864
	ds_read_b128 v[212:215], v151 offset:37888
	ds_read_b128 v[216:219], v151 offset:38912
	ds_read_b128 v[240:243], v151 offset:39936
	global_load_lds_dwordx4 v[226:227], off
	v_lshl_add_u64 v[146:147], v[146:147], 0, v[130:131]
	s_mov_b32 m0, s52
	s_nop 0
	global_load_lds_dwordx4 v[146:147], off
	s_waitcnt vmcnt(16)
	s_waitcnt lgkmcnt(0)
	s_barrier
; #define PG8_STAGE(bufoff, gbase, voff) do { _Pragma("unroll") for (int _i = 0; _i < 2; ++_i) \
;         __builtin_amdgcn_global_load_lds((const unsigned*)((const char*)(gbase) + (voff)[_i]), (LAS unsigned*)(lds + (bufoff) + ldsw + _i * 8192), 16, 0, 0); } while (0)
; #define PG8_LDA(dst, b, h) do { _Pragma("unroll") for (int m = 0; m < 4; ++m) _Pragma("unroll") for (int k = 0; k < 2; ++k) dst[m][k] = *(const LAS bf16x8*)(lds + PG8_SA(b, h) + aoff + m * 2048 + k * 1024); } while (0)
; #define PG8_LDB(dst, b, h) do { _Pragma("unroll") for (int n = 0; n < 2; ++n) _Pragma("unroll") for (int k = 0; k < 2; ++k) dst[n][k] = *(const LAS bf16x8*)(lds + PG8_SB(b, h) + boff + n * 2048 + k * 1024); } while (0)
; #define PG8_MMA(ai, bj, At, Bt) do { __builtin_amdgcn_s_setprio(1); _Pragma("unroll") for (int k = 0; k < 2; ++k) _Pragma("unroll") for (int m = 0; m < 4; ++m) _Pragma("unroll") for (int n = 0; n < 2; ++n) \
;         acc[ai][bj][m][n] = __builtin_amdgcn_mfma_f32_16x16x32_bf16(Bt[n][k], At[m][k], acc[ai][bj][m][n], 0, 0, 0); __builtin_amdgcn_s_setprio(0); } while (0)
; #define PG8_WAIT_V(n) asm volatile("s_waitcnt vmcnt(" #n ")" ::: "memory")
; #define PG8_WAIT_L(n) asm volatile("s_waitcnt lgkmcnt(" #n ")" ::: "memory")
; #define PG8_BAR __builtin_amdgcn_s_barrier()
; #define PG8_SCHED __builtin_amdgcn_sched_barrier(0)
; template <class Epi, bool ALIGN_EPI>
; __device__ __forceinline__ void gemm_phase(LAS unsigned char* lds, const Gemm g, const StaticOrder& S, const Epi& E, const int tid) {
;     ...
;             PG8_LDB(B0, 1, 0); PG8_LDB(B1, 1, 1); PG8_SCHED; PG8_LDA(At, 1, 0); PG8_STAGE(PG8_SA(0, 1), a2 + hA, voffA);
;             PG8_WAIT_V(8); PG8_WAIT_L(0); PG8_BAR; PG8_MMA(0, 0, At, B0); PG8_MMA(0, 1, At, B1); PG8_BAR; PG8_SCHED;
;             PG8_LDA(At, 1, 1); PG8_STAGE(PG8_SB(1, 0), b3, voffB); PG8_STAGE(PG8_SB(1, 1), b3 + hB, voffB); PG8_STAGE(PG8_SA(1, 0), a3, voffA);
;             PG8_WAIT_V(8); PG8_WAIT_L(0); PG8_BAR; PG8_MMA(1, 0, At, B0); PG8_MMA(1, 1, At, B1); PG8_BAR; PG8_SCHED;
;         }
	s_setprio 1
	s_waitcnt lgkmcnt(0)
	v_mfma_f32_16x16x32_bf16 v[124:127], v[152:155], v[192:195], v[124:127]
	v_mfma_f32_16x16x32_bf16 v[120:123], v[160:163], v[192:195], v[120:123]
	v_mfma_f32_16x16x32_bf16 v[108:111], v[152:155], v[200:203], v[108:111]
	v_mfma_f32_16x16x32_bf16 v[104:107], v[160:163], v[200:203], v[104:107]
	v_mfma_f32_16x16x32_bf16 v[92:95], v[152:155], v[208:211], v[92:95]
	v_mfma_f32_16x16x32_bf16 v[88:91], v[160:163], v[208:211], v[88:91]
	v_mfma_f32_16x16x32_bf16 v[76:79], v[152:155], v[216:219], v[76:79]
	v_mfma_f32_16x16x32_bf16 v[72:75], v[160:163], v[216:219], v[72:75]
	v_mfma_f32_16x16x32_bf16 v[124:127], v[156:159], v[196:199], v[124:127]
	v_mfma_f32_16x16x32_bf16 v[120:123], v[164:167], v[196:199], v[120:123]
	v_mfma_f32_16x16x32_bf16 v[108:111], v[156:159], v[204:207], v[108:111]
	v_mfma_f32_16x16x32_bf16 v[104:107], v[164:167], v[204:207], v[104:107]
	v_mfma_f32_16x16x32_bf16 v[92:95], v[156:159], v[212:215], v[92:95]
	v_mfma_f32_16x16x32_bf16 v[88:91], v[164:167], v[212:215], v[88:91]
	v_mfma_f32_16x16x32_bf16 v[76:79], v[156:159], v[240:243], v[76:79]
	v_mfma_f32_16x16x32_bf16 v[72:75], v[164:167], v[240:243], v[72:75]
	s_setprio 0
	s_setprio 1
	v_mfma_f32_16x16x32_bf16 v[116:119], v[176:179], v[192:195], v[116:119]
	v_mfma_f32_16x16x32_bf16 v[112:115], v[184:187], v[192:195], v[112:115]
	v_mfma_f32_16x16x32_bf16 v[100:103], v[176:179], v[200:203], v[100:103]
	v_mfma_f32_16x16x32_bf16 v[96:99], v[184:187], v[200:203], v[96:99]
	v_mfma_f32_16x16x32_bf16 v[84:87], v[176:179], v[208:211], v[84:87]
	v_mfma_f32_16x16x32_bf16 v[80:83], v[184:187], v[208:211], v[80:83]
	v_mfma_f32_16x16x32_bf16 v[68:71], v[176:179], v[216:219], v[68:71]
	v_mfma_f32_16x16x32_bf16 v[64:67], v[184:187], v[216:219], v[64:67]
	v_mfma_f32_16x16x32_bf16 v[116:119], v[180:183], v[196:199], v[116:119]
	v_mfma_f32_16x16x32_bf16 v[112:115], v[188:191], v[196:199], v[112:115]
	v_mfma_f32_16x16x32_bf16 v[100:103], v[180:183], v[204:207], v[100:103]
	v_mfma_f32_16x16x32_bf16 v[96:99], v[188:191], v[204:207], v[96:99]
	v_mfma_f32_16x16x32_bf16 v[84:87], v[180:183], v[212:215], v[84:87]
	v_mfma_f32_16x16x32_bf16 v[80:83], v[188:191], v[212:215], v[80:83]
	v_mfma_f32_16x16x32_bf16 v[68:71], v[180:183], v[240:243], v[68:71]
	v_mfma_f32_16x16x32_bf16 v[64:67], v[188:191], v[240:243], v[64:67]
	s_setprio 0
	s_barrier
	s_add_i32 s10, s10, s45
	v_lshl_add_u64 v[146:147], v[244:245], 0, s[92:93]
	s_mov_b32 m0, s10
	ds_read_b128 v[192:195], v151 offset:49152
	ds_read_b128 v[196:199], v151 offset:50176
	ds_read_b128 v[200:203], v151 offset:51200
	ds_read_b128 v[204:207], v151 offset:52224
	ds_read_b128 v[208:211], v151 offset:53248
	ds_read_b128 v[212:215], v151 offset:54272
	ds_read_b128 v[216:219], v151 offset:55296
	ds_read_b128 v[240:243], v151 offset:56320
	global_load_lds_dwordx4 v[146:147], off
	v_lshl_add_u64 v[146:147], v[246:247], 0, s[92:93]
	s_add_i32 m0, s10, 0x2000
	s_add_i32 s10, s62, s45
	global_load_lds_dwordx4 v[146:147], off
	v_lshl_add_u64 v[146:147], v[248:249], 0, s[92:93]
	s_mov_b32 m0, s10
	s_nop 0
	global_load_lds_dwordx4 v[146:147], off
	v_lshl_add_u64 v[146:147], v[220:221], 0, s[92:93]
	s_add_i32 m0, s10, 0x2000
	s_nop 0
	global_load_lds_dwordx4 v[146:147], off
	v_lshl_add_u64 v[146:147], v[250:251], 0, s[92:93]
	s_mov_b32 m0, s53
	s_nop 0
	global_load_lds_dwordx4 v[146:147], off
	v_lshl_add_u64 v[146:147], v[252:253], 0, s[92:93]
	s_mov_b32 m0, s54
	s_nop 0
	global_load_lds_dwordx4 v[146:147], off
	s_waitcnt vmcnt(8)
	s_waitcnt lgkmcnt(0)
	s_barrier
	s_setprio 1
	s_waitcnt lgkmcnt(0)
	v_mfma_f32_16x16x32_bf16 v[60:63], v[152:155], v[192:195], v[60:63]
	v_mfma_f32_16x16x32_bf16 v[56:59], v[160:163], v[192:195], v[56:59]
	v_mfma_f32_16x16x32_bf16 v[44:47], v[152:155], v[200:203], v[44:47]
	v_mfma_f32_16x16x32_bf16 v[40:43], v[160:163], v[200:203], v[40:43]
	v_mfma_f32_16x16x32_bf16 v[28:31], v[152:155], v[208:211], v[28:31]
	v_mfma_f32_16x16x32_bf16 v[24:27], v[160:163], v[208:211], v[24:27]
	v_mfma_f32_16x16x32_bf16 v[12:15], v[152:155], v[216:219], v[12:15]
	v_mfma_f32_16x16x32_bf16 v[8:11], v[160:163], v[216:219], v[8:11]
	v_mfma_f32_16x16x32_bf16 v[60:63], v[156:159], v[196:199], v[60:63]
	v_mfma_f32_16x16x32_bf16 v[56:59], v[164:167], v[196:199], v[56:59]
	v_mfma_f32_16x16x32_bf16 v[44:47], v[156:159], v[204:207], v[44:47]
	v_mfma_f32_16x16x32_bf16 v[40:43], v[164:167], v[204:207], v[40:43]
	v_mfma_f32_16x16x32_bf16 v[28:31], v[156:159], v[212:215], v[28:31]
	v_mfma_f32_16x16x32_bf16 v[24:27], v[164:167], v[212:215], v[24:27]
	v_mfma_f32_16x16x32_bf16 v[12:15], v[156:159], v[240:243], v[12:15]
	v_mfma_f32_16x16x32_bf16 v[8:11], v[164:167], v[240:243], v[8:11]
	s_setprio 0
	s_setprio 1
	v_mfma_f32_16x16x32_bf16 v[52:55], v[176:179], v[192:195], v[52:55]
	v_mfma_f32_16x16x32_bf16 v[48:51], v[184:187], v[192:195], v[48:51]
	v_mfma_f32_16x16x32_bf16 v[36:39], v[176:179], v[200:203], v[36:39]
	v_mfma_f32_16x16x32_bf16 v[32:35], v[184:187], v[200:203], v[32:35]
	v_mfma_f32_16x16x32_bf16 v[20:23], v[176:179], v[208:211], v[20:23]
	v_mfma_f32_16x16x32_bf16 v[16:19], v[184:187], v[208:211], v[16:19]
	v_mfma_f32_16x16x32_bf16 v[4:7], v[176:179], v[216:219], v[4:7]
	v_mfma_f32_16x16x32_bf16 v[0:3], v[184:187], v[216:219], v[0:3]
	v_mfma_f32_16x16x32_bf16 v[52:55], v[180:183], v[196:199], v[52:55]
	v_mfma_f32_16x16x32_bf16 v[48:51], v[188:191], v[196:199], v[48:51]
	v_mfma_f32_16x16x32_bf16 v[36:39], v[180:183], v[204:207], v[36:39]
	v_mfma_f32_16x16x32_bf16 v[32:35], v[188:191], v[204:207], v[32:35]
	v_mfma_f32_16x16x32_bf16 v[20:23], v[180:183], v[212:215], v[20:23]
	v_mfma_f32_16x16x32_bf16 v[16:19], v[188:191], v[212:215], v[16:19]
	v_mfma_f32_16x16x32_bf16 v[4:7], v[180:183], v[240:243], v[4:7]
	v_mfma_f32_16x16x32_bf16 v[0:3], v[188:191], v[240:243], v[0:3]
	s_setprio 0
	v_lshl_add_u64 v[142:143], v[142:143], 0, s[80:81]
	v_lshl_add_u64 v[144:145], v[144:145], 0, s[80:81]
	s_mov_b32 s10, s11
	s_cmp_eq_u32 s10, s55
	s_barrier
	s_cbranch_scc1 .Lq5_last
	s_branch .LBB0_354
; #define PG8_STAGE(bufoff, gbase, voff) do { _Pragma("unroll") for (int _i = 0; _i < 2; ++_i) \
;         __builtin_amdgcn_global_load_lds((const unsigned*)((const char*)(gbase) + (voff)[_i]), (LAS unsigned*)(lds + (bufoff) + ldsw + _i * 8192), 16, 0, 0); } while (0)
; #define PG8_LDA(dst, b, h) do { _Pragma("unroll") for (int m = 0; m < 4; ++m) _Pragma("unroll") for (int k = 0; k < 2; ++k) dst[m][k] = *(const LAS bf16x8*)(lds + PG8_SA(b, h) + aoff + m * 2048 + k * 1024); } while (0)
; #define PG8_LDB(dst, b, h) do { _Pragma("unroll") for (int n = 0; n < 2; ++n) _Pragma("unroll") for (int k = 0; k < 2; ++k) dst[n][k] = *(const LAS bf16x8*)(lds + PG8_SB(b, h) + boff + n * 2048 + k * 1024); } while (0)
; #define PG8_MMA(ai, bj, At, Bt) do { __builtin_amdgcn_s_setprio(1); _Pragma("unroll") for (int k = 0; k < 2; ++k) _Pragma("unroll") for (int m = 0; m < 4; ++m) _Pragma("unroll") for (int n = 0; n < 2; ++n) \
;         acc[ai][bj][m][n] = __builtin_amdgcn_mfma_f32_16x16x32_bf16(Bt[n][k], At[m][k], acc[ai][bj][m][n], 0, 0, 0); __builtin_amdgcn_s_setprio(0); } while (0)
; #define PG8_WAIT_V(n) asm volatile("s_waitcnt vmcnt(" #n ")" ::: "memory")
; #define PG8_WAIT_L(n) asm volatile("s_waitcnt lgkmcnt(" #n ")" ::: "memory")
; #define PG8_BAR __builtin_amdgcn_s_barrier()
; #define PG8_SCHED __builtin_amdgcn_sched_barrier(0)
; template <class Epi, bool ALIGN_EPI>
; __device__ __forceinline__ void gemm_phase(LAS unsigned char* lds, const Gemm g, const StaticOrder& S, const Epi& E, const int tid) {
;     ...
;             const bool last = (t == nt - 2);
;             const char* a1 = cA + (size_t)(t + 1) * kstep;
;             const char* a2 = last ? nA : cA + (size_t)(t + 2) * kstep; const char* b2 = last ? nB : cB + (size_t)(t + 2) * kstep;
;             const char* a3 = a2 + kstep; const char* b3 = b2 + kstep;
;             PG8_LDB(B0, 0, 0); PG8_LDB(B1, 0, 1); PG8_SCHED; PG8_LDA(At, 0, 0); PG8_STAGE(PG8_SA(1, 1), a1 + hA, voffA);
;             PG8_WAIT_V(8); PG8_WAIT_L(0); PG8_BAR; PG8_MMA(0, 0, At, B0); PG8_MMA(0, 1, At, B1); PG8_BAR; PG8_SCHED;
;             PG8_LDA(At, 0, 1); PG8_STAGE(PG8_SB(0, 0), b2, voffB); PG8_STAGE(PG8_SB(0, 1), b2 + hB, voffB); PG8_STAGE(PG8_SA(0, 0), a2, voffA);
;             PG8_WAIT_V(8); PG8_WAIT_L(0); PG8_BAR; PG8_MMA(1, 0, At, B0); PG8_MMA(1, 1, At, B1); PG8_BAR; PG8_SCHED;
.Lq5_first:
	s_add_i32 s11, s10, 2
	s_cmp_eq_u32 s55, s10
	s_cselect_b64 vcc, -1, 0
	v_add_u32_e32 v148, s33, v149
	s_add_i32 s10, 0, 0x14000
	ds_read_b128 v[152:155], v148
	ds_read_b128 v[156:159], v148 offset:1024
	ds_read_b128 v[160:163], v148 offset:2048
	ds_read_b128 v[164:167], v148 offset:3072
	v_add_u32_e32 v148, s10, v149
	ds_read_b128 v[176:179], v148
	ds_read_b128 v[180:183], v148 offset:1024
	ds_read_b128 v[184:187], v148 offset:2048
	ds_read_b128 v[188:191], v148 offset:3072
	v_lshl_add_u64 v[146:147], v[142:143], 0, s[92:93]
	v_cndmask_b32_e32 v147, v147, v139, vcc
	v_cndmask_b32_e32 v146, v146, v138, vcc
	v_cndmask_b32_e32 v221, v145, v141, vcc
	v_cndmask_b32_e32 v220, v144, v140, vcc
	v_lshl_add_u64 v[244:245], v[142:143], 0, v[134:135]
	s_add_i32 m0, s25, 0xc000
	ds_read_b128 v[192:195], v151
	ds_read_b128 v[196:199], v151 offset:1024
	ds_read_b128 v[200:203], v151 offset:2048
	ds_read_b128 v[204:207], v151 offset:3072
	ds_read_b128 v[208:211], v151 offset:4096
	ds_read_b128 v[212:215], v151 offset:5120
	ds_read_b128 v[216:219], v151 offset:6144
	ds_read_b128 v[240:243], v151 offset:7168
	global_load_lds_dwordx4 v[244:245], off
	v_lshl_add_u64 v[244:245], v[142:143], 0, v[136:137]
	s_add_i32 m0, s25, 0xe000
	s_nop 0
	global_load_lds_dwordx4 v[244:245], off
	s_waitcnt vmcnt(8)
	s_waitcnt lgkmcnt(0)
	s_barrier
	s_setprio 1
	s_waitcnt lgkmcnt(0)
	v_mfma_f32_16x16x32_bf16 v[124:127], v[152:155], v[192:195], 0
	v_mfma_f32_16x16x32_bf16 v[120:123], v[160:163], v[192:195], 0
	v_mfma_f32_16x16x32_bf16 v[108:111], v[152:155], v[200:203], 0
	v_mfma_f32_16x16x32_bf16 v[104:107], v[160:163], v[200:203], 0
	v_mfma_f32_16x16x32_bf16 v[92:95], v[152:155], v[208:211], 0
	v_mfma_f32_16x16x32_bf16 v[88:91], v[160:163], v[208:211], 0
	v_mfma_f32_16x16x32_bf16 v[76:79], v[152:155], v[216:219], 0
	v_mfma_f32_16x16x32_bf16 v[72:75], v[160:163], v[216:219], 0
	v_mfma_f32_16x16x32_bf16 v[124:127], v[156:159], v[196:199], v[124:127]
	v_mfma_f32_16x16x32_bf16 v[120:123], v[164:167], v[196:199], v[120:123]
	v_mfma_f32_16x16x32_bf16 v[108:111], v[156:159], v[204:207], v[108:111]
	v_mfma_f32_16x16x32_bf16 v[104:107], v[164:167], v[204:207], v[104:107]
	v_mfma_f32_16x16x32_bf16 v[92:95], v[156:159], v[212:215], v[92:95]
	v_mfma_f32_16x16x32_bf16 v[88:91], v[164:167], v[212:215], v[88:91]
	v_mfma_f32_16x16x32_bf16 v[76:79], v[156:159], v[240:243], v[76:79]
	v_mfma_f32_16x16x32_bf16 v[72:75], v[164:167], v[240:243], v[72:75]
	s_setprio 0
	s_setprio 1
	v_mfma_f32_16x16x32_bf16 v[116:119], v[176:179], v[192:195], 0
	v_mfma_f32_16x16x32_bf16 v[112:115], v[184:187], v[192:195], 0
	v_mfma_f32_16x16x32_bf16 v[100:103], v[176:179], v[200:203], 0
	v_mfma_f32_16x16x32_bf16 v[96:99], v[184:187], v[200:203], 0
	v_mfma_f32_16x16x32_bf16 v[84:87], v[176:179], v[208:211], 0
	v_mfma_f32_16x16x32_bf16 v[80:83], v[184:187], v[208:211], 0
	v_mfma_f32_16x16x32_bf16 v[68:71], v[176:179], v[216:219], 0
	v_mfma_f32_16x16x32_bf16 v[64:67], v[184:187], v[216:219], 0
	v_mfma_f32_16x16x32_bf16 v[116:119], v[180:183], v[196:199], v[116:119]
	v_mfma_f32_16x16x32_bf16 v[112:115], v[188:191], v[196:199], v[112:115]
	v_mfma_f32_16x16x32_bf16 v[100:103], v[180:183], v[204:207], v[100:103]
	v_mfma_f32_16x16x32_bf16 v[96:99], v[188:191], v[204:207], v[96:99]
	v_mfma_f32_16x16x32_bf16 v[84:87], v[180:183], v[212:215], v[84:87]
	v_mfma_f32_16x16x32_bf16 v[80:83], v[188:191], v[212:215], v[80:83]
	v_mfma_f32_16x16x32_bf16 v[68:71], v[180:183], v[240:243], v[68:71]
	v_mfma_f32_16x16x32_bf16 v[64:67], v[188:191], v[240:243], v[64:67]
	s_setprio 0
	s_barrier
	s_add_i32 s62, s33, s45
	v_lshl_add_u64 v[244:245], v[220:221], 0, v[168:169]
	s_mov_b32 m0, s62
	ds_read_b128 v[192:195], v151 offset:16384
	ds_read_b128 v[196:199], v151 offset:17408
	ds_read_b128 v[200:203], v151 offset:18432
	ds_read_b128 v[204:207], v151 offset:19456
	ds_read_b128 v[208:211], v151 offset:20480
	ds_read_b128 v[212:215], v151 offset:21504
	ds_read_b128 v[216:219], v151 offset:22528
	ds_read_b128 v[240:243], v151 offset:23552
	global_load_lds_dwordx4 v[244:245], off
	v_lshl_add_u64 v[246:247], v[220:221], 0, v[128:129]
	s_add_i32 m0, s62, 0x2000
	v_lshl_add_u64 v[220:221], v[220:221], 0, s[12:13]
	s_add_i32 s10, s10, s45
	global_load_lds_dwordx4 v[246:247], off
	v_lshl_add_u64 v[248:249], v[220:221], 0, v[168:169]
	s_mov_b32 m0, s10
	v_lshl_add_u64 v[220:221], v[220:221], 0, v[128:129]
	global_load_lds_dwordx4 v[248:249], off
	s_add_i32 m0, s10, 0x2000
	v_lshl_add_u64 v[250:251], v[146:147], 0, v[132:133]
	global_load_lds_dwordx4 v[220:221], off
	s_mov_b32 m0, s25
	v_lshl_add_u64 v[252:253], v[146:147], 0, v[130:131]
	global_load_lds_dwordx4 v[250:251], off
	s_mov_b32 m0, s50
	s_nop 0
	global_load_lds_dwordx4 v[252:253], off
	s_waitcnt vmcnt(8)
	s_waitcnt lgkmcnt(0)
	s_barrier
; #define PG8_STAGE(bufoff, gbase, voff) do { _Pragma("unroll") for (int _i = 0; _i < 2; ++_i) \
;         __builtin_amdgcn_global_load_lds((const unsigned*)((const char*)(gbase) + (voff)[_i]), (LAS unsigned*)(lds + (bufoff) + ldsw + _i * 8192), 16, 0, 0); } while (0)
; #define PG8_LDA(dst, b, h) do { _Pragma("unroll") for (int m = 0; m < 4; ++m) _Pragma("unroll") for (int k = 0; k < 2; ++k) dst[m][k] = *(const LAS bf16x8*)(lds + PG8_SA(b, h) + aoff + m * 2048 + k * 1024); } while (0)
; #define PG8_LDB(dst, b, h) do { _Pragma("unroll") for (int n = 0; n < 2; ++n) _Pragma("unroll") for (int k = 0; k < 2; ++k) dst[n][k] = *(const LAS bf16x8*)(lds + PG8_SB(b, h) + boff + n * 2048 + k * 1024); } while (0)
; #define PG8_MMA(ai, bj, At, Bt) do { __builtin_amdgcn_s_setprio(1); _Pragma("unroll") for (int k = 0; k < 2; ++k) _Pragma("unroll") for (int m = 0; m < 4; ++m) _Pragma("unroll") for (int n = 0; n < 2; ++n) \
;         acc[ai][bj][m][n] = __builtin_amdgcn_mfma_f32_16x16x32_bf16(Bt[n][k], At[m][k], acc[ai][bj][m][n], 0, 0, 0); __builtin_amdgcn_s_setprio(0); } while (0)
; #define PG8_WAIT_V(n) asm volatile("s_waitcnt vmcnt(" #n ")" ::: "memory")
; #define PG8_WAIT_L(n) asm volatile("s_waitcnt lgkmcnt(" #n ")" ::: "memory")
; #define PG8_BAR __builtin_amdgcn_s_barrier()
; #define PG8_SCHED __builtin_amdgcn_sched_barrier(0)
; template <class Epi, bool ALIGN_EPI>
; __device__ __forceinline__ void gemm_phase(LAS unsigned char* lds, const Gemm g, const StaticOrder& S, const Epi& E, const int tid) {
;     ...
;             PG8_WAIT_V(8); PG8_WAIT_L(0); PG8_BAR; PG8_MMA(1, 0, At, B0); PG8_MMA(1, 1, At, B1); PG8_BAR; PG8_SCHED;
;             PG8_LDB(B0, 1, 0); PG8_LDB(B1, 1, 1); PG8_SCHED; PG8_LDA(At, 1, 0); PG8_STAGE(PG8_SA(0, 1), a2 + hA, voffA);
;             PG8_WAIT_V(8); PG8_WAIT_L(0); PG8_BAR; PG8_MMA(0, 0, At, B0); PG8_MMA(0, 1, At, B1); PG8_BAR; PG8_SCHED;
	s_setprio 1
	s_waitcnt lgkmcnt(0)
	v_mfma_f32_16x16x32_bf16 v[60:63], v[152:155], v[192:195], 0
	v_mfma_f32_16x16x32_bf16 v[56:59], v[160:163], v[192:195], 0
	v_mfma_f32_16x16x32_bf16 v[44:47], v[152:155], v[200:203], 0
	v_mfma_f32_16x16x32_bf16 v[40:43], v[160:163], v[200:203], 0
	v_mfma_f32_16x16x32_bf16 v[28:31], v[152:155], v[208:211], 0
	v_mfma_f32_16x16x32_bf16 v[24:27], v[160:163], v[208:211], 0
	v_mfma_f32_16x16x32_bf16 v[12:15], v[152:155], v[216:219], 0
	v_mfma_f32_16x16x32_bf16 v[8:11], v[160:163], v[216:219], 0
	v_mfma_f32_16x16x32_bf16 v[60:63], v[156:159], v[196:199], v[60:63]
	v_mfma_f32_16x16x32_bf16 v[56:59], v[164:167], v[196:199], v[56:59]
	v_mfma_f32_16x16x32_bf16 v[44:47], v[156:159], v[204:207], v[44:47]
	v_mfma_f32_16x16x32_bf16 v[40:43], v[164:167], v[204:207], v[40:43]
	v_mfma_f32_16x16x32_bf16 v[28:31], v[156:159], v[212:215], v[28:31]
	v_mfma_f32_16x16x32_bf16 v[24:27], v[164:167], v[212:215], v[24:27]
	v_mfma_f32_16x16x32_bf16 v[12:15], v[156:159], v[240:243], v[12:15]
	v_mfma_f32_16x16x32_bf16 v[8:11], v[164:167], v[240:243], v[8:11]
	s_setprio 0
	s_setprio 1
	v_mfma_f32_16x16x32_bf16 v[52:55], v[176:179], v[192:195], 0
	v_mfma_f32_16x16x32_bf16 v[48:51], v[184:187], v[192:195], 0
	v_mfma_f32_16x16x32_bf16 v[36:39], v[176:179], v[200:203], 0
	v_mfma_f32_16x16x32_bf16 v[32:35], v[184:187], v[200:203], 0
	v_mfma_f32_16x16x32_bf16 v[20:23], v[176:179], v[208:211], 0
	v_mfma_f32_16x16x32_bf16 v[16:19], v[184:187], v[208:211], 0
	v_mfma_f32_16x16x32_bf16 v[4:7], v[176:179], v[216:219], 0
	v_mfma_f32_16x16x32_bf16 v[0:3], v[184:187], v[216:219], 0
	v_mfma_f32_16x16x32_bf16 v[52:55], v[180:183], v[196:199], v[52:55]
	v_mfma_f32_16x16x32_bf16 v[48:51], v[188:191], v[196:199], v[48:51]
	v_mfma_f32_16x16x32_bf16 v[36:39], v[180:183], v[204:207], v[36:39]
	v_mfma_f32_16x16x32_bf16 v[32:35], v[188:191], v[204:207], v[32:35]
	v_mfma_f32_16x16x32_bf16 v[20:23], v[180:183], v[212:215], v[20:23]
	v_mfma_f32_16x16x32_bf16 v[16:19], v[188:191], v[212:215], v[16:19]
	v_mfma_f32_16x16x32_bf16 v[4:7], v[180:183], v[240:243], v[4:7]
	v_mfma_f32_16x16x32_bf16 v[0:3], v[188:191], v[240:243], v[0:3]
	s_setprio 0
	s_barrier
	s_add_i32 s10, 0, 0x18000
	v_add_u32_e32 v148, s10, v149
	s_add_i32 s62, 0, 0x1c000
	ds_read_b128 v[152:155], v148
	ds_read_b128 v[156:159], v148 offset:1024
	ds_read_b128 v[160:163], v148 offset:2048
	ds_read_b128 v[164:167], v148 offset:3072
	v_add_u32_e32 v148, s62, v149
	ds_read_b128 v[176:179], v148
	ds_read_b128 v[180:183], v148 offset:1024
	ds_read_b128 v[184:187], v148 offset:2048
	ds_read_b128 v[188:191], v148 offset:3072
	v_lshl_add_u64 v[146:147], v[146:147], 0, s[94:95]
	s_mov_b32 m0, s51
	v_lshl_add_u64 v[226:227], v[146:147], 0, v[132:133]
	ds_read_b128 v[192:195], v151 offset:32768
	ds_read_b128 v[196:199], v151 offset:33792
	ds_read_b128 v[200:203], v151 offset:34816
	ds_read_b128 v[204:207], v151 offset:35840
	ds_read_b128 v[208:211], v151 offset:36864
	ds_read_b128 v[212:215], v151 offset:37888
	ds_read_b128 v[216:219], v151 offset:38912
	ds_read_b128 v[240:243], v151 offset:39936
	global_load_lds_dwordx4 v[226:227], off
	v_lshl_add_u64 v[146:147], v[146:147], 0, v[130:131]
	s_mov_b32 m0, s52
	s_nop 0
	global_load_lds_dwordx4 v[146:147], off
	s_waitcnt vmcnt(8)
	s_waitcnt lgkmcnt(0)
	s_barrier
	s_setprio 1
	s_waitcnt lgkmcnt(0)
	v_mfma_f32_16x16x32_bf16 v[124:127], v[152:155], v[192:195], v[124:127]
	v_mfma_f32_16x16x32_bf16 v[120:123], v[160:163], v[192:195], v[120:123]
	v_mfma_f32_16x16x32_bf16 v[108:111], v[152:155], v[200:203], v[108:111]
	v_mfma_f32_16x16x32_bf16 v[104:107], v[160:163], v[200:203], v[104:107]
	v_mfma_f32_16x16x32_bf16 v[92:95], v[152:155], v[208:211], v[92:95]
	v_mfma_f32_16x16x32_bf16 v[88:91], v[160:163], v[208:211], v[88:91]
	v_mfma_f32_16x16x32_bf16 v[76:79], v[152:155], v[216:219], v[76:79]
	v_mfma_f32_16x16x32_bf16 v[72:75], v[160:163], v[216:219], v[72:75]
	v_mfma_f32_16x16x32_bf16 v[124:127], v[156:159], v[196:199], v[124:127]
	v_mfma_f32_16x16x32_bf16 v[120:123], v[164:167], v[196:199], v[120:123]
	v_mfma_f32_16x16x32_bf16 v[108:111], v[156:159], v[204:207], v[108:111]
	v_mfma_f32_16x16x32_bf16 v[104:107], v[164:167], v[204:207], v[104:107]
	v_mfma_f32_16x16x32_bf16 v[92:95], v[156:159], v[212:215], v[92:95]
	v_mfma_f32_16x16x32_bf16 v[88:91], v[164:167], v[212:215], v[88:91]
	v_mfma_f32_16x16x32_bf16 v[76:79], v[156:159], v[240:243], v[76:79]
	v_mfma_f32_16x16x32_bf16 v[72:75], v[164:167], v[240:243], v[72:75]
	s_setprio 0
	s_setprio 1
	v_mfma_f32_16x16x32_bf16 v[116:119], v[176:179], v[192:195], v[116:119]
	v_mfma_f32_16x16x32_bf16 v[112:115], v[184:187], v[192:195], v[112:115]
	v_mfma_f32_16x16x32_bf16 v[100:103], v[176:179], v[200:203], v[100:103]
	v_mfma_f32_16x16x32_bf16 v[96:99], v[184:187], v[200:203], v[96:99]
	v_mfma_f32_16x16x32_bf16 v[84:87], v[176:179], v[208:211], v[84:87]
	v_mfma_f32_16x16x32_bf16 v[80:83], v[184:187], v[208:211], v[80:83]
	v_mfma_f32_16x16x32_bf16 v[68:71], v[176:179], v[216:219], v[68:71]
	v_mfma_f32_16x16x32_bf16 v[64:67], v[184:187], v[216:219], v[64:67]
	v_mfma_f32_16x16x32_bf16 v[116:119], v[180:183], v[196:199], v[116:119]
	v_mfma_f32_16x16x32_bf16 v[112:115], v[188:191], v[196:199], v[112:115]
	v_mfma_f32_16x16x32_bf16 v[100:103], v[180:183], v[204:207], v[100:103]
	v_mfma_f32_16x16x32_bf16 v[96:99], v[188:191], v[204:207], v[96:99]
	v_mfma_f32_16x16x32_bf16 v[84:87], v[180:183], v[212:215], v[84:87]
	v_mfma_f32_16x16x32_bf16 v[80:83], v[188:191], v[212:215], v[80:83]
	v_mfma_f32_16x16x32_bf16 v[68:71], v[180:183], v[240:243], v[68:71]
	v_mfma_f32_16x16x32_bf16 v[64:67], v[188:191], v[240:243], v[64:67]
	s_setprio 0
	s_barrier
; #define PG8_STAGE(bufoff, gbase, voff) do { _Pragma("unroll") for (int _i = 0; _i < 2; ++_i) \
;         __builtin_amdgcn_global_load_lds((const unsigned*)((const char*)(gbase) + (voff)[_i]), (LAS unsigned*)(lds + (bufoff) + ldsw + _i * 8192), 16, 0, 0); } while (0)
; #define PG8_LDA(dst, b, h) do { _Pragma("unroll") for (int m = 0; m < 4; ++m) _Pragma("unroll") for (int k = 0; k < 2; ++k) dst[m][k] = *(const LAS bf16x8*)(lds + PG8_SA(b, h) + aoff + m * 2048 + k * 1024); } while (0)
; #define PG8_LDB(dst, b, h) do { _Pragma("unroll") for (int n = 0; n < 2; ++n) _Pragma("unroll") for (int k = 0; k < 2; ++k) dst[n][k] = *(const LAS bf16x8*)(lds + PG8_SB(b, h) + boff + n * 2048 + k * 1024); } while (0)
; #define PG8_MMA(ai, bj, At, Bt) do { __builtin_amdgcn_s_setprio(1); _Pragma("unroll") for (int k = 0; k < 2; ++k) _Pragma("unroll") for (int m = 0; m < 4; ++m) _Pragma("unroll") for (int n = 0; n < 2; ++n) \
;         acc[ai][bj][m][n] = __builtin_amdgcn_mfma_f32_16x16x32_bf16(Bt[n][k], At[m][k], acc[ai][bj][m][n], 0, 0, 0); __builtin_amdgcn_s_setprio(0); } while (0)
; #define PG8_WAIT_V(n) asm volatile("s_waitcnt vmcnt(" #n ")" ::: "memory")
; template <class Epi, bool ALIGN_EPI>
; __device__ __forceinline__ void gemm_phase(LAS unsigned char* lds, const Gemm g, const StaticOrder& S, const Epi& E, const int tid) {
;     ...
;             PG8_LDB(B0, 0, 0); PG8_LDB(B1, 0, 1); PG8_SCHED; PG8_LDA(At, 0, 0); PG8_STAGE(PG8_SA(1, 1), a1 + hA, voffA);
;             PG8_WAIT_V(8); PG8_WAIT_L(0); PG8_BAR; PG8_MMA(0, 0, At, B0); PG8_MMA(0, 1, At, B1); PG8_BAR; PG8_SCHED;
;             PG8_LDA(At, 0, 1); PG8_STAGE(PG8_SB(0, 0), b2, voffB); PG8_STAGE(PG8_SB(0, 1), b2 + hB, voffB); PG8_STAGE(PG8_SA(0, 0), a2, voffA);
;             PG8_WAIT_V(8); PG8_WAIT_L(0); PG8_BAR; PG8_MMA(1, 0, At, B0); PG8_MMA(1, 1, At, B1); PG8_BAR; PG8_SCHED;
;             PG8_LDB(B0, 1, 0); PG8_LDB(B1, 1, 1); PG8_SCHED; PG8_LDA(At, 1, 0); PG8_STAGE(PG8_SA(0, 1), a2 + hA, voffA);
;             PG8_WAIT_V(8); PG8_WAIT_L(0); PG8_BAR; PG8_MMA(0, 0, At, B0); PG8_MMA(0, 1, At, B1); PG8_BAR; PG8_SCHED;
;             PG8_LDA(At, 1, 1); PG8_STAGE(PG8_SB(1, 0), b3, voffB); PG8_STAGE(PG8_SB(1, 1), b3 + hB, voffB); PG8_STAGE(PG8_SA(1, 0), a3, voffA);
;             PG8_WAIT_V(8); PG8_WAIT_L(0); PG8_BAR; PG8_MMA(1, 0, At, B0); PG8_MMA(1, 1, At, B1); PG8_BAR; PG8_SCHED;
;         }
	s_add_i32 s10, s10, s45
	v_lshl_add_u64 v[146:147], v[244:245], 0, s[92:93]
	s_mov_b32 m0, s10
	ds_read_b128 v[192:195], v151 offset:49152
	ds_read_b128 v[196:199], v151 offset:50176
	ds_read_b128 v[200:203], v151 offset:51200
	ds_read_b128 v[204:207], v151 offset:52224
	ds_read_b128 v[208:211], v151 offset:53248
	ds_read_b128 v[212:215], v151 offset:54272
	ds_read_b128 v[216:219], v151 offset:55296
	ds_read_b128 v[240:243], v151 offset:56320
	global_load_lds_dwordx4 v[146:147], off
	v_lshl_add_u64 v[146:147], v[246:247], 0, s[92:93]
	s_add_i32 m0, s10, 0x2000
	s_add_i32 s10, s62, s45
	global_load_lds_dwordx4 v[146:147], off
	v_lshl_add_u64 v[146:147], v[248:249], 0, s[92:93]
	s_mov_b32 m0, s10
	s_nop 0
	global_load_lds_dwordx4 v[146:147], off
	v_lshl_add_u64 v[146:147], v[220:221], 0, s[92:93]
	s_add_i32 m0, s10, 0x2000
	s_nop 0
	global_load_lds_dwordx4 v[146:147], off
	v_lshl_add_u64 v[146:147], v[250:251], 0, s[92:93]
	s_mov_b32 m0, s53
	s_nop 0
	global_load_lds_dwordx4 v[146:147], off
	v_lshl_add_u64 v[146:147], v[252:253], 0, s[92:93]
	s_mov_b32 m0, s54
	s_nop 0
	global_load_lds_dwordx4 v[146:147], off
	s_waitcnt vmcnt(8)
	s_waitcnt lgkmcnt(0)
	s_barrier
	s_setprio 1
	s_waitcnt lgkmcnt(0)
	v_mfma_f32_16x16x32_bf16 v[60:63], v[152:155], v[192:195], v[60:63]
	v_mfma_f32_16x16x32_bf16 v[56:59], v[160:163], v[192:195], v[56:59]
	v_mfma_f32_16x16x32_bf16 v[44:47], v[152:155], v[200:203], v[44:47]
	v_mfma_f32_16x16x32_bf16 v[40:43], v[160:163], v[200:203], v[40:43]
	v_mfma_f32_16x16x32_bf16 v[28:31], v[152:155], v[208:211], v[28:31]
	v_mfma_f32_16x16x32_bf16 v[24:27], v[160:163], v[208:211], v[24:27]
	v_mfma_f32_16x16x32_bf16 v[12:15], v[152:155], v[216:219], v[12:15]
	v_mfma_f32_16x16x32_bf16 v[8:11], v[160:163], v[216:219], v[8:11]
	v_mfma_f32_16x16x32_bf16 v[60:63], v[156:159], v[196:199], v[60:63]
	v_mfma_f32_16x16x32_bf16 v[56:59], v[164:167], v[196:199], v[56:59]
	v_mfma_f32_16x16x32_bf16 v[44:47], v[156:159], v[204:207], v[44:47]
	v_mfma_f32_16x16x32_bf16 v[40:43], v[164:167], v[204:207], v[40:43]
	v_mfma_f32_16x16x32_bf16 v[28:31], v[156:159], v[212:215], v[28:31]
	v_mfma_f32_16x16x32_bf16 v[24:27], v[164:167], v[212:215], v[24:27]
	v_mfma_f32_16x16x32_bf16 v[12:15], v[156:159], v[240:243], v[12:15]
	v_mfma_f32_16x16x32_bf16 v[8:11], v[164:167], v[240:243], v[8:11]
	s_setprio 0
	s_setprio 1
	v_mfma_f32_16x16x32_bf16 v[52:55], v[176:179], v[192:195], v[52:55]
	v_mfma_f32_16x16x32_bf16 v[48:51], v[184:187], v[192:195], v[48:51]
	v_mfma_f32_16x16x32_bf16 v[36:39], v[176:179], v[200:203], v[36:39]
	v_mfma_f32_16x16x32_bf16 v[32:35], v[184:187], v[200:203], v[32:35]
	v_mfma_f32_16x16x32_bf16 v[20:23], v[176:179], v[208:211], v[20:23]
	v_mfma_f32_16x16x32_bf16 v[16:19], v[184:187], v[208:211], v[16:19]
	v_mfma_f32_16x16x32_bf16 v[4:7], v[176:179], v[216:219], v[4:7]
	v_mfma_f32_16x16x32_bf16 v[0:3], v[184:187], v[216:219], v[0:3]
	v_mfma_f32_16x16x32_bf16 v[52:55], v[180:183], v[196:199], v[52:55]
	v_mfma_f32_16x16x32_bf16 v[48:51], v[188:191], v[196:199], v[48:51]
	v_mfma_f32_16x16x32_bf16 v[36:39], v[180:183], v[204:207], v[36:39]
	v_mfma_f32_16x16x32_bf16 v[32:35], v[188:191], v[204:207], v[32:35]
	v_mfma_f32_16x16x32_bf16 v[20:23], v[180:183], v[212:215], v[20:23]
	v_mfma_f32_16x16x32_bf16 v[16:19], v[188:191], v[212:215], v[16:19]
	v_mfma_f32_16x16x32_bf16 v[4:7], v[180:183], v[240:243], v[4:7]
	v_mfma_f32_16x16x32_bf16 v[0:3], v[188:191], v[240:243], v[0:3]
	s_setprio 0
	v_lshl_add_u64 v[142:143], v[142:143], 0, s[80:81]
	v_lshl_add_u64 v[144:145], v[144:145], 0, s[80:81]
	s_mov_b32 s10, s11
	s_cmp_eq_u32 s10, s55
	s_barrier
	s_cbranch_scc1 .Lq5_last
.LBB0_354:
	s_add_i32 s11, s10, 2
	s_cmp_eq_u32 s55, s10
	s_cselect_b64 vcc, -1, 0
	v_add_u32_e32 v148, s33, v149
	s_add_i32 s10, 0, 0x14000
	ds_read_b128 v[152:155], v148
	ds_read_b128 v[156:159], v148 offset:1024
	ds_read_b128 v[160:163], v148 offset:2048
	ds_read_b128 v[164:167], v148 offset:3072
	v_add_u32_e32 v148, s10, v149
	ds_read_b128 v[176:179], v148
	ds_read_b128 v[180:183], v148 offset:1024
	ds_read_b128 v[184:187], v148 offset:2048
	ds_read_b128 v[188:191], v148 offset:3072
	v_lshl_add_u64 v[146:147], v[142:143], 0, s[92:93]
	v_cndmask_b32_e32 v147, v147, v139, vcc
	v_cndmask_b32_e32 v146, v146, v138, vcc
	v_cndmask_b32_e32 v221, v145, v141, vcc
	v_cndmask_b32_e32 v220, v144, v140, vcc
	v_lshl_add_u64 v[244:245], v[142:143], 0, v[134:135]
	s_add_i32 m0, s25, 0xc000
	ds_read_b128 v[192:195], v151
	ds_read_b128 v[196:199], v151 offset:1024
	ds_read_b128 v[200:203], v151 offset:2048
	ds_read_b128 v[204:207], v151 offset:3072
	ds_read_b128 v[208:211], v151 offset:4096
	ds_read_b128 v[212:215], v151 offset:5120
	ds_read_b128 v[216:219], v151 offset:6144
	ds_read_b128 v[240:243], v151 offset:7168
	global_load_lds_dwordx4 v[244:245], off
	v_lshl_add_u64 v[244:245], v[142:143], 0, v[136:137]
	s_add_i32 m0, s25, 0xe000
	s_nop 0
	global_load_lds_dwordx4 v[244:245], off
	s_waitcnt vmcnt(8)
	s_waitcnt lgkmcnt(0)
	s_barrier
; #define PG8_STAGE(bufoff, gbase, voff) do { _Pragma("unroll") for (int _i = 0; _i < 2; ++_i) \
;         __builtin_amdgcn_global_load_lds((const unsigned*)((const char*)(gbase) + (voff)[_i]), (LAS unsigned*)(lds + (bufoff) + ldsw + _i * 8192), 16, 0, 0); } while (0)
; #define PG8_LDA(dst, b, h) do { _Pragma("unroll") for (int m = 0; m < 4; ++m) _Pragma("unroll") for (int k = 0; k < 2; ++k) dst[m][k] = *(const LAS bf16x8*)(lds + PG8_SA(b, h) + aoff + m * 2048 + k * 1024); } while (0)
; #define PG8_LDB(dst, b, h) do { _Pragma("unroll") for (int n = 0; n < 2; ++n) _Pragma("unroll") for (int k = 0; k < 2; ++k) dst[n][k] = *(const LAS bf16x8*)(lds + PG8_SB(b, h) + boff + n * 2048 + k * 1024); } while (0)
; #define PG8_MMA(ai, bj, At, Bt) do { __builtin_amdgcn_s_setprio(1); _Pragma("unroll") for (int k = 0; k < 2; ++k) _Pragma("unroll") for (int m = 0; m < 4; ++m) _Pragma("unroll") for (int n = 0; n < 2; ++n) \
;         acc[ai][bj][m][n] = __builtin_amdgcn_mfma_f32_16x16x32_bf16(Bt[n][k], At[m][k], acc[ai][bj][m][n], 0, 0, 0); __builtin_amdgcn_s_setprio(0); } while (0)
; #define PG8_WAIT_V(n) asm volatile("s_waitcnt vmcnt(" #n ")" ::: "memory")
; #define PG8_WAIT_L(n) asm volatile("s_waitcnt lgkmcnt(" #n ")" ::: "memory")
; #define PG8_BAR __builtin_amdgcn_s_barrier()
; #define PG8_SCHED __builtin_amdgcn_sched_barrier(0)
; template <class Epi, bool ALIGN_EPI>
; __device__ __forceinline__ void gemm_phase(LAS unsigned char* lds, const Gemm g, const StaticOrder& S, const Epi& E, const int tid) {
;     ...
;             PG8_WAIT_V(8); PG8_WAIT_L(0); PG8_BAR; PG8_MMA(0, 0, At, B0); PG8_MMA(0, 1, At, B1); PG8_BAR; PG8_SCHED;
;             PG8_LDA(At, 0, 1); PG8_STAGE(PG8_SB(0, 0), b2, voffB); PG8_STAGE(PG8_SB(0, 1), b2 + hB, voffB); PG8_STAGE(PG8_SA(0, 0), a2, voffA);
;             PG8_WAIT_V(8); PG8_WAIT_L(0); PG8_BAR; PG8_MMA(1, 0, At, B0); PG8_MMA(1, 1, At, B1); PG8_BAR; PG8_SCHED;
;             PG8_LDB(B0, 1, 0); PG8_LDB(B1, 1, 1); PG8_SCHED; PG8_LDA(At, 1, 0); PG8_STAGE(PG8_SA(0, 1), a2 + hA, voffA);
;             PG8_WAIT_V(8); PG8_WAIT_L(0); PG8_BAR; PG8_MMA(0, 0, At, B0); PG8_MMA(0, 1, At, B1); PG8_BAR; PG8_SCHED;
	s_setprio 1
	s_waitcnt lgkmcnt(0)
	v_mfma_f32_16x16x32_bf16 v[124:127], v[152:155], v[192:195], v[124:127]
	v_mfma_f32_16x16x32_bf16 v[120:123], v[160:163], v[192:195], v[120:123]
	v_mfma_f32_16x16x32_bf16 v[108:111], v[152:155], v[200:203], v[108:111]
	v_mfma_f32_16x16x32_bf16 v[104:107], v[160:163], v[200:203], v[104:107]
	v_mfma_f32_16x16x32_bf16 v[92:95], v[152:155], v[208:211], v[92:95]
	v_mfma_f32_16x16x32_bf16 v[88:91], v[160:163], v[208:211], v[88:91]
	v_mfma_f32_16x16x32_bf16 v[76:79], v[152:155], v[216:219], v[76:79]
	v_mfma_f32_16x16x32_bf16 v[72:75], v[160:163], v[216:219], v[72:75]
	v_mfma_f32_16x16x32_bf16 v[124:127], v[156:159], v[196:199], v[124:127]
	v_mfma_f32_16x16x32_bf16 v[120:123], v[164:167], v[196:199], v[120:123]
	v_mfma_f32_16x16x32_bf16 v[108:111], v[156:159], v[204:207], v[108:111]
	v_mfma_f32_16x16x32_bf16 v[104:107], v[164:167], v[204:207], v[104:107]
	v_mfma_f32_16x16x32_bf16 v[92:95], v[156:159], v[212:215], v[92:95]
	v_mfma_f32_16x16x32_bf16 v[88:91], v[164:167], v[212:215], v[88:91]
	v_mfma_f32_16x16x32_bf16 v[76:79], v[156:159], v[240:243], v[76:79]
	v_mfma_f32_16x16x32_bf16 v[72:75], v[164:167], v[240:243], v[72:75]
	s_setprio 0
	s_setprio 1
	v_mfma_f32_16x16x32_bf16 v[116:119], v[176:179], v[192:195], v[116:119]
	v_mfma_f32_16x16x32_bf16 v[112:115], v[184:187], v[192:195], v[112:115]
	v_mfma_f32_16x16x32_bf16 v[100:103], v[176:179], v[200:203], v[100:103]
	v_mfma_f32_16x16x32_bf16 v[96:99], v[184:187], v[200:203], v[96:99]
	v_mfma_f32_16x16x32_bf16 v[84:87], v[176:179], v[208:211], v[84:87]
	v_mfma_f32_16x16x32_bf16 v[80:83], v[184:187], v[208:211], v[80:83]
	v_mfma_f32_16x16x32_bf16 v[68:71], v[176:179], v[216:219], v[68:71]
	v_mfma_f32_16x16x32_bf16 v[64:67], v[184:187], v[216:219], v[64:67]
	v_mfma_f32_16x16x32_bf16 v[116:119], v[180:183], v[196:199], v[116:119]
	v_mfma_f32_16x16x32_bf16 v[112:115], v[188:191], v[196:199], v[112:115]
	v_mfma_f32_16x16x32_bf16 v[100:103], v[180:183], v[204:207], v[100:103]
	v_mfma_f32_16x16x32_bf16 v[96:99], v[188:191], v[204:207], v[96:99]
	v_mfma_f32_16x16x32_bf16 v[84:87], v[180:183], v[212:215], v[84:87]
	v_mfma_f32_16x16x32_bf16 v[80:83], v[188:191], v[212:215], v[80:83]
	v_mfma_f32_16x16x32_bf16 v[68:71], v[180:183], v[240:243], v[68:71]
	v_mfma_f32_16x16x32_bf16 v[64:67], v[188:191], v[240:243], v[64:67]
	s_setprio 0
	s_barrier
	s_add_i32 s62, s33, s45
	v_lshl_add_u64 v[244:245], v[220:221], 0, v[168:169]
	s_mov_b32 m0, s62
	ds_read_b128 v[192:195], v151 offset:16384
	ds_read_b128 v[196:199], v151 offset:17408
	ds_read_b128 v[200:203], v151 offset:18432
	ds_read_b128 v[204:207], v151 offset:19456
	ds_read_b128 v[208:211], v151 offset:20480
	ds_read_b128 v[212:215], v151 offset:21504
	ds_read_b128 v[216:219], v151 offset:22528
	ds_read_b128 v[240:243], v151 offset:23552
	global_load_lds_dwordx4 v[244:245], off
	v_lshl_add_u64 v[246:247], v[220:221], 0, v[128:129]
	s_add_i32 m0, s62, 0x2000
	v_lshl_add_u64 v[220:221], v[220:221], 0, s[12:13]
	s_add_i32 s10, s10, s45
	global_load_lds_dwordx4 v[246:247], off
	v_lshl_add_u64 v[248:249], v[220:221], 0, v[168:169]
	s_mov_b32 m0, s10
	v_lshl_add_u64 v[220:221], v[220:221], 0, v[128:129]
	global_load_lds_dwordx4 v[248:249], off
	s_add_i32 m0, s10, 0x2000
	v_lshl_add_u64 v[250:251], v[146:147], 0, v[132:133]
	global_load_lds_dwordx4 v[220:221], off
	s_mov_b32 m0, s25
	v_lshl_add_u64 v[252:253], v[146:147], 0, v[130:131]
	global_load_lds_dwordx4 v[250:251], off
	s_mov_b32 m0, s50
	s_nop 0
	global_load_lds_dwordx4 v[252:253], off
	s_waitcnt vmcnt(8)
	s_waitcnt lgkmcnt(0)
	s_barrier
	s_setprio 1
	s_waitcnt lgkmcnt(0)
	v_mfma_f32_16x16x32_bf16 v[60:63], v[152:155], v[192:195], v[60:63]
	v_mfma_f32_16x16x32_bf16 v[56:59], v[160:163], v[192:195], v[56:59]
	v_mfma_f32_16x16x32_bf16 v[44:47], v[152:155], v[200:203], v[44:47]
	v_mfma_f32_16x16x32_bf16 v[40:43], v[160:163], v[200:203], v[40:43]
	v_mfma_f32_16x16x32_bf16 v[28:31], v[152:155], v[208:211], v[28:31]
	v_mfma_f32_16x16x32_bf16 v[24:27], v[160:163], v[208:211], v[24:27]
	v_mfma_f32_16x16x32_bf16 v[12:15], v[152:155], v[216:219], v[12:15]
	v_mfma_f32_16x16x32_bf16 v[8:11], v[160:163], v[216:219], v[8:11]
	v_mfma_f32_16x16x32_bf16 v[60:63], v[156:159], v[196:199], v[60:63]
	v_mfma_f32_16x16x32_bf16 v[56:59], v[164:167], v[196:199], v[56:59]
	v_mfma_f32_16x16x32_bf16 v[44:47], v[156:159], v[204:207], v[44:47]
	v_mfma_f32_16x16x32_bf16 v[40:43], v[164:167], v[204:207], v[40:43]
	v_mfma_f32_16x16x32_bf16 v[28:31], v[156:159], v[212:215], v[28:31]
	v_mfma_f32_16x16x32_bf16 v[24:27], v[164:167], v[212:215], v[24:27]
	v_mfma_f32_16x16x32_bf16 v[12:15], v[156:159], v[240:243], v[12:15]
	v_mfma_f32_16x16x32_bf16 v[8:11], v[164:167], v[240:243], v[8:11]
	s_setprio 0
	s_setprio 1
	v_mfma_f32_16x16x32_bf16 v[52:55], v[176:179], v[192:195], v[52:55]
	v_mfma_f32_16x16x32_bf16 v[48:51], v[184:187], v[192:195], v[48:51]
	v_mfma_f32_16x16x32_bf16 v[36:39], v[176:179], v[200:203], v[36:39]
	v_mfma_f32_16x16x32_bf16 v[32:35], v[184:187], v[200:203], v[32:35]
	v_mfma_f32_16x16x32_bf16 v[20:23], v[176:179], v[208:211], v[20:23]
	v_mfma_f32_16x16x32_bf16 v[16:19], v[184:187], v[208:211], v[16:19]
	v_mfma_f32_16x16x32_bf16 v[4:7], v[176:179], v[216:219], v[4:7]
	v_mfma_f32_16x16x32_bf16 v[0:3], v[184:187], v[216:219], v[0:3]
	v_mfma_f32_16x16x32_bf16 v[52:55], v[180:183], v[196:199], v[52:55]
	v_mfma_f32_16x16x32_bf16 v[48:51], v[188:191], v[196:199], v[48:51]
	v_mfma_f32_16x16x32_bf16 v[36:39], v[180:183], v[204:207], v[36:39]
	v_mfma_f32_16x16x32_bf16 v[32:35], v[188:191], v[204:207], v[32:35]
	v_mfma_f32_16x16x32_bf16 v[20:23], v[180:183], v[212:215], v[20:23]
	v_mfma_f32_16x16x32_bf16 v[16:19], v[188:191], v[212:215], v[16:19]
	v_mfma_f32_16x16x32_bf16 v[4:7], v[180:183], v[240:243], v[4:7]
	v_mfma_f32_16x16x32_bf16 v[0:3], v[188:191], v[240:243], v[0:3]
	s_setprio 0
	s_barrier
; #define PG8_STAGE(bufoff, gbase, voff) do { _Pragma("unroll") for (int _i = 0; _i < 2; ++_i) \
;         __builtin_amdgcn_global_load_lds((const unsigned*)((const char*)(gbase) + (voff)[_i]), (LAS unsigned*)(lds + (bufoff) + ldsw + _i * 8192), 16, 0, 0); } while (0)
; #define PG8_LDA(dst, b, h) do { _Pragma("unroll") for (int m = 0; m < 4; ++m) _Pragma("unroll") for (int k = 0; k < 2; ++k) dst[m][k] = *(const LAS bf16x8*)(lds + PG8_SA(b, h) + aoff + m * 2048 + k * 1024); } while (0)
; #define PG8_LDB(dst, b, h) do { _Pragma("unroll") for (int n = 0; n < 2; ++n) _Pragma("unroll") for (int k = 0; k < 2; ++k) dst[n][k] = *(const LAS bf16x8*)(lds + PG8_SB(b, h) + boff + n * 2048 + k * 1024); } while (0)
; #define PG8_MMA(ai, bj, At, Bt) do { __builtin_amdgcn_s_setprio(1); _Pragma("unroll") for (int k = 0; k < 2; ++k) _Pragma("unroll") for (int m = 0; m < 4; ++m) _Pragma("unroll") for (int n = 0; n < 2; ++n) \
;         acc[ai][bj][m][n] = __builtin_amdgcn_mfma_f32_16x16x32_bf16(Bt[n][k], At[m][k], acc[ai][bj][m][n], 0, 0, 0); __builtin_amdgcn_s_setprio(0); } while (0)
; #define PG8_WAIT_V(n) asm volatile("s_waitcnt vmcnt(" #n ")" ::: "memory")
; #define PG8_WAIT_L(n) asm volatile("s_waitcnt lgkmcnt(" #n ")" ::: "memory")
; #define PG8_BAR __builtin_amdgcn_s_barrier()
; #define PG8_SCHED __builtin_amdgcn_sched_barrier(0)
; template <class Epi, bool ALIGN_EPI>
; __device__ __forceinline__ void gemm_phase(LAS unsigned char* lds, const Gemm g, const StaticOrder& S, const Epi& E, const int tid) {
;     ...
;             PG8_LDB(B0, 1, 0); PG8_LDB(B1, 1, 1); PG8_SCHED; PG8_LDA(At, 1, 0); PG8_STAGE(PG8_SA(0, 1), a2 + hA, voffA);
;             PG8_WAIT_V(8); PG8_WAIT_L(0); PG8_BAR; PG8_MMA(0, 0, At, B0); PG8_MMA(0, 1, At, B1); PG8_BAR; PG8_SCHED;
;             PG8_LDA(At, 1, 1); PG8_STAGE(PG8_SB(1, 0), b3, voffB); PG8_STAGE(PG8_SB(1, 1), b3 + hB, voffB); PG8_STAGE(PG8_SA(1, 0), a3, voffA);
;             PG8_WAIT_V(8); PG8_WAIT_L(0); PG8_BAR; PG8_MMA(1, 0, At, B0); PG8_MMA(1, 1, At, B1); PG8_BAR; PG8_SCHED;
	s_add_i32 s10, 0, 0x18000
	v_add_u32_e32 v148, s10, v149
	s_add_i32 s62, 0, 0x1c000
	ds_read_b128 v[152:155], v148
	ds_read_b128 v[156:159], v148 offset:1024
	ds_read_b128 v[160:163], v148 offset:2048
	ds_read_b128 v[164:167], v148 offset:3072
	v_add_u32_e32 v148, s62, v149
	ds_read_b128 v[176:179], v148
	ds_read_b128 v[180:183], v148 offset:1024
	ds_read_b128 v[184:187], v148 offset:2048
	ds_read_b128 v[188:191], v148 offset:3072
	v_lshl_add_u64 v[146:147], v[146:147], 0, s[94:95]
	s_mov_b32 m0, s51
	v_lshl_add_u64 v[226:227], v[146:147], 0, v[132:133]
	ds_read_b128 v[192:195], v151 offset:32768
	ds_read_b128 v[196:199], v151 offset:33792
	ds_read_b128 v[200:203], v151 offset:34816
	ds_read_b128 v[204:207], v151 offset:35840
	ds_read_b128 v[208:211], v151 offset:36864
	ds_read_b128 v[212:215], v151 offset:37888
	ds_read_b128 v[216:219], v151 offset:38912
	ds_read_b128 v[240:243], v151 offset:39936
	global_load_lds_dwordx4 v[226:227], off
	v_lshl_add_u64 v[146:147], v[146:147], 0, v[130:131]
	s_mov_b32 m0, s52
	s_nop 0
	global_load_lds_dwordx4 v[146:147], off
	s_waitcnt vmcnt(8)
	s_waitcnt lgkmcnt(0)
	s_barrier
	s_setprio 1
	s_waitcnt lgkmcnt(0)
	v_mfma_f32_16x16x32_bf16 v[124:127], v[152:155], v[192:195], v[124:127]
	v_mfma_f32_16x16x32_bf16 v[120:123], v[160:163], v[192:195], v[120:123]
	v_mfma_f32_16x16x32_bf16 v[108:111], v[152:155], v[200:203], v[108:111]
	v_mfma_f32_16x16x32_bf16 v[104:107], v[160:163], v[200:203], v[104:107]
	v_mfma_f32_16x16x32_bf16 v[92:95], v[152:155], v[208:211], v[92:95]
	v_mfma_f32_16x16x32_bf16 v[88:91], v[160:163], v[208:211], v[88:91]
	v_mfma_f32_16x16x32_bf16 v[76:79], v[152:155], v[216:219], v[76:79]
	v_mfma_f32_16x16x32_bf16 v[72:75], v[160:163], v[216:219], v[72:75]
	v_mfma_f32_16x16x32_bf16 v[124:127], v[156:159], v[196:199], v[124:127]
	v_mfma_f32_16x16x32_bf16 v[120:123], v[164:167], v[196:199], v[120:123]
	v_mfma_f32_16x16x32_bf16 v[108:111], v[156:159], v[204:207], v[108:111]
	v_mfma_f32_16x16x32_bf16 v[104:107], v[164:167], v[204:207], v[104:107]
	v_mfma_f32_16x16x32_bf16 v[92:95], v[156:159], v[212:215], v[92:95]
	v_mfma_f32_16x16x32_bf16 v[88:91], v[164:167], v[212:215], v[88:91]
	v_mfma_f32_16x16x32_bf16 v[76:79], v[156:159], v[240:243], v[76:79]
	v_mfma_f32_16x16x32_bf16 v[72:75], v[164:167], v[240:243], v[72:75]
	s_setprio 0
	s_setprio 1
	v_mfma_f32_16x16x32_bf16 v[116:119], v[176:179], v[192:195], v[116:119]
	v_mfma_f32_16x16x32_bf16 v[112:115], v[184:187], v[192:195], v[112:115]
	v_mfma_f32_16x16x32_bf16 v[100:103], v[176:179], v[200:203], v[100:103]
	v_mfma_f32_16x16x32_bf16 v[96:99], v[184:187], v[200:203], v[96:99]
	v_mfma_f32_16x16x32_bf16 v[84:87], v[176:179], v[208:211], v[84:87]
	v_mfma_f32_16x16x32_bf16 v[80:83], v[184:187], v[208:211], v[80:83]
	v_mfma_f32_16x16x32_bf16 v[68:71], v[176:179], v[216:219], v[68:71]
	v_mfma_f32_16x16x32_bf16 v[64:67], v[184:187], v[216:219], v[64:67]
	v_mfma_f32_16x16x32_bf16 v[116:119], v[180:183], v[196:199], v[116:119]
	v_mfma_f32_16x16x32_bf16 v[112:115], v[188:191], v[196:199], v[112:115]
	v_mfma_f32_16x16x32_bf16 v[100:103], v[180:183], v[204:207], v[100:103]
	v_mfma_f32_16x16x32_bf16 v[96:99], v[188:191], v[204:207], v[96:99]
	v_mfma_f32_16x16x32_bf16 v[84:87], v[180:183], v[212:215], v[84:87]
	v_mfma_f32_16x16x32_bf16 v[80:83], v[188:191], v[212:215], v[80:83]
	v_mfma_f32_16x16x32_bf16 v[68:71], v[180:183], v[240:243], v[68:71]
	v_mfma_f32_16x16x32_bf16 v[64:67], v[188:191], v[240:243], v[64:67]
	s_setprio 0
	s_barrier
	s_add_i32 s10, s10, s45
	v_lshl_add_u64 v[146:147], v[244:245], 0, s[92:93]
	s_mov_b32 m0, s10
	ds_read_b128 v[192:195], v151 offset:49152
	ds_read_b128 v[196:199], v151 offset:50176
	ds_read_b128 v[200:203], v151 offset:51200
	ds_read_b128 v[204:207], v151 offset:52224
	ds_read_b128 v[208:211], v151 offset:53248
	ds_read_b128 v[212:215], v151 offset:54272
	ds_read_b128 v[216:219], v151 offset:55296
	ds_read_b128 v[240:243], v151 offset:56320
	global_load_lds_dwordx4 v[146:147], off
	v_lshl_add_u64 v[146:147], v[246:247], 0, s[92:93]
	s_add_i32 m0, s10, 0x2000
	s_add_i32 s10, s62, s45
	global_load_lds_dwordx4 v[146:147], off
	v_lshl_add_u64 v[146:147], v[248:249], 0, s[92:93]
	s_mov_b32 m0, s10
	s_nop 0
	global_load_lds_dwordx4 v[146:147], off
	v_lshl_add_u64 v[146:147], v[220:221], 0, s[92:93]
	s_add_i32 m0, s10, 0x2000
	s_nop 0
	global_load_lds_dwordx4 v[146:147], off
	v_lshl_add_u64 v[146:147], v[250:251], 0, s[92:93]
	s_mov_b32 m0, s53
	s_nop 0
	global_load_lds_dwordx4 v[146:147], off
	v_lshl_add_u64 v[146:147], v[252:253], 0, s[92:93]
	s_mov_b32 m0, s54
	s_nop 0
	global_load_lds_dwordx4 v[146:147], off
	s_waitcnt vmcnt(8)
	s_waitcnt lgkmcnt(0)
	s_barrier
; #define PG8_STAGE(bufoff, gbase, voff) do { _Pragma("unroll") for (int _i = 0; _i < 2; ++_i) \
;         __builtin_amdgcn_global_load_lds((const unsigned*)((const char*)(gbase) + (voff)[_i]), (LAS unsigned*)(lds + (bufoff) + ldsw + _i * 8192), 16, 0, 0); } while (0)
; #define PG8_LDA(dst, b, h) do { _Pragma("unroll") for (int m = 0; m < 4; ++m) _Pragma("unroll") for (int k = 0; k < 2; ++k) dst[m][k] = *(const LAS bf16x8*)(lds + PG8_SA(b, h) + aoff + m * 2048 + k * 1024); } while (0)
; #define PG8_LDB(dst, b, h) do { _Pragma("unroll") for (int n = 0; n < 2; ++n) _Pragma("unroll") for (int k = 0; k < 2; ++k) dst[n][k] = *(const LAS bf16x8*)(lds + PG8_SB(b, h) + boff + n * 2048 + k * 1024); } while (0)
; #define PG8_WAIT_V(n) asm volatile("s_waitcnt vmcnt(" #n ")" ::: "memory")
; #define PG8_BAR __builtin_amdgcn_s_barrier()
; template <class Epi, bool ALIGN_EPI>
; __device__ __forceinline__ void gemm_phase(LAS unsigned char* lds, const Gemm g, const StaticOrder& S, const Epi& E, const int tid) {
;     ...
;         for (int t = 0; t < nt; t += 2) {
;             const bool last = (t == nt - 2);
;             const char* a1 = cA + (size_t)(t + 1) * kstep;
;             const char* a2 = last ? nA : cA + (size_t)(t + 2) * kstep; const char* b2 = last ? nB : cB + (size_t)(t + 2) * kstep;
;             const char* a3 = a2 + kstep; const char* b3 = b2 + kstep;
;             PG8_LDB(B0, 0, 0); PG8_LDB(B1, 0, 1); PG8_SCHED; PG8_LDA(At, 0, 0); PG8_STAGE(PG8_SA(1, 1), a1 + hA, voffA);
;             PG8_WAIT_V(8); PG8_WAIT_L(0); PG8_BAR; PG8_MMA(0, 0, At, B0); PG8_MMA(0, 1, At, B1); PG8_BAR; PG8_SCHED;
;             PG8_LDA(At, 0, 1); PG8_STAGE(PG8_SB(0, 0), b2, voffB); PG8_STAGE(PG8_SB(0, 1), b2 + hB, voffB); PG8_STAGE(PG8_SA(0, 0), a2, voffA);
;             PG8_WAIT_V(8); PG8_WAIT_L(0); PG8_BAR; PG8_MMA(1, 0, At, B0); PG8_MMA(1, 1, At, B1); PG8_BAR; PG8_SCHED;
;             PG8_LDB(B0, 1, 0); PG8_LDB(B1, 1, 1); PG8_SCHED; PG8_LDA(At, 1, 0); PG8_STAGE(PG8_SA(0, 1), a2 + hA, voffA);
;             PG8_WAIT_V(8); PG8_WAIT_L(0); PG8_BAR; PG8_MMA(0, 0, At, B0); PG8_MMA(0, 1, At, B1); PG8_BAR; PG8_SCHED;
;             PG8_LDA(At, 1, 1); PG8_STAGE(PG8_SB(1, 0), b3, voffB); PG8_STAGE(PG8_SB(1, 1), b3 + hB, voffB); PG8_STAGE(PG8_SA(1, 0), a3, voffA);
;             PG8_WAIT_V(8); PG8_WAIT_L(0); PG8_BAR; PG8_MMA(1, 0, At, B0); PG8_MMA(1, 1, At, B1); PG8_BAR; PG8_SCHED;
	s_setprio 1
	s_waitcnt lgkmcnt(0)
	v_mfma_f32_16x16x32_bf16 v[60:63], v[152:155], v[192:195], v[60:63]
	v_mfma_f32_16x16x32_bf16 v[56:59], v[160:163], v[192:195], v[56:59]
	v_mfma_f32_16x16x32_bf16 v[44:47], v[152:155], v[200:203], v[44:47]
	v_mfma_f32_16x16x32_bf16 v[40:43], v[160:163], v[200:203], v[40:43]
	v_mfma_f32_16x16x32_bf16 v[28:31], v[152:155], v[208:211], v[28:31]
	v_mfma_f32_16x16x32_bf16 v[24:27], v[160:163], v[208:211], v[24:27]
	v_mfma_f32_16x16x32_bf16 v[12:15], v[152:155], v[216:219], v[12:15]
	v_mfma_f32_16x16x32_bf16 v[8:11], v[160:163], v[216:219], v[8:11]
	v_mfma_f32_16x16x32_bf16 v[60:63], v[156:159], v[196:199], v[60:63]
	v_mfma_f32_16x16x32_bf16 v[56:59], v[164:167], v[196:199], v[56:59]
	v_mfma_f32_16x16x32_bf16 v[44:47], v[156:159], v[204:207], v[44:47]
	v_mfma_f32_16x16x32_bf16 v[40:43], v[164:167], v[204:207], v[40:43]
	v_mfma_f32_16x16x32_bf16 v[28:31], v[156:159], v[212:215], v[28:31]
	v_mfma_f32_16x16x32_bf16 v[24:27], v[164:167], v[212:215], v[24:27]
	v_mfma_f32_16x16x32_bf16 v[12:15], v[156:159], v[240:243], v[12:15]
	v_mfma_f32_16x16x32_bf16 v[8:11], v[164:167], v[240:243], v[8:11]
	s_setprio 0
	s_setprio 1
	v_mfma_f32_16x16x32_bf16 v[52:55], v[176:179], v[192:195], v[52:55]
	v_mfma_f32_16x16x32_bf16 v[48:51], v[184:187], v[192:195], v[48:51]
	v_mfma_f32_16x16x32_bf16 v[36:39], v[176:179], v[200:203], v[36:39]
	v_mfma_f32_16x16x32_bf16 v[32:35], v[184:187], v[200:203], v[32:35]
	v_mfma_f32_16x16x32_bf16 v[20:23], v[176:179], v[208:211], v[20:23]
	v_mfma_f32_16x16x32_bf16 v[16:19], v[184:187], v[208:211], v[16:19]
	v_mfma_f32_16x16x32_bf16 v[4:7], v[176:179], v[216:219], v[4:7]
	v_mfma_f32_16x16x32_bf16 v[0:3], v[184:187], v[216:219], v[0:3]
	v_mfma_f32_16x16x32_bf16 v[52:55], v[180:183], v[196:199], v[52:55]
	v_mfma_f32_16x16x32_bf16 v[48:51], v[188:191], v[196:199], v[48:51]
	v_mfma_f32_16x16x32_bf16 v[36:39], v[180:183], v[204:207], v[36:39]
	v_mfma_f32_16x16x32_bf16 v[32:35], v[188:191], v[204:207], v[32:35]
	v_mfma_f32_16x16x32_bf16 v[20:23], v[180:183], v[212:215], v[20:23]
	v_mfma_f32_16x16x32_bf16 v[16:19], v[188:191], v[212:215], v[16:19]
	v_mfma_f32_16x16x32_bf16 v[4:7], v[180:183], v[240:243], v[4:7]
	v_mfma_f32_16x16x32_bf16 v[0:3], v[188:191], v[240:243], v[0:3]
	s_setprio 0
	v_lshl_add_u64 v[142:143], v[142:143], 0, s[80:81]
	v_lshl_add_u64 v[144:145], v[144:145], 0, s[80:81]
	s_mov_b32 s10, s11
	s_cmp_lg_u32 s10, s55
	s_barrier
	s_cbranch_scc1 .LBB0_354
.Lq5_last:
	s_add_i32 s11, s10, 2
	s_cmp_eq_u32 s55, s10
	s_cselect_b64 vcc, -1, 0
	v_add_u32_e32 v148, s33, v149
	s_add_i32 s10, 0, 0x14000
	ds_read_b128 v[152:155], v148
	ds_read_b128 v[156:159], v148 offset:1024
	ds_read_b128 v[160:163], v148 offset:2048
	ds_read_b128 v[164:167], v148 offset:3072
	v_add_u32_e32 v148, s10, v149
	ds_read_b128 v[176:179], v148
	ds_read_b128 v[180:183], v148 offset:1024
	ds_read_b128 v[184:187], v148 offset:2048
	ds_read_b128 v[188:191], v148 offset:3072
	v_lshl_add_u64 v[146:147], v[142:143], 0, s[92:93]
	v_cndmask_b32_e32 v147, v147, v139, vcc
	v_cndmask_b32_e32 v146, v146, v138, vcc
	v_cndmask_b32_e32 v221, v145, v141, vcc
	v_cndmask_b32_e32 v220, v144, v140, vcc
	v_lshl_add_u64 v[244:245], v[142:143], 0, v[134:135]
	s_add_i32 m0, s25, 0xc000
	ds_read_b128 v[192:195], v151
	ds_read_b128 v[196:199], v151 offset:1024
	ds_read_b128 v[200:203], v151 offset:2048
	ds_read_b128 v[204:207], v151 offset:3072
	ds_read_b128 v[208:211], v151 offset:4096
	ds_read_b128 v[212:215], v151 offset:5120
	ds_read_b128 v[216:219], v151 offset:6144
	ds_read_b128 v[240:243], v151 offset:7168
	global_load_lds_dwordx4 v[244:245], off
	v_lshl_add_u64 v[244:245], v[142:143], 0, v[136:137]
	s_add_i32 m0, s25, 0xe000
	s_nop 0
	global_load_lds_dwordx4 v[244:245], off
	s_waitcnt vmcnt(8)
	s_waitcnt lgkmcnt(0)
	s_barrier
	s_setprio 1
	s_waitcnt lgkmcnt(0)
	v_mfma_f32_16x16x32_bf16 v[124:127], v[152:155], v[192:195], v[124:127]
	v_mfma_f32_16x16x32_bf16 v[120:123], v[160:163], v[192:195], v[120:123]
	v_mfma_f32_16x16x32_bf16 v[108:111], v[152:155], v[200:203], v[108:111]
	v_mfma_f32_16x16x32_bf16 v[104:107], v[160:163], v[200:203], v[104:107]
	v_mfma_f32_16x16x32_bf16 v[92:95], v[152:155], v[208:211], v[92:95]
	v_mfma_f32_16x16x32_bf16 v[88:91], v[160:163], v[208:211], v[88:91]
	v_mfma_f32_16x16x32_bf16 v[76:79], v[152:155], v[216:219], v[76:79]
	v_mfma_f32_16x16x32_bf16 v[72:75], v[160:163], v[216:219], v[72:75]
	v_mfma_f32_16x16x32_bf16 v[124:127], v[156:159], v[196:199], v[124:127]
	v_mfma_f32_16x16x32_bf16 v[120:123], v[164:167], v[196:199], v[120:123]
	v_mfma_f32_16x16x32_bf16 v[108:111], v[156:159], v[204:207], v[108:111]
	v_mfma_f32_16x16x32_bf16 v[104:107], v[164:167], v[204:207], v[104:107]
	v_mfma_f32_16x16x32_bf16 v[92:95], v[156:159], v[212:215], v[92:95]
	v_mfma_f32_16x16x32_bf16 v[88:91], v[164:167], v[212:215], v[88:91]
	v_mfma_f32_16x16x32_bf16 v[76:79], v[156:159], v[240:243], v[76:79]
	v_mfma_f32_16x16x32_bf16 v[72:75], v[164:167], v[240:243], v[72:75]
	s_setprio 0
	s_setprio 1
	v_mfma_f32_16x16x32_bf16 v[116:119], v[176:179], v[192:195], v[116:119]
	v_mfma_f32_16x16x32_bf16 v[112:115], v[184:187], v[192:195], v[112:115]
	v_mfma_f32_16x16x32_bf16 v[100:103], v[176:179], v[200:203], v[100:103]
	v_mfma_f32_16x16x32_bf16 v[96:99], v[184:187], v[200:203], v[96:99]
	v_mfma_f32_16x16x32_bf16 v[84:87], v[176:179], v[208:211], v[84:87]
	v_mfma_f32_16x16x32_bf16 v[80:83], v[184:187], v[208:211], v[80:83]
	v_mfma_f32_16x16x32_bf16 v[68:71], v[176:179], v[216:219], v[68:71]
	v_mfma_f32_16x16x32_bf16 v[64:67], v[184:187], v[216:219], v[64:67]
	v_mfma_f32_16x16x32_bf16 v[116:119], v[180:183], v[196:199], v[116:119]
	v_mfma_f32_16x16x32_bf16 v[112:115], v[188:191], v[196:199], v[112:115]
	v_mfma_f32_16x16x32_bf16 v[100:103], v[180:183], v[204:207], v[100:103]
	v_mfma_f32_16x16x32_bf16 v[96:99], v[188:191], v[204:207], v[96:99]
	v_mfma_f32_16x16x32_bf16 v[84:87], v[180:183], v[212:215], v[84:87]
	v_mfma_f32_16x16x32_bf16 v[80:83], v[188:191], v[212:215], v[80:83]
	v_mfma_f32_16x16x32_bf16 v[68:71], v[180:183], v[240:243], v[68:71]
	v_mfma_f32_16x16x32_bf16 v[64:67], v[188:191], v[240:243], v[64:67]
	s_setprio 0
	s_barrier
; #define PG8_STAGE(bufoff, gbase, voff) do { _Pragma("unroll") for (int _i = 0; _i < 2; ++_i) \
;         __builtin_amdgcn_global_load_lds((const unsigned*)((const char*)(gbase) + (voff)[_i]), (LAS unsigned*)(lds + (bufoff) + ldsw + _i * 8192), 16, 0, 0); } while (0)
; #define PG8_LDA(dst, b, h) do { _Pragma("unroll") for (int m = 0; m < 4; ++m) _Pragma("unroll") for (int k = 0; k < 2; ++k) dst[m][k] = *(const LAS bf16x8*)(lds + PG8_SA(b, h) + aoff + m * 2048 + k * 1024); } while (0)
; #define PG8_LDB(dst, b, h) do { _Pragma("unroll") for (int n = 0; n < 2; ++n) _Pragma("unroll") for (int k = 0; k < 2; ++k) dst[n][k] = *(const LAS bf16x8*)(lds + PG8_SB(b, h) + boff + n * 2048 + k * 1024); } while (0)
; #define PG8_MMA(ai, bj, At, Bt) do { __builtin_amdgcn_s_setprio(1); _Pragma("unroll") for (int k = 0; k < 2; ++k) _Pragma("unroll") for (int m = 0; m < 4; ++m) _Pragma("unroll") for (int n = 0; n < 2; ++n) \
;         acc[ai][bj][m][n] = __builtin_amdgcn_mfma_f32_16x16x32_bf16(Bt[n][k], At[m][k], acc[ai][bj][m][n], 0, 0, 0); __builtin_amdgcn_s_setprio(0); } while (0)
; #define PG8_WAIT_V(n) asm volatile("s_waitcnt vmcnt(" #n ")" ::: "memory")
; #define PG8_WAIT_L(n) asm volatile("s_waitcnt lgkmcnt(" #n ")" ::: "memory")
; #define PG8_BAR __builtin_amdgcn_s_barrier()
; #define PG8_SCHED __builtin_amdgcn_sched_barrier(0)
; template <class Epi, bool ALIGN_EPI>
; __device__ __forceinline__ void gemm_phase(LAS unsigned char* lds, const Gemm g, const StaticOrder& S, const Epi& E, const int tid) {
;     ...
;             PG8_LDA(At, 0, 1); PG8_STAGE(PG8_SB(0, 0), b2, voffB); PG8_STAGE(PG8_SB(0, 1), b2 + hB, voffB); PG8_STAGE(PG8_SA(0, 0), a2, voffA);
;             PG8_WAIT_V(8); PG8_WAIT_L(0); PG8_BAR; PG8_MMA(1, 0, At, B0); PG8_MMA(1, 1, At, B1); PG8_BAR; PG8_SCHED;
;             PG8_LDB(B0, 1, 0); PG8_LDB(B1, 1, 1); PG8_SCHED; PG8_LDA(At, 1, 0); PG8_STAGE(PG8_SA(0, 1), a2 + hA, voffA);
;             PG8_WAIT_V(8); PG8_WAIT_L(0); PG8_BAR; PG8_MMA(0, 0, At, B0); PG8_MMA(0, 1, At, B1); PG8_BAR; PG8_SCHED;
	s_add_i32 s62, s33, s45
	v_lshl_add_u64 v[244:245], v[220:221], 0, v[168:169]
	s_mov_b32 m0, s62
	ds_read_b128 v[192:195], v151 offset:16384
	ds_read_b128 v[196:199], v151 offset:17408
	ds_read_b128 v[200:203], v151 offset:18432
	ds_read_b128 v[204:207], v151 offset:19456
	ds_read_b128 v[208:211], v151 offset:20480
	ds_read_b128 v[212:215], v151 offset:21504
	ds_read_b128 v[216:219], v151 offset:22528
	ds_read_b128 v[240:243], v151 offset:23552
	global_load_lds_dwordx4 v[244:245], off
	v_lshl_add_u64 v[246:247], v[220:221], 0, v[128:129]
	s_add_i32 m0, s62, 0x2000
	v_lshl_add_u64 v[220:221], v[220:221], 0, s[12:13]
	s_add_i32 s10, s10, s45
	global_load_lds_dwordx4 v[246:247], off
	v_lshl_add_u64 v[248:249], v[220:221], 0, v[168:169]
	s_mov_b32 m0, s10
	v_lshl_add_u64 v[220:221], v[220:221], 0, v[128:129]
	global_load_lds_dwordx4 v[248:249], off
	s_add_i32 m0, s10, 0x2000
	v_lshl_add_u64 v[250:251], v[146:147], 0, v[132:133]
	global_load_lds_dwordx4 v[220:221], off
	s_mov_b32 m0, s25
	v_lshl_add_u64 v[252:253], v[146:147], 0, v[130:131]
	global_load_lds_dwordx4 v[250:251], off
	s_mov_b32 m0, s50
	s_nop 0
	global_load_lds_dwordx4 v[252:253], off
	s_waitcnt vmcnt(8)
	s_waitcnt lgkmcnt(0)
	s_barrier
	s_setprio 1
	s_waitcnt lgkmcnt(0)
	v_mfma_f32_16x16x32_bf16 v[60:63], v[152:155], v[192:195], v[60:63]
	v_mfma_f32_16x16x32_bf16 v[56:59], v[160:163], v[192:195], v[56:59]
	v_mfma_f32_16x16x32_bf16 v[44:47], v[152:155], v[200:203], v[44:47]
	v_mfma_f32_16x16x32_bf16 v[40:43], v[160:163], v[200:203], v[40:43]
	v_mfma_f32_16x16x32_bf16 v[28:31], v[152:155], v[208:211], v[28:31]
	v_mfma_f32_16x16x32_bf16 v[24:27], v[160:163], v[208:211], v[24:27]
	v_mfma_f32_16x16x32_bf16 v[12:15], v[152:155], v[216:219], v[12:15]
	v_mfma_f32_16x16x32_bf16 v[8:11], v[160:163], v[216:219], v[8:11]
	v_mfma_f32_16x16x32_bf16 v[60:63], v[156:159], v[196:199], v[60:63]
	v_mfma_f32_16x16x32_bf16 v[56:59], v[164:167], v[196:199], v[56:59]
	v_mfma_f32_16x16x32_bf16 v[44:47], v[156:159], v[204:207], v[44:47]
	v_mfma_f32_16x16x32_bf16 v[40:43], v[164:167], v[204:207], v[40:43]
	v_mfma_f32_16x16x32_bf16 v[28:31], v[156:159], v[212:215], v[28:31]
	v_mfma_f32_16x16x32_bf16 v[24:27], v[164:167], v[212:215], v[24:27]
	v_mfma_f32_16x16x32_bf16 v[12:15], v[156:159], v[240:243], v[12:15]
	v_mfma_f32_16x16x32_bf16 v[8:11], v[164:167], v[240:243], v[8:11]
	s_setprio 0
	s_setprio 1
	v_mfma_f32_16x16x32_bf16 v[52:55], v[176:179], v[192:195], v[52:55]
	v_mfma_f32_16x16x32_bf16 v[48:51], v[184:187], v[192:195], v[48:51]
	v_mfma_f32_16x16x32_bf16 v[36:39], v[176:179], v[200:203], v[36:39]
	v_mfma_f32_16x16x32_bf16 v[32:35], v[184:187], v[200:203], v[32:35]
	v_mfma_f32_16x16x32_bf16 v[20:23], v[176:179], v[208:211], v[20:23]
	v_mfma_f32_16x16x32_bf16 v[16:19], v[184:187], v[208:211], v[16:19]
	v_mfma_f32_16x16x32_bf16 v[4:7], v[176:179], v[216:219], v[4:7]
	v_mfma_f32_16x16x32_bf16 v[0:3], v[184:187], v[216:219], v[0:3]
	v_mfma_f32_16x16x32_bf16 v[52:55], v[180:183], v[196:199], v[52:55]
	v_mfma_f32_16x16x32_bf16 v[48:51], v[188:191], v[196:199], v[48:51]
	v_mfma_f32_16x16x32_bf16 v[36:39], v[180:183], v[204:207], v[36:39]
	v_mfma_f32_16x16x32_bf16 v[32:35], v[188:191], v[204:207], v[32:35]
	v_mfma_f32_16x16x32_bf16 v[20:23], v[180:183], v[212:215], v[20:23]
	v_mfma_f32_16x16x32_bf16 v[16:19], v[188:191], v[212:215], v[16:19]
	v_mfma_f32_16x16x32_bf16 v[4:7], v[180:183], v[240:243], v[4:7]
	v_mfma_f32_16x16x32_bf16 v[0:3], v[188:191], v[240:243], v[0:3]
	s_setprio 0
	s_barrier
	s_add_i32 s10, 0, 0x18000
	v_add_u32_e32 v148, s10, v149
	s_add_i32 s62, 0, 0x1c000
	ds_read_b128 v[152:155], v148
	ds_read_b128 v[156:159], v148 offset:1024
	ds_read_b128 v[160:163], v148 offset:2048
	ds_read_b128 v[164:167], v148 offset:3072
	v_add_u32_e32 v148, s62, v149
	ds_read_b128 v[176:179], v148
	ds_read_b128 v[180:183], v148 offset:1024
	ds_read_b128 v[184:187], v148 offset:2048
	ds_read_b128 v[188:191], v148 offset:3072
	v_lshl_add_u64 v[146:147], v[146:147], 0, s[94:95]
	s_mov_b32 m0, s51
	v_lshl_add_u64 v[226:227], v[146:147], 0, v[132:133]
	ds_read_b128 v[192:195], v151 offset:32768
	ds_read_b128 v[196:199], v151 offset:33792
	ds_read_b128 v[200:203], v151 offset:34816
	ds_read_b128 v[204:207], v151 offset:35840
	ds_read_b128 v[208:211], v151 offset:36864
	ds_read_b128 v[212:215], v151 offset:37888
	ds_read_b128 v[216:219], v151 offset:38912
	ds_read_b128 v[240:243], v151 offset:39936
	global_load_lds_dwordx4 v[226:227], off
	v_lshl_add_u64 v[146:147], v[146:147], 0, v[130:131]
	s_mov_b32 m0, s52
	s_nop 0
	global_load_lds_dwordx4 v[146:147], off
	s_waitcnt vmcnt(8)
	s_waitcnt lgkmcnt(0)
	s_barrier
; __device__ __forceinline__ unsigned cvt_pk_bf16(float lo, float hi) { unsigned r; asm volatile("v_cvt_pk_bf16_f32 %0, %1, %2" : "=v"(r) : "v"(lo), "v"(hi)); return r; }
; __device__ __forceinline__ float gelu_tanh(float x) { const float u = 0.7978845608028654f * (x + 0.044715f * x * x * x); return x * fast_rcp(1.0f + fast_exp2(-2.0f * LOG2E * u)); }
; #define PG8_STAGE(bufoff, gbase, voff) do { _Pragma("unroll") for (int _i = 0; _i < 2; ++_i) \
;         __builtin_amdgcn_global_load_lds((const unsigned*)((const char*)(gbase) + (voff)[_i]), (LAS unsigned*)(lds + (bufoff) + ldsw + _i * 8192), 16, 0, 0); } while (0)
; #define PG8_LDA(dst, b, h) do { _Pragma("unroll") for (int m = 0; m < 4; ++m) _Pragma("unroll") for (int k = 0; k < 2; ++k) dst[m][k] = *(const LAS bf16x8*)(lds + PG8_SA(b, h) + aoff + m * 2048 + k * 1024); } while (0)
; #define PG8_WAIT_V(n) asm volatile("s_waitcnt vmcnt(" #n ")" ::: "memory")
;     __device__ __forceinline__ void operator()(const f32x4 (&acc)[2][2][4][2], const Unit& u, int wr, int wc, int fr, int fq) const {
;         const int row0 = u.pm * BM + wr * 64 + fr, col0 = u.pn * BM + wc * 32 + 8 * fq;
;         float rsv[2][4]; load_rstd(rsv, ssq, row0);
; #pragma unroll
;         for (int ai = 0; ai < 2; ++ai)
; #pragma unroll
;             for (int m = 0; m < 4; ++m) { const int row = row0 + ai * HALF + m * 16; bf16_t* rowp = O + (size_t)row * ldc + col0; const float rs = rsv[ai][m];
; #pragma unroll
;                 for (int bj = 0; bj < 2; ++bj) { f32x4 v0 = acc[ai][bj][m][0] * rs, v1 = acc[ai][bj][m][1] * rs;
;                     if (ACT == 1) {
; #pragma unroll
;                         for (int j = 0; j < 4; ++j) { v0[j] = gelu_tanh(v0[j]); v1[j] = gelu_tanh(v1[j]); } }
;                     u32x4 w; w.x = cvt_pk_bf16(v0[0], v0[1]); w.y = cvt_pk_bf16(v0[2], v0[3]); w.z = cvt_pk_bf16(v1[0], v1[1]); w.w = cvt_pk_bf16(v1[2], v1[3]);
;                     *(u32x4*)(rowp + bj * HALF) = w; } }
; template <class Epi, bool ALIGN_EPI>
; __device__ __forceinline__ void gemm_phase(LAS unsigned char* lds, const Gemm g, const StaticOrder& S, const Epi& E, const int tid) {
;     ...
;             PG8_LDA(At, 1, 1); PG8_STAGE(PG8_SB(1, 0), b3, voffB); PG8_STAGE(PG8_SB(1, 1), b3 + hB, voffB); PG8_STAGE(PG8_SA(1, 0), a3, voffA);
;             PG8_WAIT_V(8); PG8_WAIT_L(0); PG8_BAR; PG8_MMA(1, 0, At, B0); PG8_MMA(1, 1, At, B1); PG8_BAR; PG8_SCHED;
	s_setprio 1
	s_waitcnt lgkmcnt(0)
	v_mfma_f32_16x16x32_bf16 v[124:127], v[152:155], v[192:195], v[124:127]
	v_mfma_f32_16x16x32_bf16 v[120:123], v[160:163], v[192:195], v[120:123]
	v_mfma_f32_16x16x32_bf16 v[108:111], v[152:155], v[200:203], v[108:111]
	v_mfma_f32_16x16x32_bf16 v[104:107], v[160:163], v[200:203], v[104:107]
	v_mfma_f32_16x16x32_bf16 v[92:95], v[152:155], v[208:211], v[92:95]
	v_mfma_f32_16x16x32_bf16 v[88:91], v[160:163], v[208:211], v[88:91]
	v_mfma_f32_16x16x32_bf16 v[76:79], v[152:155], v[216:219], v[76:79]
	v_mfma_f32_16x16x32_bf16 v[72:75], v[160:163], v[216:219], v[72:75]
	v_mfma_f32_16x16x32_bf16 v[124:127], v[156:159], v[196:199], v[124:127]
	v_mfma_f32_16x16x32_bf16 v[120:123], v[164:167], v[196:199], v[120:123]
	v_mfma_f32_16x16x32_bf16 v[108:111], v[156:159], v[204:207], v[108:111]
	v_mfma_f32_16x16x32_bf16 v[104:107], v[164:167], v[204:207], v[104:107]
	v_mfma_f32_16x16x32_bf16 v[92:95], v[156:159], v[212:215], v[92:95]
	v_mfma_f32_16x16x32_bf16 v[88:91], v[164:167], v[212:215], v[88:91]
	v_mfma_f32_16x16x32_bf16 v[76:79], v[156:159], v[240:243], v[76:79]
	v_mfma_f32_16x16x32_bf16 v[72:75], v[164:167], v[240:243], v[72:75]
	s_setprio 0
	s_setprio 1
	v_mfma_f32_16x16x32_bf16 v[116:119], v[176:179], v[192:195], v[116:119]
	v_mfma_f32_16x16x32_bf16 v[112:115], v[184:187], v[192:195], v[112:115]
	v_mfma_f32_16x16x32_bf16 v[100:103], v[176:179], v[200:203], v[100:103]
	v_mfma_f32_16x16x32_bf16 v[96:99], v[184:187], v[200:203], v[96:99]
	v_mfma_f32_16x16x32_bf16 v[84:87], v[176:179], v[208:211], v[84:87]
	v_mfma_f32_16x16x32_bf16 v[80:83], v[184:187], v[208:211], v[80:83]
	v_mfma_f32_16x16x32_bf16 v[68:71], v[176:179], v[216:219], v[68:71]
	v_mfma_f32_16x16x32_bf16 v[64:67], v[184:187], v[216:219], v[64:67]
	v_mfma_f32_16x16x32_bf16 v[116:119], v[180:183], v[196:199], v[116:119]
	v_mfma_f32_16x16x32_bf16 v[112:115], v[188:191], v[196:199], v[112:115]
	v_mfma_f32_16x16x32_bf16 v[100:103], v[180:183], v[204:207], v[100:103]
	v_mfma_f32_16x16x32_bf16 v[96:99], v[188:191], v[204:207], v[96:99]
	v_mfma_f32_16x16x32_bf16 v[84:87], v[180:183], v[212:215], v[84:87]
	v_mfma_f32_16x16x32_bf16 v[80:83], v[188:191], v[212:215], v[80:83]
	v_mfma_f32_16x16x32_bf16 v[68:71], v[180:183], v[240:243], v[68:71]
	v_mfma_f32_16x16x32_bf16 v[64:67], v[188:191], v[240:243], v[64:67]
	s_setprio 0
	s_barrier
	s_add_i32 s10, s10, s45
	v_lshl_add_u64 v[146:147], v[244:245], 0, s[92:93]
	s_mov_b32 m0, s10
	ds_read_b128 v[192:195], v151 offset:49152
	ds_read_b128 v[196:199], v151 offset:50176
	ds_read_b128 v[200:203], v151 offset:51200
	ds_read_b128 v[204:207], v151 offset:52224
	ds_read_b128 v[208:211], v151 offset:53248
	ds_read_b128 v[212:215], v151 offset:54272
	ds_read_b128 v[216:219], v151 offset:55296
	ds_read_b128 v[240:243], v151 offset:56320
	global_load_lds_dwordx4 v[146:147], off
	v_lshl_add_u64 v[146:147], v[246:247], 0, s[92:93]
	s_add_i32 m0, s10, 0x2000
	s_add_i32 s10, s62, s45
	global_load_lds_dwordx4 v[146:147], off
	v_lshl_add_u64 v[146:147], v[248:249], 0, s[92:93]
	s_mov_b32 m0, s10
	s_nop 0
	global_load_lds_dwordx4 v[146:147], off
	v_lshl_add_u64 v[146:147], v[220:221], 0, s[92:93]
	s_add_i32 m0, s10, 0x2000
	s_nop 0
	global_load_lds_dwordx4 v[146:147], off
	v_lshl_add_u64 v[146:147], v[250:251], 0, s[92:93]
	s_mov_b32 m0, s53
	s_nop 0
	global_load_lds_dwordx4 v[146:147], off
	v_lshl_add_u64 v[146:147], v[252:253], 0, s[92:93]
	s_mov_b32 m0, s54
	s_nop 0
	global_load_lds_dwordx4 v[146:147], off
	s_waitcnt vmcnt(8)
	s_waitcnt lgkmcnt(0)
	s_barrier
	s_setprio 1
	s_waitcnt lgkmcnt(0)
	v_mfma_f32_16x16x32_bf16 v[60:63], v[152:155], v[192:195], v[60:63]
	v_lshrrev_b32_e32 v171, 8, v170
	v_and_b32_e32 v234, 15, v170
	v_lshl_add_u32 v171, v171, 6, v234
	s_lshl_b32 s98, s61, 8
	v_add_u32_e32 v171, s98, v171
	v_mfma_f32_16x16x32_bf16 v[56:59], v[160:163], v[192:195], v[56:59]
	v_mul_lo_u32 v171, v171, s28
	v_bfe_u32 v234, v170, 6, 2
	v_bfe_u32 v224, v170, 4, 2
	v_lshlrev_b32_e32 v234, 5, v234
	v_lshl_or_b32 v234, v224, 3, v234
	v_mfma_f32_16x16x32_bf16 v[44:47], v[152:155], v[200:203], v[44:47]
	s_lshl_b32 s98, s60, 8
	v_add_u32_e32 v234, s98, v234
	v_add_lshl_u32 v232, v171, v234, 1
	v_mov_b32_e32 v233, 0
	v_lshl_add_u64 v[232:233], v[232:233], 0, s[30:31]
	v_mfma_f32_16x16x32_bf16 v[40:43], v[160:163], v[200:203], v[40:43]
	s_lshl_b32 s98, s28, 5
	s_mov_b32 s99, 0
	v_mul_f32_e32 v124, v172, v124
	v_mul_f32_e32 v125, v172, v125
	v_mul_f32_e32 v126, v172, v126
	v_mfma_f32_16x16x32_bf16 v[28:31], v[152:155], v[208:211], v[28:31]
	v_mul_f32_e32 v127, v172, v127
	v_mul_f32_e32 v120, v172, v120
	v_mul_f32_e32 v121, v172, v121
	v_mul_f32_e32 v122, v172, v122
	v_mul_f32_e32 v123, v172, v123
	v_mfma_f32_16x16x32_bf16 v[24:27], v[160:163], v[208:211], v[24:27]
	v_cvt_pk_bf16_f32 v124, v124, v125
	v_cvt_pk_bf16_f32 v125, v126, v127
	v_cvt_pk_bf16_f32 v126, v120, v121
	v_cvt_pk_bf16_f32 v127, v122, v123
	global_store_dwordx4 v[232:233], v[124:127], off
	v_mfma_f32_16x16x32_bf16 v[12:15], v[152:155], v[216:219], v[12:15]
	v_mul_f32_e32 v116, v172, v116
	v_mul_f32_e32 v117, v172, v117
	v_mul_f32_e32 v118, v172, v118
	v_mul_f32_e32 v119, v172, v119
	v_mul_f32_e32 v112, v172, v112
	v_mfma_f32_16x16x32_bf16 v[8:11], v[160:163], v[216:219], v[8:11]
	v_mul_f32_e32 v113, v172, v113
	v_mul_f32_e32 v114, v172, v114
; __device__ __forceinline__ unsigned cvt_pk_bf16(float lo, float hi) { unsigned r; asm volatile("v_cvt_pk_bf16_f32 %0, %1, %2" : "=v"(r) : "v"(lo), "v"(hi)); return r; }
; __device__ __forceinline__ float gelu_tanh(float x) { const float u = 0.7978845608028654f * (x + 0.044715f * x * x * x); return x * fast_rcp(1.0f + fast_exp2(-2.0f * LOG2E * u)); }
; #define PG8_BAR __builtin_amdgcn_s_barrier()
;     __device__ __forceinline__ void operator()(const f32x4 (&acc)[2][2][4][2], const Unit& u, int wr, int wc, int fr, int fq) const {
;     ...
;             for (int m = 0; m < 4; ++m) { const int row = row0 + ai * HALF + m * 16; bf16_t* rowp = O + (size_t)row * ldc + col0; const float rs = rsv[ai][m];
; #pragma unroll
;                 for (int bj = 0; bj < 2; ++bj) { f32x4 v0 = acc[ai][bj][m][0] * rs, v1 = acc[ai][bj][m][1] * rs;
;                     if (ACT == 1) {
; #pragma unroll
;                         for (int j = 0; j < 4; ++j) { v0[j] = gelu_tanh(v0[j]); v1[j] = gelu_tanh(v1[j]); } }
;                     u32x4 w; w.x = cvt_pk_bf16(v0[0], v0[1]); w.y = cvt_pk_bf16(v0[2], v0[3]); w.z = cvt_pk_bf16(v1[0], v1[1]); w.w = cvt_pk_bf16(v1[2], v1[3]);
;                     *(u32x4*)(rowp + bj * HALF) = w; } }
; template <class Epi, bool ALIGN_EPI>
; __device__ __forceinline__ void gemm_phase(LAS unsigned char* lds, const Gemm g, const StaticOrder& S, const Epi& E, const int tid) {
;     ...
;         if constexpr (ALIGN_EPI) { if (wr == 0) PG8_BAR; }
;         { int t2 = tid; asm volatile("" : "+v"(t2)); const int l2 = t2 & 63, w2 = __builtin_amdgcn_readfirstlane(t2 >> 6); E(acc, cur, w2 >> 2, w2 & 3, l2 & 15, l2 >> 4); }
;         if (!has_next) break;
; #pragma unroll
;         for (int a = 0; a < 2; ++a)
; #pragma unroll
;             for (int b = 0; b < 2; ++b)
; #pragma unroll
;                 for (int m = 0; m < 4; ++m)
; #pragma unroll
;                     for (int n = 0; n < 2; ++n) acc[a][b][m][n] = (f32x4){0.f, 0.f, 0.f, 0.f};
;         cur = nxt; cA = nA; cB = nB; ++ui;
;         if constexpr (ALIGN_EPI) { if (wr == 1) PG8_BAR; }
	v_mul_f32_e32 v115, v172, v115
	v_cvt_pk_bf16_f32 v116, v116, v117
	v_cvt_pk_bf16_f32 v117, v118, v119
	v_mfma_f32_16x16x32_bf16 v[60:63], v[156:159], v[196:199], v[60:63]
	v_cvt_pk_bf16_f32 v118, v112, v113
	v_cvt_pk_bf16_f32 v119, v114, v115
	global_store_dwordx4 v[232:233], v[116:119], off offset:256
	v_lshl_add_u64 v[232:233], v[232:233], 0, s[98:99]
	v_mul_f32_e32 v108, v173, v108
	v_mfma_f32_16x16x32_bf16 v[56:59], v[164:167], v[196:199], v[56:59]
	v_mul_f32_e32 v109, v173, v109
	v_mul_f32_e32 v110, v173, v110
	v_mul_f32_e32 v111, v173, v111
	v_mul_f32_e32 v104, v173, v104
	v_mul_f32_e32 v105, v173, v105
	v_mfma_f32_16x16x32_bf16 v[44:47], v[156:159], v[204:207], v[44:47]
	v_mul_f32_e32 v106, v173, v106
	v_mul_f32_e32 v107, v173, v107
	v_cvt_pk_bf16_f32 v108, v108, v109
	v_cvt_pk_bf16_f32 v109, v110, v111
	v_cvt_pk_bf16_f32 v110, v104, v105
	v_mfma_f32_16x16x32_bf16 v[40:43], v[164:167], v[204:207], v[40:43]
	v_cvt_pk_bf16_f32 v111, v106, v107
	global_store_dwordx4 v[232:233], v[108:111], off
	v_mul_f32_e32 v100, v173, v100
	v_mul_f32_e32 v101, v173, v101
	v_mul_f32_e32 v102, v173, v102
	v_mfma_f32_16x16x32_bf16 v[28:31], v[156:159], v[212:215], v[28:31]
	v_mul_f32_e32 v103, v173, v103
	v_mul_f32_e32 v96, v173, v96
	v_mul_f32_e32 v97, v173, v97
	v_mul_f32_e32 v98, v173, v98
	v_mul_f32_e32 v99, v173, v99
	v_mfma_f32_16x16x32_bf16 v[24:27], v[164:167], v[212:215], v[24:27]
	v_cvt_pk_bf16_f32 v100, v100, v101
	v_cvt_pk_bf16_f32 v101, v102, v103
	v_cvt_pk_bf16_f32 v102, v96, v97
	v_cvt_pk_bf16_f32 v103, v98, v99
	global_store_dwordx4 v[232:233], v[100:103], off offset:256
	v_mfma_f32_16x16x32_bf16 v[12:15], v[156:159], v[240:243], v[12:15]
	v_lshl_add_u64 v[232:233], v[232:233], 0, s[98:99]
	v_mul_f32_e32 v92, v236, v92
	v_mul_f32_e32 v93, v236, v93
	v_mul_f32_e32 v94, v236, v94
	v_mul_f32_e32 v95, v236, v95
	v_mfma_f32_16x16x32_bf16 v[8:11], v[164:167], v[240:243], v[8:11]
	v_mul_f32_e32 v88, v236, v88
	v_mul_f32_e32 v89, v236, v89
	v_mul_f32_e32 v90, v236, v90
	v_mul_f32_e32 v91, v236, v91
	v_cvt_pk_bf16_f32 v92, v92, v93
	s_setprio 0
	s_setprio 1
	v_mfma_f32_16x16x32_bf16 v[52:55], v[176:179], v[192:195], v[52:55]
	v_cvt_pk_bf16_f32 v93, v94, v95
	v_cvt_pk_bf16_f32 v94, v88, v89
	v_cvt_pk_bf16_f32 v95, v90, v91
	global_store_dwordx4 v[232:233], v[92:95], off
	v_mul_f32_e32 v84, v236, v84
	v_mfma_f32_16x16x32_bf16 v[48:51], v[184:187], v[192:195], v[48:51]
	v_mul_f32_e32 v85, v236, v85
	v_mul_f32_e32 v86, v236, v86
	v_mul_f32_e32 v87, v236, v87
	v_mul_f32_e32 v80, v236, v80
	v_mul_f32_e32 v81, v236, v81
	v_mfma_f32_16x16x32_bf16 v[36:39], v[176:179], v[200:203], v[36:39]
	v_mul_f32_e32 v82, v236, v82
	v_mul_f32_e32 v83, v236, v83
	v_cvt_pk_bf16_f32 v84, v84, v85
	v_cvt_pk_bf16_f32 v85, v86, v87
	v_cvt_pk_bf16_f32 v86, v80, v81
	v_mfma_f32_16x16x32_bf16 v[32:35], v[184:187], v[200:203], v[32:35]
	v_cvt_pk_bf16_f32 v87, v82, v83
	global_store_dwordx4 v[232:233], v[84:87], off offset:256
	v_lshl_add_u64 v[232:233], v[232:233], 0, s[98:99]
	v_mul_f32_e32 v76, v237, v76
	v_mul_f32_e32 v77, v237, v77
	v_mfma_f32_16x16x32_bf16 v[20:23], v[176:179], v[208:211], v[20:23]
	v_mul_f32_e32 v78, v237, v78
	v_mul_f32_e32 v79, v237, v79
	v_mul_f32_e32 v72, v237, v72
	v_mul_f32_e32 v73, v237, v73
	v_mul_f32_e32 v74, v237, v74
	v_mfma_f32_16x16x32_bf16 v[16:19], v[184:187], v[208:211], v[16:19]
	v_mul_f32_e32 v75, v237, v75
	v_cvt_pk_bf16_f32 v76, v76, v77
	v_cvt_pk_bf16_f32 v77, v78, v79
	v_cvt_pk_bf16_f32 v78, v72, v73
	v_cvt_pk_bf16_f32 v79, v74, v75
	v_mfma_f32_16x16x32_bf16 v[4:7], v[176:179], v[216:219], v[4:7]
	global_store_dwordx4 v[232:233], v[76:79], off
	v_mul_f32_e32 v68, v237, v68
	v_mul_f32_e32 v69, v237, v69
	v_mul_f32_e32 v70, v237, v70
	v_mul_f32_e32 v71, v237, v71
	v_mfma_f32_16x16x32_bf16 v[0:3], v[184:187], v[216:219], v[0:3]
	v_mul_f32_e32 v64, v237, v64
	v_mul_f32_e32 v65, v237, v65
	v_mul_f32_e32 v66, v237, v66
	v_mul_f32_e32 v67, v237, v67
	v_cvt_pk_bf16_f32 v68, v68, v69
	v_mfma_f32_16x16x32_bf16 v[52:55], v[180:183], v[196:199], v[52:55]
	v_cvt_pk_bf16_f32 v69, v70, v71
	v_cvt_pk_bf16_f32 v70, v64, v65
	v_cvt_pk_bf16_f32 v71, v66, v67
	global_store_dwordx4 v[232:233], v[68:71], off offset:256
	v_lshl_add_u64 v[232:233], v[232:233], 0, s[98:99]
	v_mfma_f32_16x16x32_bf16 v[48:51], v[188:191], v[196:199], v[48:51]
	v_lshl_add_u64 v[232:233], v[232:233], 0, s[98:99]
	v_lshl_add_u64 v[232:233], v[232:233], 0, s[98:99]
	v_lshl_add_u64 v[232:233], v[232:233], 0, s[98:99]
	v_lshl_add_u64 v[232:233], v[232:233], 0, s[98:99]
	v_mfma_f32_16x16x32_bf16 v[36:39], v[180:183], v[204:207], v[36:39]
	v_mfma_f32_16x16x32_bf16 v[32:35], v[188:191], v[204:207], v[32:35]
	v_mfma_f32_16x16x32_bf16 v[20:23], v[180:183], v[212:215], v[20:23]
	v_mfma_f32_16x16x32_bf16 v[16:19], v[188:191], v[212:215], v[16:19]
	v_mfma_f32_16x16x32_bf16 v[4:7], v[180:183], v[240:243], v[4:7]
	v_mfma_f32_16x16x32_bf16 v[0:3], v[188:191], v[240:243], v[0:3]
	s_setprio 0
	v_lshl_add_u64 v[142:143], v[142:143], 0, s[80:81]
	v_lshl_add_u64 v[144:145], v[144:145], 0, s[80:81]
	s_and_b64 vcc, exec, s[8:9]
	s_barrier
	s_cbranch_vccnz .Lq5_notdefer
	s_cmp_lg_u32 s59, s61
	s_cbranch_scc1 .Lq5_notdefer
	s_mov_b32 s101, 1
	s_mov_b32 s60, s58
	s_mov_b32 s61, s59
	v_mov_b64_e32 v[144:145], v[140:141]
	v_mov_b64_e32 v[142:143], v[138:139]
	s_branch .LBB0_346

; #define PG8_STAGE(bufoff, gbase, voff) do { _Pragma("unroll") for (int _i = 0; _i < 2; ++_i) \
;         __builtin_amdgcn_global_load_lds((const unsigned*)((const char*)(gbase) + (voff)[_i]), (LAS unsigned*)(lds + (bufoff) + ldsw + _i * 8192), 16, 0, 0); } while (0)
; #define PG8_LDA(dst, b, h) do { _Pragma("unroll") for (int m = 0; m < 4; ++m) _Pragma("unroll") for (int k = 0; k < 2; ++k) dst[m][k] = *(const LAS bf16x8*)(lds + PG8_SA(b, h) + aoff + m * 2048 + k * 1024); } while (0)
; #define PG8_LDB(dst, b, h) do { _Pragma("unroll") for (int n = 0; n < 2; ++n) _Pragma("unroll") for (int k = 0; k < 2; ++k) dst[n][k] = *(const LAS bf16x8*)(lds + PG8_SB(b, h) + boff + n * 2048 + k * 1024); } while (0)
; #define PG8_MMA(ai, bj, At, Bt) do { __builtin_amdgcn_s_setprio(1); _Pragma("unroll") for (int k = 0; k < 2; ++k) _Pragma("unroll") for (int m = 0; m < 4; ++m) _Pragma("unroll") for (int n = 0; n < 2; ++n) \
;         acc[ai][bj][m][n] = __builtin_amdgcn_mfma_f32_16x16x32_bf16(Bt[n][k], At[m][k], acc[ai][bj][m][n], 0, 0, 0); __builtin_amdgcn_s_setprio(0); } while (0)
; #define PG8_WAIT_V(n) asm volatile("s_waitcnt vmcnt(" #n ")" ::: "memory")
; #define PG8_WAIT_L(n) asm volatile("s_waitcnt lgkmcnt(" #n ")" ::: "memory")
; #define PG8_BAR __builtin_amdgcn_s_barrier()
; #define PG8_SCHED __builtin_amdgcn_sched_barrier(0)
; template <class Epi, bool ALIGN_EPI>
; __device__ __forceinline__ void gemm_phase(LAS unsigned char* lds, const Gemm g, const StaticOrder& S, const Epi& E, const int tid) {
;     ...
;         for (int t = 0; t < nt; t += 2) {
;             const bool last = (t == nt - 2);
;             const char* a1 = cA + (size_t)(t + 1) * kstep;
;             const char* a2 = last ? nA : cA + (size_t)(t + 2) * kstep; const char* b2 = last ? nB : cB + (size_t)(t + 2) * kstep;
;             const char* a3 = a2 + kstep; const char* b3 = b2 + kstep;
;             PG8_LDB(B0, 0, 0); PG8_LDB(B1, 0, 1); PG8_SCHED; PG8_LDA(At, 0, 0); PG8_STAGE(PG8_SA(1, 1), a1 + hA, voffA);
;             PG8_WAIT_V(8); PG8_WAIT_L(0); PG8_BAR; PG8_MMA(0, 0, At, B0); PG8_MMA(0, 1, At, B1); PG8_BAR; PG8_SCHED;
;             PG8_LDA(At, 0, 1); PG8_STAGE(PG8_SB(0, 0), b2, voffB); PG8_STAGE(PG8_SB(0, 1), b2 + hB, voffB); PG8_STAGE(PG8_SA(0, 0), a2, voffA);
;             PG8_WAIT_V(8); PG8_WAIT_L(0); PG8_BAR; PG8_MMA(1, 0, At, B0); PG8_MMA(1, 1, At, B1); PG8_BAR; PG8_SCHED;
.LBB0_379:
	s_add_u32 s41, s34, s40
	s_addc_u32 s46, s35, 0
	s_add_u32 s44, s41, 0x100
	s_addc_u32 s45, s46, 0
	s_and_b64 s[42:43], s[38:39], exec
	s_cselect_b32 s43, s17, s45
	s_cselect_b32 s42, s59, s44
	s_add_u32 s40, s30, s40
	s_addc_u32 s44, s31, 0
	s_add_u32 s40, s40, 0x100
	s_addc_u32 s44, s44, 0
	s_and_b64 s[38:39], s[38:39], exec
	s_cselect_b32 s45, s15, s44
	s_cselect_b32 s44, s60, s40
	s_add_i32 s39, 0, 0x14000
	s_add_u32 s48, s41, 0x10080
	s_addc_u32 s49, s46, 0
	s_add_i32 s68, s33, s50
	s_add_i32 m0, s51, 0xc000
	s_add_i32 s71, s51, 0xe000
	s_add_i32 s65, s68, 0x2000
	v_add_u32_e32 v138, s33, v141
	s_add_u32 s46, s44, 0x10000
	ds_read_b128 v[134:137], v138
	ds_read_b128 v[146:149], v138 offset:1024
	ds_read_b128 v[150:153], v138 offset:2048
	ds_read_b128 v[154:157], v138 offset:3072
	v_add_u32_e32 v138, s39, v141
	s_addc_u32 s47, s45, 0
	s_add_i32 s67, s39, s50
	ds_read_b128 v[158:161], v138
	ds_read_b128 v[162:165], v138 offset:1024
	ds_read_b128 v[174:177], v138 offset:2048
	ds_read_b128 v[178:181], v138 offset:3072
	s_add_i32 s66, s67, 0x2000
	s_add_i32 s64, 0, 0x18000
	s_add_i32 s63, 0, 0x1c000
	s_add_u32 s40, s42, 0x10000
	s_addc_u32 s41, s43, 0
	s_add_i32 s62, s64, s50
	s_add_i32 s61, s62, 0x2000
	s_add_u32 s38, s44, 0x10080
	s_addc_u32 s39, s45, 0
	s_add_i32 s70, s63, s50
	s_add_i32 s69, s70, 0x2000
	v_lshl_add_u64 v[138:139], s[48:49], 0, v[128:129]
	ds_read_b128 v[182:185], v145
	ds_read_b128 v[186:189], v145 offset:1024
	ds_read_b128 v[190:193], v145 offset:2048
	ds_read_b128 v[194:197], v145 offset:3072
	ds_read_b128 v[198:201], v145 offset:4096
	ds_read_b128 v[202:205], v145 offset:5120
	ds_read_b128 v[206:209], v145 offset:6144
	ds_read_b128 v[210:213], v145 offset:7168
	global_load_lds_dwordx4 v[138:139], off
	v_lshl_add_u64 v[138:139], s[48:49], 0, v[130:131]
	s_mov_b32 m0, s71
	s_nop 0
	global_load_lds_dwordx4 v[138:139], off
	s_waitcnt vmcnt(8)
	s_waitcnt lgkmcnt(0)
	s_barrier
	s_setprio 1
	s_waitcnt lgkmcnt(0)
	v_mfma_f32_16x16x32_bf16 v[124:127], v[134:137], v[182:185], v[124:127]
	v_mfma_f32_16x16x32_bf16 v[120:123], v[150:153], v[182:185], v[120:123]
	v_mfma_f32_16x16x32_bf16 v[108:111], v[134:137], v[190:193], v[108:111]
	v_mfma_f32_16x16x32_bf16 v[104:107], v[150:153], v[190:193], v[104:107]
	v_mfma_f32_16x16x32_bf16 v[92:95], v[134:137], v[198:201], v[92:95]
	v_mfma_f32_16x16x32_bf16 v[88:91], v[150:153], v[198:201], v[88:91]
	v_mfma_f32_16x16x32_bf16 v[76:79], v[134:137], v[206:209], v[76:79]
	v_mfma_f32_16x16x32_bf16 v[72:75], v[150:153], v[206:209], v[72:75]
	v_mfma_f32_16x16x32_bf16 v[124:127], v[146:149], v[186:189], v[124:127]
	v_mfma_f32_16x16x32_bf16 v[120:123], v[154:157], v[186:189], v[120:123]
	v_mfma_f32_16x16x32_bf16 v[108:111], v[146:149], v[194:197], v[108:111]
	v_mfma_f32_16x16x32_bf16 v[104:107], v[154:157], v[194:197], v[104:107]
	v_mfma_f32_16x16x32_bf16 v[92:95], v[146:149], v[202:205], v[92:95]
	v_mfma_f32_16x16x32_bf16 v[88:91], v[154:157], v[202:205], v[88:91]
	v_mfma_f32_16x16x32_bf16 v[76:79], v[146:149], v[210:213], v[76:79]
	v_mfma_f32_16x16x32_bf16 v[72:75], v[154:157], v[210:213], v[72:75]
	s_setprio 0
	s_setprio 1
	v_mfma_f32_16x16x32_bf16 v[116:119], v[158:161], v[182:185], v[116:119]
	v_mfma_f32_16x16x32_bf16 v[112:115], v[174:177], v[182:185], v[112:115]
	v_mfma_f32_16x16x32_bf16 v[100:103], v[158:161], v[190:193], v[100:103]
	v_mfma_f32_16x16x32_bf16 v[96:99], v[174:177], v[190:193], v[96:99]
	v_mfma_f32_16x16x32_bf16 v[84:87], v[158:161], v[198:201], v[84:87]
	v_mfma_f32_16x16x32_bf16 v[80:83], v[174:177], v[198:201], v[80:83]
	v_mfma_f32_16x16x32_bf16 v[68:71], v[158:161], v[206:209], v[68:71]
	v_mfma_f32_16x16x32_bf16 v[64:67], v[174:177], v[206:209], v[64:67]
	v_mfma_f32_16x16x32_bf16 v[116:119], v[162:165], v[186:189], v[116:119]
	v_mfma_f32_16x16x32_bf16 v[112:115], v[178:181], v[186:189], v[112:115]
	v_mfma_f32_16x16x32_bf16 v[100:103], v[162:165], v[194:197], v[100:103]
	v_mfma_f32_16x16x32_bf16 v[96:99], v[178:181], v[194:197], v[96:99]
	v_mfma_f32_16x16x32_bf16 v[84:87], v[162:165], v[202:205], v[84:87]
	v_mfma_f32_16x16x32_bf16 v[80:83], v[178:181], v[202:205], v[80:83]
	v_mfma_f32_16x16x32_bf16 v[68:71], v[162:165], v[210:213], v[68:71]
	v_mfma_f32_16x16x32_bf16 v[64:67], v[178:181], v[210:213], v[64:67]
	s_setprio 0
	s_barrier
	s_mov_b32 m0, s68
	v_lshl_add_u64 v[138:139], s[44:45], 0, v[168:169]
	ds_read_b128 v[182:185], v145 offset:16384
	ds_read_b128 v[186:189], v145 offset:17408
	ds_read_b128 v[190:193], v145 offset:18432
	ds_read_b128 v[194:197], v145 offset:19456
	ds_read_b128 v[198:201], v145 offset:20480
	ds_read_b128 v[202:205], v145 offset:21504
	ds_read_b128 v[206:209], v145 offset:22528
	ds_read_b128 v[210:213], v145 offset:23552
	global_load_lds_dwordx4 v[138:139], off
	v_lshl_add_u64 v[142:143], s[44:45], 0, v[132:133]
	s_mov_b32 m0, s65
	v_lshl_add_u64 v[166:167], s[46:47], 0, v[168:169]
	global_load_lds_dwordx4 v[142:143], off
	s_mov_b32 m0, s67
	v_lshl_add_u64 v[214:215], s[42:43], 0, v[130:131]
	global_load_lds_dwordx4 v[166:167], off
	v_lshl_add_u64 v[166:167], s[46:47], 0, v[132:133]
	s_mov_b32 m0, s66
	s_nop 0
	global_load_lds_dwordx4 v[166:167], off
	v_lshl_add_u64 v[166:167], s[42:43], 0, v[128:129]
	s_mov_b32 m0, s51
	s_nop 0
	global_load_lds_dwordx4 v[166:167], off
	s_mov_b32 m0, s52
	s_nop 0
	global_load_lds_dwordx4 v[214:215], off
	s_waitcnt vmcnt(8)
	s_waitcnt lgkmcnt(0)
	s_barrier
; #define PG8_STAGE(bufoff, gbase, voff) do { _Pragma("unroll") for (int _i = 0; _i < 2; ++_i) \
;         __builtin_amdgcn_global_load_lds((const unsigned*)((const char*)(gbase) + (voff)[_i]), (LAS unsigned*)(lds + (bufoff) + ldsw + _i * 8192), 16, 0, 0); } while (0)
; #define PG8_LDA(dst, b, h) do { _Pragma("unroll") for (int m = 0; m < 4; ++m) _Pragma("unroll") for (int k = 0; k < 2; ++k) dst[m][k] = *(const LAS bf16x8*)(lds + PG8_SA(b, h) + aoff + m * 2048 + k * 1024); } while (0)
; #define PG8_LDB(dst, b, h) do { _Pragma("unroll") for (int n = 0; n < 2; ++n) _Pragma("unroll") for (int k = 0; k < 2; ++k) dst[n][k] = *(const LAS bf16x8*)(lds + PG8_SB(b, h) + boff + n * 2048 + k * 1024); } while (0)
; #define PG8_MMA(ai, bj, At, Bt) do { __builtin_amdgcn_s_setprio(1); _Pragma("unroll") for (int k = 0; k < 2; ++k) _Pragma("unroll") for (int m = 0; m < 4; ++m) _Pragma("unroll") for (int n = 0; n < 2; ++n) \
;         acc[ai][bj][m][n] = __builtin_amdgcn_mfma_f32_16x16x32_bf16(Bt[n][k], At[m][k], acc[ai][bj][m][n], 0, 0, 0); __builtin_amdgcn_s_setprio(0); } while (0)
; #define PG8_WAIT_V(n) asm volatile("s_waitcnt vmcnt(" #n ")" ::: "memory")
; #define PG8_WAIT_L(n) asm volatile("s_waitcnt lgkmcnt(" #n ")" ::: "memory")
; #define PG8_BAR __builtin_amdgcn_s_barrier()
; #define PG8_SCHED __builtin_amdgcn_sched_barrier(0)
; template <class Epi, bool ALIGN_EPI>
; __device__ __forceinline__ void gemm_phase(LAS unsigned char* lds, const Gemm g, const StaticOrder& S, const Epi& E, const int tid) {
;     ...
;             PG8_WAIT_V(8); PG8_WAIT_L(0); PG8_BAR; PG8_MMA(1, 0, At, B0); PG8_MMA(1, 1, At, B1); PG8_BAR; PG8_SCHED;
;             PG8_LDB(B0, 1, 0); PG8_LDB(B1, 1, 1); PG8_SCHED; PG8_LDA(At, 1, 0); PG8_STAGE(PG8_SA(0, 1), a2 + hA, voffA);
;             PG8_WAIT_V(8); PG8_WAIT_L(0); PG8_BAR; PG8_MMA(0, 0, At, B0); PG8_MMA(0, 1, At, B1); PG8_BAR; PG8_SCHED;
	s_setprio 1
	s_waitcnt lgkmcnt(0)
	v_mfma_f32_16x16x32_bf16 v[60:63], v[134:137], v[182:185], v[60:63]
	v_mfma_f32_16x16x32_bf16 v[56:59], v[150:153], v[182:185], v[56:59]
	v_mfma_f32_16x16x32_bf16 v[48:51], v[134:137], v[190:193], v[48:51]
	v_mfma_f32_16x16x32_bf16 v[40:43], v[150:153], v[190:193], v[40:43]
	v_mfma_f32_16x16x32_bf16 v[32:35], v[134:137], v[198:201], v[32:35]
	v_mfma_f32_16x16x32_bf16 v[24:27], v[150:153], v[198:201], v[24:27]
	v_mfma_f32_16x16x32_bf16 v[16:19], v[134:137], v[206:209], v[16:19]
	v_mfma_f32_16x16x32_bf16 v[8:11], v[150:153], v[206:209], v[8:11]
	v_mfma_f32_16x16x32_bf16 v[60:63], v[146:149], v[186:189], v[60:63]
	v_mfma_f32_16x16x32_bf16 v[56:59], v[154:157], v[186:189], v[56:59]
	v_mfma_f32_16x16x32_bf16 v[48:51], v[146:149], v[194:197], v[48:51]
	v_mfma_f32_16x16x32_bf16 v[40:43], v[154:157], v[194:197], v[40:43]
	v_mfma_f32_16x16x32_bf16 v[32:35], v[146:149], v[202:205], v[32:35]
	v_mfma_f32_16x16x32_bf16 v[24:27], v[154:157], v[202:205], v[24:27]
	v_mfma_f32_16x16x32_bf16 v[16:19], v[146:149], v[210:213], v[16:19]
	v_mfma_f32_16x16x32_bf16 v[8:11], v[154:157], v[210:213], v[8:11]
	s_setprio 0
	s_setprio 1
	v_mfma_f32_16x16x32_bf16 v[52:55], v[158:161], v[182:185], v[52:55]
	v_mfma_f32_16x16x32_bf16 v[44:47], v[174:177], v[182:185], v[44:47]
	v_mfma_f32_16x16x32_bf16 v[36:39], v[158:161], v[190:193], v[36:39]
	v_mfma_f32_16x16x32_bf16 v[28:31], v[174:177], v[190:193], v[28:31]
	v_mfma_f32_16x16x32_bf16 v[20:23], v[158:161], v[198:201], v[20:23]
	v_mfma_f32_16x16x32_bf16 v[12:15], v[174:177], v[198:201], v[12:15]
	v_mfma_f32_16x16x32_bf16 v[4:7], v[158:161], v[206:209], v[4:7]
	v_mfma_f32_16x16x32_bf16 v[0:3], v[174:177], v[206:209], v[0:3]
	v_mfma_f32_16x16x32_bf16 v[52:55], v[162:165], v[186:189], v[52:55]
	v_mfma_f32_16x16x32_bf16 v[44:47], v[178:181], v[186:189], v[44:47]
	v_mfma_f32_16x16x32_bf16 v[36:39], v[162:165], v[194:197], v[36:39]
	v_mfma_f32_16x16x32_bf16 v[28:31], v[178:181], v[194:197], v[28:31]
	v_mfma_f32_16x16x32_bf16 v[20:23], v[162:165], v[202:205], v[20:23]
	v_mfma_f32_16x16x32_bf16 v[12:15], v[178:181], v[202:205], v[12:15]
	v_mfma_f32_16x16x32_bf16 v[4:7], v[162:165], v[210:213], v[4:7]
	v_mfma_f32_16x16x32_bf16 v[0:3], v[178:181], v[210:213], v[0:3]
	s_setprio 0
	s_barrier
	v_add_u32_e32 v140, s64, v141
	ds_read_b128 v[134:137], v140
	ds_read_b128 v[146:149], v140 offset:1024
	ds_read_b128 v[150:153], v140 offset:2048
	ds_read_b128 v[154:157], v140 offset:3072
	v_add_u32_e32 v140, s63, v141
	ds_read_b128 v[158:161], v140
	ds_read_b128 v[162:165], v140 offset:1024
	ds_read_b128 v[174:177], v140 offset:2048
	ds_read_b128 v[178:181], v140 offset:3072
	s_mov_b32 m0, s53
	v_lshl_add_u64 v[216:217], s[40:41], 0, v[128:129]
	ds_read_b128 v[182:185], v145 offset:32768
	ds_read_b128 v[186:189], v145 offset:33792
	ds_read_b128 v[190:193], v145 offset:34816
	ds_read_b128 v[194:197], v145 offset:35840
	ds_read_b128 v[198:201], v145 offset:36864
	ds_read_b128 v[202:205], v145 offset:37888
	ds_read_b128 v[206:209], v145 offset:38912
	ds_read_b128 v[210:213], v145 offset:39936
	global_load_lds_dwordx4 v[216:217], off
	v_lshl_add_u64 v[216:217], s[40:41], 0, v[130:131]
	s_mov_b32 m0, s54
	s_nop 0
	global_load_lds_dwordx4 v[216:217], off
	s_waitcnt vmcnt(8)
	s_waitcnt lgkmcnt(0)
	s_barrier
	s_setprio 1
	s_waitcnt lgkmcnt(0)
	v_mfma_f32_16x16x32_bf16 v[124:127], v[134:137], v[182:185], v[124:127]
	v_mfma_f32_16x16x32_bf16 v[120:123], v[150:153], v[182:185], v[120:123]
	v_mfma_f32_16x16x32_bf16 v[108:111], v[134:137], v[190:193], v[108:111]
	v_mfma_f32_16x16x32_bf16 v[104:107], v[150:153], v[190:193], v[104:107]
	v_mfma_f32_16x16x32_bf16 v[92:95], v[134:137], v[198:201], v[92:95]
	v_mfma_f32_16x16x32_bf16 v[88:91], v[150:153], v[198:201], v[88:91]
	v_mfma_f32_16x16x32_bf16 v[76:79], v[134:137], v[206:209], v[76:79]
	v_mfma_f32_16x16x32_bf16 v[72:75], v[150:153], v[206:209], v[72:75]
	v_mfma_f32_16x16x32_bf16 v[124:127], v[146:149], v[186:189], v[124:127]
	v_mfma_f32_16x16x32_bf16 v[120:123], v[154:157], v[186:189], v[120:123]
	v_mfma_f32_16x16x32_bf16 v[108:111], v[146:149], v[194:197], v[108:111]
	v_mfma_f32_16x16x32_bf16 v[104:107], v[154:157], v[194:197], v[104:107]
	v_mfma_f32_16x16x32_bf16 v[92:95], v[146:149], v[202:205], v[92:95]
	v_mfma_f32_16x16x32_bf16 v[88:91], v[154:157], v[202:205], v[88:91]
	v_mfma_f32_16x16x32_bf16 v[76:79], v[146:149], v[210:213], v[76:79]
	v_mfma_f32_16x16x32_bf16 v[72:75], v[154:157], v[210:213], v[72:75]
	s_setprio 0
	s_setprio 1
	v_mfma_f32_16x16x32_bf16 v[116:119], v[158:161], v[182:185], v[116:119]
	v_mfma_f32_16x16x32_bf16 v[112:115], v[174:177], v[182:185], v[112:115]
	v_mfma_f32_16x16x32_bf16 v[100:103], v[158:161], v[190:193], v[100:103]
	v_mfma_f32_16x16x32_bf16 v[96:99], v[174:177], v[190:193], v[96:99]
	v_mfma_f32_16x16x32_bf16 v[84:87], v[158:161], v[198:201], v[84:87]
	v_mfma_f32_16x16x32_bf16 v[80:83], v[174:177], v[198:201], v[80:83]
	v_mfma_f32_16x16x32_bf16 v[68:71], v[158:161], v[206:209], v[68:71]
	v_mfma_f32_16x16x32_bf16 v[64:67], v[174:177], v[206:209], v[64:67]
	v_mfma_f32_16x16x32_bf16 v[116:119], v[162:165], v[186:189], v[116:119]
	v_mfma_f32_16x16x32_bf16 v[112:115], v[178:181], v[186:189], v[112:115]
	v_mfma_f32_16x16x32_bf16 v[100:103], v[162:165], v[194:197], v[100:103]
	v_mfma_f32_16x16x32_bf16 v[96:99], v[178:181], v[194:197], v[96:99]
	v_mfma_f32_16x16x32_bf16 v[84:87], v[162:165], v[202:205], v[84:87]
	v_mfma_f32_16x16x32_bf16 v[80:83], v[178:181], v[202:205], v[80:83]
	v_mfma_f32_16x16x32_bf16 v[68:71], v[162:165], v[210:213], v[68:71]
	v_mfma_f32_16x16x32_bf16 v[64:67], v[178:181], v[210:213], v[64:67]
	s_setprio 0
	s_barrier
; #define PG8_STAGE(bufoff, gbase, voff) do { _Pragma("unroll") for (int _i = 0; _i < 2; ++_i) \
;         __builtin_amdgcn_global_load_lds((const unsigned*)((const char*)(gbase) + (voff)[_i]), (LAS unsigned*)(lds + (bufoff) + ldsw + _i * 8192), 16, 0, 0); } while (0)
; #define PG8_LDA(dst, b, h) do { _Pragma("unroll") for (int m = 0; m < 4; ++m) _Pragma("unroll") for (int k = 0; k < 2; ++k) dst[m][k] = *(const LAS bf16x8*)(lds + PG8_SA(b, h) + aoff + m * 2048 + k * 1024); } while (0)
; #define PG8_MMA(ai, bj, At, Bt) do { __builtin_amdgcn_s_setprio(1); _Pragma("unroll") for (int k = 0; k < 2; ++k) _Pragma("unroll") for (int m = 0; m < 4; ++m) _Pragma("unroll") for (int n = 0; n < 2; ++n) \
;         acc[ai][bj][m][n] = __builtin_amdgcn_mfma_f32_16x16x32_bf16(Bt[n][k], At[m][k], acc[ai][bj][m][n], 0, 0, 0); __builtin_amdgcn_s_setprio(0); } while (0)
; #define PG8_WAIT_V(n) asm volatile("s_waitcnt vmcnt(" #n ")" ::: "memory")
; #define PG8_WAIT_L(n) asm volatile("s_waitcnt lgkmcnt(" #n ")" ::: "memory")
; #define PG8_BAR __builtin_amdgcn_s_barrier()
; #define PG8_SCHED __builtin_amdgcn_sched_barrier(0)
; template <class Epi, bool ALIGN_EPI>
; __device__ __forceinline__ void gemm_phase(LAS unsigned char* lds, const Gemm g, const StaticOrder& S, const Epi& E, const int tid) {
;     ...
;             PG8_LDA(At, 1, 1); PG8_STAGE(PG8_SB(1, 0), b3, voffB); PG8_STAGE(PG8_SB(1, 1), b3 + hB, voffB); PG8_STAGE(PG8_SA(1, 0), a3, voffA);
;             PG8_WAIT_V(8); PG8_WAIT_L(0); PG8_BAR; PG8_MMA(1, 0, At, B0); PG8_MMA(1, 1, At, B1); PG8_BAR; PG8_SCHED;
;         }
	s_mov_b32 m0, s62
	v_lshl_add_u64 v[138:139], v[138:139], 0, s[92:93]
	ds_read_b128 v[182:185], v145 offset:49152
	ds_read_b128 v[186:189], v145 offset:50176
	ds_read_b128 v[190:193], v145 offset:51200
	ds_read_b128 v[194:197], v145 offset:52224
	ds_read_b128 v[198:201], v145 offset:53248
	ds_read_b128 v[202:205], v145 offset:54272
	ds_read_b128 v[206:209], v145 offset:55296
	ds_read_b128 v[210:213], v145 offset:56320
	global_load_lds_dwordx4 v[138:139], off
	v_lshl_add_u64 v[138:139], v[142:143], 0, s[92:93]
	s_mov_b32 m0, s61
	s_nop 0
	global_load_lds_dwordx4 v[138:139], off
	v_lshl_add_u64 v[138:139], s[38:39], 0, v[168:169]
	s_mov_b32 m0, s70
	s_nop 0
	global_load_lds_dwordx4 v[138:139], off
	v_lshl_add_u64 v[138:139], s[38:39], 0, v[132:133]
	s_mov_b32 m0, s69
	s_nop 0
	global_load_lds_dwordx4 v[138:139], off
	v_lshl_add_u64 v[138:139], v[166:167], 0, s[92:93]
	s_mov_b32 m0, s55
	s_nop 0
	global_load_lds_dwordx4 v[138:139], off
	v_lshl_add_u64 v[138:139], v[214:215], 0, s[92:93]
	s_mov_b32 m0, s56
	s_nop 0
	global_load_lds_dwordx4 v[138:139], off
	s_waitcnt vmcnt(8)
	s_waitcnt lgkmcnt(0)
	s_barrier
	s_setprio 1
	s_waitcnt lgkmcnt(0)
	v_mfma_f32_16x16x32_bf16 v[60:63], v[134:137], v[182:185], v[60:63]
	v_mfma_f32_16x16x32_bf16 v[56:59], v[150:153], v[182:185], v[56:59]
	v_mfma_f32_16x16x32_bf16 v[48:51], v[134:137], v[190:193], v[48:51]
	v_mfma_f32_16x16x32_bf16 v[40:43], v[150:153], v[190:193], v[40:43]
	v_mfma_f32_16x16x32_bf16 v[32:35], v[134:137], v[198:201], v[32:35]
	v_mfma_f32_16x16x32_bf16 v[24:27], v[150:153], v[198:201], v[24:27]
	v_mfma_f32_16x16x32_bf16 v[16:19], v[134:137], v[206:209], v[16:19]
	v_mfma_f32_16x16x32_bf16 v[8:11], v[150:153], v[206:209], v[8:11]
	v_mfma_f32_16x16x32_bf16 v[60:63], v[146:149], v[186:189], v[60:63]
	v_mfma_f32_16x16x32_bf16 v[56:59], v[154:157], v[186:189], v[56:59]
	v_mfma_f32_16x16x32_bf16 v[48:51], v[146:149], v[194:197], v[48:51]
	v_mfma_f32_16x16x32_bf16 v[40:43], v[154:157], v[194:197], v[40:43]
	v_mfma_f32_16x16x32_bf16 v[32:35], v[146:149], v[202:205], v[32:35]
	v_mfma_f32_16x16x32_bf16 v[24:27], v[154:157], v[202:205], v[24:27]
	v_mfma_f32_16x16x32_bf16 v[16:19], v[146:149], v[210:213], v[16:19]
	v_mfma_f32_16x16x32_bf16 v[8:11], v[154:157], v[210:213], v[8:11]
	s_setprio 0
	s_setprio 1
	v_mfma_f32_16x16x32_bf16 v[52:55], v[158:161], v[182:185], v[52:55]
	v_mfma_f32_16x16x32_bf16 v[44:47], v[174:177], v[182:185], v[44:47]
	v_mfma_f32_16x16x32_bf16 v[36:39], v[158:161], v[190:193], v[36:39]
	v_mfma_f32_16x16x32_bf16 v[28:31], v[174:177], v[190:193], v[28:31]
	v_mfma_f32_16x16x32_bf16 v[20:23], v[158:161], v[198:201], v[20:23]
	v_mfma_f32_16x16x32_bf16 v[12:15], v[174:177], v[198:201], v[12:15]
	v_mfma_f32_16x16x32_bf16 v[4:7], v[158:161], v[206:209], v[4:7]
	v_mfma_f32_16x16x32_bf16 v[0:3], v[174:177], v[206:209], v[0:3]
	v_mfma_f32_16x16x32_bf16 v[52:55], v[162:165], v[186:189], v[52:55]
	v_mfma_f32_16x16x32_bf16 v[44:47], v[178:181], v[186:189], v[44:47]
	v_mfma_f32_16x16x32_bf16 v[36:39], v[162:165], v[194:197], v[36:39]
	v_mfma_f32_16x16x32_bf16 v[28:31], v[178:181], v[194:197], v[28:31]
	v_mfma_f32_16x16x32_bf16 v[20:23], v[162:165], v[202:205], v[20:23]
	v_mfma_f32_16x16x32_bf16 v[12:15], v[178:181], v[202:205], v[12:15]
	v_mfma_f32_16x16x32_bf16 v[4:7], v[162:165], v[210:213], v[4:7]
	v_mfma_f32_16x16x32_bf16 v[0:3], v[178:181], v[210:213], v[0:3]
	s_setprio 0
	s_movk_i32 s40, 0x100
	s_andn2_b64 vcc, exec, s[36:37]
	s_mov_b64 s[38:39], -1
	s_mov_b64 s[36:37], 0
	s_barrier
	s_cbranch_vccz .LBB0_379
	v_readlane_b32 s60, v255, 51
	s_and_b64 vcc, exec, s[12:13]
	v_readlane_b32 s61, v255, 52
	s_cbranch_vccz .LBB0_382
	s_barrier
